# E16: MFMA issue order inside each 16-block changed to keep the weight fragment operand stationary for 4 consecutive MFMAs (k,n,m order); bitwise same math; on N5 base
# baseline (speedup 1.0000x reference)
.LBB0_303:
	s_lshl_b32 s18, s91, 20
	s_and_b64 s[8:9], s[34:35], exec
	s_cselect_b32 s8, s18, s94
	s_lshl_b32 s19, s90, 20
	s_and_b64 s[42:43], s[34:35], exec
	s_cselect_b32 s9, s19, s95
	s_add_i32 s94, s94, 0x80080
	s_addk_i32 s95, 0x100
	s_mov_b32 vcc_lo, -2
	ds_read_b128 v[142:145], v136
	ds_read_b128 v[170:173], v136 offset:1024
	ds_read_b128 v[174:177], v136 offset:2048
	ds_read_b128 v[178:181], v136 offset:3072
	ds_read_b128 v[182:185], v137
	ds_read_b128 v[186:189], v137 offset:1024
	ds_read_b128 v[190:193], v137 offset:2048
	ds_read_b128 v[194:197], v137 offset:3072
	s_add_i32 s42, s94, 0xfff80080
	s_cmp_eq_u32 vcc_lo, 28
	s_cselect_b32 s97, s8, s42
	s_cselect_b32 s52, s9, s95
	s_or_b32 vcc_hi, s97, 0x80
	s_mov_b32 m0, s72
	ds_read_b128 v[198:201], v138
	ds_read_b128 v[202:205], v138 offset:1024
	ds_read_b128 v[228:231], v138 offset:2048
	ds_read_b128 v[232:235], v138 offset:3072
	ds_read_b128 v[236:239], v138 offset:4096
	ds_read_b128 v[240:243], v138 offset:5120
	ds_read_b128 v[244:247], v138 offset:6144
	ds_read_b128 v[248:251], v138 offset:7168
	buffer_load_dwordx4 v132, s[60:63], s94 offen lds
	s_mov_b32 m0, s47
	s_nop 0
	buffer_load_dwordx4 v134, s[60:63], s94 offen lds
	s_waitcnt vmcnt(8)
	s_waitcnt lgkmcnt(0)
	s_setprio 1
	s_barrier
	v_mfma_f32_16x16x32_bf16 v[114:117], v[142:145], v[198:201], 0
	v_mfma_f32_16x16x32_bf16 v[106:109], v[142:145], v[228:231], 0
	v_mfma_f32_16x16x32_bf16 v[94:97], v[142:145], v[236:239], 0
	v_mfma_f32_16x16x32_bf16 v[78:81], v[142:145], v[244:247], 0
	v_mfma_f32_16x16x32_bf16 v[110:113], v[174:177], v[198:201], 0
	v_mfma_f32_16x16x32_bf16 v[102:105], v[174:177], v[228:231], 0
	v_mfma_f32_16x16x32_bf16 v[86:89], v[174:177], v[236:239], 0
	v_mfma_f32_16x16x32_bf16 v[70:73], v[174:177], v[244:247], 0
	v_mfma_f32_16x16x32_bf16 v[114:117], v[170:173], v[202:205], v[114:117]
	v_mfma_f32_16x16x32_bf16 v[106:109], v[170:173], v[232:235], v[106:109]
	v_mfma_f32_16x16x32_bf16 v[94:97], v[170:173], v[240:243], v[94:97]
	v_mfma_f32_16x16x32_bf16 v[78:81], v[170:173], v[248:251], v[78:81]
	v_mfma_f32_16x16x32_bf16 v[110:113], v[178:181], v[202:205], v[110:113]
	v_mfma_f32_16x16x32_bf16 v[102:105], v[178:181], v[232:235], v[102:105]
	v_mfma_f32_16x16x32_bf16 v[86:89], v[178:181], v[240:243], v[86:89]
	v_mfma_f32_16x16x32_bf16 v[70:73], v[178:181], v[248:251], v[70:73]
	v_mfma_f32_16x16x32_bf16 v[126:129], v[182:185], v[198:201], 0
	v_mfma_f32_16x16x32_bf16 v[118:121], v[182:185], v[228:231], 0
	v_mfma_f32_16x16x32_bf16 v[90:93], v[182:185], v[236:239], 0
	v_mfma_f32_16x16x32_bf16 v[74:77], v[182:185], v[244:247], 0
	v_mfma_f32_16x16x32_bf16 v[122:125], v[190:193], v[198:201], 0
	v_mfma_f32_16x16x32_bf16 v[98:101], v[190:193], v[228:231], 0
	v_mfma_f32_16x16x32_bf16 v[82:85], v[190:193], v[236:239], 0
	v_mfma_f32_16x16x32_bf16 v[66:69], v[190:193], v[244:247], 0
	v_mfma_f32_16x16x32_bf16 v[126:129], v[186:189], v[202:205], v[126:129]
	v_mfma_f32_16x16x32_bf16 v[118:121], v[186:189], v[232:235], v[118:121]
	v_mfma_f32_16x16x32_bf16 v[90:93], v[186:189], v[240:243], v[90:93]
	v_mfma_f32_16x16x32_bf16 v[74:77], v[186:189], v[248:251], v[74:77]
	v_mfma_f32_16x16x32_bf16 v[122:125], v[194:197], v[202:205], v[122:125]
	v_mfma_f32_16x16x32_bf16 v[98:101], v[194:197], v[232:235], v[98:101]
	v_mfma_f32_16x16x32_bf16 v[82:85], v[194:197], v[240:243], v[82:85]
	v_mfma_f32_16x16x32_bf16 v[66:69], v[194:197], v[248:251], v[66:69]
	s_barrier
	s_setprio 0
	s_mov_b32 m0, s13
	s_mov_b32 s42, s62
	s_mov_b32 s43, s63
	ds_read_b128 v[198:201], v138 offset:16384
	ds_read_b128 v[202:205], v138 offset:17408
	ds_read_b128 v[228:231], v138 offset:18432
	ds_read_b128 v[232:235], v138 offset:19456
	ds_read_b128 v[236:239], v138 offset:20480
	ds_read_b128 v[240:243], v138 offset:21504
	ds_read_b128 v[244:247], v138 offset:22528
	ds_read_b128 v[248:251], v138 offset:23552
	buffer_load_dwordx4 v133, s[40:43], s52 offen lds
	s_mov_b32 m0, s14
	s_add_i32 s96, s52, 0x80000
	buffer_load_dwordx4 v135, s[40:43], s52 offen lds
	s_mov_b32 m0, s15
	s_nop 0
	buffer_load_dwordx4 v133, s[40:43], s96 offen lds
	s_mov_b32 m0, s16
	s_nop 0
	buffer_load_dwordx4 v135, s[40:43], s96 offen lds
	s_mov_b32 m0, s2
	s_nop 0
	buffer_load_dwordx4 v132, s[60:63], s97 offen lds
	s_mov_b32 m0, s21
	s_nop 0
	buffer_load_dwordx4 v134, s[60:63], s97 offen lds
	s_waitcnt vmcnt(8)
	s_waitcnt lgkmcnt(0)
	s_setprio 1
	s_barrier
	v_mfma_f32_16x16x32_bf16 v[62:65], v[142:145], v[198:201], 0
	v_mfma_f32_16x16x32_bf16 v[46:49], v[142:145], v[228:231], 0
	v_mfma_f32_16x16x32_bf16 v[30:33], v[142:145], v[236:239], 0
	v_mfma_f32_16x16x32_bf16 v[14:17], v[142:145], v[244:247], 0
	v_mfma_f32_16x16x32_bf16 v[54:57], v[174:177], v[198:201], 0
	v_mfma_f32_16x16x32_bf16 v[38:41], v[174:177], v[228:231], 0
	v_mfma_f32_16x16x32_bf16 v[22:25], v[174:177], v[236:239], 0
	v_mfma_f32_16x16x32_bf16 v[6:9], v[174:177], v[244:247], 0
	v_mfma_f32_16x16x32_bf16 v[62:65], v[170:173], v[202:205], v[62:65]
	v_mfma_f32_16x16x32_bf16 v[46:49], v[170:173], v[232:235], v[46:49]
	v_mfma_f32_16x16x32_bf16 v[30:33], v[170:173], v[240:243], v[30:33]
	v_mfma_f32_16x16x32_bf16 v[14:17], v[170:173], v[248:251], v[14:17]
	v_mfma_f32_16x16x32_bf16 v[54:57], v[178:181], v[202:205], v[54:57]
	v_mfma_f32_16x16x32_bf16 v[38:41], v[178:181], v[232:235], v[38:41]
	v_mfma_f32_16x16x32_bf16 v[22:25], v[178:181], v[240:243], v[22:25]
	v_mfma_f32_16x16x32_bf16 v[6:9], v[178:181], v[248:251], v[6:9]
	v_mfma_f32_16x16x32_bf16 v[58:61], v[182:185], v[198:201], 0
	v_mfma_f32_16x16x32_bf16 v[42:45], v[182:185], v[228:231], 0
	v_mfma_f32_16x16x32_bf16 v[26:29], v[182:185], v[236:239], 0
	v_mfma_f32_16x16x32_bf16 v[10:13], v[182:185], v[244:247], 0
	v_mfma_f32_16x16x32_bf16 v[50:53], v[190:193], v[198:201], 0
	v_mfma_f32_16x16x32_bf16 v[34:37], v[190:193], v[228:231], 0
	v_mfma_f32_16x16x32_bf16 v[18:21], v[190:193], v[236:239], 0
	v_mfma_f32_16x16x32_bf16 v[2:5], v[190:193], v[244:247], 0
	v_mfma_f32_16x16x32_bf16 v[58:61], v[186:189], v[202:205], v[58:61]
	v_mfma_f32_16x16x32_bf16 v[42:45], v[186:189], v[232:235], v[42:45]
	v_mfma_f32_16x16x32_bf16 v[26:29], v[186:189], v[240:243], v[26:29]
	v_mfma_f32_16x16x32_bf16 v[10:13], v[186:189], v[248:251], v[10:13]
	v_mfma_f32_16x16x32_bf16 v[50:53], v[194:197], v[202:205], v[50:53]
	v_mfma_f32_16x16x32_bf16 v[34:37], v[194:197], v[232:235], v[34:37]
	v_mfma_f32_16x16x32_bf16 v[18:21], v[194:197], v[240:243], v[18:21]
	v_mfma_f32_16x16x32_bf16 v[2:5], v[194:197], v[248:251], v[2:5]
	s_barrier
	s_setprio 0
	ds_read_b128 v[142:145], v139
	ds_read_b128 v[170:173], v139 offset:1024
	ds_read_b128 v[174:177], v139 offset:2048
	ds_read_b128 v[178:181], v139 offset:3072
	ds_read_b128 v[182:185], v140
	ds_read_b128 v[186:189], v140 offset:1024
	ds_read_b128 v[190:193], v140 offset:2048
	ds_read_b128 v[194:197], v140 offset:3072
	s_add_i32 s97, s97, 0x80000
	s_mov_b32 m0, s23
	ds_read_b128 v[198:201], v138 offset:32768
	ds_read_b128 v[202:205], v138 offset:33792
	ds_read_b128 v[228:231], v138 offset:34816
	ds_read_b128 v[232:235], v138 offset:35840
	ds_read_b128 v[236:239], v138 offset:36864
	ds_read_b128 v[240:243], v138 offset:37888
	ds_read_b128 v[244:247], v138 offset:38912
	ds_read_b128 v[248:251], v138 offset:39936
	buffer_load_dwordx4 v132, s[60:63], s97 offen lds
	s_mov_b32 m0, s24
	s_nop 0
	buffer_load_dwordx4 v134, s[60:63], s97 offen lds
	s_waitcnt vmcnt(8)
	s_waitcnt lgkmcnt(0)
	s_setprio 1
	s_barrier
	v_mfma_f32_16x16x32_bf16 v[114:117], v[142:145], v[198:201], v[114:117]
	v_mfma_f32_16x16x32_bf16 v[106:109], v[142:145], v[228:231], v[106:109]
	v_mfma_f32_16x16x32_bf16 v[94:97], v[142:145], v[236:239], v[94:97]
	v_mfma_f32_16x16x32_bf16 v[78:81], v[142:145], v[244:247], v[78:81]
	v_mfma_f32_16x16x32_bf16 v[110:113], v[174:177], v[198:201], v[110:113]
	v_mfma_f32_16x16x32_bf16 v[102:105], v[174:177], v[228:231], v[102:105]
	v_mfma_f32_16x16x32_bf16 v[86:89], v[174:177], v[236:239], v[86:89]
	v_mfma_f32_16x16x32_bf16 v[70:73], v[174:177], v[244:247], v[70:73]
	v_mfma_f32_16x16x32_bf16 v[114:117], v[170:173], v[202:205], v[114:117]
	v_mfma_f32_16x16x32_bf16 v[106:109], v[170:173], v[232:235], v[106:109]
	v_mfma_f32_16x16x32_bf16 v[94:97], v[170:173], v[240:243], v[94:97]
	v_mfma_f32_16x16x32_bf16 v[78:81], v[170:173], v[248:251], v[78:81]
	v_mfma_f32_16x16x32_bf16 v[110:113], v[178:181], v[202:205], v[110:113]
	v_mfma_f32_16x16x32_bf16 v[102:105], v[178:181], v[232:235], v[102:105]
	v_mfma_f32_16x16x32_bf16 v[86:89], v[178:181], v[240:243], v[86:89]
	v_mfma_f32_16x16x32_bf16 v[70:73], v[178:181], v[248:251], v[70:73]
	v_mfma_f32_16x16x32_bf16 v[126:129], v[182:185], v[198:201], v[126:129]
	v_mfma_f32_16x16x32_bf16 v[118:121], v[182:185], v[228:231], v[118:121]
	v_mfma_f32_16x16x32_bf16 v[90:93], v[182:185], v[236:239], v[90:93]
	v_mfma_f32_16x16x32_bf16 v[74:77], v[182:185], v[244:247], v[74:77]
	v_mfma_f32_16x16x32_bf16 v[122:125], v[190:193], v[198:201], v[122:125]
	v_mfma_f32_16x16x32_bf16 v[98:101], v[190:193], v[228:231], v[98:101]
	v_mfma_f32_16x16x32_bf16 v[82:85], v[190:193], v[236:239], v[82:85]
	v_mfma_f32_16x16x32_bf16 v[66:69], v[190:193], v[244:247], v[66:69]
	v_mfma_f32_16x16x32_bf16 v[126:129], v[186:189], v[202:205], v[126:129]
	v_mfma_f32_16x16x32_bf16 v[118:121], v[186:189], v[232:235], v[118:121]
	v_mfma_f32_16x16x32_bf16 v[90:93], v[186:189], v[240:243], v[90:93]
	v_mfma_f32_16x16x32_bf16 v[74:77], v[186:189], v[248:251], v[74:77]
	v_mfma_f32_16x16x32_bf16 v[122:125], v[194:197], v[202:205], v[122:125]
	v_mfma_f32_16x16x32_bf16 v[98:101], v[194:197], v[232:235], v[98:101]
	v_mfma_f32_16x16x32_bf16 v[82:85], v[194:197], v[240:243], v[82:85]
	v_mfma_f32_16x16x32_bf16 v[66:69], v[194:197], v[248:251], v[66:69]
	s_barrier
	s_setprio 0
	s_mov_b32 m0, s31
	s_or_b32 s53, s52, 0x80
	ds_read_b128 v[198:201], v138 offset:49152
	ds_read_b128 v[202:205], v138 offset:50176
	ds_read_b128 v[228:231], v138 offset:51200
	ds_read_b128 v[232:235], v138 offset:52224
	ds_read_b128 v[236:239], v138 offset:53248
	ds_read_b128 v[240:243], v138 offset:54272
	ds_read_b128 v[244:247], v138 offset:55296
	ds_read_b128 v[248:251], v138 offset:56320
	buffer_load_dwordx4 v133, s[40:43], s53 offen lds
	s_mov_b32 m0, s33
	s_add_i32 s52, s52, 0x80080
	buffer_load_dwordx4 v135, s[40:43], s53 offen lds
	s_mov_b32 m0, s68
	s_nop 0
	buffer_load_dwordx4 v133, s[40:43], s52 offen lds
	s_mov_b32 m0, s69
	s_nop 0
	buffer_load_dwordx4 v135, s[40:43], s52 offen lds
	s_mov_b32 m0, s36
	s_nop 0
	buffer_load_dwordx4 v132, s[60:63], vcc_hi offen lds
	s_mov_b32 m0, s37
	s_nop 0
	buffer_load_dwordx4 v134, s[60:63], vcc_hi offen lds
	s_waitcnt vmcnt(8)
	s_waitcnt lgkmcnt(0)
	s_setprio 1
	s_barrier
	v_mfma_f32_16x16x32_bf16 v[62:65], v[142:145], v[198:201], v[62:65]
	v_mfma_f32_16x16x32_bf16 v[46:49], v[142:145], v[228:231], v[46:49]
	v_mfma_f32_16x16x32_bf16 v[30:33], v[142:145], v[236:239], v[30:33]
	v_mfma_f32_16x16x32_bf16 v[14:17], v[142:145], v[244:247], v[14:17]
	v_mfma_f32_16x16x32_bf16 v[54:57], v[174:177], v[198:201], v[54:57]
	v_mfma_f32_16x16x32_bf16 v[38:41], v[174:177], v[228:231], v[38:41]
	v_mfma_f32_16x16x32_bf16 v[22:25], v[174:177], v[236:239], v[22:25]
	v_mfma_f32_16x16x32_bf16 v[6:9], v[174:177], v[244:247], v[6:9]
	v_mfma_f32_16x16x32_bf16 v[62:65], v[170:173], v[202:205], v[62:65]
	v_mfma_f32_16x16x32_bf16 v[46:49], v[170:173], v[232:235], v[46:49]
	v_mfma_f32_16x16x32_bf16 v[30:33], v[170:173], v[240:243], v[30:33]
	v_mfma_f32_16x16x32_bf16 v[14:17], v[170:173], v[248:251], v[14:17]
	v_mfma_f32_16x16x32_bf16 v[54:57], v[178:181], v[202:205], v[54:57]
	v_mfma_f32_16x16x32_bf16 v[38:41], v[178:181], v[232:235], v[38:41]
	v_mfma_f32_16x16x32_bf16 v[22:25], v[178:181], v[240:243], v[22:25]
	v_mfma_f32_16x16x32_bf16 v[6:9], v[178:181], v[248:251], v[6:9]
	v_mfma_f32_16x16x32_bf16 v[58:61], v[182:185], v[198:201], v[58:61]
	v_mfma_f32_16x16x32_bf16 v[42:45], v[182:185], v[228:231], v[42:45]
	v_mfma_f32_16x16x32_bf16 v[26:29], v[182:185], v[236:239], v[26:29]
	v_mfma_f32_16x16x32_bf16 v[10:13], v[182:185], v[244:247], v[10:13]
	v_mfma_f32_16x16x32_bf16 v[50:53], v[190:193], v[198:201], v[50:53]
	v_mfma_f32_16x16x32_bf16 v[34:37], v[190:193], v[228:231], v[34:37]
	v_mfma_f32_16x16x32_bf16 v[18:21], v[190:193], v[236:239], v[18:21]
	v_mfma_f32_16x16x32_bf16 v[2:5], v[190:193], v[244:247], v[2:5]
	v_mfma_f32_16x16x32_bf16 v[58:61], v[186:189], v[202:205], v[58:61]
	v_mfma_f32_16x16x32_bf16 v[42:45], v[186:189], v[232:235], v[42:45]
	v_mfma_f32_16x16x32_bf16 v[26:29], v[186:189], v[240:243], v[26:29]
	v_mfma_f32_16x16x32_bf16 v[10:13], v[186:189], v[248:251], v[10:13]
	v_mfma_f32_16x16x32_bf16 v[50:53], v[194:197], v[202:205], v[50:53]
	v_mfma_f32_16x16x32_bf16 v[34:37], v[194:197], v[232:235], v[34:37]
	v_mfma_f32_16x16x32_bf16 v[18:21], v[194:197], v[240:243], v[18:21]
	v_mfma_f32_16x16x32_bf16 v[2:5], v[194:197], v[248:251], v[2:5]
	s_barrier
	s_setprio 0
	s_add_i32 vcc_lo, vcc_lo, 2
	s_addk_i32 s94, 0x100
	s_addk_i32 s95, 0x100
	s_cmp_gt_u32 vcc_lo, 29
.LBB0_304:
	ds_read_b128 v[142:145], v136
	ds_read_b128 v[170:173], v136 offset:1024
	ds_read_b128 v[174:177], v136 offset:2048
	ds_read_b128 v[178:181], v136 offset:3072
	ds_read_b128 v[182:185], v137
	ds_read_b128 v[186:189], v137 offset:1024
	ds_read_b128 v[190:193], v137 offset:2048
	ds_read_b128 v[194:197], v137 offset:3072
	s_add_i32 s42, s94, 0xfff80080
	s_cmp_eq_u32 vcc_lo, 28
	s_cselect_b32 s97, s8, s42
	s_cselect_b32 s52, s9, s95
	s_or_b32 vcc_hi, s97, 0x80
	s_mov_b32 m0, s72
	ds_read_b128 v[198:201], v138
	ds_read_b128 v[202:205], v138 offset:1024
	ds_read_b128 v[228:231], v138 offset:2048
	ds_read_b128 v[232:235], v138 offset:3072
	ds_read_b128 v[236:239], v138 offset:4096
	ds_read_b128 v[240:243], v138 offset:5120
	ds_read_b128 v[244:247], v138 offset:6144
	ds_read_b128 v[248:251], v138 offset:7168
	buffer_load_dwordx4 v132, s[60:63], s94 offen lds
	s_mov_b32 m0, s47
	s_nop 0
	buffer_load_dwordx4 v134, s[60:63], s94 offen lds
	s_waitcnt vmcnt(8)
	s_waitcnt lgkmcnt(0)
	s_setprio 1
	s_barrier
	v_mfma_f32_16x16x32_bf16 v[114:117], v[142:145], v[198:201], v[114:117]
	v_mfma_f32_16x16x32_bf16 v[106:109], v[142:145], v[228:231], v[106:109]
	v_mfma_f32_16x16x32_bf16 v[94:97], v[142:145], v[236:239], v[94:97]
	v_mfma_f32_16x16x32_bf16 v[78:81], v[142:145], v[244:247], v[78:81]
	v_mfma_f32_16x16x32_bf16 v[110:113], v[174:177], v[198:201], v[110:113]
	v_mfma_f32_16x16x32_bf16 v[102:105], v[174:177], v[228:231], v[102:105]
	v_mfma_f32_16x16x32_bf16 v[86:89], v[174:177], v[236:239], v[86:89]
	v_mfma_f32_16x16x32_bf16 v[70:73], v[174:177], v[244:247], v[70:73]
	v_mfma_f32_16x16x32_bf16 v[114:117], v[170:173], v[202:205], v[114:117]
	v_mfma_f32_16x16x32_bf16 v[106:109], v[170:173], v[232:235], v[106:109]
	v_mfma_f32_16x16x32_bf16 v[94:97], v[170:173], v[240:243], v[94:97]
	v_mfma_f32_16x16x32_bf16 v[78:81], v[170:173], v[248:251], v[78:81]
	v_mfma_f32_16x16x32_bf16 v[110:113], v[178:181], v[202:205], v[110:113]
	v_mfma_f32_16x16x32_bf16 v[102:105], v[178:181], v[232:235], v[102:105]
	v_mfma_f32_16x16x32_bf16 v[86:89], v[178:181], v[240:243], v[86:89]
	v_mfma_f32_16x16x32_bf16 v[70:73], v[178:181], v[248:251], v[70:73]
	v_mfma_f32_16x16x32_bf16 v[126:129], v[182:185], v[198:201], v[126:129]
	v_mfma_f32_16x16x32_bf16 v[118:121], v[182:185], v[228:231], v[118:121]
	v_mfma_f32_16x16x32_bf16 v[90:93], v[182:185], v[236:239], v[90:93]
	v_mfma_f32_16x16x32_bf16 v[74:77], v[182:185], v[244:247], v[74:77]
	v_mfma_f32_16x16x32_bf16 v[122:125], v[190:193], v[198:201], v[122:125]
	v_mfma_f32_16x16x32_bf16 v[98:101], v[190:193], v[228:231], v[98:101]
	v_mfma_f32_16x16x32_bf16 v[82:85], v[190:193], v[236:239], v[82:85]
	v_mfma_f32_16x16x32_bf16 v[66:69], v[190:193], v[244:247], v[66:69]
	v_mfma_f32_16x16x32_bf16 v[126:129], v[186:189], v[202:205], v[126:129]
	v_mfma_f32_16x16x32_bf16 v[118:121], v[186:189], v[232:235], v[118:121]
	v_mfma_f32_16x16x32_bf16 v[90:93], v[186:189], v[240:243], v[90:93]
	v_mfma_f32_16x16x32_bf16 v[74:77], v[186:189], v[248:251], v[74:77]
	v_mfma_f32_16x16x32_bf16 v[122:125], v[194:197], v[202:205], v[122:125]
	v_mfma_f32_16x16x32_bf16 v[98:101], v[194:197], v[232:235], v[98:101]
	v_mfma_f32_16x16x32_bf16 v[82:85], v[194:197], v[240:243], v[82:85]
	v_mfma_f32_16x16x32_bf16 v[66:69], v[194:197], v[248:251], v[66:69]
	s_barrier
	s_setprio 0
	s_mov_b32 m0, s13
	s_mov_b32 s42, s62
	s_mov_b32 s43, s63
	ds_read_b128 v[198:201], v138 offset:16384
	ds_read_b128 v[202:205], v138 offset:17408
	ds_read_b128 v[228:231], v138 offset:18432
	ds_read_b128 v[232:235], v138 offset:19456
	ds_read_b128 v[236:239], v138 offset:20480
	ds_read_b128 v[240:243], v138 offset:21504
	ds_read_b128 v[244:247], v138 offset:22528
	ds_read_b128 v[248:251], v138 offset:23552
	buffer_load_dwordx4 v133, s[40:43], s52 offen lds
	s_mov_b32 m0, s14
	s_add_i32 s96, s52, 0x80000
	buffer_load_dwordx4 v135, s[40:43], s52 offen lds
	s_mov_b32 m0, s15
	s_nop 0
	buffer_load_dwordx4 v133, s[40:43], s96 offen lds
	s_mov_b32 m0, s16
	s_nop 0
	buffer_load_dwordx4 v135, s[40:43], s96 offen lds
	s_mov_b32 m0, s2
	s_nop 0
	buffer_load_dwordx4 v132, s[60:63], s97 offen lds
	s_mov_b32 m0, s21
	s_nop 0
	buffer_load_dwordx4 v134, s[60:63], s97 offen lds
	s_waitcnt vmcnt(8)
	s_waitcnt lgkmcnt(0)
	s_setprio 1
	s_barrier
	v_mfma_f32_16x16x32_bf16 v[62:65], v[142:145], v[198:201], v[62:65]
	v_mfma_f32_16x16x32_bf16 v[46:49], v[142:145], v[228:231], v[46:49]
	v_mfma_f32_16x16x32_bf16 v[30:33], v[142:145], v[236:239], v[30:33]
	v_mfma_f32_16x16x32_bf16 v[14:17], v[142:145], v[244:247], v[14:17]
	v_mfma_f32_16x16x32_bf16 v[54:57], v[174:177], v[198:201], v[54:57]
	v_mfma_f32_16x16x32_bf16 v[38:41], v[174:177], v[228:231], v[38:41]
	v_mfma_f32_16x16x32_bf16 v[22:25], v[174:177], v[236:239], v[22:25]
	v_mfma_f32_16x16x32_bf16 v[6:9], v[174:177], v[244:247], v[6:9]
	v_mfma_f32_16x16x32_bf16 v[62:65], v[170:173], v[202:205], v[62:65]
	v_mfma_f32_16x16x32_bf16 v[46:49], v[170:173], v[232:235], v[46:49]
	v_mfma_f32_16x16x32_bf16 v[30:33], v[170:173], v[240:243], v[30:33]
	v_mfma_f32_16x16x32_bf16 v[14:17], v[170:173], v[248:251], v[14:17]
	v_mfma_f32_16x16x32_bf16 v[54:57], v[178:181], v[202:205], v[54:57]
	v_mfma_f32_16x16x32_bf16 v[38:41], v[178:181], v[232:235], v[38:41]
	v_mfma_f32_16x16x32_bf16 v[22:25], v[178:181], v[240:243], v[22:25]
	v_mfma_f32_16x16x32_bf16 v[6:9], v[178:181], v[248:251], v[6:9]
	v_mfma_f32_16x16x32_bf16 v[58:61], v[182:185], v[198:201], v[58:61]
	v_mfma_f32_16x16x32_bf16 v[42:45], v[182:185], v[228:231], v[42:45]
	v_mfma_f32_16x16x32_bf16 v[26:29], v[182:185], v[236:239], v[26:29]
	v_mfma_f32_16x16x32_bf16 v[10:13], v[182:185], v[244:247], v[10:13]
	v_mfma_f32_16x16x32_bf16 v[50:53], v[190:193], v[198:201], v[50:53]
	v_mfma_f32_16x16x32_bf16 v[34:37], v[190:193], v[228:231], v[34:37]
	v_mfma_f32_16x16x32_bf16 v[18:21], v[190:193], v[236:239], v[18:21]
	v_mfma_f32_16x16x32_bf16 v[2:5], v[190:193], v[244:247], v[2:5]
	v_mfma_f32_16x16x32_bf16 v[58:61], v[186:189], v[202:205], v[58:61]
	v_mfma_f32_16x16x32_bf16 v[42:45], v[186:189], v[232:235], v[42:45]
	v_mfma_f32_16x16x32_bf16 v[26:29], v[186:189], v[240:243], v[26:29]
	v_mfma_f32_16x16x32_bf16 v[10:13], v[186:189], v[248:251], v[10:13]
	v_mfma_f32_16x16x32_bf16 v[50:53], v[194:197], v[202:205], v[50:53]
	v_mfma_f32_16x16x32_bf16 v[34:37], v[194:197], v[232:235], v[34:37]
	v_mfma_f32_16x16x32_bf16 v[18:21], v[194:197], v[240:243], v[18:21]
	v_mfma_f32_16x16x32_bf16 v[2:5], v[194:197], v[248:251], v[2:5]
	s_barrier
	s_setprio 0
	ds_read_b128 v[142:145], v139
	ds_read_b128 v[170:173], v139 offset:1024
	ds_read_b128 v[174:177], v139 offset:2048
	ds_read_b128 v[178:181], v139 offset:3072
	ds_read_b128 v[182:185], v140
	ds_read_b128 v[186:189], v140 offset:1024
	ds_read_b128 v[190:193], v140 offset:2048
	ds_read_b128 v[194:197], v140 offset:3072
	s_add_i32 s97, s97, 0x80000
	s_mov_b32 m0, s23
	ds_read_b128 v[198:201], v138 offset:32768
	ds_read_b128 v[202:205], v138 offset:33792
	ds_read_b128 v[228:231], v138 offset:34816
	ds_read_b128 v[232:235], v138 offset:35840
	ds_read_b128 v[236:239], v138 offset:36864
	ds_read_b128 v[240:243], v138 offset:37888
	ds_read_b128 v[244:247], v138 offset:38912
	ds_read_b128 v[248:251], v138 offset:39936
	buffer_load_dwordx4 v132, s[60:63], s97 offen lds
	s_mov_b32 m0, s24
	s_nop 0
	buffer_load_dwordx4 v134, s[60:63], s97 offen lds
	s_waitcnt vmcnt(8)
	s_waitcnt lgkmcnt(0)
	s_setprio 1
	s_barrier
	v_mfma_f32_16x16x32_bf16 v[114:117], v[142:145], v[198:201], v[114:117]
	v_mfma_f32_16x16x32_bf16 v[106:109], v[142:145], v[228:231], v[106:109]
	v_mfma_f32_16x16x32_bf16 v[94:97], v[142:145], v[236:239], v[94:97]
	v_mfma_f32_16x16x32_bf16 v[78:81], v[142:145], v[244:247], v[78:81]
	v_mfma_f32_16x16x32_bf16 v[110:113], v[174:177], v[198:201], v[110:113]
	v_mfma_f32_16x16x32_bf16 v[102:105], v[174:177], v[228:231], v[102:105]
	v_mfma_f32_16x16x32_bf16 v[86:89], v[174:177], v[236:239], v[86:89]
	v_mfma_f32_16x16x32_bf16 v[70:73], v[174:177], v[244:247], v[70:73]
	v_mfma_f32_16x16x32_bf16 v[114:117], v[170:173], v[202:205], v[114:117]
	v_mfma_f32_16x16x32_bf16 v[106:109], v[170:173], v[232:235], v[106:109]
	v_mfma_f32_16x16x32_bf16 v[94:97], v[170:173], v[240:243], v[94:97]
	v_mfma_f32_16x16x32_bf16 v[78:81], v[170:173], v[248:251], v[78:81]
	v_mfma_f32_16x16x32_bf16 v[110:113], v[178:181], v[202:205], v[110:113]
	v_mfma_f32_16x16x32_bf16 v[102:105], v[178:181], v[232:235], v[102:105]
	v_mfma_f32_16x16x32_bf16 v[86:89], v[178:181], v[240:243], v[86:89]
	v_mfma_f32_16x16x32_bf16 v[70:73], v[178:181], v[248:251], v[70:73]
	v_mfma_f32_16x16x32_bf16 v[126:129], v[182:185], v[198:201], v[126:129]
	v_mfma_f32_16x16x32_bf16 v[118:121], v[182:185], v[228:231], v[118:121]
	v_mfma_f32_16x16x32_bf16 v[90:93], v[182:185], v[236:239], v[90:93]
	v_mfma_f32_16x16x32_bf16 v[74:77], v[182:185], v[244:247], v[74:77]
	v_mfma_f32_16x16x32_bf16 v[122:125], v[190:193], v[198:201], v[122:125]
	v_mfma_f32_16x16x32_bf16 v[98:101], v[190:193], v[228:231], v[98:101]
	v_mfma_f32_16x16x32_bf16 v[82:85], v[190:193], v[236:239], v[82:85]
	v_mfma_f32_16x16x32_bf16 v[66:69], v[190:193], v[244:247], v[66:69]
	v_mfma_f32_16x16x32_bf16 v[126:129], v[186:189], v[202:205], v[126:129]
	v_mfma_f32_16x16x32_bf16 v[118:121], v[186:189], v[232:235], v[118:121]
	v_mfma_f32_16x16x32_bf16 v[90:93], v[186:189], v[240:243], v[90:93]
	v_mfma_f32_16x16x32_bf16 v[74:77], v[186:189], v[248:251], v[74:77]
	v_mfma_f32_16x16x32_bf16 v[122:125], v[194:197], v[202:205], v[122:125]
	v_mfma_f32_16x16x32_bf16 v[98:101], v[194:197], v[232:235], v[98:101]
	v_mfma_f32_16x16x32_bf16 v[82:85], v[194:197], v[240:243], v[82:85]
	v_mfma_f32_16x16x32_bf16 v[66:69], v[194:197], v[248:251], v[66:69]
	s_barrier
	s_setprio 0
	s_mov_b32 m0, s31
	s_or_b32 s53, s52, 0x80
	ds_read_b128 v[198:201], v138 offset:49152
	ds_read_b128 v[202:205], v138 offset:50176
	ds_read_b128 v[228:231], v138 offset:51200
	ds_read_b128 v[232:235], v138 offset:52224
	ds_read_b128 v[236:239], v138 offset:53248
	ds_read_b128 v[240:243], v138 offset:54272
	ds_read_b128 v[244:247], v138 offset:55296
	ds_read_b128 v[248:251], v138 offset:56320
	buffer_load_dwordx4 v133, s[40:43], s53 offen lds
	s_mov_b32 m0, s33
	s_add_i32 s52, s52, 0x80080
	buffer_load_dwordx4 v135, s[40:43], s53 offen lds
	s_mov_b32 m0, s68
	s_nop 0
	buffer_load_dwordx4 v133, s[40:43], s52 offen lds
	s_mov_b32 m0, s69
	s_nop 0
	buffer_load_dwordx4 v135, s[40:43], s52 offen lds
	s_mov_b32 m0, s36
	s_nop 0
	buffer_load_dwordx4 v132, s[60:63], vcc_hi offen lds
	s_mov_b32 m0, s37
	s_nop 0
	buffer_load_dwordx4 v134, s[60:63], vcc_hi offen lds
	s_waitcnt vmcnt(8)
	s_waitcnt lgkmcnt(0)
	s_setprio 1
	s_barrier
	v_mfma_f32_16x16x32_bf16 v[62:65], v[142:145], v[198:201], v[62:65]
	v_mfma_f32_16x16x32_bf16 v[46:49], v[142:145], v[228:231], v[46:49]
	v_mfma_f32_16x16x32_bf16 v[30:33], v[142:145], v[236:239], v[30:33]
	v_mfma_f32_16x16x32_bf16 v[14:17], v[142:145], v[244:247], v[14:17]
	v_mfma_f32_16x16x32_bf16 v[54:57], v[174:177], v[198:201], v[54:57]
	v_mfma_f32_16x16x32_bf16 v[38:41], v[174:177], v[228:231], v[38:41]
	v_mfma_f32_16x16x32_bf16 v[22:25], v[174:177], v[236:239], v[22:25]
	v_mfma_f32_16x16x32_bf16 v[6:9], v[174:177], v[244:247], v[6:9]
	v_mfma_f32_16x16x32_bf16 v[62:65], v[170:173], v[202:205], v[62:65]
	v_mfma_f32_16x16x32_bf16 v[46:49], v[170:173], v[232:235], v[46:49]
	v_mfma_f32_16x16x32_bf16 v[30:33], v[170:173], v[240:243], v[30:33]
	v_mfma_f32_16x16x32_bf16 v[14:17], v[170:173], v[248:251], v[14:17]
	v_mfma_f32_16x16x32_bf16 v[54:57], v[178:181], v[202:205], v[54:57]
	v_mfma_f32_16x16x32_bf16 v[38:41], v[178:181], v[232:235], v[38:41]
	v_mfma_f32_16x16x32_bf16 v[22:25], v[178:181], v[240:243], v[22:25]
	v_mfma_f32_16x16x32_bf16 v[6:9], v[178:181], v[248:251], v[6:9]
	v_mfma_f32_16x16x32_bf16 v[58:61], v[182:185], v[198:201], v[58:61]
	v_mfma_f32_16x16x32_bf16 v[42:45], v[182:185], v[228:231], v[42:45]
	v_mfma_f32_16x16x32_bf16 v[26:29], v[182:185], v[236:239], v[26:29]
	v_mfma_f32_16x16x32_bf16 v[10:13], v[182:185], v[244:247], v[10:13]
	v_mfma_f32_16x16x32_bf16 v[50:53], v[190:193], v[198:201], v[50:53]
	v_mfma_f32_16x16x32_bf16 v[34:37], v[190:193], v[228:231], v[34:37]
	v_mfma_f32_16x16x32_bf16 v[18:21], v[190:193], v[236:239], v[18:21]
	v_mfma_f32_16x16x32_bf16 v[2:5], v[190:193], v[244:247], v[2:5]
	v_mfma_f32_16x16x32_bf16 v[58:61], v[186:189], v[202:205], v[58:61]
	v_mfma_f32_16x16x32_bf16 v[42:45], v[186:189], v[232:235], v[42:45]
	v_mfma_f32_16x16x32_bf16 v[26:29], v[186:189], v[240:243], v[26:29]
	v_mfma_f32_16x16x32_bf16 v[10:13], v[186:189], v[248:251], v[10:13]
	v_mfma_f32_16x16x32_bf16 v[50:53], v[194:197], v[202:205], v[50:53]
	v_mfma_f32_16x16x32_bf16 v[34:37], v[194:197], v[232:235], v[34:37]
	v_mfma_f32_16x16x32_bf16 v[18:21], v[194:197], v[240:243], v[18:21]
	v_mfma_f32_16x16x32_bf16 v[2:5], v[194:197], v[248:251], v[2:5]
	s_barrier
	s_setprio 0
	s_add_i32 vcc_lo, vcc_lo, 2
	s_addk_i32 s94, 0x100
	s_addk_i32 s95, 0x100
	s_cmp_gt_u32 vcc_lo, 29
	s_cbranch_scc0 .LBB0_304
	s_and_b64 vcc, exec, s[48:49]
	s_cbranch_vccz .LBB0_307
	s_barrier

.LBB0_579:
	s_mul_i32 s73, s72, 0x2c0000
	s_and_b64 s[8:9], s[42:43], exec
	s_mul_i32 s84, s71, 0x2c0000
	s_cselect_b32 s8, s73, s21
	s_cselect_b32 s9, s84, s13
	s_addk_i32 s13, 0x100
	s_add_i32 s21, s21, 0xc000
	s_mov_b32 s22, -2
	s_waitcnt lgkmcnt(0)
	v_add_u32_e32 v154, 0x10000, v140
	ds_read_b128 v[132:135], v154
	ds_read_b128 v[142:145], v154 offset:1024
	ds_read_b128 v[170:173], v154 offset:2048
	ds_read_b128 v[174:177], v154 offset:3072
	v_add_u32_e32 v154, 0x14000, v140
	ds_read_b128 v[178:181], v154
	ds_read_b128 v[182:185], v154 offset:1024
	ds_read_b128 v[186:189], v154 offset:2048
	ds_read_b128 v[190:193], v154 offset:3072
	s_add_i32 s23, s21, 0x4000
	s_cmpk_eq_i32 s22, 0x54
	s_cselect_b32 s27, s8, s23
	s_cselect_b32 s26, s9, s13
	s_or_b32 s23, s27, 0x8000
	s_mov_b32 m0, s68
	ds_read_b128 v[194:197], v141
	ds_read_b128 v[198:201], v141 offset:1024
	ds_read_b128 v[202:205], v141 offset:2048
	ds_read_b128 v[228:231], v141 offset:3072
	ds_read_b128 v[232:235], v141 offset:4096
	ds_read_b128 v[236:239], v141 offset:5120
	ds_read_b128 v[240:243], v141 offset:6144
	ds_read_b128 v[244:247], v141 offset:7168
	buffer_load_dwordx4 v136, s[60:63], s21 offen lds
	s_mov_b32 m0, s70
	s_nop 0
	buffer_load_dwordx4 v138, s[60:63], s21 offen lds
	s_waitcnt vmcnt(8)
	s_waitcnt lgkmcnt(0)
	s_setprio 1
	s_barrier
	v_mfma_f32_16x16x32_bf16 v[126:129], v[132:135], v[194:197], 0
	v_mfma_f32_16x16x32_bf16 v[118:121], v[132:135], v[202:205], 0
	v_mfma_f32_16x16x32_bf16 v[94:97], v[132:135], v[232:235], 0
	v_mfma_f32_16x16x32_bf16 v[78:81], v[132:135], v[240:243], 0
	v_mfma_f32_16x16x32_bf16 v[106:109], v[170:173], v[194:197], 0
	v_mfma_f32_16x16x32_bf16 v[114:117], v[170:173], v[202:205], 0
	v_mfma_f32_16x16x32_bf16 v[90:93], v[170:173], v[232:235], 0
	v_mfma_f32_16x16x32_bf16 v[74:77], v[170:173], v[240:243], 0
	v_mfma_f32_16x16x32_bf16 v[126:129], v[142:145], v[198:201], v[126:129]
	v_mfma_f32_16x16x32_bf16 v[118:121], v[142:145], v[228:231], v[118:121]
	v_mfma_f32_16x16x32_bf16 v[94:97], v[142:145], v[236:239], v[94:97]
	v_mfma_f32_16x16x32_bf16 v[78:81], v[142:145], v[244:247], v[78:81]
	v_mfma_f32_16x16x32_bf16 v[106:109], v[174:177], v[198:201], v[106:109]
	v_mfma_f32_16x16x32_bf16 v[114:117], v[174:177], v[228:231], v[114:117]
	v_mfma_f32_16x16x32_bf16 v[90:93], v[174:177], v[236:239], v[90:93]
	v_mfma_f32_16x16x32_bf16 v[74:77], v[174:177], v[244:247], v[74:77]
	v_mfma_f32_16x16x32_bf16 v[122:125], v[178:181], v[194:197], 0
	v_mfma_f32_16x16x32_bf16 v[102:105], v[178:181], v[202:205], 0
	v_mfma_f32_16x16x32_bf16 v[86:89], v[178:181], v[232:235], 0
	v_mfma_f32_16x16x32_bf16 v[70:73], v[178:181], v[240:243], 0
	v_mfma_f32_16x16x32_bf16 v[110:113], v[186:189], v[194:197], 0
	v_mfma_f32_16x16x32_bf16 v[98:101], v[186:189], v[202:205], 0
	v_mfma_f32_16x16x32_bf16 v[82:85], v[186:189], v[232:235], 0
	v_mfma_f32_16x16x32_bf16 v[66:69], v[186:189], v[240:243], 0
	v_mfma_f32_16x16x32_bf16 v[122:125], v[182:185], v[198:201], v[122:125]
	v_mfma_f32_16x16x32_bf16 v[102:105], v[182:185], v[228:231], v[102:105]
	v_mfma_f32_16x16x32_bf16 v[86:89], v[182:185], v[236:239], v[86:89]
	v_mfma_f32_16x16x32_bf16 v[70:73], v[182:185], v[244:247], v[70:73]
	v_mfma_f32_16x16x32_bf16 v[110:113], v[190:193], v[198:201], v[110:113]
	v_mfma_f32_16x16x32_bf16 v[98:101], v[190:193], v[228:231], v[98:101]
	v_mfma_f32_16x16x32_bf16 v[82:85], v[190:193], v[236:239], v[82:85]
	v_mfma_f32_16x16x32_bf16 v[66:69], v[190:193], v[244:247], v[66:69]
	s_barrier
	s_setprio 0
	s_mov_b32 m0, s15
	s_mov_b32 s46, s62
	s_mov_b32 s47, s63
	ds_read_b128 v[194:197], v141 offset:16384
	ds_read_b128 v[198:201], v141 offset:17408
	ds_read_b128 v[202:205], v141 offset:18432
	ds_read_b128 v[228:231], v141 offset:19456
	ds_read_b128 v[232:235], v141 offset:20480
	ds_read_b128 v[236:239], v141 offset:21504
	ds_read_b128 v[240:243], v141 offset:22528
	ds_read_b128 v[244:247], v141 offset:23552
	buffer_load_dwordx4 v137, s[44:47], s26 offen lds
	s_mov_b32 m0, s16
	s_add_i32 s52, s26, 0x160000
	buffer_load_dwordx4 v139, s[44:47], s26 offen lds
	s_mov_b32 m0, s18
	s_nop 0
	buffer_load_dwordx4 v137, s[44:47], s52 offen lds
	s_mov_b32 m0, s19
	s_nop 0
	buffer_load_dwordx4 v139, s[44:47], s52 offen lds
	s_mov_b32 m0, s14
	s_nop 0
	buffer_load_dwordx4 v136, s[60:63], s27 offen lds
	s_mov_b32 m0, s24
	s_nop 0
	buffer_load_dwordx4 v138, s[60:63], s27 offen lds
	s_waitcnt vmcnt(8)
	s_waitcnt lgkmcnt(0)
	s_setprio 1
	s_barrier
	v_mfma_f32_16x16x32_bf16 v[62:65], v[132:135], v[194:197], 0
	v_mfma_f32_16x16x32_bf16 v[46:49], v[132:135], v[202:205], 0
	v_mfma_f32_16x16x32_bf16 v[30:33], v[132:135], v[232:235], 0
	v_mfma_f32_16x16x32_bf16 v[14:17], v[132:135], v[240:243], 0
	v_mfma_f32_16x16x32_bf16 v[58:61], v[170:173], v[194:197], 0
	v_mfma_f32_16x16x32_bf16 v[42:45], v[170:173], v[202:205], 0
	v_mfma_f32_16x16x32_bf16 v[26:29], v[170:173], v[232:235], 0
	v_mfma_f32_16x16x32_bf16 v[10:13], v[170:173], v[240:243], 0
	v_mfma_f32_16x16x32_bf16 v[62:65], v[142:145], v[198:201], v[62:65]
	v_mfma_f32_16x16x32_bf16 v[46:49], v[142:145], v[228:231], v[46:49]
	v_mfma_f32_16x16x32_bf16 v[30:33], v[142:145], v[236:239], v[30:33]
	v_mfma_f32_16x16x32_bf16 v[14:17], v[142:145], v[244:247], v[14:17]
	v_mfma_f32_16x16x32_bf16 v[58:61], v[174:177], v[198:201], v[58:61]
	v_mfma_f32_16x16x32_bf16 v[42:45], v[174:177], v[228:231], v[42:45]
	v_mfma_f32_16x16x32_bf16 v[26:29], v[174:177], v[236:239], v[26:29]
	v_mfma_f32_16x16x32_bf16 v[10:13], v[174:177], v[244:247], v[10:13]
	v_mfma_f32_16x16x32_bf16 v[54:57], v[178:181], v[194:197], 0
	v_mfma_f32_16x16x32_bf16 v[38:41], v[178:181], v[202:205], 0
	v_mfma_f32_16x16x32_bf16 v[22:25], v[178:181], v[232:235], 0
	v_mfma_f32_16x16x32_bf16 v[6:9], v[178:181], v[240:243], 0
	v_mfma_f32_16x16x32_bf16 v[50:53], v[186:189], v[194:197], 0
	v_mfma_f32_16x16x32_bf16 v[34:37], v[186:189], v[202:205], 0
	v_mfma_f32_16x16x32_bf16 v[18:21], v[186:189], v[232:235], 0
	v_mfma_f32_16x16x32_bf16 v[2:5], v[186:189], v[240:243], 0
	v_mfma_f32_16x16x32_bf16 v[54:57], v[182:185], v[198:201], v[54:57]
	v_mfma_f32_16x16x32_bf16 v[38:41], v[182:185], v[228:231], v[38:41]
	v_mfma_f32_16x16x32_bf16 v[22:25], v[182:185], v[236:239], v[22:25]
	v_mfma_f32_16x16x32_bf16 v[6:9], v[182:185], v[244:247], v[6:9]
	v_mfma_f32_16x16x32_bf16 v[50:53], v[190:193], v[198:201], v[50:53]
	v_mfma_f32_16x16x32_bf16 v[34:37], v[190:193], v[228:231], v[34:37]
	v_mfma_f32_16x16x32_bf16 v[18:21], v[190:193], v[236:239], v[18:21]
	v_mfma_f32_16x16x32_bf16 v[2:5], v[190:193], v[244:247], v[2:5]
	s_barrier
	s_setprio 0
	v_add_u32_e32 v154, 0x18000, v140
	ds_read_b128 v[132:135], v154
	ds_read_b128 v[142:145], v154 offset:1024
	ds_read_b128 v[170:173], v154 offset:2048
	ds_read_b128 v[174:177], v154 offset:3072
	v_add_u32_e32 v154, 0x1c000, v140
	ds_read_b128 v[178:181], v154
	ds_read_b128 v[182:185], v154 offset:1024
	ds_read_b128 v[186:189], v154 offset:2048
	ds_read_b128 v[190:193], v154 offset:3072
	s_bitset1_b32 s27, 14
	s_mov_b32 m0, s25
	ds_read_b128 v[194:197], v141 offset:32768
	ds_read_b128 v[198:201], v141 offset:33792
	ds_read_b128 v[202:205], v141 offset:34816
	ds_read_b128 v[228:231], v141 offset:35840
	ds_read_b128 v[232:235], v141 offset:36864
	ds_read_b128 v[236:239], v141 offset:37888
	ds_read_b128 v[240:243], v141 offset:38912
	ds_read_b128 v[244:247], v141 offset:39936
	buffer_load_dwordx4 v136, s[60:63], s27 offen lds
	s_mov_b32 m0, s30
	s_nop 0
	buffer_load_dwordx4 v138, s[60:63], s27 offen lds
	s_waitcnt vmcnt(8)
	s_waitcnt lgkmcnt(0)
	s_setprio 1
	s_barrier
	v_mfma_f32_16x16x32_bf16 v[126:129], v[132:135], v[194:197], v[126:129]
	v_mfma_f32_16x16x32_bf16 v[118:121], v[132:135], v[202:205], v[118:121]
	v_mfma_f32_16x16x32_bf16 v[94:97], v[132:135], v[232:235], v[94:97]
	v_mfma_f32_16x16x32_bf16 v[78:81], v[132:135], v[240:243], v[78:81]
	v_mfma_f32_16x16x32_bf16 v[106:109], v[170:173], v[194:197], v[106:109]
	v_mfma_f32_16x16x32_bf16 v[114:117], v[170:173], v[202:205], v[114:117]
	v_mfma_f32_16x16x32_bf16 v[90:93], v[170:173], v[232:235], v[90:93]
	v_mfma_f32_16x16x32_bf16 v[74:77], v[170:173], v[240:243], v[74:77]
	v_mfma_f32_16x16x32_bf16 v[126:129], v[142:145], v[198:201], v[126:129]
	v_mfma_f32_16x16x32_bf16 v[118:121], v[142:145], v[228:231], v[118:121]
	v_mfma_f32_16x16x32_bf16 v[94:97], v[142:145], v[236:239], v[94:97]
	v_mfma_f32_16x16x32_bf16 v[78:81], v[142:145], v[244:247], v[78:81]
	v_mfma_f32_16x16x32_bf16 v[106:109], v[174:177], v[198:201], v[106:109]
	v_mfma_f32_16x16x32_bf16 v[114:117], v[174:177], v[228:231], v[114:117]
	v_mfma_f32_16x16x32_bf16 v[90:93], v[174:177], v[236:239], v[90:93]
	v_mfma_f32_16x16x32_bf16 v[74:77], v[174:177], v[244:247], v[74:77]
	v_mfma_f32_16x16x32_bf16 v[122:125], v[178:181], v[194:197], v[122:125]
	v_mfma_f32_16x16x32_bf16 v[102:105], v[178:181], v[202:205], v[102:105]
	v_mfma_f32_16x16x32_bf16 v[86:89], v[178:181], v[232:235], v[86:89]
	v_mfma_f32_16x16x32_bf16 v[70:73], v[178:181], v[240:243], v[70:73]
	v_mfma_f32_16x16x32_bf16 v[110:113], v[186:189], v[194:197], v[110:113]
	v_mfma_f32_16x16x32_bf16 v[98:101], v[186:189], v[202:205], v[98:101]
	v_mfma_f32_16x16x32_bf16 v[82:85], v[186:189], v[232:235], v[82:85]
	v_mfma_f32_16x16x32_bf16 v[66:69], v[186:189], v[240:243], v[66:69]
	v_mfma_f32_16x16x32_bf16 v[122:125], v[182:185], v[198:201], v[122:125]
	v_mfma_f32_16x16x32_bf16 v[102:105], v[182:185], v[228:231], v[102:105]
	v_mfma_f32_16x16x32_bf16 v[86:89], v[182:185], v[236:239], v[86:89]
	v_mfma_f32_16x16x32_bf16 v[70:73], v[182:185], v[244:247], v[70:73]
	v_mfma_f32_16x16x32_bf16 v[110:113], v[190:193], v[198:201], v[110:113]
	v_mfma_f32_16x16x32_bf16 v[98:101], v[190:193], v[228:231], v[98:101]
	v_mfma_f32_16x16x32_bf16 v[82:85], v[190:193], v[236:239], v[82:85]
	v_mfma_f32_16x16x32_bf16 v[66:69], v[190:193], v[244:247], v[66:69]
	s_barrier
	s_setprio 0
	s_mov_b32 m0, s36
	s_or_b32 s27, s26, 0x80
	ds_read_b128 v[194:197], v141 offset:49152
	ds_read_b128 v[198:201], v141 offset:50176
	ds_read_b128 v[202:205], v141 offset:51200
	ds_read_b128 v[228:231], v141 offset:52224
	ds_read_b128 v[232:235], v141 offset:53248
	ds_read_b128 v[236:239], v141 offset:54272
	ds_read_b128 v[240:243], v141 offset:55296
	ds_read_b128 v[244:247], v141 offset:56320
	buffer_load_dwordx4 v137, s[44:47], s27 offen lds
	s_mov_b32 m0, s37
	s_add_i32 s26, s26, 0x160080
	buffer_load_dwordx4 v139, s[44:47], s27 offen lds
	s_mov_b32 m0, s66
	s_nop 0
	buffer_load_dwordx4 v137, s[44:47], s26 offen lds
	s_mov_b32 m0, s67
	s_nop 0
	buffer_load_dwordx4 v139, s[44:47], s26 offen lds
	s_mov_b32 m0, s48
	s_nop 0
	buffer_load_dwordx4 v136, s[60:63], s23 offen lds
	s_mov_b32 m0, s49
	s_nop 0
	buffer_load_dwordx4 v138, s[60:63], s23 offen lds
	s_waitcnt vmcnt(8)
	s_waitcnt lgkmcnt(0)
	s_setprio 1
	s_barrier
	v_mfma_f32_16x16x32_bf16 v[62:65], v[132:135], v[194:197], v[62:65]
	v_mfma_f32_16x16x32_bf16 v[46:49], v[132:135], v[202:205], v[46:49]
	v_mfma_f32_16x16x32_bf16 v[30:33], v[132:135], v[232:235], v[30:33]
	v_mfma_f32_16x16x32_bf16 v[14:17], v[132:135], v[240:243], v[14:17]
	v_mfma_f32_16x16x32_bf16 v[58:61], v[170:173], v[194:197], v[58:61]
	v_mfma_f32_16x16x32_bf16 v[42:45], v[170:173], v[202:205], v[42:45]
	v_mfma_f32_16x16x32_bf16 v[26:29], v[170:173], v[232:235], v[26:29]
	v_mfma_f32_16x16x32_bf16 v[10:13], v[170:173], v[240:243], v[10:13]
	v_mfma_f32_16x16x32_bf16 v[62:65], v[142:145], v[198:201], v[62:65]
	v_mfma_f32_16x16x32_bf16 v[46:49], v[142:145], v[228:231], v[46:49]
	v_mfma_f32_16x16x32_bf16 v[30:33], v[142:145], v[236:239], v[30:33]
	v_mfma_f32_16x16x32_bf16 v[14:17], v[142:145], v[244:247], v[14:17]
	v_mfma_f32_16x16x32_bf16 v[58:61], v[174:177], v[198:201], v[58:61]
	v_mfma_f32_16x16x32_bf16 v[42:45], v[174:177], v[228:231], v[42:45]
	v_mfma_f32_16x16x32_bf16 v[26:29], v[174:177], v[236:239], v[26:29]
	v_mfma_f32_16x16x32_bf16 v[10:13], v[174:177], v[244:247], v[10:13]
	v_mfma_f32_16x16x32_bf16 v[54:57], v[178:181], v[194:197], v[54:57]
	v_mfma_f32_16x16x32_bf16 v[38:41], v[178:181], v[202:205], v[38:41]
	v_mfma_f32_16x16x32_bf16 v[22:25], v[178:181], v[232:235], v[22:25]
	v_mfma_f32_16x16x32_bf16 v[6:9], v[178:181], v[240:243], v[6:9]
	v_mfma_f32_16x16x32_bf16 v[50:53], v[186:189], v[194:197], v[50:53]
	v_mfma_f32_16x16x32_bf16 v[34:37], v[186:189], v[202:205], v[34:37]
	v_mfma_f32_16x16x32_bf16 v[18:21], v[186:189], v[232:235], v[18:21]
	v_mfma_f32_16x16x32_bf16 v[2:5], v[186:189], v[240:243], v[2:5]
	v_mfma_f32_16x16x32_bf16 v[54:57], v[182:185], v[198:201], v[54:57]
	v_mfma_f32_16x16x32_bf16 v[38:41], v[182:185], v[228:231], v[38:41]
	v_mfma_f32_16x16x32_bf16 v[22:25], v[182:185], v[236:239], v[22:25]
	v_mfma_f32_16x16x32_bf16 v[6:9], v[182:185], v[244:247], v[6:9]
	v_mfma_f32_16x16x32_bf16 v[50:53], v[190:193], v[198:201], v[50:53]
	v_mfma_f32_16x16x32_bf16 v[34:37], v[190:193], v[228:231], v[34:37]
	v_mfma_f32_16x16x32_bf16 v[18:21], v[190:193], v[236:239], v[18:21]
	v_mfma_f32_16x16x32_bf16 v[2:5], v[190:193], v[244:247], v[2:5]
	s_barrier
	s_setprio 0
	s_addk_i32 s13, 0x100
	s_add_i32 s22, s22, 2
	s_add_i32 s21, s21, 0x10000
	s_cmpk_gt_u32 s22, 0x55
.LBB0_580:
	v_add_u32_e32 v154, 0x10000, v140
	ds_read_b128 v[132:135], v154
	ds_read_b128 v[142:145], v154 offset:1024
	ds_read_b128 v[170:173], v154 offset:2048
	ds_read_b128 v[174:177], v154 offset:3072
	v_add_u32_e32 v154, 0x14000, v140
	ds_read_b128 v[178:181], v154
	ds_read_b128 v[182:185], v154 offset:1024
	ds_read_b128 v[186:189], v154 offset:2048
	ds_read_b128 v[190:193], v154 offset:3072
	s_add_i32 s23, s21, 0x4000
	s_cmpk_eq_i32 s22, 0x54
	s_cselect_b32 s27, s8, s23
	s_cselect_b32 s26, s9, s13
	s_or_b32 s23, s27, 0x8000
	s_mov_b32 m0, s68
	ds_read_b128 v[194:197], v141
	ds_read_b128 v[198:201], v141 offset:1024
	ds_read_b128 v[202:205], v141 offset:2048
	ds_read_b128 v[228:231], v141 offset:3072
	ds_read_b128 v[232:235], v141 offset:4096
	ds_read_b128 v[236:239], v141 offset:5120
	ds_read_b128 v[240:243], v141 offset:6144
	ds_read_b128 v[244:247], v141 offset:7168
	buffer_load_dwordx4 v136, s[60:63], s21 offen lds
	s_mov_b32 m0, s70
	s_nop 0
	buffer_load_dwordx4 v138, s[60:63], s21 offen lds
	s_waitcnt vmcnt(8)
	s_waitcnt lgkmcnt(0)
	s_setprio 1
	s_barrier
	v_mfma_f32_16x16x32_bf16 v[126:129], v[132:135], v[194:197], v[126:129]
	v_mfma_f32_16x16x32_bf16 v[118:121], v[132:135], v[202:205], v[118:121]
	v_mfma_f32_16x16x32_bf16 v[94:97], v[132:135], v[232:235], v[94:97]
	v_mfma_f32_16x16x32_bf16 v[78:81], v[132:135], v[240:243], v[78:81]
	v_mfma_f32_16x16x32_bf16 v[106:109], v[170:173], v[194:197], v[106:109]
	v_mfma_f32_16x16x32_bf16 v[114:117], v[170:173], v[202:205], v[114:117]
	v_mfma_f32_16x16x32_bf16 v[90:93], v[170:173], v[232:235], v[90:93]
	v_mfma_f32_16x16x32_bf16 v[74:77], v[170:173], v[240:243], v[74:77]
	v_mfma_f32_16x16x32_bf16 v[126:129], v[142:145], v[198:201], v[126:129]
	v_mfma_f32_16x16x32_bf16 v[118:121], v[142:145], v[228:231], v[118:121]
	v_mfma_f32_16x16x32_bf16 v[94:97], v[142:145], v[236:239], v[94:97]
	v_mfma_f32_16x16x32_bf16 v[78:81], v[142:145], v[244:247], v[78:81]
	v_mfma_f32_16x16x32_bf16 v[106:109], v[174:177], v[198:201], v[106:109]
	v_mfma_f32_16x16x32_bf16 v[114:117], v[174:177], v[228:231], v[114:117]
	v_mfma_f32_16x16x32_bf16 v[90:93], v[174:177], v[236:239], v[90:93]
	v_mfma_f32_16x16x32_bf16 v[74:77], v[174:177], v[244:247], v[74:77]
	v_mfma_f32_16x16x32_bf16 v[122:125], v[178:181], v[194:197], v[122:125]
	v_mfma_f32_16x16x32_bf16 v[102:105], v[178:181], v[202:205], v[102:105]
	v_mfma_f32_16x16x32_bf16 v[86:89], v[178:181], v[232:235], v[86:89]
	v_mfma_f32_16x16x32_bf16 v[70:73], v[178:181], v[240:243], v[70:73]
	v_mfma_f32_16x16x32_bf16 v[110:113], v[186:189], v[194:197], v[110:113]
	v_mfma_f32_16x16x32_bf16 v[98:101], v[186:189], v[202:205], v[98:101]
	v_mfma_f32_16x16x32_bf16 v[82:85], v[186:189], v[232:235], v[82:85]
	v_mfma_f32_16x16x32_bf16 v[66:69], v[186:189], v[240:243], v[66:69]
	v_mfma_f32_16x16x32_bf16 v[122:125], v[182:185], v[198:201], v[122:125]
	v_mfma_f32_16x16x32_bf16 v[102:105], v[182:185], v[228:231], v[102:105]
	v_mfma_f32_16x16x32_bf16 v[86:89], v[182:185], v[236:239], v[86:89]
	v_mfma_f32_16x16x32_bf16 v[70:73], v[182:185], v[244:247], v[70:73]
	v_mfma_f32_16x16x32_bf16 v[110:113], v[190:193], v[198:201], v[110:113]
	v_mfma_f32_16x16x32_bf16 v[98:101], v[190:193], v[228:231], v[98:101]
	v_mfma_f32_16x16x32_bf16 v[82:85], v[190:193], v[236:239], v[82:85]
	v_mfma_f32_16x16x32_bf16 v[66:69], v[190:193], v[244:247], v[66:69]
	s_barrier
	s_setprio 0
	s_mov_b32 m0, s15
	s_mov_b32 s46, s62
	s_mov_b32 s47, s63
	ds_read_b128 v[194:197], v141 offset:16384
	ds_read_b128 v[198:201], v141 offset:17408
	ds_read_b128 v[202:205], v141 offset:18432
	ds_read_b128 v[228:231], v141 offset:19456
	ds_read_b128 v[232:235], v141 offset:20480
	ds_read_b128 v[236:239], v141 offset:21504
	ds_read_b128 v[240:243], v141 offset:22528
	ds_read_b128 v[244:247], v141 offset:23552
	buffer_load_dwordx4 v137, s[44:47], s26 offen lds
	s_mov_b32 m0, s16
	s_add_i32 s52, s26, 0x160000
	buffer_load_dwordx4 v139, s[44:47], s26 offen lds
	s_mov_b32 m0, s18
	s_nop 0
	buffer_load_dwordx4 v137, s[44:47], s52 offen lds
	s_mov_b32 m0, s19
	s_nop 0
	buffer_load_dwordx4 v139, s[44:47], s52 offen lds
	s_mov_b32 m0, s14
	s_nop 0
	buffer_load_dwordx4 v136, s[60:63], s27 offen lds
	s_mov_b32 m0, s24
	s_nop 0
	buffer_load_dwordx4 v138, s[60:63], s27 offen lds
	s_waitcnt vmcnt(8)
	s_waitcnt lgkmcnt(0)
	s_setprio 1
	s_barrier
	v_mfma_f32_16x16x32_bf16 v[62:65], v[132:135], v[194:197], v[62:65]
	v_mfma_f32_16x16x32_bf16 v[46:49], v[132:135], v[202:205], v[46:49]
	v_mfma_f32_16x16x32_bf16 v[30:33], v[132:135], v[232:235], v[30:33]
	v_mfma_f32_16x16x32_bf16 v[14:17], v[132:135], v[240:243], v[14:17]
	v_mfma_f32_16x16x32_bf16 v[58:61], v[170:173], v[194:197], v[58:61]
	v_mfma_f32_16x16x32_bf16 v[42:45], v[170:173], v[202:205], v[42:45]
	v_mfma_f32_16x16x32_bf16 v[26:29], v[170:173], v[232:235], v[26:29]
	v_mfma_f32_16x16x32_bf16 v[10:13], v[170:173], v[240:243], v[10:13]
	v_mfma_f32_16x16x32_bf16 v[62:65], v[142:145], v[198:201], v[62:65]
	v_mfma_f32_16x16x32_bf16 v[46:49], v[142:145], v[228:231], v[46:49]
	v_mfma_f32_16x16x32_bf16 v[30:33], v[142:145], v[236:239], v[30:33]
	v_mfma_f32_16x16x32_bf16 v[14:17], v[142:145], v[244:247], v[14:17]
	v_mfma_f32_16x16x32_bf16 v[58:61], v[174:177], v[198:201], v[58:61]
	v_mfma_f32_16x16x32_bf16 v[42:45], v[174:177], v[228:231], v[42:45]
	v_mfma_f32_16x16x32_bf16 v[26:29], v[174:177], v[236:239], v[26:29]
	v_mfma_f32_16x16x32_bf16 v[10:13], v[174:177], v[244:247], v[10:13]
	v_mfma_f32_16x16x32_bf16 v[54:57], v[178:181], v[194:197], v[54:57]
	v_mfma_f32_16x16x32_bf16 v[38:41], v[178:181], v[202:205], v[38:41]
	v_mfma_f32_16x16x32_bf16 v[22:25], v[178:181], v[232:235], v[22:25]
	v_mfma_f32_16x16x32_bf16 v[6:9], v[178:181], v[240:243], v[6:9]
	v_mfma_f32_16x16x32_bf16 v[50:53], v[186:189], v[194:197], v[50:53]
	v_mfma_f32_16x16x32_bf16 v[34:37], v[186:189], v[202:205], v[34:37]
	v_mfma_f32_16x16x32_bf16 v[18:21], v[186:189], v[232:235], v[18:21]
	v_mfma_f32_16x16x32_bf16 v[2:5], v[186:189], v[240:243], v[2:5]
	v_mfma_f32_16x16x32_bf16 v[54:57], v[182:185], v[198:201], v[54:57]
	v_mfma_f32_16x16x32_bf16 v[38:41], v[182:185], v[228:231], v[38:41]
	v_mfma_f32_16x16x32_bf16 v[22:25], v[182:185], v[236:239], v[22:25]
	v_mfma_f32_16x16x32_bf16 v[6:9], v[182:185], v[244:247], v[6:9]
	v_mfma_f32_16x16x32_bf16 v[50:53], v[190:193], v[198:201], v[50:53]
	v_mfma_f32_16x16x32_bf16 v[34:37], v[190:193], v[228:231], v[34:37]
	v_mfma_f32_16x16x32_bf16 v[18:21], v[190:193], v[236:239], v[18:21]
	v_mfma_f32_16x16x32_bf16 v[2:5], v[190:193], v[244:247], v[2:5]
	s_barrier
	s_setprio 0
	v_add_u32_e32 v154, 0x18000, v140
	ds_read_b128 v[132:135], v154
	ds_read_b128 v[142:145], v154 offset:1024
	ds_read_b128 v[170:173], v154 offset:2048
	ds_read_b128 v[174:177], v154 offset:3072
	v_add_u32_e32 v154, 0x1c000, v140
	ds_read_b128 v[178:181], v154
	ds_read_b128 v[182:185], v154 offset:1024
	ds_read_b128 v[186:189], v154 offset:2048
	ds_read_b128 v[190:193], v154 offset:3072
	s_bitset1_b32 s27, 14
	s_mov_b32 m0, s25
	ds_read_b128 v[194:197], v141 offset:32768
	ds_read_b128 v[198:201], v141 offset:33792
	ds_read_b128 v[202:205], v141 offset:34816
	ds_read_b128 v[228:231], v141 offset:35840
	ds_read_b128 v[232:235], v141 offset:36864
	ds_read_b128 v[236:239], v141 offset:37888
	ds_read_b128 v[240:243], v141 offset:38912
	ds_read_b128 v[244:247], v141 offset:39936
	buffer_load_dwordx4 v136, s[60:63], s27 offen lds
	s_mov_b32 m0, s30
	s_nop 0
	buffer_load_dwordx4 v138, s[60:63], s27 offen lds
	s_waitcnt vmcnt(8)
	s_waitcnt lgkmcnt(0)
	s_setprio 1
	s_barrier
	v_mfma_f32_16x16x32_bf16 v[126:129], v[132:135], v[194:197], v[126:129]
	v_mfma_f32_16x16x32_bf16 v[118:121], v[132:135], v[202:205], v[118:121]
	v_mfma_f32_16x16x32_bf16 v[94:97], v[132:135], v[232:235], v[94:97]
	v_mfma_f32_16x16x32_bf16 v[78:81], v[132:135], v[240:243], v[78:81]
	v_mfma_f32_16x16x32_bf16 v[106:109], v[170:173], v[194:197], v[106:109]
	v_mfma_f32_16x16x32_bf16 v[114:117], v[170:173], v[202:205], v[114:117]
	v_mfma_f32_16x16x32_bf16 v[90:93], v[170:173], v[232:235], v[90:93]
	v_mfma_f32_16x16x32_bf16 v[74:77], v[170:173], v[240:243], v[74:77]
	v_mfma_f32_16x16x32_bf16 v[126:129], v[142:145], v[198:201], v[126:129]
	v_mfma_f32_16x16x32_bf16 v[118:121], v[142:145], v[228:231], v[118:121]
	v_mfma_f32_16x16x32_bf16 v[94:97], v[142:145], v[236:239], v[94:97]
	v_mfma_f32_16x16x32_bf16 v[78:81], v[142:145], v[244:247], v[78:81]
	v_mfma_f32_16x16x32_bf16 v[106:109], v[174:177], v[198:201], v[106:109]
	v_mfma_f32_16x16x32_bf16 v[114:117], v[174:177], v[228:231], v[114:117]
	v_mfma_f32_16x16x32_bf16 v[90:93], v[174:177], v[236:239], v[90:93]
	v_mfma_f32_16x16x32_bf16 v[74:77], v[174:177], v[244:247], v[74:77]
	v_mfma_f32_16x16x32_bf16 v[122:125], v[178:181], v[194:197], v[122:125]
	v_mfma_f32_16x16x32_bf16 v[102:105], v[178:181], v[202:205], v[102:105]
	v_mfma_f32_16x16x32_bf16 v[86:89], v[178:181], v[232:235], v[86:89]
	v_mfma_f32_16x16x32_bf16 v[70:73], v[178:181], v[240:243], v[70:73]
	v_mfma_f32_16x16x32_bf16 v[110:113], v[186:189], v[194:197], v[110:113]
	v_mfma_f32_16x16x32_bf16 v[98:101], v[186:189], v[202:205], v[98:101]
	v_mfma_f32_16x16x32_bf16 v[82:85], v[186:189], v[232:235], v[82:85]
	v_mfma_f32_16x16x32_bf16 v[66:69], v[186:189], v[240:243], v[66:69]
	v_mfma_f32_16x16x32_bf16 v[122:125], v[182:185], v[198:201], v[122:125]
	v_mfma_f32_16x16x32_bf16 v[102:105], v[182:185], v[228:231], v[102:105]
	v_mfma_f32_16x16x32_bf16 v[86:89], v[182:185], v[236:239], v[86:89]
	v_mfma_f32_16x16x32_bf16 v[70:73], v[182:185], v[244:247], v[70:73]
	v_mfma_f32_16x16x32_bf16 v[110:113], v[190:193], v[198:201], v[110:113]
	v_mfma_f32_16x16x32_bf16 v[98:101], v[190:193], v[228:231], v[98:101]
	v_mfma_f32_16x16x32_bf16 v[82:85], v[190:193], v[236:239], v[82:85]
	v_mfma_f32_16x16x32_bf16 v[66:69], v[190:193], v[244:247], v[66:69]
	s_barrier
	s_setprio 0
	s_mov_b32 m0, s36
	s_or_b32 s27, s26, 0x80
	ds_read_b128 v[194:197], v141 offset:49152
	ds_read_b128 v[198:201], v141 offset:50176
	ds_read_b128 v[202:205], v141 offset:51200
	ds_read_b128 v[228:231], v141 offset:52224
	ds_read_b128 v[232:235], v141 offset:53248
	ds_read_b128 v[236:239], v141 offset:54272
	ds_read_b128 v[240:243], v141 offset:55296
	ds_read_b128 v[244:247], v141 offset:56320
	buffer_load_dwordx4 v137, s[44:47], s27 offen lds
	s_mov_b32 m0, s37
	s_add_i32 s26, s26, 0x160080
	buffer_load_dwordx4 v139, s[44:47], s27 offen lds
	s_mov_b32 m0, s66
	s_nop 0
	buffer_load_dwordx4 v137, s[44:47], s26 offen lds
	s_mov_b32 m0, s67
	s_nop 0
	buffer_load_dwordx4 v139, s[44:47], s26 offen lds
	s_mov_b32 m0, s48
	s_nop 0
	buffer_load_dwordx4 v136, s[60:63], s23 offen lds
	s_mov_b32 m0, s49
	s_nop 0
	buffer_load_dwordx4 v138, s[60:63], s23 offen lds
	s_waitcnt vmcnt(8)
	s_waitcnt lgkmcnt(0)
	s_setprio 1
	s_barrier
	v_mfma_f32_16x16x32_bf16 v[62:65], v[132:135], v[194:197], v[62:65]
	v_mfma_f32_16x16x32_bf16 v[46:49], v[132:135], v[202:205], v[46:49]
	v_mfma_f32_16x16x32_bf16 v[30:33], v[132:135], v[232:235], v[30:33]
	v_mfma_f32_16x16x32_bf16 v[14:17], v[132:135], v[240:243], v[14:17]
	v_mfma_f32_16x16x32_bf16 v[58:61], v[170:173], v[194:197], v[58:61]
	v_mfma_f32_16x16x32_bf16 v[42:45], v[170:173], v[202:205], v[42:45]
	v_mfma_f32_16x16x32_bf16 v[26:29], v[170:173], v[232:235], v[26:29]
	v_mfma_f32_16x16x32_bf16 v[10:13], v[170:173], v[240:243], v[10:13]
	v_mfma_f32_16x16x32_bf16 v[62:65], v[142:145], v[198:201], v[62:65]
	v_mfma_f32_16x16x32_bf16 v[46:49], v[142:145], v[228:231], v[46:49]
	v_mfma_f32_16x16x32_bf16 v[30:33], v[142:145], v[236:239], v[30:33]
	v_mfma_f32_16x16x32_bf16 v[14:17], v[142:145], v[244:247], v[14:17]
	v_mfma_f32_16x16x32_bf16 v[58:61], v[174:177], v[198:201], v[58:61]
	v_mfma_f32_16x16x32_bf16 v[42:45], v[174:177], v[228:231], v[42:45]
	v_mfma_f32_16x16x32_bf16 v[26:29], v[174:177], v[236:239], v[26:29]
	v_mfma_f32_16x16x32_bf16 v[10:13], v[174:177], v[244:247], v[10:13]
	v_mfma_f32_16x16x32_bf16 v[54:57], v[178:181], v[194:197], v[54:57]
	v_mfma_f32_16x16x32_bf16 v[38:41], v[178:181], v[202:205], v[38:41]
	v_mfma_f32_16x16x32_bf16 v[22:25], v[178:181], v[232:235], v[22:25]
	v_mfma_f32_16x16x32_bf16 v[6:9], v[178:181], v[240:243], v[6:9]
	v_mfma_f32_16x16x32_bf16 v[50:53], v[186:189], v[194:197], v[50:53]
	v_mfma_f32_16x16x32_bf16 v[34:37], v[186:189], v[202:205], v[34:37]
	v_mfma_f32_16x16x32_bf16 v[18:21], v[186:189], v[232:235], v[18:21]
	v_mfma_f32_16x16x32_bf16 v[2:5], v[186:189], v[240:243], v[2:5]
	v_mfma_f32_16x16x32_bf16 v[54:57], v[182:185], v[198:201], v[54:57]
	v_mfma_f32_16x16x32_bf16 v[38:41], v[182:185], v[228:231], v[38:41]
	v_mfma_f32_16x16x32_bf16 v[22:25], v[182:185], v[236:239], v[22:25]
	v_mfma_f32_16x16x32_bf16 v[6:9], v[182:185], v[244:247], v[6:9]
	v_mfma_f32_16x16x32_bf16 v[50:53], v[190:193], v[198:201], v[50:53]
	v_mfma_f32_16x16x32_bf16 v[34:37], v[190:193], v[228:231], v[34:37]
	v_mfma_f32_16x16x32_bf16 v[18:21], v[190:193], v[236:239], v[18:21]
	v_mfma_f32_16x16x32_bf16 v[2:5], v[190:193], v[244:247], v[2:5]
	s_barrier
	s_setprio 0
	s_addk_i32 s13, 0x100
	s_add_i32 s22, s22, 2
	s_add_i32 s21, s21, 0x10000
	s_cmpk_gt_u32 s22, 0x55
	s_cbranch_scc0 .LBB0_580
	s_and_b64 vcc, exec, s[64:65]
	s_cbranch_vccz .LBB0_583
	s_barrier

.LBB0_858:
	s_lshl_b32 s2, s21, 20
	s_and_b64 s[8:9], s[42:43], exec
	s_cselect_b32 s8, s2, s18
	s_lshl_b32 s82, s71, 20
	s_and_b64 s[26:27], s[42:43], exec
	s_cselect_b32 s9, s82, s19
	s_add_i32 s18, s18, 0x80080
	s_addk_i32 s19, 0x100
	s_mov_b32 s22, -2
	v_add_u32_e32 v146, 0x10000, v195
	ds_read_b128 v[130:133], v146
	ds_read_b128 v[138:141], v146 offset:1024
	ds_read_b128 v[142:145], v146 offset:2048
	ds_read_b128 v[154:157], v146 offset:3072
	v_add_u32_e32 v146, 0x14000, v195
	ds_read_b128 v[170:173], v146
	ds_read_b128 v[174:177], v146 offset:1024
	ds_read_b128 v[178:181], v146 offset:2048
	ds_read_b128 v[182:185], v146 offset:3072
	s_add_i32 s26, s18, 0xfff80080
	s_cmp_eq_u32 s22, 28
	s_cselect_b32 s52, s8, s26
	s_cselect_b32 s27, s9, s19
	s_or_b32 s26, s52, 0x80
	s_mov_b32 m0, s85
	ds_read_b128 v[186:189], v196
	ds_read_b128 v[198:201], v196 offset:1024
	ds_read_b128 v[202:205], v196 offset:2048
	ds_read_b128 v[228:231], v196 offset:3072
	ds_read_b128 v[232:235], v196 offset:4096
	ds_read_b128 v[236:239], v196 offset:5120
	ds_read_b128 v[240:243], v196 offset:6144
	ds_read_b128 v[244:247], v196 offset:7168
	buffer_load_dwordx4 v135, s[44:47], s18 offen lds
	s_mov_b32 m0, s15
	s_nop 0
	buffer_load_dwordx4 v193, s[44:47], s18 offen lds
	s_waitcnt vmcnt(8)
	s_waitcnt lgkmcnt(0)
	s_setprio 1
	s_barrier
	v_mfma_f32_16x16x32_bf16 v[126:129], v[130:133], v[186:189], 0
	v_mfma_f32_16x16x32_bf16 v[110:113], v[130:133], v[202:205], 0
	v_mfma_f32_16x16x32_bf16 v[94:97], v[130:133], v[232:235], 0
	v_mfma_f32_16x16x32_bf16 v[78:81], v[130:133], v[240:243], 0
	v_mfma_f32_16x16x32_bf16 v[122:125], v[142:145], v[186:189], 0
	v_mfma_f32_16x16x32_bf16 v[106:109], v[142:145], v[202:205], 0
	v_mfma_f32_16x16x32_bf16 v[90:93], v[142:145], v[232:235], 0
	v_mfma_f32_16x16x32_bf16 v[74:77], v[142:145], v[240:243], 0
	v_mfma_f32_16x16x32_bf16 v[126:129], v[138:141], v[198:201], v[126:129]
	v_mfma_f32_16x16x32_bf16 v[110:113], v[138:141], v[228:231], v[110:113]
	v_mfma_f32_16x16x32_bf16 v[94:97], v[138:141], v[236:239], v[94:97]
	v_mfma_f32_16x16x32_bf16 v[78:81], v[138:141], v[244:247], v[78:81]
	v_mfma_f32_16x16x32_bf16 v[122:125], v[154:157], v[198:201], v[122:125]
	v_mfma_f32_16x16x32_bf16 v[106:109], v[154:157], v[228:231], v[106:109]
	v_mfma_f32_16x16x32_bf16 v[90:93], v[154:157], v[236:239], v[90:93]
	v_mfma_f32_16x16x32_bf16 v[74:77], v[154:157], v[244:247], v[74:77]
	v_mfma_f32_16x16x32_bf16 v[118:121], v[170:173], v[186:189], 0
	v_mfma_f32_16x16x32_bf16 v[102:105], v[170:173], v[202:205], 0
	v_mfma_f32_16x16x32_bf16 v[86:89], v[170:173], v[232:235], 0
	v_mfma_f32_16x16x32_bf16 v[70:73], v[170:173], v[240:243], 0
	v_mfma_f32_16x16x32_bf16 v[114:117], v[178:181], v[186:189], 0
	v_mfma_f32_16x16x32_bf16 v[98:101], v[178:181], v[202:205], 0
	v_mfma_f32_16x16x32_bf16 v[82:85], v[178:181], v[232:235], 0
	v_mfma_f32_16x16x32_bf16 v[66:69], v[178:181], v[240:243], 0
	v_mfma_f32_16x16x32_bf16 v[118:121], v[174:177], v[198:201], v[118:121]
	v_mfma_f32_16x16x32_bf16 v[102:105], v[174:177], v[228:231], v[102:105]
	v_mfma_f32_16x16x32_bf16 v[86:89], v[174:177], v[236:239], v[86:89]
	v_mfma_f32_16x16x32_bf16 v[70:73], v[174:177], v[244:247], v[70:73]
	v_mfma_f32_16x16x32_bf16 v[114:117], v[182:185], v[198:201], v[114:117]
	v_mfma_f32_16x16x32_bf16 v[98:101], v[182:185], v[228:231], v[98:101]
	v_mfma_f32_16x16x32_bf16 v[82:85], v[182:185], v[236:239], v[82:85]
	v_mfma_f32_16x16x32_bf16 v[66:69], v[182:185], v[244:247], v[66:69]
	s_barrier
	s_setprio 0
	s_mov_b32 m0, s23
	s_mov_b32 s66, s46
	s_mov_b32 s67, s47
	ds_read_b128 v[186:189], v196 offset:16384
	ds_read_b128 v[198:201], v196 offset:17408
	ds_read_b128 v[202:205], v196 offset:18432
	ds_read_b128 v[228:231], v196 offset:19456
	ds_read_b128 v[232:235], v196 offset:20480
	ds_read_b128 v[236:239], v196 offset:21504
	ds_read_b128 v[240:243], v196 offset:22528
	ds_read_b128 v[244:247], v196 offset:23552
	buffer_load_dwordx4 v192, s[64:67], s27 offen lds
	s_mov_b32 m0, s24
	s_add_i32 s53, s27, 0x80000
	buffer_load_dwordx4 v194, s[64:67], s27 offen lds
	s_mov_b32 m0, s25
	s_nop 0
	buffer_load_dwordx4 v192, s[64:67], s53 offen lds
	s_mov_b32 m0, s33
	s_nop 0
	buffer_load_dwordx4 v194, s[64:67], s53 offen lds
	s_mov_b32 m0, s13
	s_nop 0
	buffer_load_dwordx4 v135, s[44:47], s52 offen lds
	s_mov_b32 m0, s34
	s_nop 0
	buffer_load_dwordx4 v193, s[44:47], s52 offen lds
	s_waitcnt vmcnt(8)
	s_waitcnt lgkmcnt(0)
	s_setprio 1
	s_barrier
	v_mfma_f32_16x16x32_bf16 v[62:65], v[130:133], v[186:189], 0
	v_mfma_f32_16x16x32_bf16 v[46:49], v[130:133], v[202:205], 0
	v_mfma_f32_16x16x32_bf16 v[30:33], v[130:133], v[232:235], 0
	v_mfma_f32_16x16x32_bf16 v[14:17], v[130:133], v[240:243], 0
	v_mfma_f32_16x16x32_bf16 v[58:61], v[142:145], v[186:189], 0
	v_mfma_f32_16x16x32_bf16 v[42:45], v[142:145], v[202:205], 0
	v_mfma_f32_16x16x32_bf16 v[26:29], v[142:145], v[232:235], 0
	v_mfma_f32_16x16x32_bf16 v[10:13], v[142:145], v[240:243], 0
	v_mfma_f32_16x16x32_bf16 v[62:65], v[138:141], v[198:201], v[62:65]
	v_mfma_f32_16x16x32_bf16 v[46:49], v[138:141], v[228:231], v[46:49]
	v_mfma_f32_16x16x32_bf16 v[30:33], v[138:141], v[236:239], v[30:33]
	v_mfma_f32_16x16x32_bf16 v[14:17], v[138:141], v[244:247], v[14:17]
	v_mfma_f32_16x16x32_bf16 v[58:61], v[154:157], v[198:201], v[58:61]
	v_mfma_f32_16x16x32_bf16 v[42:45], v[154:157], v[228:231], v[42:45]
	v_mfma_f32_16x16x32_bf16 v[26:29], v[154:157], v[236:239], v[26:29]
	v_mfma_f32_16x16x32_bf16 v[10:13], v[154:157], v[244:247], v[10:13]
	v_mfma_f32_16x16x32_bf16 v[54:57], v[170:173], v[186:189], 0
	v_mfma_f32_16x16x32_bf16 v[38:41], v[170:173], v[202:205], 0
	v_mfma_f32_16x16x32_bf16 v[22:25], v[170:173], v[232:235], 0
	v_mfma_f32_16x16x32_bf16 v[6:9], v[170:173], v[240:243], 0
	v_mfma_f32_16x16x32_bf16 v[50:53], v[178:181], v[186:189], 0
	v_mfma_f32_16x16x32_bf16 v[34:37], v[178:181], v[202:205], 0
	v_mfma_f32_16x16x32_bf16 v[18:21], v[178:181], v[232:235], 0
	v_mfma_f32_16x16x32_bf16 v[2:5], v[178:181], v[240:243], 0
	v_mfma_f32_16x16x32_bf16 v[54:57], v[174:177], v[198:201], v[54:57]
	v_mfma_f32_16x16x32_bf16 v[38:41], v[174:177], v[228:231], v[38:41]
	v_mfma_f32_16x16x32_bf16 v[22:25], v[174:177], v[236:239], v[22:25]
	v_mfma_f32_16x16x32_bf16 v[6:9], v[174:177], v[244:247], v[6:9]
	v_mfma_f32_16x16x32_bf16 v[50:53], v[182:185], v[198:201], v[50:53]
	v_mfma_f32_16x16x32_bf16 v[34:37], v[182:185], v[228:231], v[34:37]
	v_mfma_f32_16x16x32_bf16 v[18:21], v[182:185], v[236:239], v[18:21]
	v_mfma_f32_16x16x32_bf16 v[2:5], v[182:185], v[244:247], v[2:5]
	s_barrier
	s_setprio 0
	v_add_u32_e32 v146, 0x18000, v195
	ds_read_b128 v[130:133], v146
	ds_read_b128 v[138:141], v146 offset:1024
	ds_read_b128 v[142:145], v146 offset:2048
	ds_read_b128 v[154:157], v146 offset:3072
	v_add_u32_e32 v146, 0x1c000, v195
	ds_read_b128 v[170:173], v146
	ds_read_b128 v[174:177], v146 offset:1024
	ds_read_b128 v[178:181], v146 offset:2048
	ds_read_b128 v[182:185], v146 offset:3072
	s_add_i32 s52, s52, 0x80000
	s_mov_b32 m0, s35
	ds_read_b128 v[186:189], v196 offset:32768
	ds_read_b128 v[198:201], v196 offset:33792
	ds_read_b128 v[202:205], v196 offset:34816
	ds_read_b128 v[228:231], v196 offset:35840
	ds_read_b128 v[232:235], v196 offset:36864
	ds_read_b128 v[236:239], v196 offset:37888
	ds_read_b128 v[240:243], v196 offset:38912
	ds_read_b128 v[244:247], v196 offset:39936
	buffer_load_dwordx4 v135, s[44:47], s52 offen lds
	s_mov_b32 m0, s36
	s_nop 0
	buffer_load_dwordx4 v193, s[44:47], s52 offen lds
	s_waitcnt vmcnt(8)
	s_waitcnt lgkmcnt(0)
	s_setprio 1
	s_barrier
	v_mfma_f32_16x16x32_bf16 v[126:129], v[130:133], v[186:189], v[126:129]
	v_mfma_f32_16x16x32_bf16 v[110:113], v[130:133], v[202:205], v[110:113]
	v_mfma_f32_16x16x32_bf16 v[94:97], v[130:133], v[232:235], v[94:97]
	v_mfma_f32_16x16x32_bf16 v[78:81], v[130:133], v[240:243], v[78:81]
	v_mfma_f32_16x16x32_bf16 v[122:125], v[142:145], v[186:189], v[122:125]
	v_mfma_f32_16x16x32_bf16 v[106:109], v[142:145], v[202:205], v[106:109]
	v_mfma_f32_16x16x32_bf16 v[90:93], v[142:145], v[232:235], v[90:93]
	v_mfma_f32_16x16x32_bf16 v[74:77], v[142:145], v[240:243], v[74:77]
	v_mfma_f32_16x16x32_bf16 v[126:129], v[138:141], v[198:201], v[126:129]
	v_mfma_f32_16x16x32_bf16 v[110:113], v[138:141], v[228:231], v[110:113]
	v_mfma_f32_16x16x32_bf16 v[94:97], v[138:141], v[236:239], v[94:97]
	v_mfma_f32_16x16x32_bf16 v[78:81], v[138:141], v[244:247], v[78:81]
	v_mfma_f32_16x16x32_bf16 v[122:125], v[154:157], v[198:201], v[122:125]
	v_mfma_f32_16x16x32_bf16 v[106:109], v[154:157], v[228:231], v[106:109]
	v_mfma_f32_16x16x32_bf16 v[90:93], v[154:157], v[236:239], v[90:93]
	v_mfma_f32_16x16x32_bf16 v[74:77], v[154:157], v[244:247], v[74:77]
	v_mfma_f32_16x16x32_bf16 v[118:121], v[170:173], v[186:189], v[118:121]
	v_mfma_f32_16x16x32_bf16 v[102:105], v[170:173], v[202:205], v[102:105]
	v_mfma_f32_16x16x32_bf16 v[86:89], v[170:173], v[232:235], v[86:89]
	v_mfma_f32_16x16x32_bf16 v[70:73], v[170:173], v[240:243], v[70:73]
	v_mfma_f32_16x16x32_bf16 v[114:117], v[178:181], v[186:189], v[114:117]
	v_mfma_f32_16x16x32_bf16 v[98:101], v[178:181], v[202:205], v[98:101]
	v_mfma_f32_16x16x32_bf16 v[82:85], v[178:181], v[232:235], v[82:85]
	v_mfma_f32_16x16x32_bf16 v[66:69], v[178:181], v[240:243], v[66:69]
	v_mfma_f32_16x16x32_bf16 v[118:121], v[174:177], v[198:201], v[118:121]
	v_mfma_f32_16x16x32_bf16 v[102:105], v[174:177], v[228:231], v[102:105]
	v_mfma_f32_16x16x32_bf16 v[86:89], v[174:177], v[236:239], v[86:89]
	v_mfma_f32_16x16x32_bf16 v[70:73], v[174:177], v[244:247], v[70:73]
	v_mfma_f32_16x16x32_bf16 v[114:117], v[182:185], v[198:201], v[114:117]
	v_mfma_f32_16x16x32_bf16 v[98:101], v[182:185], v[228:231], v[98:101]
	v_mfma_f32_16x16x32_bf16 v[82:85], v[182:185], v[236:239], v[82:85]
	v_mfma_f32_16x16x32_bf16 v[66:69], v[182:185], v[244:247], v[66:69]
	s_barrier
	s_setprio 0
	s_mov_b32 m0, s41
	s_or_b32 s52, s27, 0x80
	ds_read_b128 v[186:189], v196 offset:49152
	ds_read_b128 v[198:201], v196 offset:50176
	ds_read_b128 v[202:205], v196 offset:51200
	ds_read_b128 v[228:231], v196 offset:52224
	ds_read_b128 v[232:235], v196 offset:53248
	ds_read_b128 v[236:239], v196 offset:54272
	ds_read_b128 v[240:243], v196 offset:55296
	ds_read_b128 v[244:247], v196 offset:56320
	buffer_load_dwordx4 v192, s[64:67], s52 offen lds
	s_mov_b32 m0, s48
	s_add_i32 s27, s27, 0x80080
	buffer_load_dwordx4 v194, s[64:67], s52 offen lds
	s_mov_b32 m0, s69
	s_nop 0
	buffer_load_dwordx4 v192, s[64:67], s27 offen lds
	s_mov_b32 m0, s72
	s_nop 0
	buffer_load_dwordx4 v194, s[64:67], s27 offen lds
	s_mov_b32 m0, s49
	s_nop 0
	buffer_load_dwordx4 v135, s[44:47], s26 offen lds
	s_mov_b32 m0, s68
	s_nop 0
	buffer_load_dwordx4 v193, s[44:47], s26 offen lds
	s_waitcnt vmcnt(8)
	s_waitcnt lgkmcnt(0)
	s_setprio 1
	s_barrier
	v_mfma_f32_16x16x32_bf16 v[62:65], v[130:133], v[186:189], v[62:65]
	v_mfma_f32_16x16x32_bf16 v[46:49], v[130:133], v[202:205], v[46:49]
	v_mfma_f32_16x16x32_bf16 v[30:33], v[130:133], v[232:235], v[30:33]
	v_mfma_f32_16x16x32_bf16 v[14:17], v[130:133], v[240:243], v[14:17]
	v_mfma_f32_16x16x32_bf16 v[58:61], v[142:145], v[186:189], v[58:61]
	v_mfma_f32_16x16x32_bf16 v[42:45], v[142:145], v[202:205], v[42:45]
	v_mfma_f32_16x16x32_bf16 v[26:29], v[142:145], v[232:235], v[26:29]
	v_mfma_f32_16x16x32_bf16 v[10:13], v[142:145], v[240:243], v[10:13]
	v_mfma_f32_16x16x32_bf16 v[62:65], v[138:141], v[198:201], v[62:65]
	v_mfma_f32_16x16x32_bf16 v[46:49], v[138:141], v[228:231], v[46:49]
	v_mfma_f32_16x16x32_bf16 v[30:33], v[138:141], v[236:239], v[30:33]
	v_mfma_f32_16x16x32_bf16 v[14:17], v[138:141], v[244:247], v[14:17]
	v_mfma_f32_16x16x32_bf16 v[58:61], v[154:157], v[198:201], v[58:61]
	v_mfma_f32_16x16x32_bf16 v[42:45], v[154:157], v[228:231], v[42:45]
	v_mfma_f32_16x16x32_bf16 v[26:29], v[154:157], v[236:239], v[26:29]
	v_mfma_f32_16x16x32_bf16 v[10:13], v[154:157], v[244:247], v[10:13]
	v_mfma_f32_16x16x32_bf16 v[54:57], v[170:173], v[186:189], v[54:57]
	v_mfma_f32_16x16x32_bf16 v[38:41], v[170:173], v[202:205], v[38:41]
	v_mfma_f32_16x16x32_bf16 v[22:25], v[170:173], v[232:235], v[22:25]
	v_mfma_f32_16x16x32_bf16 v[6:9], v[170:173], v[240:243], v[6:9]
	v_mfma_f32_16x16x32_bf16 v[50:53], v[178:181], v[186:189], v[50:53]
	v_mfma_f32_16x16x32_bf16 v[34:37], v[178:181], v[202:205], v[34:37]
	v_mfma_f32_16x16x32_bf16 v[18:21], v[178:181], v[232:235], v[18:21]
	v_mfma_f32_16x16x32_bf16 v[2:5], v[178:181], v[240:243], v[2:5]
	v_mfma_f32_16x16x32_bf16 v[54:57], v[174:177], v[198:201], v[54:57]
	v_mfma_f32_16x16x32_bf16 v[38:41], v[174:177], v[228:231], v[38:41]
	v_mfma_f32_16x16x32_bf16 v[22:25], v[174:177], v[236:239], v[22:25]
	v_mfma_f32_16x16x32_bf16 v[6:9], v[174:177], v[244:247], v[6:9]
	v_mfma_f32_16x16x32_bf16 v[50:53], v[182:185], v[198:201], v[50:53]
	v_mfma_f32_16x16x32_bf16 v[34:37], v[182:185], v[228:231], v[34:37]
	v_mfma_f32_16x16x32_bf16 v[18:21], v[182:185], v[236:239], v[18:21]
	v_mfma_f32_16x16x32_bf16 v[2:5], v[182:185], v[244:247], v[2:5]
	s_barrier
	s_setprio 0
	s_add_i32 s22, s22, 2
	s_addk_i32 s18, 0x100
	s_addk_i32 s19, 0x100
	s_cmp_gt_u32 s22, 29
.LBB0_859:
	v_add_u32_e32 v146, 0x10000, v195
	ds_read_b128 v[130:133], v146
	ds_read_b128 v[138:141], v146 offset:1024
	ds_read_b128 v[142:145], v146 offset:2048
	ds_read_b128 v[154:157], v146 offset:3072
	v_add_u32_e32 v146, 0x14000, v195
	ds_read_b128 v[170:173], v146
	ds_read_b128 v[174:177], v146 offset:1024
	ds_read_b128 v[178:181], v146 offset:2048
	ds_read_b128 v[182:185], v146 offset:3072
	s_add_i32 s26, s18, 0xfff80080
	s_cmp_eq_u32 s22, 28
	s_cselect_b32 s52, s8, s26
	s_cselect_b32 s27, s9, s19
	s_or_b32 s26, s52, 0x80
	s_mov_b32 m0, s85
	ds_read_b128 v[186:189], v196
	ds_read_b128 v[198:201], v196 offset:1024
	ds_read_b128 v[202:205], v196 offset:2048
	ds_read_b128 v[228:231], v196 offset:3072
	ds_read_b128 v[232:235], v196 offset:4096
	ds_read_b128 v[236:239], v196 offset:5120
	ds_read_b128 v[240:243], v196 offset:6144
	ds_read_b128 v[244:247], v196 offset:7168
	buffer_load_dwordx4 v135, s[44:47], s18 offen lds
	s_mov_b32 m0, s15
	s_nop 0
	buffer_load_dwordx4 v193, s[44:47], s18 offen lds
	s_waitcnt vmcnt(8)
	s_waitcnt lgkmcnt(0)
	s_setprio 1
	s_barrier
	v_mfma_f32_16x16x32_bf16 v[126:129], v[130:133], v[186:189], v[126:129]
	v_mfma_f32_16x16x32_bf16 v[110:113], v[130:133], v[202:205], v[110:113]
	v_mfma_f32_16x16x32_bf16 v[94:97], v[130:133], v[232:235], v[94:97]
	v_mfma_f32_16x16x32_bf16 v[78:81], v[130:133], v[240:243], v[78:81]
	v_mfma_f32_16x16x32_bf16 v[122:125], v[142:145], v[186:189], v[122:125]
	v_mfma_f32_16x16x32_bf16 v[106:109], v[142:145], v[202:205], v[106:109]
	v_mfma_f32_16x16x32_bf16 v[90:93], v[142:145], v[232:235], v[90:93]
	v_mfma_f32_16x16x32_bf16 v[74:77], v[142:145], v[240:243], v[74:77]
	v_mfma_f32_16x16x32_bf16 v[126:129], v[138:141], v[198:201], v[126:129]
	v_mfma_f32_16x16x32_bf16 v[110:113], v[138:141], v[228:231], v[110:113]
	v_mfma_f32_16x16x32_bf16 v[94:97], v[138:141], v[236:239], v[94:97]
	v_mfma_f32_16x16x32_bf16 v[78:81], v[138:141], v[244:247], v[78:81]
	v_mfma_f32_16x16x32_bf16 v[122:125], v[154:157], v[198:201], v[122:125]
	v_mfma_f32_16x16x32_bf16 v[106:109], v[154:157], v[228:231], v[106:109]
	v_mfma_f32_16x16x32_bf16 v[90:93], v[154:157], v[236:239], v[90:93]
	v_mfma_f32_16x16x32_bf16 v[74:77], v[154:157], v[244:247], v[74:77]
	v_mfma_f32_16x16x32_bf16 v[118:121], v[170:173], v[186:189], v[118:121]
	v_mfma_f32_16x16x32_bf16 v[102:105], v[170:173], v[202:205], v[102:105]
	v_mfma_f32_16x16x32_bf16 v[86:89], v[170:173], v[232:235], v[86:89]
	v_mfma_f32_16x16x32_bf16 v[70:73], v[170:173], v[240:243], v[70:73]
	v_mfma_f32_16x16x32_bf16 v[114:117], v[178:181], v[186:189], v[114:117]
	v_mfma_f32_16x16x32_bf16 v[98:101], v[178:181], v[202:205], v[98:101]
	v_mfma_f32_16x16x32_bf16 v[82:85], v[178:181], v[232:235], v[82:85]
	v_mfma_f32_16x16x32_bf16 v[66:69], v[178:181], v[240:243], v[66:69]
	v_mfma_f32_16x16x32_bf16 v[118:121], v[174:177], v[198:201], v[118:121]
	v_mfma_f32_16x16x32_bf16 v[102:105], v[174:177], v[228:231], v[102:105]
	v_mfma_f32_16x16x32_bf16 v[86:89], v[174:177], v[236:239], v[86:89]
	v_mfma_f32_16x16x32_bf16 v[70:73], v[174:177], v[244:247], v[70:73]
	v_mfma_f32_16x16x32_bf16 v[114:117], v[182:185], v[198:201], v[114:117]
	v_mfma_f32_16x16x32_bf16 v[98:101], v[182:185], v[228:231], v[98:101]
	v_mfma_f32_16x16x32_bf16 v[82:85], v[182:185], v[236:239], v[82:85]
	v_mfma_f32_16x16x32_bf16 v[66:69], v[182:185], v[244:247], v[66:69]
	s_barrier
	s_setprio 0
	s_mov_b32 m0, s23
	s_mov_b32 s66, s46
	s_mov_b32 s67, s47
	ds_read_b128 v[186:189], v196 offset:16384
	ds_read_b128 v[198:201], v196 offset:17408
	ds_read_b128 v[202:205], v196 offset:18432
	ds_read_b128 v[228:231], v196 offset:19456
	ds_read_b128 v[232:235], v196 offset:20480
	ds_read_b128 v[236:239], v196 offset:21504
	ds_read_b128 v[240:243], v196 offset:22528
	ds_read_b128 v[244:247], v196 offset:23552
	buffer_load_dwordx4 v192, s[64:67], s27 offen lds
	s_mov_b32 m0, s24
	s_add_i32 s53, s27, 0x80000
	buffer_load_dwordx4 v194, s[64:67], s27 offen lds
	s_mov_b32 m0, s25
	s_nop 0
	buffer_load_dwordx4 v192, s[64:67], s53 offen lds
	s_mov_b32 m0, s33
	s_nop 0
	buffer_load_dwordx4 v194, s[64:67], s53 offen lds
	s_mov_b32 m0, s13
	s_nop 0
	buffer_load_dwordx4 v135, s[44:47], s52 offen lds
	s_mov_b32 m0, s34
	s_nop 0
	buffer_load_dwordx4 v193, s[44:47], s52 offen lds
	s_waitcnt vmcnt(8)
	s_waitcnt lgkmcnt(0)
	s_setprio 1
	s_barrier
	v_mfma_f32_16x16x32_bf16 v[62:65], v[130:133], v[186:189], v[62:65]
	v_mfma_f32_16x16x32_bf16 v[46:49], v[130:133], v[202:205], v[46:49]
	v_mfma_f32_16x16x32_bf16 v[30:33], v[130:133], v[232:235], v[30:33]
	v_mfma_f32_16x16x32_bf16 v[14:17], v[130:133], v[240:243], v[14:17]
	v_mfma_f32_16x16x32_bf16 v[58:61], v[142:145], v[186:189], v[58:61]
	v_mfma_f32_16x16x32_bf16 v[42:45], v[142:145], v[202:205], v[42:45]
	v_mfma_f32_16x16x32_bf16 v[26:29], v[142:145], v[232:235], v[26:29]
	v_mfma_f32_16x16x32_bf16 v[10:13], v[142:145], v[240:243], v[10:13]
	v_mfma_f32_16x16x32_bf16 v[62:65], v[138:141], v[198:201], v[62:65]
	v_mfma_f32_16x16x32_bf16 v[46:49], v[138:141], v[228:231], v[46:49]
	v_mfma_f32_16x16x32_bf16 v[30:33], v[138:141], v[236:239], v[30:33]
	v_mfma_f32_16x16x32_bf16 v[14:17], v[138:141], v[244:247], v[14:17]
	v_mfma_f32_16x16x32_bf16 v[58:61], v[154:157], v[198:201], v[58:61]
	v_mfma_f32_16x16x32_bf16 v[42:45], v[154:157], v[228:231], v[42:45]
	v_mfma_f32_16x16x32_bf16 v[26:29], v[154:157], v[236:239], v[26:29]
	v_mfma_f32_16x16x32_bf16 v[10:13], v[154:157], v[244:247], v[10:13]
	v_mfma_f32_16x16x32_bf16 v[54:57], v[170:173], v[186:189], v[54:57]
	v_mfma_f32_16x16x32_bf16 v[38:41], v[170:173], v[202:205], v[38:41]
	v_mfma_f32_16x16x32_bf16 v[22:25], v[170:173], v[232:235], v[22:25]
	v_mfma_f32_16x16x32_bf16 v[6:9], v[170:173], v[240:243], v[6:9]
	v_mfma_f32_16x16x32_bf16 v[50:53], v[178:181], v[186:189], v[50:53]
	v_mfma_f32_16x16x32_bf16 v[34:37], v[178:181], v[202:205], v[34:37]
	v_mfma_f32_16x16x32_bf16 v[18:21], v[178:181], v[232:235], v[18:21]
	v_mfma_f32_16x16x32_bf16 v[2:5], v[178:181], v[240:243], v[2:5]
	v_mfma_f32_16x16x32_bf16 v[54:57], v[174:177], v[198:201], v[54:57]
	v_mfma_f32_16x16x32_bf16 v[38:41], v[174:177], v[228:231], v[38:41]
	v_mfma_f32_16x16x32_bf16 v[22:25], v[174:177], v[236:239], v[22:25]
	v_mfma_f32_16x16x32_bf16 v[6:9], v[174:177], v[244:247], v[6:9]
	v_mfma_f32_16x16x32_bf16 v[50:53], v[182:185], v[198:201], v[50:53]
	v_mfma_f32_16x16x32_bf16 v[34:37], v[182:185], v[228:231], v[34:37]
	v_mfma_f32_16x16x32_bf16 v[18:21], v[182:185], v[236:239], v[18:21]
	v_mfma_f32_16x16x32_bf16 v[2:5], v[182:185], v[244:247], v[2:5]
	s_barrier
	s_setprio 0
	v_add_u32_e32 v146, 0x18000, v195
	ds_read_b128 v[130:133], v146
	ds_read_b128 v[138:141], v146 offset:1024
	ds_read_b128 v[142:145], v146 offset:2048
	ds_read_b128 v[154:157], v146 offset:3072
	v_add_u32_e32 v146, 0x1c000, v195
	ds_read_b128 v[170:173], v146
	ds_read_b128 v[174:177], v146 offset:1024
	ds_read_b128 v[178:181], v146 offset:2048
	ds_read_b128 v[182:185], v146 offset:3072
	s_add_i32 s52, s52, 0x80000
	s_mov_b32 m0, s35
	ds_read_b128 v[186:189], v196 offset:32768
	ds_read_b128 v[198:201], v196 offset:33792
	ds_read_b128 v[202:205], v196 offset:34816
	ds_read_b128 v[228:231], v196 offset:35840
	ds_read_b128 v[232:235], v196 offset:36864
	ds_read_b128 v[236:239], v196 offset:37888
	ds_read_b128 v[240:243], v196 offset:38912
	ds_read_b128 v[244:247], v196 offset:39936
	buffer_load_dwordx4 v135, s[44:47], s52 offen lds
	s_mov_b32 m0, s36
	s_nop 0
	buffer_load_dwordx4 v193, s[44:47], s52 offen lds
	s_waitcnt vmcnt(8)
	s_waitcnt lgkmcnt(0)
	s_setprio 1
	s_barrier
	v_mfma_f32_16x16x32_bf16 v[126:129], v[130:133], v[186:189], v[126:129]
	v_mfma_f32_16x16x32_bf16 v[110:113], v[130:133], v[202:205], v[110:113]
	v_mfma_f32_16x16x32_bf16 v[94:97], v[130:133], v[232:235], v[94:97]
	v_mfma_f32_16x16x32_bf16 v[78:81], v[130:133], v[240:243], v[78:81]
	v_mfma_f32_16x16x32_bf16 v[122:125], v[142:145], v[186:189], v[122:125]
	v_mfma_f32_16x16x32_bf16 v[106:109], v[142:145], v[202:205], v[106:109]
	v_mfma_f32_16x16x32_bf16 v[90:93], v[142:145], v[232:235], v[90:93]
	v_mfma_f32_16x16x32_bf16 v[74:77], v[142:145], v[240:243], v[74:77]
	v_mfma_f32_16x16x32_bf16 v[126:129], v[138:141], v[198:201], v[126:129]
	v_mfma_f32_16x16x32_bf16 v[110:113], v[138:141], v[228:231], v[110:113]
	v_mfma_f32_16x16x32_bf16 v[94:97], v[138:141], v[236:239], v[94:97]
	v_mfma_f32_16x16x32_bf16 v[78:81], v[138:141], v[244:247], v[78:81]
	v_mfma_f32_16x16x32_bf16 v[122:125], v[154:157], v[198:201], v[122:125]
	v_mfma_f32_16x16x32_bf16 v[106:109], v[154:157], v[228:231], v[106:109]
	v_mfma_f32_16x16x32_bf16 v[90:93], v[154:157], v[236:239], v[90:93]
	v_mfma_f32_16x16x32_bf16 v[74:77], v[154:157], v[244:247], v[74:77]
	v_mfma_f32_16x16x32_bf16 v[118:121], v[170:173], v[186:189], v[118:121]
	v_mfma_f32_16x16x32_bf16 v[102:105], v[170:173], v[202:205], v[102:105]
	v_mfma_f32_16x16x32_bf16 v[86:89], v[170:173], v[232:235], v[86:89]
	v_mfma_f32_16x16x32_bf16 v[70:73], v[170:173], v[240:243], v[70:73]
	v_mfma_f32_16x16x32_bf16 v[114:117], v[178:181], v[186:189], v[114:117]
	v_mfma_f32_16x16x32_bf16 v[98:101], v[178:181], v[202:205], v[98:101]
	v_mfma_f32_16x16x32_bf16 v[82:85], v[178:181], v[232:235], v[82:85]
	v_mfma_f32_16x16x32_bf16 v[66:69], v[178:181], v[240:243], v[66:69]
	v_mfma_f32_16x16x32_bf16 v[118:121], v[174:177], v[198:201], v[118:121]
	v_mfma_f32_16x16x32_bf16 v[102:105], v[174:177], v[228:231], v[102:105]
	v_mfma_f32_16x16x32_bf16 v[86:89], v[174:177], v[236:239], v[86:89]
	v_mfma_f32_16x16x32_bf16 v[70:73], v[174:177], v[244:247], v[70:73]
	v_mfma_f32_16x16x32_bf16 v[114:117], v[182:185], v[198:201], v[114:117]
	v_mfma_f32_16x16x32_bf16 v[98:101], v[182:185], v[228:231], v[98:101]
	v_mfma_f32_16x16x32_bf16 v[82:85], v[182:185], v[236:239], v[82:85]
	v_mfma_f32_16x16x32_bf16 v[66:69], v[182:185], v[244:247], v[66:69]
	s_barrier
	s_setprio 0
	s_mov_b32 m0, s41
	s_or_b32 s52, s27, 0x80
	ds_read_b128 v[186:189], v196 offset:49152
	ds_read_b128 v[198:201], v196 offset:50176
	ds_read_b128 v[202:205], v196 offset:51200
	ds_read_b128 v[228:231], v196 offset:52224
	ds_read_b128 v[232:235], v196 offset:53248
	ds_read_b128 v[236:239], v196 offset:54272
	ds_read_b128 v[240:243], v196 offset:55296
	ds_read_b128 v[244:247], v196 offset:56320
	buffer_load_dwordx4 v192, s[64:67], s52 offen lds
	s_mov_b32 m0, s48
	s_add_i32 s27, s27, 0x80080
	buffer_load_dwordx4 v194, s[64:67], s52 offen lds
	s_mov_b32 m0, s69
	s_nop 0
	buffer_load_dwordx4 v192, s[64:67], s27 offen lds
	s_mov_b32 m0, s72
	s_nop 0
	buffer_load_dwordx4 v194, s[64:67], s27 offen lds
	s_mov_b32 m0, s49
	s_nop 0
	buffer_load_dwordx4 v135, s[44:47], s26 offen lds
	s_mov_b32 m0, s68
	s_nop 0
	buffer_load_dwordx4 v193, s[44:47], s26 offen lds
	s_waitcnt vmcnt(8)
	s_waitcnt lgkmcnt(0)
	s_setprio 1
	s_barrier
	v_mfma_f32_16x16x32_bf16 v[62:65], v[130:133], v[186:189], v[62:65]
	v_mfma_f32_16x16x32_bf16 v[46:49], v[130:133], v[202:205], v[46:49]
	v_mfma_f32_16x16x32_bf16 v[30:33], v[130:133], v[232:235], v[30:33]
	v_mfma_f32_16x16x32_bf16 v[14:17], v[130:133], v[240:243], v[14:17]
	v_mfma_f32_16x16x32_bf16 v[58:61], v[142:145], v[186:189], v[58:61]
	v_mfma_f32_16x16x32_bf16 v[42:45], v[142:145], v[202:205], v[42:45]
	v_mfma_f32_16x16x32_bf16 v[26:29], v[142:145], v[232:235], v[26:29]
	v_mfma_f32_16x16x32_bf16 v[10:13], v[142:145], v[240:243], v[10:13]
	v_mfma_f32_16x16x32_bf16 v[62:65], v[138:141], v[198:201], v[62:65]
	v_mfma_f32_16x16x32_bf16 v[46:49], v[138:141], v[228:231], v[46:49]
	v_mfma_f32_16x16x32_bf16 v[30:33], v[138:141], v[236:239], v[30:33]
	v_mfma_f32_16x16x32_bf16 v[14:17], v[138:141], v[244:247], v[14:17]
	v_mfma_f32_16x16x32_bf16 v[58:61], v[154:157], v[198:201], v[58:61]
	v_mfma_f32_16x16x32_bf16 v[42:45], v[154:157], v[228:231], v[42:45]
	v_mfma_f32_16x16x32_bf16 v[26:29], v[154:157], v[236:239], v[26:29]
	v_mfma_f32_16x16x32_bf16 v[10:13], v[154:157], v[244:247], v[10:13]
	v_mfma_f32_16x16x32_bf16 v[54:57], v[170:173], v[186:189], v[54:57]
	v_mfma_f32_16x16x32_bf16 v[38:41], v[170:173], v[202:205], v[38:41]
	v_mfma_f32_16x16x32_bf16 v[22:25], v[170:173], v[232:235], v[22:25]
	v_mfma_f32_16x16x32_bf16 v[6:9], v[170:173], v[240:243], v[6:9]
	v_mfma_f32_16x16x32_bf16 v[50:53], v[178:181], v[186:189], v[50:53]
	v_mfma_f32_16x16x32_bf16 v[34:37], v[178:181], v[202:205], v[34:37]
	v_mfma_f32_16x16x32_bf16 v[18:21], v[178:181], v[232:235], v[18:21]
	v_mfma_f32_16x16x32_bf16 v[2:5], v[178:181], v[240:243], v[2:5]
	v_mfma_f32_16x16x32_bf16 v[54:57], v[174:177], v[198:201], v[54:57]
	v_mfma_f32_16x16x32_bf16 v[38:41], v[174:177], v[228:231], v[38:41]
	v_mfma_f32_16x16x32_bf16 v[22:25], v[174:177], v[236:239], v[22:25]
	v_mfma_f32_16x16x32_bf16 v[6:9], v[174:177], v[244:247], v[6:9]
	v_mfma_f32_16x16x32_bf16 v[50:53], v[182:185], v[198:201], v[50:53]
	v_mfma_f32_16x16x32_bf16 v[34:37], v[182:185], v[228:231], v[34:37]
	v_mfma_f32_16x16x32_bf16 v[18:21], v[182:185], v[236:239], v[18:21]
	v_mfma_f32_16x16x32_bf16 v[2:5], v[182:185], v[244:247], v[2:5]
	s_barrier
	s_setprio 0
	s_add_i32 s22, s22, 2
	s_addk_i32 s18, 0x100
	s_addk_i32 s19, 0x100
	s_cmp_gt_u32 s22, 29
	s_cbranch_scc0 .LBB0_859
	s_and_b64 vcc, exec, s[60:61]
	s_cbranch_vccz .LBB0_862
	s_barrier

.LBB0_880:
	s_lshl_b32 s14, s85, 20
	s_and_b64 s[8:9], s[42:43], exec
	s_cselect_b32 s8, s14, s12
	s_lshl_b32 s15, s66, 20
	s_and_b64 s[22:23], s[42:43], exec
	s_cselect_b32 s9, s15, s13
	s_add_i32 s12, s12, 0x80080
	s_addk_i32 s13, 0x100
	s_mov_b32 s16, -2
	v_add_u32_e32 v139, 0x10000, v234
	ds_read_b128 v[130:133], v139
	ds_read_b128 v[140:143], v139 offset:1024
	ds_read_b128 v[170:173], v139 offset:2048
	ds_read_b128 v[174:177], v139 offset:3072
	v_add_u32_e32 v139, 0x14000, v234
	ds_read_b128 v[178:181], v139
	ds_read_b128 v[182:185], v139 offset:1024
	ds_read_b128 v[186:189], v139 offset:2048
	ds_read_b128 v[190:193], v139 offset:3072
	s_add_i32 s21, s12, 0xfff80080
	s_cmp_eq_u32 s16, 28
	s_cselect_b32 s23, s8, s21
	s_cselect_b32 s22, s9, s13
	s_or_b32 s21, s23, 0x80
	s_mov_b32 m0, s72
	ds_read_b128 v[194:197], v235
	ds_read_b128 v[198:201], v235 offset:1024
	ds_read_b128 v[202:205], v235 offset:2048
	ds_read_b128 v[236:239], v235 offset:3072
	ds_read_b128 v[240:243], v235 offset:4096
	ds_read_b128 v[244:247], v235 offset:5120
	ds_read_b128 v[248:251], v235 offset:6144
	ds_read_b128 v[154:157], v235 offset:7168
	buffer_load_dwordx4 v228, s[60:63], s12 offen lds
	s_mov_b32 m0, s73
	s_nop 0
	buffer_load_dwordx4 v230, s[60:63], s12 offen lds
	s_waitcnt vmcnt(8)
	s_waitcnt lgkmcnt(0)
	s_setprio 1
	s_barrier
	v_mfma_f32_16x16x32_bf16 v[126:129], v[130:133], v[194:197], 0
	v_mfma_f32_16x16x32_bf16 v[114:117], v[130:133], v[202:205], 0
	v_mfma_f32_16x16x32_bf16 v[98:101], v[130:133], v[240:243], 0
	v_mfma_f32_16x16x32_bf16 v[82:85], v[130:133], v[248:251], 0
	v_mfma_f32_16x16x32_bf16 v[122:125], v[170:173], v[194:197], 0
	v_mfma_f32_16x16x32_bf16 v[106:109], v[170:173], v[202:205], 0
	v_mfma_f32_16x16x32_bf16 v[90:93], v[170:173], v[240:243], 0
	v_mfma_f32_16x16x32_bf16 v[74:77], v[170:173], v[248:251], 0
	v_mfma_f32_16x16x32_bf16 v[126:129], v[140:143], v[198:201], v[126:129]
	v_mfma_f32_16x16x32_bf16 v[114:117], v[140:143], v[236:239], v[114:117]
	v_mfma_f32_16x16x32_bf16 v[98:101], v[140:143], v[244:247], v[98:101]
	v_mfma_f32_16x16x32_bf16 v[82:85], v[140:143], v[154:157], v[82:85]
	v_mfma_f32_16x16x32_bf16 v[122:125], v[174:177], v[198:201], v[122:125]
	v_mfma_f32_16x16x32_bf16 v[106:109], v[174:177], v[236:239], v[106:109]
	v_mfma_f32_16x16x32_bf16 v[90:93], v[174:177], v[244:247], v[90:93]
	v_mfma_f32_16x16x32_bf16 v[74:77], v[174:177], v[154:157], v[74:77]
	v_mfma_f32_16x16x32_bf16 v[118:121], v[178:181], v[194:197], 0
	v_mfma_f32_16x16x32_bf16 v[102:105], v[178:181], v[202:205], 0
	v_mfma_f32_16x16x32_bf16 v[86:89], v[178:181], v[240:243], 0
	v_mfma_f32_16x16x32_bf16 v[70:73], v[178:181], v[248:251], 0
	v_mfma_f32_16x16x32_bf16 v[110:113], v[186:189], v[194:197], 0
	v_mfma_f32_16x16x32_bf16 v[94:97], v[186:189], v[202:205], 0
	v_mfma_f32_16x16x32_bf16 v[78:81], v[186:189], v[240:243], 0
	v_mfma_f32_16x16x32_bf16 v[66:69], v[186:189], v[248:251], 0
	v_mfma_f32_16x16x32_bf16 v[118:121], v[182:185], v[198:201], v[118:121]
	v_mfma_f32_16x16x32_bf16 v[102:105], v[182:185], v[236:239], v[102:105]
	v_mfma_f32_16x16x32_bf16 v[86:89], v[182:185], v[244:247], v[86:89]
	v_mfma_f32_16x16x32_bf16 v[70:73], v[182:185], v[154:157], v[70:73]
	v_mfma_f32_16x16x32_bf16 v[110:113], v[190:193], v[198:201], v[110:113]
	v_mfma_f32_16x16x32_bf16 v[94:97], v[190:193], v[236:239], v[94:97]
	v_mfma_f32_16x16x32_bf16 v[78:81], v[190:193], v[244:247], v[78:81]
	v_mfma_f32_16x16x32_bf16 v[66:69], v[190:193], v[154:157], v[66:69]
	s_barrier
	s_setprio 0
	s_mov_b32 m0, s26
	s_mov_b32 s46, s62
	s_mov_b32 s47, s63
	ds_read_b128 v[154:157], v235 offset:16384
	ds_read_b128 v[194:197], v235 offset:17408
	ds_read_b128 v[198:201], v235 offset:18432
	ds_read_b128 v[202:205], v235 offset:19456
	ds_read_b128 v[236:239], v235 offset:20480
	ds_read_b128 v[240:243], v235 offset:21504
	ds_read_b128 v[244:247], v235 offset:22528
	ds_read_b128 v[248:251], v235 offset:23552
	buffer_load_dwordx4 v229, s[44:47], s22 offen lds
	s_mov_b32 m0, s27
	s_add_i32 s38, s22, 0x80000
	buffer_load_dwordx4 v231, s[44:47], s22 offen lds
	s_mov_b32 m0, s34
	s_nop 0
	buffer_load_dwordx4 v229, s[44:47], s38 offen lds
	s_mov_b32 m0, s35
	s_nop 0
	buffer_load_dwordx4 v231, s[44:47], s38 offen lds
	s_mov_b32 m0, s19
	s_nop 0
	buffer_load_dwordx4 v228, s[60:63], s23 offen lds
	s_mov_b32 m0, s36
	s_nop 0
	buffer_load_dwordx4 v230, s[60:63], s23 offen lds
	s_waitcnt vmcnt(8)
	s_waitcnt lgkmcnt(0)
	s_setprio 1
	s_barrier
	v_mfma_f32_16x16x32_bf16 v[62:65], v[130:133], v[154:157], 0
	v_mfma_f32_16x16x32_bf16 v[50:53], v[130:133], v[198:201], 0
	v_mfma_f32_16x16x32_bf16 v[34:37], v[130:133], v[236:239], 0
	v_mfma_f32_16x16x32_bf16 v[18:21], v[130:133], v[244:247], 0
	v_mfma_f32_16x16x32_bf16 v[58:61], v[170:173], v[154:157], 0
	v_mfma_f32_16x16x32_bf16 v[42:45], v[170:173], v[198:201], 0
	v_mfma_f32_16x16x32_bf16 v[26:29], v[170:173], v[236:239], 0
	v_mfma_f32_16x16x32_bf16 v[10:13], v[170:173], v[244:247], 0
	v_mfma_f32_16x16x32_bf16 v[62:65], v[140:143], v[194:197], v[62:65]
	v_mfma_f32_16x16x32_bf16 v[50:53], v[140:143], v[202:205], v[50:53]
	v_mfma_f32_16x16x32_bf16 v[34:37], v[140:143], v[240:243], v[34:37]
	v_mfma_f32_16x16x32_bf16 v[18:21], v[140:143], v[248:251], v[18:21]
	v_mfma_f32_16x16x32_bf16 v[58:61], v[174:177], v[194:197], v[58:61]
	v_mfma_f32_16x16x32_bf16 v[42:45], v[174:177], v[202:205], v[42:45]
	v_mfma_f32_16x16x32_bf16 v[26:29], v[174:177], v[240:243], v[26:29]
	v_mfma_f32_16x16x32_bf16 v[10:13], v[174:177], v[248:251], v[10:13]
	v_mfma_f32_16x16x32_bf16 v[54:57], v[178:181], v[154:157], 0
	v_mfma_f32_16x16x32_bf16 v[38:41], v[178:181], v[198:201], 0
	v_mfma_f32_16x16x32_bf16 v[22:25], v[178:181], v[236:239], 0
	v_mfma_f32_16x16x32_bf16 v[6:9], v[178:181], v[244:247], 0
	v_mfma_f32_16x16x32_bf16 v[46:49], v[186:189], v[154:157], 0
	v_mfma_f32_16x16x32_bf16 v[30:33], v[186:189], v[198:201], 0
	v_mfma_f32_16x16x32_bf16 v[14:17], v[186:189], v[236:239], 0
	v_mfma_f32_16x16x32_bf16 v[2:5], v[186:189], v[244:247], 0
	v_mfma_f32_16x16x32_bf16 v[54:57], v[182:185], v[194:197], v[54:57]
	v_mfma_f32_16x16x32_bf16 v[38:41], v[182:185], v[202:205], v[38:41]
	v_mfma_f32_16x16x32_bf16 v[22:25], v[182:185], v[240:243], v[22:25]
	v_mfma_f32_16x16x32_bf16 v[6:9], v[182:185], v[248:251], v[6:9]
	v_mfma_f32_16x16x32_bf16 v[46:49], v[190:193], v[194:197], v[46:49]
	v_mfma_f32_16x16x32_bf16 v[30:33], v[190:193], v[202:205], v[30:33]
	v_mfma_f32_16x16x32_bf16 v[14:17], v[190:193], v[240:243], v[14:17]
	v_mfma_f32_16x16x32_bf16 v[2:5], v[190:193], v[248:251], v[2:5]
	s_barrier
	s_setprio 0
	v_add_u32_e32 v139, 0x18000, v234
	ds_read_b128 v[130:133], v139
	ds_read_b128 v[140:143], v139 offset:1024
	ds_read_b128 v[154:157], v139 offset:2048
	ds_read_b128 v[170:173], v139 offset:3072
	v_add_u32_e32 v139, 0x1c000, v234
	ds_read_b128 v[174:177], v139
	ds_read_b128 v[178:181], v139 offset:1024
	ds_read_b128 v[182:185], v139 offset:2048
	ds_read_b128 v[186:189], v139 offset:3072
	s_add_i32 s23, s23, 0x80000
	s_mov_b32 m0, s37
	ds_read_b128 v[190:193], v235 offset:32768
	ds_read_b128 v[194:197], v235 offset:33792
	ds_read_b128 v[198:201], v235 offset:34816
	ds_read_b128 v[202:205], v235 offset:35840
	ds_read_b128 v[236:239], v235 offset:36864
	ds_read_b128 v[240:243], v235 offset:37888
	ds_read_b128 v[244:247], v235 offset:38912
	ds_read_b128 v[248:251], v235 offset:39936
	buffer_load_dwordx4 v228, s[60:63], s23 offen lds
	s_mov_b32 m0, s18
	s_nop 0
	buffer_load_dwordx4 v230, s[60:63], s23 offen lds
	s_waitcnt vmcnt(8)
	s_waitcnt lgkmcnt(0)
	s_setprio 1
	s_barrier
	v_mfma_f32_16x16x32_bf16 v[126:129], v[130:133], v[190:193], v[126:129]
	v_mfma_f32_16x16x32_bf16 v[114:117], v[130:133], v[198:201], v[114:117]
	v_mfma_f32_16x16x32_bf16 v[98:101], v[130:133], v[236:239], v[98:101]
	v_mfma_f32_16x16x32_bf16 v[82:85], v[130:133], v[244:247], v[82:85]
	v_mfma_f32_16x16x32_bf16 v[122:125], v[154:157], v[190:193], v[122:125]
	v_mfma_f32_16x16x32_bf16 v[106:109], v[154:157], v[198:201], v[106:109]
	v_mfma_f32_16x16x32_bf16 v[90:93], v[154:157], v[236:239], v[90:93]
	v_mfma_f32_16x16x32_bf16 v[74:77], v[154:157], v[244:247], v[74:77]
	v_mfma_f32_16x16x32_bf16 v[126:129], v[140:143], v[194:197], v[126:129]
	v_mfma_f32_16x16x32_bf16 v[114:117], v[140:143], v[202:205], v[114:117]
	v_mfma_f32_16x16x32_bf16 v[98:101], v[140:143], v[240:243], v[98:101]
	v_mfma_f32_16x16x32_bf16 v[82:85], v[140:143], v[248:251], v[82:85]
	v_mfma_f32_16x16x32_bf16 v[122:125], v[170:173], v[194:197], v[122:125]
	v_mfma_f32_16x16x32_bf16 v[106:109], v[170:173], v[202:205], v[106:109]
	v_mfma_f32_16x16x32_bf16 v[90:93], v[170:173], v[240:243], v[90:93]
	v_mfma_f32_16x16x32_bf16 v[74:77], v[170:173], v[248:251], v[74:77]
	v_mfma_f32_16x16x32_bf16 v[118:121], v[174:177], v[190:193], v[118:121]
	v_mfma_f32_16x16x32_bf16 v[102:105], v[174:177], v[198:201], v[102:105]
	v_mfma_f32_16x16x32_bf16 v[86:89], v[174:177], v[236:239], v[86:89]
	v_mfma_f32_16x16x32_bf16 v[70:73], v[174:177], v[244:247], v[70:73]
	v_mfma_f32_16x16x32_bf16 v[110:113], v[182:185], v[190:193], v[110:113]
	v_mfma_f32_16x16x32_bf16 v[94:97], v[182:185], v[198:201], v[94:97]
	v_mfma_f32_16x16x32_bf16 v[78:81], v[182:185], v[236:239], v[78:81]
	v_mfma_f32_16x16x32_bf16 v[66:69], v[182:185], v[244:247], v[66:69]
	v_mfma_f32_16x16x32_bf16 v[118:121], v[178:181], v[194:197], v[118:121]
	v_mfma_f32_16x16x32_bf16 v[102:105], v[178:181], v[202:205], v[102:105]
	v_mfma_f32_16x16x32_bf16 v[86:89], v[178:181], v[240:243], v[86:89]
	v_mfma_f32_16x16x32_bf16 v[70:73], v[178:181], v[248:251], v[70:73]
	v_mfma_f32_16x16x32_bf16 v[110:113], v[186:189], v[194:197], v[110:113]
	v_mfma_f32_16x16x32_bf16 v[94:97], v[186:189], v[202:205], v[94:97]
	v_mfma_f32_16x16x32_bf16 v[78:81], v[186:189], v[240:243], v[78:81]
	v_mfma_f32_16x16x32_bf16 v[66:69], v[186:189], v[248:251], v[66:69]
	s_barrier
	s_setprio 0
	s_mov_b32 m0, s24
	s_or_b32 s23, s22, 0x80
	ds_read_b128 v[190:193], v235 offset:49152
	ds_read_b128 v[194:197], v235 offset:50176
	ds_read_b128 v[198:201], v235 offset:51200
	ds_read_b128 v[202:205], v235 offset:52224
	ds_read_b128 v[236:239], v235 offset:53248
	ds_read_b128 v[240:243], v235 offset:54272
	ds_read_b128 v[244:247], v235 offset:55296
	ds_read_b128 v[248:251], v235 offset:56320
	buffer_load_dwordx4 v229, s[44:47], s23 offen lds
	s_mov_b32 m0, s25
	s_add_i32 s22, s22, 0x80080
	buffer_load_dwordx4 v231, s[44:47], s23 offen lds
	s_mov_b32 m0, s64
	s_nop 0
	buffer_load_dwordx4 v229, s[44:47], s22 offen lds
	s_mov_b32 m0, s65
	s_nop 0
	buffer_load_dwordx4 v231, s[44:47], s22 offen lds
	s_mov_b32 m0, s48
	s_nop 0
	buffer_load_dwordx4 v228, s[60:63], s21 offen lds
	s_mov_b32 m0, s49
	s_nop 0
	buffer_load_dwordx4 v230, s[60:63], s21 offen lds
	s_waitcnt vmcnt(8)
	s_waitcnt lgkmcnt(0)
	s_setprio 1
	s_barrier
	v_mfma_f32_16x16x32_bf16 v[62:65], v[130:133], v[190:193], v[62:65]
	v_mfma_f32_16x16x32_bf16 v[50:53], v[130:133], v[198:201], v[50:53]
	v_mfma_f32_16x16x32_bf16 v[34:37], v[130:133], v[236:239], v[34:37]
	v_mfma_f32_16x16x32_bf16 v[18:21], v[130:133], v[244:247], v[18:21]
	v_mfma_f32_16x16x32_bf16 v[58:61], v[154:157], v[190:193], v[58:61]
	v_mfma_f32_16x16x32_bf16 v[42:45], v[154:157], v[198:201], v[42:45]
	v_mfma_f32_16x16x32_bf16 v[26:29], v[154:157], v[236:239], v[26:29]
	v_mfma_f32_16x16x32_bf16 v[10:13], v[154:157], v[244:247], v[10:13]
	v_mfma_f32_16x16x32_bf16 v[62:65], v[140:143], v[194:197], v[62:65]
	v_mfma_f32_16x16x32_bf16 v[50:53], v[140:143], v[202:205], v[50:53]
	v_mfma_f32_16x16x32_bf16 v[34:37], v[140:143], v[240:243], v[34:37]
	v_mfma_f32_16x16x32_bf16 v[18:21], v[140:143], v[248:251], v[18:21]
	v_mfma_f32_16x16x32_bf16 v[58:61], v[170:173], v[194:197], v[58:61]
	v_mfma_f32_16x16x32_bf16 v[42:45], v[170:173], v[202:205], v[42:45]
	v_mfma_f32_16x16x32_bf16 v[26:29], v[170:173], v[240:243], v[26:29]
	v_mfma_f32_16x16x32_bf16 v[10:13], v[170:173], v[248:251], v[10:13]
	v_mfma_f32_16x16x32_bf16 v[54:57], v[174:177], v[190:193], v[54:57]
	v_mfma_f32_16x16x32_bf16 v[38:41], v[174:177], v[198:201], v[38:41]
	v_mfma_f32_16x16x32_bf16 v[22:25], v[174:177], v[236:239], v[22:25]
	v_mfma_f32_16x16x32_bf16 v[6:9], v[174:177], v[244:247], v[6:9]
	v_mfma_f32_16x16x32_bf16 v[46:49], v[182:185], v[190:193], v[46:49]
	v_mfma_f32_16x16x32_bf16 v[30:33], v[182:185], v[198:201], v[30:33]
	v_mfma_f32_16x16x32_bf16 v[14:17], v[182:185], v[236:239], v[14:17]
	v_mfma_f32_16x16x32_bf16 v[2:5], v[182:185], v[244:247], v[2:5]
	v_mfma_f32_16x16x32_bf16 v[54:57], v[178:181], v[194:197], v[54:57]
	v_mfma_f32_16x16x32_bf16 v[38:41], v[178:181], v[202:205], v[38:41]
	v_mfma_f32_16x16x32_bf16 v[22:25], v[178:181], v[240:243], v[22:25]
	v_mfma_f32_16x16x32_bf16 v[6:9], v[178:181], v[248:251], v[6:9]
	v_mfma_f32_16x16x32_bf16 v[46:49], v[186:189], v[194:197], v[46:49]
	v_mfma_f32_16x16x32_bf16 v[30:33], v[186:189], v[202:205], v[30:33]
	v_mfma_f32_16x16x32_bf16 v[14:17], v[186:189], v[240:243], v[14:17]
	v_mfma_f32_16x16x32_bf16 v[2:5], v[186:189], v[248:251], v[2:5]
	s_barrier
	s_setprio 0
	s_add_i32 s16, s16, 2
	s_addk_i32 s12, 0x100
	s_addk_i32 s13, 0x100
	s_cmp_gt_u32 s16, 29
.LBB0_881:
	v_add_u32_e32 v139, 0x10000, v234
	ds_read_b128 v[130:133], v139
	ds_read_b128 v[140:143], v139 offset:1024
	ds_read_b128 v[170:173], v139 offset:2048
	ds_read_b128 v[174:177], v139 offset:3072
	v_add_u32_e32 v139, 0x14000, v234
	ds_read_b128 v[178:181], v139
	ds_read_b128 v[182:185], v139 offset:1024
	ds_read_b128 v[186:189], v139 offset:2048
	ds_read_b128 v[190:193], v139 offset:3072
	s_add_i32 s21, s12, 0xfff80080
	s_cmp_eq_u32 s16, 28
	s_cselect_b32 s23, s8, s21
	s_cselect_b32 s22, s9, s13
	s_or_b32 s21, s23, 0x80
	s_mov_b32 m0, s72
	ds_read_b128 v[194:197], v235
	ds_read_b128 v[198:201], v235 offset:1024
	ds_read_b128 v[202:205], v235 offset:2048
	ds_read_b128 v[236:239], v235 offset:3072
	ds_read_b128 v[240:243], v235 offset:4096
	ds_read_b128 v[244:247], v235 offset:5120
	ds_read_b128 v[248:251], v235 offset:6144
	ds_read_b128 v[154:157], v235 offset:7168
	buffer_load_dwordx4 v228, s[60:63], s12 offen lds
	s_mov_b32 m0, s73
	s_nop 0
	buffer_load_dwordx4 v230, s[60:63], s12 offen lds
	s_waitcnt vmcnt(8)
	s_waitcnt lgkmcnt(0)
	s_setprio 1
	s_barrier
	v_mfma_f32_16x16x32_bf16 v[126:129], v[130:133], v[194:197], v[126:129]
	v_mfma_f32_16x16x32_bf16 v[114:117], v[130:133], v[202:205], v[114:117]
	v_mfma_f32_16x16x32_bf16 v[98:101], v[130:133], v[240:243], v[98:101]
	v_mfma_f32_16x16x32_bf16 v[82:85], v[130:133], v[248:251], v[82:85]
	v_mfma_f32_16x16x32_bf16 v[122:125], v[170:173], v[194:197], v[122:125]
	v_mfma_f32_16x16x32_bf16 v[106:109], v[170:173], v[202:205], v[106:109]
	v_mfma_f32_16x16x32_bf16 v[90:93], v[170:173], v[240:243], v[90:93]
	v_mfma_f32_16x16x32_bf16 v[74:77], v[170:173], v[248:251], v[74:77]
	v_mfma_f32_16x16x32_bf16 v[126:129], v[140:143], v[198:201], v[126:129]
	v_mfma_f32_16x16x32_bf16 v[114:117], v[140:143], v[236:239], v[114:117]
	v_mfma_f32_16x16x32_bf16 v[98:101], v[140:143], v[244:247], v[98:101]
	v_mfma_f32_16x16x32_bf16 v[82:85], v[140:143], v[154:157], v[82:85]
	v_mfma_f32_16x16x32_bf16 v[122:125], v[174:177], v[198:201], v[122:125]
	v_mfma_f32_16x16x32_bf16 v[106:109], v[174:177], v[236:239], v[106:109]
	v_mfma_f32_16x16x32_bf16 v[90:93], v[174:177], v[244:247], v[90:93]
	v_mfma_f32_16x16x32_bf16 v[74:77], v[174:177], v[154:157], v[74:77]
	v_mfma_f32_16x16x32_bf16 v[118:121], v[178:181], v[194:197], v[118:121]
	v_mfma_f32_16x16x32_bf16 v[102:105], v[178:181], v[202:205], v[102:105]
	v_mfma_f32_16x16x32_bf16 v[86:89], v[178:181], v[240:243], v[86:89]
	v_mfma_f32_16x16x32_bf16 v[70:73], v[178:181], v[248:251], v[70:73]
	v_mfma_f32_16x16x32_bf16 v[110:113], v[186:189], v[194:197], v[110:113]
	v_mfma_f32_16x16x32_bf16 v[94:97], v[186:189], v[202:205], v[94:97]
	v_mfma_f32_16x16x32_bf16 v[78:81], v[186:189], v[240:243], v[78:81]
	v_mfma_f32_16x16x32_bf16 v[66:69], v[186:189], v[248:251], v[66:69]
	v_mfma_f32_16x16x32_bf16 v[118:121], v[182:185], v[198:201], v[118:121]
	v_mfma_f32_16x16x32_bf16 v[102:105], v[182:185], v[236:239], v[102:105]
	v_mfma_f32_16x16x32_bf16 v[86:89], v[182:185], v[244:247], v[86:89]
	v_mfma_f32_16x16x32_bf16 v[70:73], v[182:185], v[154:157], v[70:73]
	v_mfma_f32_16x16x32_bf16 v[110:113], v[190:193], v[198:201], v[110:113]
	v_mfma_f32_16x16x32_bf16 v[94:97], v[190:193], v[236:239], v[94:97]
	v_mfma_f32_16x16x32_bf16 v[78:81], v[190:193], v[244:247], v[78:81]
	v_mfma_f32_16x16x32_bf16 v[66:69], v[190:193], v[154:157], v[66:69]
	s_barrier
	s_setprio 0
	s_mov_b32 m0, s26
	s_mov_b32 s46, s62
	s_mov_b32 s47, s63
	ds_read_b128 v[154:157], v235 offset:16384
	ds_read_b128 v[194:197], v235 offset:17408
	ds_read_b128 v[198:201], v235 offset:18432
	ds_read_b128 v[202:205], v235 offset:19456
	ds_read_b128 v[236:239], v235 offset:20480
	ds_read_b128 v[240:243], v235 offset:21504
	ds_read_b128 v[244:247], v235 offset:22528
	ds_read_b128 v[248:251], v235 offset:23552
	buffer_load_dwordx4 v229, s[44:47], s22 offen lds
	s_mov_b32 m0, s27
	s_add_i32 s38, s22, 0x80000
	buffer_load_dwordx4 v231, s[44:47], s22 offen lds
	s_mov_b32 m0, s34
	s_nop 0
	buffer_load_dwordx4 v229, s[44:47], s38 offen lds
	s_mov_b32 m0, s35
	s_nop 0
	buffer_load_dwordx4 v231, s[44:47], s38 offen lds
	s_mov_b32 m0, s19
	s_nop 0
	buffer_load_dwordx4 v228, s[60:63], s23 offen lds
	s_mov_b32 m0, s36
	s_nop 0
	buffer_load_dwordx4 v230, s[60:63], s23 offen lds
	s_waitcnt vmcnt(8)
	s_waitcnt lgkmcnt(0)
	s_setprio 1
	s_barrier
	v_mfma_f32_16x16x32_bf16 v[62:65], v[130:133], v[154:157], v[62:65]
	v_mfma_f32_16x16x32_bf16 v[50:53], v[130:133], v[198:201], v[50:53]
	v_mfma_f32_16x16x32_bf16 v[34:37], v[130:133], v[236:239], v[34:37]
	v_mfma_f32_16x16x32_bf16 v[18:21], v[130:133], v[244:247], v[18:21]
	v_mfma_f32_16x16x32_bf16 v[58:61], v[170:173], v[154:157], v[58:61]
	v_mfma_f32_16x16x32_bf16 v[42:45], v[170:173], v[198:201], v[42:45]
	v_mfma_f32_16x16x32_bf16 v[26:29], v[170:173], v[236:239], v[26:29]
	v_mfma_f32_16x16x32_bf16 v[10:13], v[170:173], v[244:247], v[10:13]
	v_mfma_f32_16x16x32_bf16 v[62:65], v[140:143], v[194:197], v[62:65]
	v_mfma_f32_16x16x32_bf16 v[50:53], v[140:143], v[202:205], v[50:53]
	v_mfma_f32_16x16x32_bf16 v[34:37], v[140:143], v[240:243], v[34:37]
	v_mfma_f32_16x16x32_bf16 v[18:21], v[140:143], v[248:251], v[18:21]
	v_mfma_f32_16x16x32_bf16 v[58:61], v[174:177], v[194:197], v[58:61]
	v_mfma_f32_16x16x32_bf16 v[42:45], v[174:177], v[202:205], v[42:45]
	v_mfma_f32_16x16x32_bf16 v[26:29], v[174:177], v[240:243], v[26:29]
	v_mfma_f32_16x16x32_bf16 v[10:13], v[174:177], v[248:251], v[10:13]
	v_mfma_f32_16x16x32_bf16 v[54:57], v[178:181], v[154:157], v[54:57]
	v_mfma_f32_16x16x32_bf16 v[38:41], v[178:181], v[198:201], v[38:41]
	v_mfma_f32_16x16x32_bf16 v[22:25], v[178:181], v[236:239], v[22:25]
	v_mfma_f32_16x16x32_bf16 v[6:9], v[178:181], v[244:247], v[6:9]
	v_mfma_f32_16x16x32_bf16 v[46:49], v[186:189], v[154:157], v[46:49]
	v_mfma_f32_16x16x32_bf16 v[30:33], v[186:189], v[198:201], v[30:33]
	v_mfma_f32_16x16x32_bf16 v[14:17], v[186:189], v[236:239], v[14:17]
	v_mfma_f32_16x16x32_bf16 v[2:5], v[186:189], v[244:247], v[2:5]
	v_mfma_f32_16x16x32_bf16 v[54:57], v[182:185], v[194:197], v[54:57]
	v_mfma_f32_16x16x32_bf16 v[38:41], v[182:185], v[202:205], v[38:41]
	v_mfma_f32_16x16x32_bf16 v[22:25], v[182:185], v[240:243], v[22:25]
	v_mfma_f32_16x16x32_bf16 v[6:9], v[182:185], v[248:251], v[6:9]
	v_mfma_f32_16x16x32_bf16 v[46:49], v[190:193], v[194:197], v[46:49]
	v_mfma_f32_16x16x32_bf16 v[30:33], v[190:193], v[202:205], v[30:33]
	v_mfma_f32_16x16x32_bf16 v[14:17], v[190:193], v[240:243], v[14:17]
	v_mfma_f32_16x16x32_bf16 v[2:5], v[190:193], v[248:251], v[2:5]
	s_barrier
	s_setprio 0
	v_add_u32_e32 v139, 0x18000, v234
	ds_read_b128 v[130:133], v139
	ds_read_b128 v[140:143], v139 offset:1024
	ds_read_b128 v[154:157], v139 offset:2048
	ds_read_b128 v[170:173], v139 offset:3072
	v_add_u32_e32 v139, 0x1c000, v234
	ds_read_b128 v[174:177], v139
	ds_read_b128 v[178:181], v139 offset:1024
	ds_read_b128 v[182:185], v139 offset:2048
	ds_read_b128 v[186:189], v139 offset:3072
	s_add_i32 s23, s23, 0x80000
	s_mov_b32 m0, s37
	ds_read_b128 v[190:193], v235 offset:32768
	ds_read_b128 v[194:197], v235 offset:33792
	ds_read_b128 v[198:201], v235 offset:34816
	ds_read_b128 v[202:205], v235 offset:35840
	ds_read_b128 v[236:239], v235 offset:36864
	ds_read_b128 v[240:243], v235 offset:37888
	ds_read_b128 v[244:247], v235 offset:38912
	ds_read_b128 v[248:251], v235 offset:39936
	buffer_load_dwordx4 v228, s[60:63], s23 offen lds
	s_mov_b32 m0, s18
	s_nop 0
	buffer_load_dwordx4 v230, s[60:63], s23 offen lds
	s_waitcnt vmcnt(8)
	s_waitcnt lgkmcnt(0)
	s_setprio 1
	s_barrier
	v_mfma_f32_16x16x32_bf16 v[126:129], v[130:133], v[190:193], v[126:129]
	v_mfma_f32_16x16x32_bf16 v[114:117], v[130:133], v[198:201], v[114:117]
	v_mfma_f32_16x16x32_bf16 v[98:101], v[130:133], v[236:239], v[98:101]
	v_mfma_f32_16x16x32_bf16 v[82:85], v[130:133], v[244:247], v[82:85]
	v_mfma_f32_16x16x32_bf16 v[122:125], v[154:157], v[190:193], v[122:125]
	v_mfma_f32_16x16x32_bf16 v[106:109], v[154:157], v[198:201], v[106:109]
	v_mfma_f32_16x16x32_bf16 v[90:93], v[154:157], v[236:239], v[90:93]
	v_mfma_f32_16x16x32_bf16 v[74:77], v[154:157], v[244:247], v[74:77]
	v_mfma_f32_16x16x32_bf16 v[126:129], v[140:143], v[194:197], v[126:129]
	v_mfma_f32_16x16x32_bf16 v[114:117], v[140:143], v[202:205], v[114:117]
	v_mfma_f32_16x16x32_bf16 v[98:101], v[140:143], v[240:243], v[98:101]
	v_mfma_f32_16x16x32_bf16 v[82:85], v[140:143], v[248:251], v[82:85]
	v_mfma_f32_16x16x32_bf16 v[122:125], v[170:173], v[194:197], v[122:125]
	v_mfma_f32_16x16x32_bf16 v[106:109], v[170:173], v[202:205], v[106:109]
	v_mfma_f32_16x16x32_bf16 v[90:93], v[170:173], v[240:243], v[90:93]
	v_mfma_f32_16x16x32_bf16 v[74:77], v[170:173], v[248:251], v[74:77]
	v_mfma_f32_16x16x32_bf16 v[118:121], v[174:177], v[190:193], v[118:121]
	v_mfma_f32_16x16x32_bf16 v[102:105], v[174:177], v[198:201], v[102:105]
	v_mfma_f32_16x16x32_bf16 v[86:89], v[174:177], v[236:239], v[86:89]
	v_mfma_f32_16x16x32_bf16 v[70:73], v[174:177], v[244:247], v[70:73]
	v_mfma_f32_16x16x32_bf16 v[110:113], v[182:185], v[190:193], v[110:113]
	v_mfma_f32_16x16x32_bf16 v[94:97], v[182:185], v[198:201], v[94:97]
	v_mfma_f32_16x16x32_bf16 v[78:81], v[182:185], v[236:239], v[78:81]
	v_mfma_f32_16x16x32_bf16 v[66:69], v[182:185], v[244:247], v[66:69]
	v_mfma_f32_16x16x32_bf16 v[118:121], v[178:181], v[194:197], v[118:121]
	v_mfma_f32_16x16x32_bf16 v[102:105], v[178:181], v[202:205], v[102:105]
	v_mfma_f32_16x16x32_bf16 v[86:89], v[178:181], v[240:243], v[86:89]
	v_mfma_f32_16x16x32_bf16 v[70:73], v[178:181], v[248:251], v[70:73]
	v_mfma_f32_16x16x32_bf16 v[110:113], v[186:189], v[194:197], v[110:113]
	v_mfma_f32_16x16x32_bf16 v[94:97], v[186:189], v[202:205], v[94:97]
	v_mfma_f32_16x16x32_bf16 v[78:81], v[186:189], v[240:243], v[78:81]
	v_mfma_f32_16x16x32_bf16 v[66:69], v[186:189], v[248:251], v[66:69]
	s_barrier
	s_setprio 0
	s_mov_b32 m0, s24
	s_or_b32 s23, s22, 0x80
	ds_read_b128 v[190:193], v235 offset:49152
	ds_read_b128 v[194:197], v235 offset:50176
	ds_read_b128 v[198:201], v235 offset:51200
	ds_read_b128 v[202:205], v235 offset:52224
	ds_read_b128 v[236:239], v235 offset:53248
	ds_read_b128 v[240:243], v235 offset:54272
	ds_read_b128 v[244:247], v235 offset:55296
	ds_read_b128 v[248:251], v235 offset:56320
	buffer_load_dwordx4 v229, s[44:47], s23 offen lds
	s_mov_b32 m0, s25
	s_add_i32 s22, s22, 0x80080
	buffer_load_dwordx4 v231, s[44:47], s23 offen lds
	s_mov_b32 m0, s64
	s_nop 0
	buffer_load_dwordx4 v229, s[44:47], s22 offen lds
	s_mov_b32 m0, s65
	s_nop 0
	buffer_load_dwordx4 v231, s[44:47], s22 offen lds
	s_mov_b32 m0, s48
	s_nop 0
	buffer_load_dwordx4 v228, s[60:63], s21 offen lds
	s_mov_b32 m0, s49
	s_nop 0
	buffer_load_dwordx4 v230, s[60:63], s21 offen lds
	s_waitcnt vmcnt(8)
	s_waitcnt lgkmcnt(0)
	s_setprio 1
	s_barrier
	v_mfma_f32_16x16x32_bf16 v[62:65], v[130:133], v[190:193], v[62:65]
	v_mfma_f32_16x16x32_bf16 v[50:53], v[130:133], v[198:201], v[50:53]
	v_mfma_f32_16x16x32_bf16 v[34:37], v[130:133], v[236:239], v[34:37]
	v_mfma_f32_16x16x32_bf16 v[18:21], v[130:133], v[244:247], v[18:21]
	v_mfma_f32_16x16x32_bf16 v[58:61], v[154:157], v[190:193], v[58:61]
	v_mfma_f32_16x16x32_bf16 v[42:45], v[154:157], v[198:201], v[42:45]
	v_mfma_f32_16x16x32_bf16 v[26:29], v[154:157], v[236:239], v[26:29]
	v_mfma_f32_16x16x32_bf16 v[10:13], v[154:157], v[244:247], v[10:13]
	v_mfma_f32_16x16x32_bf16 v[62:65], v[140:143], v[194:197], v[62:65]
	v_mfma_f32_16x16x32_bf16 v[50:53], v[140:143], v[202:205], v[50:53]
	v_mfma_f32_16x16x32_bf16 v[34:37], v[140:143], v[240:243], v[34:37]
	v_mfma_f32_16x16x32_bf16 v[18:21], v[140:143], v[248:251], v[18:21]
	v_mfma_f32_16x16x32_bf16 v[58:61], v[170:173], v[194:197], v[58:61]
	v_mfma_f32_16x16x32_bf16 v[42:45], v[170:173], v[202:205], v[42:45]
	v_mfma_f32_16x16x32_bf16 v[26:29], v[170:173], v[240:243], v[26:29]
	v_mfma_f32_16x16x32_bf16 v[10:13], v[170:173], v[248:251], v[10:13]
	v_mfma_f32_16x16x32_bf16 v[54:57], v[174:177], v[190:193], v[54:57]
	v_mfma_f32_16x16x32_bf16 v[38:41], v[174:177], v[198:201], v[38:41]
	v_mfma_f32_16x16x32_bf16 v[22:25], v[174:177], v[236:239], v[22:25]
	v_mfma_f32_16x16x32_bf16 v[6:9], v[174:177], v[244:247], v[6:9]
	v_mfma_f32_16x16x32_bf16 v[46:49], v[182:185], v[190:193], v[46:49]
	v_mfma_f32_16x16x32_bf16 v[30:33], v[182:185], v[198:201], v[30:33]
	v_mfma_f32_16x16x32_bf16 v[14:17], v[182:185], v[236:239], v[14:17]
	v_mfma_f32_16x16x32_bf16 v[2:5], v[182:185], v[244:247], v[2:5]
	v_mfma_f32_16x16x32_bf16 v[54:57], v[178:181], v[194:197], v[54:57]
	v_mfma_f32_16x16x32_bf16 v[38:41], v[178:181], v[202:205], v[38:41]
	v_mfma_f32_16x16x32_bf16 v[22:25], v[178:181], v[240:243], v[22:25]
	v_mfma_f32_16x16x32_bf16 v[6:9], v[178:181], v[248:251], v[6:9]
	v_mfma_f32_16x16x32_bf16 v[46:49], v[186:189], v[194:197], v[46:49]
	v_mfma_f32_16x16x32_bf16 v[30:33], v[186:189], v[202:205], v[30:33]
	v_mfma_f32_16x16x32_bf16 v[14:17], v[186:189], v[240:243], v[14:17]
	v_mfma_f32_16x16x32_bf16 v[2:5], v[186:189], v[248:251], v[2:5]
	s_barrier
	s_setprio 0
	s_add_i32 s16, s16, 2
	s_addk_i32 s12, 0x100
	s_addk_i32 s13, 0x100
	s_cmp_gt_u32 s16, 29
	s_cbranch_scc0 .LBB0_881
	v_readlane_b32 s8, v255, 44
	v_readlane_b32 s9, v255, 45
	s_and_b64 vcc, exec, s[8:9]
	s_cbranch_vccz .LBB0_884
	s_barrier

.LBB0_904:
	s_lshl_b32 s73, s72, 20
	s_and_b64 s[8:9], s[42:43], exec
	s_cselect_b32 s8, s73, s13
	s_lshl_b32 s84, s71, 20
	s_and_b64 s[22:23], s[42:43], exec
	s_cselect_b32 s9, s84, s21
	s_add_i32 s13, s13, 0x80080
	s_addk_i32 s21, 0x100
	s_mov_b32 s22, -2
	v_add_u32_e32 v133, 0x10000, v178
	ds_read_b128 v[134:137], v133
	ds_read_b128 v[138:141], v133 offset:1024
	ds_read_b128 v[142:145], v133 offset:2048
	ds_read_b128 v[154:157], v133 offset:3072
	v_add_u32_e32 v133, 0x14000, v178
	ds_read_b128 v[170:173], v133
	ds_read_b128 v[180:183], v133 offset:1024
	ds_read_b128 v[184:187], v133 offset:2048
	ds_read_b128 v[188:191], v133 offset:3072
	s_add_i32 s23, s13, 0xfff80080
	s_cmp_eq_u32 s22, 28
	s_cselect_b32 s27, s8, s23
	s_cselect_b32 s26, s9, s21
	s_or_b32 s23, s27, 0x80
	s_mov_b32 s46, s62
	s_mov_b32 s47, s63
	s_mov_b32 m0, s68
	ds_read_b128 v[192:195], v179
	ds_read_b128 v[196:199], v179 offset:1024
	ds_read_b128 v[200:203], v179 offset:2048
	ds_read_b128 v[204:207], v179 offset:3072
	ds_read_b128 v[228:231], v179 offset:4096
	ds_read_b128 v[232:235], v179 offset:5120
	ds_read_b128 v[236:239], v179 offset:6144
	ds_read_b128 v[240:243], v179 offset:7168
	buffer_load_dwordx4 v174, s[44:47], s13 offen lds
	s_mov_b32 m0, s69
	s_nop 0
	buffer_load_dwordx4 v176, s[44:47], s13 offen lds
	s_waitcnt vmcnt(8)
	s_waitcnt lgkmcnt(0)
	s_setprio 1
	s_barrier
	v_mfma_f32_16x16x32_bf16 v[126:129], v[134:137], v[192:195], 0
	v_mfma_f32_16x16x32_bf16 v[110:113], v[134:137], v[200:203], 0
	v_mfma_f32_16x16x32_bf16 v[94:97], v[134:137], v[228:231], 0
	v_mfma_f32_16x16x32_bf16 v[78:81], v[134:137], v[236:239], 0
	v_mfma_f32_16x16x32_bf16 v[122:125], v[142:145], v[192:195], 0
	v_mfma_f32_16x16x32_bf16 v[106:109], v[142:145], v[200:203], 0
	v_mfma_f32_16x16x32_bf16 v[90:93], v[142:145], v[228:231], 0
	v_mfma_f32_16x16x32_bf16 v[74:77], v[142:145], v[236:239], 0
	v_mfma_f32_16x16x32_bf16 v[126:129], v[138:141], v[196:199], v[126:129]
	v_mfma_f32_16x16x32_bf16 v[110:113], v[138:141], v[204:207], v[110:113]
	v_mfma_f32_16x16x32_bf16 v[94:97], v[138:141], v[232:235], v[94:97]
	v_mfma_f32_16x16x32_bf16 v[78:81], v[138:141], v[240:243], v[78:81]
	v_mfma_f32_16x16x32_bf16 v[122:125], v[154:157], v[196:199], v[122:125]
	v_mfma_f32_16x16x32_bf16 v[106:109], v[154:157], v[204:207], v[106:109]
	v_mfma_f32_16x16x32_bf16 v[90:93], v[154:157], v[232:235], v[90:93]
	v_mfma_f32_16x16x32_bf16 v[74:77], v[154:157], v[240:243], v[74:77]
	v_mfma_f32_16x16x32_bf16 v[118:121], v[170:173], v[192:195], 0
	v_mfma_f32_16x16x32_bf16 v[102:105], v[170:173], v[200:203], 0
	v_mfma_f32_16x16x32_bf16 v[86:89], v[170:173], v[228:231], 0
	v_mfma_f32_16x16x32_bf16 v[70:73], v[170:173], v[236:239], 0
	v_mfma_f32_16x16x32_bf16 v[114:117], v[184:187], v[192:195], 0
	v_mfma_f32_16x16x32_bf16 v[98:101], v[184:187], v[200:203], 0
	v_mfma_f32_16x16x32_bf16 v[82:85], v[184:187], v[228:231], 0
	v_mfma_f32_16x16x32_bf16 v[66:69], v[184:187], v[236:239], 0
	v_mfma_f32_16x16x32_bf16 v[118:121], v[180:183], v[196:199], v[118:121]
	v_mfma_f32_16x16x32_bf16 v[102:105], v[180:183], v[204:207], v[102:105]
	v_mfma_f32_16x16x32_bf16 v[86:89], v[180:183], v[232:235], v[86:89]
	v_mfma_f32_16x16x32_bf16 v[70:73], v[180:183], v[240:243], v[70:73]
	v_mfma_f32_16x16x32_bf16 v[114:117], v[188:191], v[196:199], v[114:117]
	v_mfma_f32_16x16x32_bf16 v[98:101], v[188:191], v[204:207], v[98:101]
	v_mfma_f32_16x16x32_bf16 v[82:85], v[188:191], v[232:235], v[82:85]
	v_mfma_f32_16x16x32_bf16 v[66:69], v[188:191], v[240:243], v[66:69]
	s_barrier
	s_setprio 0
	s_mov_b32 m0, s15
	ds_read_b128 v[192:195], v179 offset:16384
	ds_read_b128 v[196:199], v179 offset:17408
	ds_read_b128 v[200:203], v179 offset:18432
	ds_read_b128 v[204:207], v179 offset:19456
	ds_read_b128 v[228:231], v179 offset:20480
	ds_read_b128 v[232:235], v179 offset:21504
	ds_read_b128 v[236:239], v179 offset:22528
	ds_read_b128 v[240:243], v179 offset:23552
	buffer_load_dwordx4 v175, s[60:63], s26 offen lds
	s_mov_b32 m0, s16
	s_add_i32 s34, s26, 0x80000
	buffer_load_dwordx4 v177, s[60:63], s26 offen lds
	s_mov_b32 m0, s18
	s_nop 0
	buffer_load_dwordx4 v175, s[60:63], s34 offen lds
	s_mov_b32 m0, s19
	s_nop 0
	buffer_load_dwordx4 v177, s[60:63], s34 offen lds
	s_mov_b32 m0, s14
	s_nop 0
	buffer_load_dwordx4 v174, s[44:47], s27 offen lds
	s_mov_b32 m0, s24
	s_nop 0
	buffer_load_dwordx4 v176, s[44:47], s27 offen lds
	s_waitcnt vmcnt(8)
	s_waitcnt lgkmcnt(0)
	s_setprio 1
	s_barrier
	v_mfma_f32_16x16x32_bf16 v[62:65], v[134:137], v[192:195], 0
	v_mfma_f32_16x16x32_bf16 v[46:49], v[134:137], v[200:203], 0
	v_mfma_f32_16x16x32_bf16 v[30:33], v[134:137], v[228:231], 0
	v_mfma_f32_16x16x32_bf16 v[14:17], v[134:137], v[236:239], 0
	v_mfma_f32_16x16x32_bf16 v[58:61], v[142:145], v[192:195], 0
	v_mfma_f32_16x16x32_bf16 v[42:45], v[142:145], v[200:203], 0
	v_mfma_f32_16x16x32_bf16 v[26:29], v[142:145], v[228:231], 0
	v_mfma_f32_16x16x32_bf16 v[10:13], v[142:145], v[236:239], 0
	v_mfma_f32_16x16x32_bf16 v[62:65], v[138:141], v[196:199], v[62:65]
	v_mfma_f32_16x16x32_bf16 v[46:49], v[138:141], v[204:207], v[46:49]
	v_mfma_f32_16x16x32_bf16 v[30:33], v[138:141], v[232:235], v[30:33]
	v_mfma_f32_16x16x32_bf16 v[14:17], v[138:141], v[240:243], v[14:17]
	v_mfma_f32_16x16x32_bf16 v[58:61], v[154:157], v[196:199], v[58:61]
	v_mfma_f32_16x16x32_bf16 v[42:45], v[154:157], v[204:207], v[42:45]
	v_mfma_f32_16x16x32_bf16 v[26:29], v[154:157], v[232:235], v[26:29]
	v_mfma_f32_16x16x32_bf16 v[10:13], v[154:157], v[240:243], v[10:13]
	v_mfma_f32_16x16x32_bf16 v[54:57], v[170:173], v[192:195], 0
	v_mfma_f32_16x16x32_bf16 v[38:41], v[170:173], v[200:203], 0
	v_mfma_f32_16x16x32_bf16 v[22:25], v[170:173], v[228:231], 0
	v_mfma_f32_16x16x32_bf16 v[6:9], v[170:173], v[236:239], 0
	v_mfma_f32_16x16x32_bf16 v[50:53], v[184:187], v[192:195], 0
	v_mfma_f32_16x16x32_bf16 v[34:37], v[184:187], v[200:203], 0
	v_mfma_f32_16x16x32_bf16 v[18:21], v[184:187], v[228:231], 0
	v_mfma_f32_16x16x32_bf16 v[2:5], v[184:187], v[236:239], 0
	v_mfma_f32_16x16x32_bf16 v[54:57], v[180:183], v[196:199], v[54:57]
	v_mfma_f32_16x16x32_bf16 v[38:41], v[180:183], v[204:207], v[38:41]
	v_mfma_f32_16x16x32_bf16 v[22:25], v[180:183], v[232:235], v[22:25]
	v_mfma_f32_16x16x32_bf16 v[6:9], v[180:183], v[240:243], v[6:9]
	v_mfma_f32_16x16x32_bf16 v[50:53], v[188:191], v[196:199], v[50:53]
	v_mfma_f32_16x16x32_bf16 v[34:37], v[188:191], v[204:207], v[34:37]
	v_mfma_f32_16x16x32_bf16 v[18:21], v[188:191], v[232:235], v[18:21]
	v_mfma_f32_16x16x32_bf16 v[2:5], v[188:191], v[240:243], v[2:5]
	s_barrier
	s_setprio 0
	v_add_u32_e32 v133, 0x18000, v178
	ds_read_b128 v[134:137], v133
	ds_read_b128 v[138:141], v133 offset:1024
	ds_read_b128 v[142:145], v133 offset:2048
	ds_read_b128 v[154:157], v133 offset:3072
	v_add_u32_e32 v133, 0x1c000, v178
	ds_read_b128 v[170:173], v133
	ds_read_b128 v[180:183], v133 offset:1024
	ds_read_b128 v[184:187], v133 offset:2048
	ds_read_b128 v[188:191], v133 offset:3072
	s_add_i32 s27, s27, 0x80000
	s_mov_b32 m0, s25
	ds_read_b128 v[192:195], v179 offset:32768
	ds_read_b128 v[196:199], v179 offset:33792
	ds_read_b128 v[200:203], v179 offset:34816
	ds_read_b128 v[204:207], v179 offset:35840
	ds_read_b128 v[228:231], v179 offset:36864
	ds_read_b128 v[232:235], v179 offset:37888
	ds_read_b128 v[236:239], v179 offset:38912
	ds_read_b128 v[240:243], v179 offset:39936
	buffer_load_dwordx4 v174, s[44:47], s27 offen lds
	s_mov_b32 m0, s30
	s_nop 0
	buffer_load_dwordx4 v176, s[44:47], s27 offen lds
	s_waitcnt vmcnt(8)
	s_waitcnt lgkmcnt(0)
	s_setprio 1
	s_barrier
	v_mfma_f32_16x16x32_bf16 v[126:129], v[134:137], v[192:195], v[126:129]
	v_mfma_f32_16x16x32_bf16 v[110:113], v[134:137], v[200:203], v[110:113]
	v_mfma_f32_16x16x32_bf16 v[94:97], v[134:137], v[228:231], v[94:97]
	v_mfma_f32_16x16x32_bf16 v[78:81], v[134:137], v[236:239], v[78:81]
	v_mfma_f32_16x16x32_bf16 v[122:125], v[142:145], v[192:195], v[122:125]
	v_mfma_f32_16x16x32_bf16 v[106:109], v[142:145], v[200:203], v[106:109]
	v_mfma_f32_16x16x32_bf16 v[90:93], v[142:145], v[228:231], v[90:93]
	v_mfma_f32_16x16x32_bf16 v[74:77], v[142:145], v[236:239], v[74:77]
	v_mfma_f32_16x16x32_bf16 v[126:129], v[138:141], v[196:199], v[126:129]
	v_mfma_f32_16x16x32_bf16 v[110:113], v[138:141], v[204:207], v[110:113]
	v_mfma_f32_16x16x32_bf16 v[94:97], v[138:141], v[232:235], v[94:97]
	v_mfma_f32_16x16x32_bf16 v[78:81], v[138:141], v[240:243], v[78:81]
	v_mfma_f32_16x16x32_bf16 v[122:125], v[154:157], v[196:199], v[122:125]
	v_mfma_f32_16x16x32_bf16 v[106:109], v[154:157], v[204:207], v[106:109]
	v_mfma_f32_16x16x32_bf16 v[90:93], v[154:157], v[232:235], v[90:93]
	v_mfma_f32_16x16x32_bf16 v[74:77], v[154:157], v[240:243], v[74:77]
	v_mfma_f32_16x16x32_bf16 v[118:121], v[170:173], v[192:195], v[118:121]
	v_mfma_f32_16x16x32_bf16 v[102:105], v[170:173], v[200:203], v[102:105]
	v_mfma_f32_16x16x32_bf16 v[86:89], v[170:173], v[228:231], v[86:89]
	v_mfma_f32_16x16x32_bf16 v[70:73], v[170:173], v[236:239], v[70:73]
	v_mfma_f32_16x16x32_bf16 v[114:117], v[184:187], v[192:195], v[114:117]
	v_mfma_f32_16x16x32_bf16 v[98:101], v[184:187], v[200:203], v[98:101]
	v_mfma_f32_16x16x32_bf16 v[82:85], v[184:187], v[228:231], v[82:85]
	v_mfma_f32_16x16x32_bf16 v[66:69], v[184:187], v[236:239], v[66:69]
	v_mfma_f32_16x16x32_bf16 v[118:121], v[180:183], v[196:199], v[118:121]
	v_mfma_f32_16x16x32_bf16 v[102:105], v[180:183], v[204:207], v[102:105]
	v_mfma_f32_16x16x32_bf16 v[86:89], v[180:183], v[232:235], v[86:89]
	v_mfma_f32_16x16x32_bf16 v[70:73], v[180:183], v[240:243], v[70:73]
	v_mfma_f32_16x16x32_bf16 v[114:117], v[188:191], v[196:199], v[114:117]
	v_mfma_f32_16x16x32_bf16 v[98:101], v[188:191], v[204:207], v[98:101]
	v_mfma_f32_16x16x32_bf16 v[82:85], v[188:191], v[232:235], v[82:85]
	v_mfma_f32_16x16x32_bf16 v[66:69], v[188:191], v[240:243], v[66:69]
	s_barrier
	s_setprio 0
	s_mov_b32 m0, s36
	s_or_b32 s27, s26, 0x80
	ds_read_b128 v[192:195], v179 offset:49152
	ds_read_b128 v[196:199], v179 offset:50176
	ds_read_b128 v[200:203], v179 offset:51200
	ds_read_b128 v[204:207], v179 offset:52224
	ds_read_b128 v[228:231], v179 offset:53248
	ds_read_b128 v[232:235], v179 offset:54272
	ds_read_b128 v[236:239], v179 offset:55296
	ds_read_b128 v[240:243], v179 offset:56320
	buffer_load_dwordx4 v175, s[60:63], s27 offen lds
	s_mov_b32 m0, s37
	s_add_i32 s26, s26, 0x80080
	buffer_load_dwordx4 v177, s[60:63], s27 offen lds
	s_mov_b32 m0, s48
	s_nop 0
	buffer_load_dwordx4 v175, s[60:63], s26 offen lds
	s_mov_b32 m0, s49
	s_nop 0
	buffer_load_dwordx4 v177, s[60:63], s26 offen lds
	s_mov_b32 m0, s40
	s_nop 0
	buffer_load_dwordx4 v174, s[44:47], s23 offen lds
	s_mov_b32 m0, s41
	s_nop 0
	buffer_load_dwordx4 v176, s[44:47], s23 offen lds
	s_waitcnt vmcnt(8)
	s_waitcnt lgkmcnt(0)
	s_setprio 1
	s_barrier
	v_mfma_f32_16x16x32_bf16 v[62:65], v[134:137], v[192:195], v[62:65]
	v_mfma_f32_16x16x32_bf16 v[46:49], v[134:137], v[200:203], v[46:49]
	v_mfma_f32_16x16x32_bf16 v[30:33], v[134:137], v[228:231], v[30:33]
	v_mfma_f32_16x16x32_bf16 v[14:17], v[134:137], v[236:239], v[14:17]
	v_mfma_f32_16x16x32_bf16 v[58:61], v[142:145], v[192:195], v[58:61]
	v_mfma_f32_16x16x32_bf16 v[42:45], v[142:145], v[200:203], v[42:45]
	v_mfma_f32_16x16x32_bf16 v[26:29], v[142:145], v[228:231], v[26:29]
	v_mfma_f32_16x16x32_bf16 v[10:13], v[142:145], v[236:239], v[10:13]
	v_mfma_f32_16x16x32_bf16 v[62:65], v[138:141], v[196:199], v[62:65]
	v_mfma_f32_16x16x32_bf16 v[46:49], v[138:141], v[204:207], v[46:49]
	v_mfma_f32_16x16x32_bf16 v[30:33], v[138:141], v[232:235], v[30:33]
	v_mfma_f32_16x16x32_bf16 v[14:17], v[138:141], v[240:243], v[14:17]
	v_mfma_f32_16x16x32_bf16 v[58:61], v[154:157], v[196:199], v[58:61]
	v_mfma_f32_16x16x32_bf16 v[42:45], v[154:157], v[204:207], v[42:45]
	v_mfma_f32_16x16x32_bf16 v[26:29], v[154:157], v[232:235], v[26:29]
	v_mfma_f32_16x16x32_bf16 v[10:13], v[154:157], v[240:243], v[10:13]
	v_mfma_f32_16x16x32_bf16 v[54:57], v[170:173], v[192:195], v[54:57]
	v_mfma_f32_16x16x32_bf16 v[38:41], v[170:173], v[200:203], v[38:41]
	v_mfma_f32_16x16x32_bf16 v[22:25], v[170:173], v[228:231], v[22:25]
	v_mfma_f32_16x16x32_bf16 v[6:9], v[170:173], v[236:239], v[6:9]
	v_mfma_f32_16x16x32_bf16 v[50:53], v[184:187], v[192:195], v[50:53]
	v_mfma_f32_16x16x32_bf16 v[34:37], v[184:187], v[200:203], v[34:37]
	v_mfma_f32_16x16x32_bf16 v[18:21], v[184:187], v[228:231], v[18:21]
	v_mfma_f32_16x16x32_bf16 v[2:5], v[184:187], v[236:239], v[2:5]
	v_mfma_f32_16x16x32_bf16 v[54:57], v[180:183], v[196:199], v[54:57]
	v_mfma_f32_16x16x32_bf16 v[38:41], v[180:183], v[204:207], v[38:41]
	v_mfma_f32_16x16x32_bf16 v[22:25], v[180:183], v[232:235], v[22:25]
	v_mfma_f32_16x16x32_bf16 v[6:9], v[180:183], v[240:243], v[6:9]
	v_mfma_f32_16x16x32_bf16 v[50:53], v[188:191], v[196:199], v[50:53]
	v_mfma_f32_16x16x32_bf16 v[34:37], v[188:191], v[204:207], v[34:37]
	v_mfma_f32_16x16x32_bf16 v[18:21], v[188:191], v[232:235], v[18:21]
	v_mfma_f32_16x16x32_bf16 v[2:5], v[188:191], v[240:243], v[2:5]
	s_barrier
	s_setprio 0
	s_add_i32 s22, s22, 2
	s_addk_i32 s13, 0x100
	s_addk_i32 s21, 0x100
	s_cmp_gt_u32 s22, 29
.LBB0_905:
	v_add_u32_e32 v133, 0x10000, v178
	ds_read_b128 v[134:137], v133
	ds_read_b128 v[138:141], v133 offset:1024
	ds_read_b128 v[142:145], v133 offset:2048
	ds_read_b128 v[154:157], v133 offset:3072
	v_add_u32_e32 v133, 0x14000, v178
	ds_read_b128 v[170:173], v133
	ds_read_b128 v[180:183], v133 offset:1024
	ds_read_b128 v[184:187], v133 offset:2048
	ds_read_b128 v[188:191], v133 offset:3072
	s_add_i32 s23, s13, 0xfff80080
	s_cmp_eq_u32 s22, 28
	s_cselect_b32 s27, s8, s23
	s_cselect_b32 s26, s9, s21
	s_or_b32 s23, s27, 0x80
	s_mov_b32 s46, s62
	s_mov_b32 s47, s63
	s_mov_b32 m0, s68
	ds_read_b128 v[192:195], v179
	ds_read_b128 v[196:199], v179 offset:1024
	ds_read_b128 v[200:203], v179 offset:2048
	ds_read_b128 v[204:207], v179 offset:3072
	ds_read_b128 v[228:231], v179 offset:4096
	ds_read_b128 v[232:235], v179 offset:5120
	ds_read_b128 v[236:239], v179 offset:6144
	ds_read_b128 v[240:243], v179 offset:7168
	buffer_load_dwordx4 v174, s[44:47], s13 offen lds
	s_mov_b32 m0, s69
	s_nop 0
	buffer_load_dwordx4 v176, s[44:47], s13 offen lds
	s_waitcnt vmcnt(8)
	s_waitcnt lgkmcnt(0)
	s_setprio 1
	s_barrier
	v_mfma_f32_16x16x32_bf16 v[126:129], v[134:137], v[192:195], v[126:129]
	v_mfma_f32_16x16x32_bf16 v[110:113], v[134:137], v[200:203], v[110:113]
	v_mfma_f32_16x16x32_bf16 v[94:97], v[134:137], v[228:231], v[94:97]
	v_mfma_f32_16x16x32_bf16 v[78:81], v[134:137], v[236:239], v[78:81]
	v_mfma_f32_16x16x32_bf16 v[122:125], v[142:145], v[192:195], v[122:125]
	v_mfma_f32_16x16x32_bf16 v[106:109], v[142:145], v[200:203], v[106:109]
	v_mfma_f32_16x16x32_bf16 v[90:93], v[142:145], v[228:231], v[90:93]
	v_mfma_f32_16x16x32_bf16 v[74:77], v[142:145], v[236:239], v[74:77]
	v_mfma_f32_16x16x32_bf16 v[126:129], v[138:141], v[196:199], v[126:129]
	v_mfma_f32_16x16x32_bf16 v[110:113], v[138:141], v[204:207], v[110:113]
	v_mfma_f32_16x16x32_bf16 v[94:97], v[138:141], v[232:235], v[94:97]
	v_mfma_f32_16x16x32_bf16 v[78:81], v[138:141], v[240:243], v[78:81]
	v_mfma_f32_16x16x32_bf16 v[122:125], v[154:157], v[196:199], v[122:125]
	v_mfma_f32_16x16x32_bf16 v[106:109], v[154:157], v[204:207], v[106:109]
	v_mfma_f32_16x16x32_bf16 v[90:93], v[154:157], v[232:235], v[90:93]
	v_mfma_f32_16x16x32_bf16 v[74:77], v[154:157], v[240:243], v[74:77]
	v_mfma_f32_16x16x32_bf16 v[118:121], v[170:173], v[192:195], v[118:121]
	v_mfma_f32_16x16x32_bf16 v[102:105], v[170:173], v[200:203], v[102:105]
	v_mfma_f32_16x16x32_bf16 v[86:89], v[170:173], v[228:231], v[86:89]
	v_mfma_f32_16x16x32_bf16 v[70:73], v[170:173], v[236:239], v[70:73]
	v_mfma_f32_16x16x32_bf16 v[114:117], v[184:187], v[192:195], v[114:117]
	v_mfma_f32_16x16x32_bf16 v[98:101], v[184:187], v[200:203], v[98:101]
	v_mfma_f32_16x16x32_bf16 v[82:85], v[184:187], v[228:231], v[82:85]
	v_mfma_f32_16x16x32_bf16 v[66:69], v[184:187], v[236:239], v[66:69]
	v_mfma_f32_16x16x32_bf16 v[118:121], v[180:183], v[196:199], v[118:121]
	v_mfma_f32_16x16x32_bf16 v[102:105], v[180:183], v[204:207], v[102:105]
	v_mfma_f32_16x16x32_bf16 v[86:89], v[180:183], v[232:235], v[86:89]
	v_mfma_f32_16x16x32_bf16 v[70:73], v[180:183], v[240:243], v[70:73]
	v_mfma_f32_16x16x32_bf16 v[114:117], v[188:191], v[196:199], v[114:117]
	v_mfma_f32_16x16x32_bf16 v[98:101], v[188:191], v[204:207], v[98:101]
	v_mfma_f32_16x16x32_bf16 v[82:85], v[188:191], v[232:235], v[82:85]
	v_mfma_f32_16x16x32_bf16 v[66:69], v[188:191], v[240:243], v[66:69]
	s_barrier
	s_setprio 0
	s_mov_b32 m0, s15
	ds_read_b128 v[192:195], v179 offset:16384
	ds_read_b128 v[196:199], v179 offset:17408
	ds_read_b128 v[200:203], v179 offset:18432
	ds_read_b128 v[204:207], v179 offset:19456
	ds_read_b128 v[228:231], v179 offset:20480
	ds_read_b128 v[232:235], v179 offset:21504
	ds_read_b128 v[236:239], v179 offset:22528
	ds_read_b128 v[240:243], v179 offset:23552
	buffer_load_dwordx4 v175, s[60:63], s26 offen lds
	s_mov_b32 m0, s16
	s_add_i32 s34, s26, 0x80000
	buffer_load_dwordx4 v177, s[60:63], s26 offen lds
	s_mov_b32 m0, s18
	s_nop 0
	buffer_load_dwordx4 v175, s[60:63], s34 offen lds
	s_mov_b32 m0, s19
	s_nop 0
	buffer_load_dwordx4 v177, s[60:63], s34 offen lds
	s_mov_b32 m0, s14
	s_nop 0
	buffer_load_dwordx4 v174, s[44:47], s27 offen lds
	s_mov_b32 m0, s24
	s_nop 0
	buffer_load_dwordx4 v176, s[44:47], s27 offen lds
	s_waitcnt vmcnt(8)
	s_waitcnt lgkmcnt(0)
	s_setprio 1
	s_barrier
	v_mfma_f32_16x16x32_bf16 v[62:65], v[134:137], v[192:195], v[62:65]
	v_mfma_f32_16x16x32_bf16 v[46:49], v[134:137], v[200:203], v[46:49]
	v_mfma_f32_16x16x32_bf16 v[30:33], v[134:137], v[228:231], v[30:33]
	v_mfma_f32_16x16x32_bf16 v[14:17], v[134:137], v[236:239], v[14:17]
	v_mfma_f32_16x16x32_bf16 v[58:61], v[142:145], v[192:195], v[58:61]
	v_mfma_f32_16x16x32_bf16 v[42:45], v[142:145], v[200:203], v[42:45]
	v_mfma_f32_16x16x32_bf16 v[26:29], v[142:145], v[228:231], v[26:29]
	v_mfma_f32_16x16x32_bf16 v[10:13], v[142:145], v[236:239], v[10:13]
	v_mfma_f32_16x16x32_bf16 v[62:65], v[138:141], v[196:199], v[62:65]
	v_mfma_f32_16x16x32_bf16 v[46:49], v[138:141], v[204:207], v[46:49]
	v_mfma_f32_16x16x32_bf16 v[30:33], v[138:141], v[232:235], v[30:33]
	v_mfma_f32_16x16x32_bf16 v[14:17], v[138:141], v[240:243], v[14:17]
	v_mfma_f32_16x16x32_bf16 v[58:61], v[154:157], v[196:199], v[58:61]
	v_mfma_f32_16x16x32_bf16 v[42:45], v[154:157], v[204:207], v[42:45]
	v_mfma_f32_16x16x32_bf16 v[26:29], v[154:157], v[232:235], v[26:29]
	v_mfma_f32_16x16x32_bf16 v[10:13], v[154:157], v[240:243], v[10:13]
	v_mfma_f32_16x16x32_bf16 v[54:57], v[170:173], v[192:195], v[54:57]
	v_mfma_f32_16x16x32_bf16 v[38:41], v[170:173], v[200:203], v[38:41]
	v_mfma_f32_16x16x32_bf16 v[22:25], v[170:173], v[228:231], v[22:25]
	v_mfma_f32_16x16x32_bf16 v[6:9], v[170:173], v[236:239], v[6:9]
	v_mfma_f32_16x16x32_bf16 v[50:53], v[184:187], v[192:195], v[50:53]
	v_mfma_f32_16x16x32_bf16 v[34:37], v[184:187], v[200:203], v[34:37]
	v_mfma_f32_16x16x32_bf16 v[18:21], v[184:187], v[228:231], v[18:21]
	v_mfma_f32_16x16x32_bf16 v[2:5], v[184:187], v[236:239], v[2:5]
	v_mfma_f32_16x16x32_bf16 v[54:57], v[180:183], v[196:199], v[54:57]
	v_mfma_f32_16x16x32_bf16 v[38:41], v[180:183], v[204:207], v[38:41]
	v_mfma_f32_16x16x32_bf16 v[22:25], v[180:183], v[232:235], v[22:25]
	v_mfma_f32_16x16x32_bf16 v[6:9], v[180:183], v[240:243], v[6:9]
	v_mfma_f32_16x16x32_bf16 v[50:53], v[188:191], v[196:199], v[50:53]
	v_mfma_f32_16x16x32_bf16 v[34:37], v[188:191], v[204:207], v[34:37]
	v_mfma_f32_16x16x32_bf16 v[18:21], v[188:191], v[232:235], v[18:21]
	v_mfma_f32_16x16x32_bf16 v[2:5], v[188:191], v[240:243], v[2:5]
	s_barrier
	s_setprio 0
	v_add_u32_e32 v133, 0x18000, v178
	ds_read_b128 v[134:137], v133
	ds_read_b128 v[138:141], v133 offset:1024
	ds_read_b128 v[142:145], v133 offset:2048
	ds_read_b128 v[154:157], v133 offset:3072
	v_add_u32_e32 v133, 0x1c000, v178
	ds_read_b128 v[170:173], v133
	ds_read_b128 v[180:183], v133 offset:1024
	ds_read_b128 v[184:187], v133 offset:2048
	ds_read_b128 v[188:191], v133 offset:3072
	s_add_i32 s27, s27, 0x80000
	s_mov_b32 m0, s25
	ds_read_b128 v[192:195], v179 offset:32768
	ds_read_b128 v[196:199], v179 offset:33792
	ds_read_b128 v[200:203], v179 offset:34816
	ds_read_b128 v[204:207], v179 offset:35840
	ds_read_b128 v[228:231], v179 offset:36864
	ds_read_b128 v[232:235], v179 offset:37888
	ds_read_b128 v[236:239], v179 offset:38912
	ds_read_b128 v[240:243], v179 offset:39936
	buffer_load_dwordx4 v174, s[44:47], s27 offen lds
	s_mov_b32 m0, s30
	s_nop 0
	buffer_load_dwordx4 v176, s[44:47], s27 offen lds
	s_waitcnt vmcnt(8)
	s_waitcnt lgkmcnt(0)
	s_setprio 1
	s_barrier
	v_mfma_f32_16x16x32_bf16 v[126:129], v[134:137], v[192:195], v[126:129]
	v_mfma_f32_16x16x32_bf16 v[110:113], v[134:137], v[200:203], v[110:113]
	v_mfma_f32_16x16x32_bf16 v[94:97], v[134:137], v[228:231], v[94:97]
	v_mfma_f32_16x16x32_bf16 v[78:81], v[134:137], v[236:239], v[78:81]
	v_mfma_f32_16x16x32_bf16 v[122:125], v[142:145], v[192:195], v[122:125]
	v_mfma_f32_16x16x32_bf16 v[106:109], v[142:145], v[200:203], v[106:109]
	v_mfma_f32_16x16x32_bf16 v[90:93], v[142:145], v[228:231], v[90:93]
	v_mfma_f32_16x16x32_bf16 v[74:77], v[142:145], v[236:239], v[74:77]
	v_mfma_f32_16x16x32_bf16 v[126:129], v[138:141], v[196:199], v[126:129]
	v_mfma_f32_16x16x32_bf16 v[110:113], v[138:141], v[204:207], v[110:113]
	v_mfma_f32_16x16x32_bf16 v[94:97], v[138:141], v[232:235], v[94:97]
	v_mfma_f32_16x16x32_bf16 v[78:81], v[138:141], v[240:243], v[78:81]
	v_mfma_f32_16x16x32_bf16 v[122:125], v[154:157], v[196:199], v[122:125]
	v_mfma_f32_16x16x32_bf16 v[106:109], v[154:157], v[204:207], v[106:109]
	v_mfma_f32_16x16x32_bf16 v[90:93], v[154:157], v[232:235], v[90:93]
	v_mfma_f32_16x16x32_bf16 v[74:77], v[154:157], v[240:243], v[74:77]
	v_mfma_f32_16x16x32_bf16 v[118:121], v[170:173], v[192:195], v[118:121]
	v_mfma_f32_16x16x32_bf16 v[102:105], v[170:173], v[200:203], v[102:105]
	v_mfma_f32_16x16x32_bf16 v[86:89], v[170:173], v[228:231], v[86:89]
	v_mfma_f32_16x16x32_bf16 v[70:73], v[170:173], v[236:239], v[70:73]
	v_mfma_f32_16x16x32_bf16 v[114:117], v[184:187], v[192:195], v[114:117]
	v_mfma_f32_16x16x32_bf16 v[98:101], v[184:187], v[200:203], v[98:101]
	v_mfma_f32_16x16x32_bf16 v[82:85], v[184:187], v[228:231], v[82:85]
	v_mfma_f32_16x16x32_bf16 v[66:69], v[184:187], v[236:239], v[66:69]
	v_mfma_f32_16x16x32_bf16 v[118:121], v[180:183], v[196:199], v[118:121]
	v_mfma_f32_16x16x32_bf16 v[102:105], v[180:183], v[204:207], v[102:105]
	v_mfma_f32_16x16x32_bf16 v[86:89], v[180:183], v[232:235], v[86:89]
	v_mfma_f32_16x16x32_bf16 v[70:73], v[180:183], v[240:243], v[70:73]
	v_mfma_f32_16x16x32_bf16 v[114:117], v[188:191], v[196:199], v[114:117]
	v_mfma_f32_16x16x32_bf16 v[98:101], v[188:191], v[204:207], v[98:101]
	v_mfma_f32_16x16x32_bf16 v[82:85], v[188:191], v[232:235], v[82:85]
	v_mfma_f32_16x16x32_bf16 v[66:69], v[188:191], v[240:243], v[66:69]
	s_barrier
	s_setprio 0
	s_mov_b32 m0, s36
	s_or_b32 s27, s26, 0x80
	ds_read_b128 v[192:195], v179 offset:49152
	ds_read_b128 v[196:199], v179 offset:50176
	ds_read_b128 v[200:203], v179 offset:51200
	ds_read_b128 v[204:207], v179 offset:52224
	ds_read_b128 v[228:231], v179 offset:53248
	ds_read_b128 v[232:235], v179 offset:54272
	ds_read_b128 v[236:239], v179 offset:55296
	ds_read_b128 v[240:243], v179 offset:56320
	buffer_load_dwordx4 v175, s[60:63], s27 offen lds
	s_mov_b32 m0, s37
	s_add_i32 s26, s26, 0x80080
	buffer_load_dwordx4 v177, s[60:63], s27 offen lds
	s_mov_b32 m0, s48
	s_nop 0
	buffer_load_dwordx4 v175, s[60:63], s26 offen lds
	s_mov_b32 m0, s49
	s_nop 0
	buffer_load_dwordx4 v177, s[60:63], s26 offen lds
	s_mov_b32 m0, s40
	s_nop 0
	buffer_load_dwordx4 v174, s[44:47], s23 offen lds
	s_mov_b32 m0, s41
	s_nop 0
	buffer_load_dwordx4 v176, s[44:47], s23 offen lds
	s_waitcnt vmcnt(8)
	s_waitcnt lgkmcnt(0)
	s_setprio 1
	s_barrier
	v_mfma_f32_16x16x32_bf16 v[62:65], v[134:137], v[192:195], v[62:65]
	v_mfma_f32_16x16x32_bf16 v[46:49], v[134:137], v[200:203], v[46:49]
	v_mfma_f32_16x16x32_bf16 v[30:33], v[134:137], v[228:231], v[30:33]
	v_mfma_f32_16x16x32_bf16 v[14:17], v[134:137], v[236:239], v[14:17]
	v_mfma_f32_16x16x32_bf16 v[58:61], v[142:145], v[192:195], v[58:61]
	v_mfma_f32_16x16x32_bf16 v[42:45], v[142:145], v[200:203], v[42:45]
	v_mfma_f32_16x16x32_bf16 v[26:29], v[142:145], v[228:231], v[26:29]
	v_mfma_f32_16x16x32_bf16 v[10:13], v[142:145], v[236:239], v[10:13]
	v_mfma_f32_16x16x32_bf16 v[62:65], v[138:141], v[196:199], v[62:65]
	v_mfma_f32_16x16x32_bf16 v[46:49], v[138:141], v[204:207], v[46:49]
	v_mfma_f32_16x16x32_bf16 v[30:33], v[138:141], v[232:235], v[30:33]
	v_mfma_f32_16x16x32_bf16 v[14:17], v[138:141], v[240:243], v[14:17]
	v_mfma_f32_16x16x32_bf16 v[58:61], v[154:157], v[196:199], v[58:61]
	v_mfma_f32_16x16x32_bf16 v[42:45], v[154:157], v[204:207], v[42:45]
	v_mfma_f32_16x16x32_bf16 v[26:29], v[154:157], v[232:235], v[26:29]
	v_mfma_f32_16x16x32_bf16 v[10:13], v[154:157], v[240:243], v[10:13]
	v_mfma_f32_16x16x32_bf16 v[54:57], v[170:173], v[192:195], v[54:57]
	v_mfma_f32_16x16x32_bf16 v[38:41], v[170:173], v[200:203], v[38:41]
	v_mfma_f32_16x16x32_bf16 v[22:25], v[170:173], v[228:231], v[22:25]
	v_mfma_f32_16x16x32_bf16 v[6:9], v[170:173], v[236:239], v[6:9]
	v_mfma_f32_16x16x32_bf16 v[50:53], v[184:187], v[192:195], v[50:53]
	v_mfma_f32_16x16x32_bf16 v[34:37], v[184:187], v[200:203], v[34:37]
	v_mfma_f32_16x16x32_bf16 v[18:21], v[184:187], v[228:231], v[18:21]
	v_mfma_f32_16x16x32_bf16 v[2:5], v[184:187], v[236:239], v[2:5]
	v_mfma_f32_16x16x32_bf16 v[54:57], v[180:183], v[196:199], v[54:57]
	v_mfma_f32_16x16x32_bf16 v[38:41], v[180:183], v[204:207], v[38:41]
	v_mfma_f32_16x16x32_bf16 v[22:25], v[180:183], v[232:235], v[22:25]
	v_mfma_f32_16x16x32_bf16 v[6:9], v[180:183], v[240:243], v[6:9]
	v_mfma_f32_16x16x32_bf16 v[50:53], v[188:191], v[196:199], v[50:53]
	v_mfma_f32_16x16x32_bf16 v[34:37], v[188:191], v[204:207], v[34:37]
	v_mfma_f32_16x16x32_bf16 v[18:21], v[188:191], v[232:235], v[18:21]
	v_mfma_f32_16x16x32_bf16 v[2:5], v[188:191], v[240:243], v[2:5]
	s_barrier
	s_setprio 0
	s_add_i32 s22, s22, 2
	s_addk_i32 s13, 0x100
	s_addk_i32 s21, 0x100
	s_cmp_gt_u32 s22, 29
	s_cbranch_scc0 .LBB0_905
	s_and_b64 vcc, exec, s[64:65]
	s_cbranch_vccz .LBB0_908
	s_barrier

.LBB0_1192:
	s_lshl_b32 s12, s70, 22
	s_and_b64 s[8:9], s[26:27], exec
	s_cselect_b32 s8, s12, s30
	s_lshl_b32 s22, s71, 22
	s_and_b64 s[66:67], s[26:27], exec
	s_cselect_b32 s9, s22, s31
	s_add_i32 s30, s30, 0x200080
	s_addk_i32 s31, 0x100
	s_mov_b32 s72, -2
	v_add_u32_e32 v141, 0x10000, v139
	ds_read_b128 v[142:145], v141
	ds_read_b128 v[154:157], v141 offset:1024
	ds_read_b128 v[170:173], v141 offset:2048
	ds_read_b128 v[174:177], v141 offset:3072
	v_add_u32_e32 v141, 0x14000, v139
	ds_read_b128 v[178:181], v141
	ds_read_b128 v[182:185], v141 offset:1024
	ds_read_b128 v[186:189], v141 offset:2048
	ds_read_b128 v[190:193], v141 offset:3072
	s_add_i32 s52, s30, 0xffe00080
	s_cmpk_eq_i32 s72, 0x7c
	s_cselect_b32 s52, s8, s52
	s_cselect_b32 s82, s9, s31
	s_or_b32 s73, s52, 0x80
	s_mov_b32 m0, s69
	ds_read_b128 v[194:197], v140
	ds_read_b128 v[198:201], v140 offset:1024
	ds_read_b128 v[202:205], v140 offset:2048
	ds_read_b128 v[228:231], v140 offset:3072
	ds_read_b128 v[232:235], v140 offset:4096
	ds_read_b128 v[236:239], v140 offset:5120
	ds_read_b128 v[240:243], v140 offset:6144
	ds_read_b128 v[244:247], v140 offset:7168
	buffer_load_dwordx4 v131, s[60:63], s30 offen lds
	s_mov_b32 m0, s46
	s_nop 0
	buffer_load_dwordx4 v135, s[60:63], s30 offen lds
	s_waitcnt vmcnt(8)
	s_waitcnt lgkmcnt(0)
	s_setprio 1
	s_barrier
	v_mfma_f32_16x16x32_bf16 v[126:129], v[142:145], v[194:197], 0
	v_mfma_f32_16x16x32_bf16 v[118:121], v[142:145], v[202:205], 0
	v_mfma_f32_16x16x32_bf16 v[110:113], v[142:145], v[232:235], 0
	v_mfma_f32_16x16x32_bf16 v[102:105], v[142:145], v[240:243], 0
	v_mfma_f32_16x16x32_bf16 v[122:125], v[170:173], v[194:197], 0
	v_mfma_f32_16x16x32_bf16 v[114:117], v[170:173], v[202:205], 0
	v_mfma_f32_16x16x32_bf16 v[106:109], v[170:173], v[232:235], 0
	v_mfma_f32_16x16x32_bf16 v[98:101], v[170:173], v[240:243], 0
	v_mfma_f32_16x16x32_bf16 v[126:129], v[154:157], v[198:201], v[126:129]
	v_mfma_f32_16x16x32_bf16 v[118:121], v[154:157], v[228:231], v[118:121]
	v_mfma_f32_16x16x32_bf16 v[110:113], v[154:157], v[236:239], v[110:113]
	v_mfma_f32_16x16x32_bf16 v[102:105], v[154:157], v[244:247], v[102:105]
	v_mfma_f32_16x16x32_bf16 v[122:125], v[174:177], v[198:201], v[122:125]
	v_mfma_f32_16x16x32_bf16 v[114:117], v[174:177], v[228:231], v[114:117]
	v_mfma_f32_16x16x32_bf16 v[106:109], v[174:177], v[236:239], v[106:109]
	v_mfma_f32_16x16x32_bf16 v[98:101], v[174:177], v[244:247], v[98:101]
	v_mfma_f32_16x16x32_bf16 v[62:65], v[178:181], v[194:197], 0
	v_mfma_f32_16x16x32_bf16 v[54:57], v[178:181], v[202:205], 0
	v_mfma_f32_16x16x32_bf16 v[46:49], v[178:181], v[232:235], 0
	v_mfma_f32_16x16x32_bf16 v[38:41], v[178:181], v[240:243], 0
	v_mfma_f32_16x16x32_bf16 v[58:61], v[186:189], v[194:197], 0
	v_mfma_f32_16x16x32_bf16 v[50:53], v[186:189], v[202:205], 0
	v_mfma_f32_16x16x32_bf16 v[42:45], v[186:189], v[232:235], 0
	v_mfma_f32_16x16x32_bf16 v[34:37], v[186:189], v[240:243], 0
	v_mfma_f32_16x16x32_bf16 v[62:65], v[182:185], v[198:201], v[62:65]
	v_mfma_f32_16x16x32_bf16 v[54:57], v[182:185], v[228:231], v[54:57]
	v_mfma_f32_16x16x32_bf16 v[46:49], v[182:185], v[236:239], v[46:49]
	v_mfma_f32_16x16x32_bf16 v[38:41], v[182:185], v[244:247], v[38:41]
	v_mfma_f32_16x16x32_bf16 v[58:61], v[190:193], v[198:201], v[58:61]
	v_mfma_f32_16x16x32_bf16 v[50:53], v[190:193], v[228:231], v[50:53]
	v_mfma_f32_16x16x32_bf16 v[42:45], v[190:193], v[236:239], v[42:45]
	v_mfma_f32_16x16x32_bf16 v[34:37], v[190:193], v[244:247], v[34:37]
	s_barrier
	s_setprio 0
	s_mov_b32 m0, s15
	s_mov_b32 s66, s62
	s_mov_b32 s67, s63
	ds_read_b128 v[194:197], v140 offset:16384
	ds_read_b128 v[198:201], v140 offset:17408
	ds_read_b128 v[202:205], v140 offset:18432
	ds_read_b128 v[228:231], v140 offset:19456
	ds_read_b128 v[232:235], v140 offset:20480
	ds_read_b128 v[236:239], v140 offset:21504
	ds_read_b128 v[240:243], v140 offset:22528
	ds_read_b128 v[244:247], v140 offset:23552
	buffer_load_dwordx4 v134, s[64:67], s82 offen lds
	s_mov_b32 m0, s16
	s_add_i32 s53, s82, 0x200000
	buffer_load_dwordx4 v136, s[64:67], s82 offen lds
	s_mov_b32 m0, s21
	s_nop 0
	buffer_load_dwordx4 v134, s[64:67], s53 offen lds
	s_mov_b32 m0, s23
	s_nop 0
	buffer_load_dwordx4 v136, s[64:67], s53 offen lds
	s_mov_b32 m0, s2
	s_nop 0
	buffer_load_dwordx4 v131, s[60:63], s52 offen lds
	s_mov_b32 m0, s24
	s_nop 0
	buffer_load_dwordx4 v135, s[60:63], s52 offen lds
	s_waitcnt vmcnt(8)
	s_waitcnt lgkmcnt(0)
	s_setprio 1
	s_barrier
	v_mfma_f32_16x16x32_bf16 v[94:97], v[142:145], v[194:197], 0
	v_mfma_f32_16x16x32_bf16 v[86:89], v[142:145], v[202:205], 0
	v_mfma_f32_16x16x32_bf16 v[78:81], v[142:145], v[232:235], 0
	v_mfma_f32_16x16x32_bf16 v[70:73], v[142:145], v[240:243], 0
	v_mfma_f32_16x16x32_bf16 v[90:93], v[170:173], v[194:197], 0
	v_mfma_f32_16x16x32_bf16 v[82:85], v[170:173], v[202:205], 0
	v_mfma_f32_16x16x32_bf16 v[74:77], v[170:173], v[232:235], 0
	v_mfma_f32_16x16x32_bf16 v[66:69], v[170:173], v[240:243], 0
	v_mfma_f32_16x16x32_bf16 v[94:97], v[154:157], v[198:201], v[94:97]
	v_mfma_f32_16x16x32_bf16 v[86:89], v[154:157], v[228:231], v[86:89]
	v_mfma_f32_16x16x32_bf16 v[78:81], v[154:157], v[236:239], v[78:81]
	v_mfma_f32_16x16x32_bf16 v[70:73], v[154:157], v[244:247], v[70:73]
	v_mfma_f32_16x16x32_bf16 v[90:93], v[174:177], v[198:201], v[90:93]
	v_mfma_f32_16x16x32_bf16 v[82:85], v[174:177], v[228:231], v[82:85]
	v_mfma_f32_16x16x32_bf16 v[74:77], v[174:177], v[236:239], v[74:77]
	v_mfma_f32_16x16x32_bf16 v[66:69], v[174:177], v[244:247], v[66:69]
	v_mfma_f32_16x16x32_bf16 v[30:33], v[178:181], v[194:197], 0
	v_mfma_f32_16x16x32_bf16 v[22:25], v[178:181], v[202:205], 0
	v_mfma_f32_16x16x32_bf16 v[14:17], v[178:181], v[232:235], 0
	v_mfma_f32_16x16x32_bf16 v[6:9], v[178:181], v[240:243], 0
	v_mfma_f32_16x16x32_bf16 v[26:29], v[186:189], v[194:197], 0
	v_mfma_f32_16x16x32_bf16 v[18:21], v[186:189], v[202:205], 0
	v_mfma_f32_16x16x32_bf16 v[10:13], v[186:189], v[232:235], 0
	v_mfma_f32_16x16x32_bf16 v[2:5], v[186:189], v[240:243], 0
	v_mfma_f32_16x16x32_bf16 v[30:33], v[182:185], v[198:201], v[30:33]
	v_mfma_f32_16x16x32_bf16 v[22:25], v[182:185], v[228:231], v[22:25]
	v_mfma_f32_16x16x32_bf16 v[14:17], v[182:185], v[236:239], v[14:17]
	v_mfma_f32_16x16x32_bf16 v[6:9], v[182:185], v[244:247], v[6:9]
	v_mfma_f32_16x16x32_bf16 v[26:29], v[190:193], v[198:201], v[26:29]
	v_mfma_f32_16x16x32_bf16 v[18:21], v[190:193], v[228:231], v[18:21]
	v_mfma_f32_16x16x32_bf16 v[10:13], v[190:193], v[236:239], v[10:13]
	v_mfma_f32_16x16x32_bf16 v[2:5], v[190:193], v[244:247], v[2:5]
	s_barrier
	s_setprio 0
	v_add_u32_e32 v141, 0x18000, v139
	ds_read_b128 v[142:145], v141
	ds_read_b128 v[154:157], v141 offset:1024
	ds_read_b128 v[170:173], v141 offset:2048
	ds_read_b128 v[174:177], v141 offset:3072
	v_add_u32_e32 v141, 0x1c000, v139
	ds_read_b128 v[178:181], v141
	ds_read_b128 v[182:185], v141 offset:1024
	ds_read_b128 v[186:189], v141 offset:2048
	ds_read_b128 v[190:193], v141 offset:3072
	s_add_i32 s52, s52, 0x200000
	s_mov_b32 m0, s25
	ds_read_b128 v[194:197], v140 offset:32768
	ds_read_b128 v[198:201], v140 offset:33792
	ds_read_b128 v[202:205], v140 offset:34816
	ds_read_b128 v[228:231], v140 offset:35840
	ds_read_b128 v[232:235], v140 offset:36864
	ds_read_b128 v[236:239], v140 offset:37888
	ds_read_b128 v[240:243], v140 offset:38912
	ds_read_b128 v[244:247], v140 offset:39936
	buffer_load_dwordx4 v131, s[60:63], s52 offen lds
	s_mov_b32 m0, s33
	s_nop 0
	buffer_load_dwordx4 v135, s[60:63], s52 offen lds
	s_waitcnt vmcnt(8)
	s_waitcnt lgkmcnt(0)
	s_setprio 1
	s_barrier
	v_mfma_f32_16x16x32_bf16 v[126:129], v[142:145], v[194:197], v[126:129]
	v_mfma_f32_16x16x32_bf16 v[118:121], v[142:145], v[202:205], v[118:121]
	v_mfma_f32_16x16x32_bf16 v[110:113], v[142:145], v[232:235], v[110:113]
	v_mfma_f32_16x16x32_bf16 v[102:105], v[142:145], v[240:243], v[102:105]
	v_mfma_f32_16x16x32_bf16 v[122:125], v[170:173], v[194:197], v[122:125]
	v_mfma_f32_16x16x32_bf16 v[114:117], v[170:173], v[202:205], v[114:117]
	v_mfma_f32_16x16x32_bf16 v[106:109], v[170:173], v[232:235], v[106:109]
	v_mfma_f32_16x16x32_bf16 v[98:101], v[170:173], v[240:243], v[98:101]
	v_mfma_f32_16x16x32_bf16 v[126:129], v[154:157], v[198:201], v[126:129]
	v_mfma_f32_16x16x32_bf16 v[118:121], v[154:157], v[228:231], v[118:121]
	v_mfma_f32_16x16x32_bf16 v[110:113], v[154:157], v[236:239], v[110:113]
	v_mfma_f32_16x16x32_bf16 v[102:105], v[154:157], v[244:247], v[102:105]
	v_mfma_f32_16x16x32_bf16 v[122:125], v[174:177], v[198:201], v[122:125]
	v_mfma_f32_16x16x32_bf16 v[114:117], v[174:177], v[228:231], v[114:117]
	v_mfma_f32_16x16x32_bf16 v[106:109], v[174:177], v[236:239], v[106:109]
	v_mfma_f32_16x16x32_bf16 v[98:101], v[174:177], v[244:247], v[98:101]
	v_mfma_f32_16x16x32_bf16 v[62:65], v[178:181], v[194:197], v[62:65]
	v_mfma_f32_16x16x32_bf16 v[54:57], v[178:181], v[202:205], v[54:57]
	v_mfma_f32_16x16x32_bf16 v[46:49], v[178:181], v[232:235], v[46:49]
	v_mfma_f32_16x16x32_bf16 v[38:41], v[178:181], v[240:243], v[38:41]
	v_mfma_f32_16x16x32_bf16 v[58:61], v[186:189], v[194:197], v[58:61]
	v_mfma_f32_16x16x32_bf16 v[50:53], v[186:189], v[202:205], v[50:53]
	v_mfma_f32_16x16x32_bf16 v[42:45], v[186:189], v[232:235], v[42:45]
	v_mfma_f32_16x16x32_bf16 v[34:37], v[186:189], v[240:243], v[34:37]
	v_mfma_f32_16x16x32_bf16 v[62:65], v[182:185], v[198:201], v[62:65]
	v_mfma_f32_16x16x32_bf16 v[54:57], v[182:185], v[228:231], v[54:57]
	v_mfma_f32_16x16x32_bf16 v[46:49], v[182:185], v[236:239], v[46:49]
	v_mfma_f32_16x16x32_bf16 v[38:41], v[182:185], v[244:247], v[38:41]
	v_mfma_f32_16x16x32_bf16 v[58:61], v[190:193], v[198:201], v[58:61]
	v_mfma_f32_16x16x32_bf16 v[50:53], v[190:193], v[228:231], v[50:53]
	v_mfma_f32_16x16x32_bf16 v[42:45], v[190:193], v[236:239], v[42:45]
	v_mfma_f32_16x16x32_bf16 v[34:37], v[190:193], v[244:247], v[34:37]
	s_barrier
	s_setprio 0
	s_mov_b32 m0, s34
	s_or_b32 s52, s82, 0x80
	ds_read_b128 v[194:197], v140 offset:49152
	ds_read_b128 v[198:201], v140 offset:50176
	ds_read_b128 v[202:205], v140 offset:51200
	ds_read_b128 v[228:231], v140 offset:52224
	ds_read_b128 v[232:235], v140 offset:53248
	ds_read_b128 v[236:239], v140 offset:54272
	ds_read_b128 v[240:243], v140 offset:55296
	ds_read_b128 v[244:247], v140 offset:56320
	buffer_load_dwordx4 v134, s[64:67], s52 offen lds
	s_mov_b32 m0, s35
	s_add_i32 s82, s82, 0x200080
	buffer_load_dwordx4 v136, s[64:67], s52 offen lds
	s_mov_b32 m0, s37
	s_nop 0
	buffer_load_dwordx4 v134, s[64:67], s82 offen lds
	s_mov_b32 m0, s44
	s_nop 0
	buffer_load_dwordx4 v136, s[64:67], s82 offen lds
	s_mov_b32 m0, s14
	s_nop 0
	buffer_load_dwordx4 v131, s[60:63], s73 offen lds
	s_mov_b32 m0, s36
	s_nop 0
	buffer_load_dwordx4 v135, s[60:63], s73 offen lds
	s_waitcnt vmcnt(8)
	s_waitcnt lgkmcnt(0)
	s_setprio 1
	s_barrier
	v_mfma_f32_16x16x32_bf16 v[94:97], v[142:145], v[194:197], v[94:97]
	v_mfma_f32_16x16x32_bf16 v[86:89], v[142:145], v[202:205], v[86:89]
	v_mfma_f32_16x16x32_bf16 v[78:81], v[142:145], v[232:235], v[78:81]
	v_mfma_f32_16x16x32_bf16 v[70:73], v[142:145], v[240:243], v[70:73]
	v_mfma_f32_16x16x32_bf16 v[90:93], v[170:173], v[194:197], v[90:93]
	v_mfma_f32_16x16x32_bf16 v[82:85], v[170:173], v[202:205], v[82:85]
	v_mfma_f32_16x16x32_bf16 v[74:77], v[170:173], v[232:235], v[74:77]
	v_mfma_f32_16x16x32_bf16 v[66:69], v[170:173], v[240:243], v[66:69]
	v_mfma_f32_16x16x32_bf16 v[94:97], v[154:157], v[198:201], v[94:97]
	v_mfma_f32_16x16x32_bf16 v[86:89], v[154:157], v[228:231], v[86:89]
	v_mfma_f32_16x16x32_bf16 v[78:81], v[154:157], v[236:239], v[78:81]
	v_mfma_f32_16x16x32_bf16 v[70:73], v[154:157], v[244:247], v[70:73]
	v_mfma_f32_16x16x32_bf16 v[90:93], v[174:177], v[198:201], v[90:93]
	v_mfma_f32_16x16x32_bf16 v[82:85], v[174:177], v[228:231], v[82:85]
	v_mfma_f32_16x16x32_bf16 v[74:77], v[174:177], v[236:239], v[74:77]
	v_mfma_f32_16x16x32_bf16 v[66:69], v[174:177], v[244:247], v[66:69]
	v_mfma_f32_16x16x32_bf16 v[30:33], v[178:181], v[194:197], v[30:33]
	v_mfma_f32_16x16x32_bf16 v[22:25], v[178:181], v[202:205], v[22:25]
	v_mfma_f32_16x16x32_bf16 v[14:17], v[178:181], v[232:235], v[14:17]
	v_mfma_f32_16x16x32_bf16 v[6:9], v[178:181], v[240:243], v[6:9]
	v_mfma_f32_16x16x32_bf16 v[26:29], v[186:189], v[194:197], v[26:29]
	v_mfma_f32_16x16x32_bf16 v[18:21], v[186:189], v[202:205], v[18:21]
	v_mfma_f32_16x16x32_bf16 v[10:13], v[186:189], v[232:235], v[10:13]
	v_mfma_f32_16x16x32_bf16 v[2:5], v[186:189], v[240:243], v[2:5]
	v_mfma_f32_16x16x32_bf16 v[30:33], v[182:185], v[198:201], v[30:33]
	v_mfma_f32_16x16x32_bf16 v[22:25], v[182:185], v[228:231], v[22:25]
	v_mfma_f32_16x16x32_bf16 v[14:17], v[182:185], v[236:239], v[14:17]
	v_mfma_f32_16x16x32_bf16 v[6:9], v[182:185], v[244:247], v[6:9]
	v_mfma_f32_16x16x32_bf16 v[26:29], v[190:193], v[198:201], v[26:29]
	v_mfma_f32_16x16x32_bf16 v[18:21], v[190:193], v[228:231], v[18:21]
	v_mfma_f32_16x16x32_bf16 v[10:13], v[190:193], v[236:239], v[10:13]
	v_mfma_f32_16x16x32_bf16 v[2:5], v[190:193], v[244:247], v[2:5]
	s_barrier
	s_setprio 0
	s_add_i32 s72, s72, 2
	s_addk_i32 s30, 0x100
	s_addk_i32 s31, 0x100
	s_cmpk_gt_u32 s72, 0x7d
.LBB0_1193:
	v_add_u32_e32 v141, 0x10000, v139
	ds_read_b128 v[142:145], v141
	ds_read_b128 v[154:157], v141 offset:1024
	ds_read_b128 v[170:173], v141 offset:2048
	ds_read_b128 v[174:177], v141 offset:3072
	v_add_u32_e32 v141, 0x14000, v139
	ds_read_b128 v[178:181], v141
	ds_read_b128 v[182:185], v141 offset:1024
	ds_read_b128 v[186:189], v141 offset:2048
	ds_read_b128 v[190:193], v141 offset:3072
	s_add_i32 s52, s30, 0xffe00080
	s_cmpk_eq_i32 s72, 0x7c
	s_cselect_b32 s52, s8, s52
	s_cselect_b32 s82, s9, s31
	s_or_b32 s73, s52, 0x80
	s_mov_b32 m0, s69
	ds_read_b128 v[194:197], v140
	ds_read_b128 v[198:201], v140 offset:1024
	ds_read_b128 v[202:205], v140 offset:2048
	ds_read_b128 v[228:231], v140 offset:3072
	ds_read_b128 v[232:235], v140 offset:4096
	ds_read_b128 v[236:239], v140 offset:5120
	ds_read_b128 v[240:243], v140 offset:6144
	ds_read_b128 v[244:247], v140 offset:7168
	buffer_load_dwordx4 v131, s[60:63], s30 offen lds
	s_mov_b32 m0, s46
	s_nop 0
	buffer_load_dwordx4 v135, s[60:63], s30 offen lds
	s_waitcnt vmcnt(8)
	s_waitcnt lgkmcnt(0)
	s_setprio 1
	s_barrier
	v_mfma_f32_16x16x32_bf16 v[126:129], v[142:145], v[194:197], v[126:129]
	v_mfma_f32_16x16x32_bf16 v[118:121], v[142:145], v[202:205], v[118:121]
	v_mfma_f32_16x16x32_bf16 v[110:113], v[142:145], v[232:235], v[110:113]
	v_mfma_f32_16x16x32_bf16 v[102:105], v[142:145], v[240:243], v[102:105]
	v_mfma_f32_16x16x32_bf16 v[122:125], v[170:173], v[194:197], v[122:125]
	v_mfma_f32_16x16x32_bf16 v[114:117], v[170:173], v[202:205], v[114:117]
	v_mfma_f32_16x16x32_bf16 v[106:109], v[170:173], v[232:235], v[106:109]
	v_mfma_f32_16x16x32_bf16 v[98:101], v[170:173], v[240:243], v[98:101]
	v_mfma_f32_16x16x32_bf16 v[126:129], v[154:157], v[198:201], v[126:129]
	v_mfma_f32_16x16x32_bf16 v[118:121], v[154:157], v[228:231], v[118:121]
	v_mfma_f32_16x16x32_bf16 v[110:113], v[154:157], v[236:239], v[110:113]
	v_mfma_f32_16x16x32_bf16 v[102:105], v[154:157], v[244:247], v[102:105]
	v_mfma_f32_16x16x32_bf16 v[122:125], v[174:177], v[198:201], v[122:125]
	v_mfma_f32_16x16x32_bf16 v[114:117], v[174:177], v[228:231], v[114:117]
	v_mfma_f32_16x16x32_bf16 v[106:109], v[174:177], v[236:239], v[106:109]
	v_mfma_f32_16x16x32_bf16 v[98:101], v[174:177], v[244:247], v[98:101]
	v_mfma_f32_16x16x32_bf16 v[62:65], v[178:181], v[194:197], v[62:65]
	v_mfma_f32_16x16x32_bf16 v[54:57], v[178:181], v[202:205], v[54:57]
	v_mfma_f32_16x16x32_bf16 v[46:49], v[178:181], v[232:235], v[46:49]
	v_mfma_f32_16x16x32_bf16 v[38:41], v[178:181], v[240:243], v[38:41]
	v_mfma_f32_16x16x32_bf16 v[58:61], v[186:189], v[194:197], v[58:61]
	v_mfma_f32_16x16x32_bf16 v[50:53], v[186:189], v[202:205], v[50:53]
	v_mfma_f32_16x16x32_bf16 v[42:45], v[186:189], v[232:235], v[42:45]
	v_mfma_f32_16x16x32_bf16 v[34:37], v[186:189], v[240:243], v[34:37]
	v_mfma_f32_16x16x32_bf16 v[62:65], v[182:185], v[198:201], v[62:65]
	v_mfma_f32_16x16x32_bf16 v[54:57], v[182:185], v[228:231], v[54:57]
	v_mfma_f32_16x16x32_bf16 v[46:49], v[182:185], v[236:239], v[46:49]
	v_mfma_f32_16x16x32_bf16 v[38:41], v[182:185], v[244:247], v[38:41]
	v_mfma_f32_16x16x32_bf16 v[58:61], v[190:193], v[198:201], v[58:61]
	v_mfma_f32_16x16x32_bf16 v[50:53], v[190:193], v[228:231], v[50:53]
	v_mfma_f32_16x16x32_bf16 v[42:45], v[190:193], v[236:239], v[42:45]
	v_mfma_f32_16x16x32_bf16 v[34:37], v[190:193], v[244:247], v[34:37]
	s_barrier
	s_setprio 0
	s_mov_b32 m0, s15
	s_mov_b32 s66, s62
	s_mov_b32 s67, s63
	ds_read_b128 v[194:197], v140 offset:16384
	ds_read_b128 v[198:201], v140 offset:17408
	ds_read_b128 v[202:205], v140 offset:18432
	ds_read_b128 v[228:231], v140 offset:19456
	ds_read_b128 v[232:235], v140 offset:20480
	ds_read_b128 v[236:239], v140 offset:21504
	ds_read_b128 v[240:243], v140 offset:22528
	ds_read_b128 v[244:247], v140 offset:23552
	buffer_load_dwordx4 v134, s[64:67], s82 offen lds
	s_mov_b32 m0, s16
	s_add_i32 s53, s82, 0x200000
	buffer_load_dwordx4 v136, s[64:67], s82 offen lds
	s_mov_b32 m0, s21
	s_nop 0
	buffer_load_dwordx4 v134, s[64:67], s53 offen lds
	s_mov_b32 m0, s23
	s_nop 0
	buffer_load_dwordx4 v136, s[64:67], s53 offen lds
	s_mov_b32 m0, s2
	s_nop 0
	buffer_load_dwordx4 v131, s[60:63], s52 offen lds
	s_mov_b32 m0, s24
	s_nop 0
	buffer_load_dwordx4 v135, s[60:63], s52 offen lds
	s_waitcnt vmcnt(8)
	s_waitcnt lgkmcnt(0)
	s_setprio 1
	s_barrier
	v_mfma_f32_16x16x32_bf16 v[94:97], v[142:145], v[194:197], v[94:97]
	v_mfma_f32_16x16x32_bf16 v[86:89], v[142:145], v[202:205], v[86:89]
	v_mfma_f32_16x16x32_bf16 v[78:81], v[142:145], v[232:235], v[78:81]
	v_mfma_f32_16x16x32_bf16 v[70:73], v[142:145], v[240:243], v[70:73]
	v_mfma_f32_16x16x32_bf16 v[90:93], v[170:173], v[194:197], v[90:93]
	v_mfma_f32_16x16x32_bf16 v[82:85], v[170:173], v[202:205], v[82:85]
	v_mfma_f32_16x16x32_bf16 v[74:77], v[170:173], v[232:235], v[74:77]
	v_mfma_f32_16x16x32_bf16 v[66:69], v[170:173], v[240:243], v[66:69]
	v_mfma_f32_16x16x32_bf16 v[94:97], v[154:157], v[198:201], v[94:97]
	v_mfma_f32_16x16x32_bf16 v[86:89], v[154:157], v[228:231], v[86:89]
	v_mfma_f32_16x16x32_bf16 v[78:81], v[154:157], v[236:239], v[78:81]
	v_mfma_f32_16x16x32_bf16 v[70:73], v[154:157], v[244:247], v[70:73]
	v_mfma_f32_16x16x32_bf16 v[90:93], v[174:177], v[198:201], v[90:93]
	v_mfma_f32_16x16x32_bf16 v[82:85], v[174:177], v[228:231], v[82:85]
	v_mfma_f32_16x16x32_bf16 v[74:77], v[174:177], v[236:239], v[74:77]
	v_mfma_f32_16x16x32_bf16 v[66:69], v[174:177], v[244:247], v[66:69]
	v_mfma_f32_16x16x32_bf16 v[30:33], v[178:181], v[194:197], v[30:33]
	v_mfma_f32_16x16x32_bf16 v[22:25], v[178:181], v[202:205], v[22:25]
	v_mfma_f32_16x16x32_bf16 v[14:17], v[178:181], v[232:235], v[14:17]
	v_mfma_f32_16x16x32_bf16 v[6:9], v[178:181], v[240:243], v[6:9]
	v_mfma_f32_16x16x32_bf16 v[26:29], v[186:189], v[194:197], v[26:29]
	v_mfma_f32_16x16x32_bf16 v[18:21], v[186:189], v[202:205], v[18:21]
	v_mfma_f32_16x16x32_bf16 v[10:13], v[186:189], v[232:235], v[10:13]
	v_mfma_f32_16x16x32_bf16 v[2:5], v[186:189], v[240:243], v[2:5]
	v_mfma_f32_16x16x32_bf16 v[30:33], v[182:185], v[198:201], v[30:33]
	v_mfma_f32_16x16x32_bf16 v[22:25], v[182:185], v[228:231], v[22:25]
	v_mfma_f32_16x16x32_bf16 v[14:17], v[182:185], v[236:239], v[14:17]
	v_mfma_f32_16x16x32_bf16 v[6:9], v[182:185], v[244:247], v[6:9]
	v_mfma_f32_16x16x32_bf16 v[26:29], v[190:193], v[198:201], v[26:29]
	v_mfma_f32_16x16x32_bf16 v[18:21], v[190:193], v[228:231], v[18:21]
	v_mfma_f32_16x16x32_bf16 v[10:13], v[190:193], v[236:239], v[10:13]
	v_mfma_f32_16x16x32_bf16 v[2:5], v[190:193], v[244:247], v[2:5]
	s_barrier
	s_setprio 0
	v_add_u32_e32 v141, 0x18000, v139
	ds_read_b128 v[142:145], v141
	ds_read_b128 v[154:157], v141 offset:1024
	ds_read_b128 v[170:173], v141 offset:2048
	ds_read_b128 v[174:177], v141 offset:3072
	v_add_u32_e32 v141, 0x1c000, v139
	ds_read_b128 v[178:181], v141
	ds_read_b128 v[182:185], v141 offset:1024
	ds_read_b128 v[186:189], v141 offset:2048
	ds_read_b128 v[190:193], v141 offset:3072
	s_add_i32 s52, s52, 0x200000
	s_mov_b32 m0, s25
	ds_read_b128 v[194:197], v140 offset:32768
	ds_read_b128 v[198:201], v140 offset:33792
	ds_read_b128 v[202:205], v140 offset:34816
	ds_read_b128 v[228:231], v140 offset:35840
	ds_read_b128 v[232:235], v140 offset:36864
	ds_read_b128 v[236:239], v140 offset:37888
	ds_read_b128 v[240:243], v140 offset:38912
	ds_read_b128 v[244:247], v140 offset:39936
	buffer_load_dwordx4 v131, s[60:63], s52 offen lds
	s_mov_b32 m0, s33
	s_nop 0
	buffer_load_dwordx4 v135, s[60:63], s52 offen lds
	s_waitcnt vmcnt(8)
	s_waitcnt lgkmcnt(0)
	s_setprio 1
	s_barrier
	v_mfma_f32_16x16x32_bf16 v[126:129], v[142:145], v[194:197], v[126:129]
	v_mfma_f32_16x16x32_bf16 v[118:121], v[142:145], v[202:205], v[118:121]
	v_mfma_f32_16x16x32_bf16 v[110:113], v[142:145], v[232:235], v[110:113]
	v_mfma_f32_16x16x32_bf16 v[102:105], v[142:145], v[240:243], v[102:105]
	v_mfma_f32_16x16x32_bf16 v[122:125], v[170:173], v[194:197], v[122:125]
	v_mfma_f32_16x16x32_bf16 v[114:117], v[170:173], v[202:205], v[114:117]
	v_mfma_f32_16x16x32_bf16 v[106:109], v[170:173], v[232:235], v[106:109]
	v_mfma_f32_16x16x32_bf16 v[98:101], v[170:173], v[240:243], v[98:101]
	v_mfma_f32_16x16x32_bf16 v[126:129], v[154:157], v[198:201], v[126:129]
	v_mfma_f32_16x16x32_bf16 v[118:121], v[154:157], v[228:231], v[118:121]
	v_mfma_f32_16x16x32_bf16 v[110:113], v[154:157], v[236:239], v[110:113]
	v_mfma_f32_16x16x32_bf16 v[102:105], v[154:157], v[244:247], v[102:105]
	v_mfma_f32_16x16x32_bf16 v[122:125], v[174:177], v[198:201], v[122:125]
	v_mfma_f32_16x16x32_bf16 v[114:117], v[174:177], v[228:231], v[114:117]
	v_mfma_f32_16x16x32_bf16 v[106:109], v[174:177], v[236:239], v[106:109]
	v_mfma_f32_16x16x32_bf16 v[98:101], v[174:177], v[244:247], v[98:101]
	v_mfma_f32_16x16x32_bf16 v[62:65], v[178:181], v[194:197], v[62:65]
	v_mfma_f32_16x16x32_bf16 v[54:57], v[178:181], v[202:205], v[54:57]
	v_mfma_f32_16x16x32_bf16 v[46:49], v[178:181], v[232:235], v[46:49]
	v_mfma_f32_16x16x32_bf16 v[38:41], v[178:181], v[240:243], v[38:41]
	v_mfma_f32_16x16x32_bf16 v[58:61], v[186:189], v[194:197], v[58:61]
	v_mfma_f32_16x16x32_bf16 v[50:53], v[186:189], v[202:205], v[50:53]
	v_mfma_f32_16x16x32_bf16 v[42:45], v[186:189], v[232:235], v[42:45]
	v_mfma_f32_16x16x32_bf16 v[34:37], v[186:189], v[240:243], v[34:37]
	v_mfma_f32_16x16x32_bf16 v[62:65], v[182:185], v[198:201], v[62:65]
	v_mfma_f32_16x16x32_bf16 v[54:57], v[182:185], v[228:231], v[54:57]
	v_mfma_f32_16x16x32_bf16 v[46:49], v[182:185], v[236:239], v[46:49]
	v_mfma_f32_16x16x32_bf16 v[38:41], v[182:185], v[244:247], v[38:41]
	v_mfma_f32_16x16x32_bf16 v[58:61], v[190:193], v[198:201], v[58:61]
	v_mfma_f32_16x16x32_bf16 v[50:53], v[190:193], v[228:231], v[50:53]
	v_mfma_f32_16x16x32_bf16 v[42:45], v[190:193], v[236:239], v[42:45]
	v_mfma_f32_16x16x32_bf16 v[34:37], v[190:193], v[244:247], v[34:37]
	s_barrier
	s_setprio 0
	s_mov_b32 m0, s34
	s_or_b32 s52, s82, 0x80
	ds_read_b128 v[194:197], v140 offset:49152
	ds_read_b128 v[198:201], v140 offset:50176
	ds_read_b128 v[202:205], v140 offset:51200
	ds_read_b128 v[228:231], v140 offset:52224
	ds_read_b128 v[232:235], v140 offset:53248
	ds_read_b128 v[236:239], v140 offset:54272
	ds_read_b128 v[240:243], v140 offset:55296
	ds_read_b128 v[244:247], v140 offset:56320
	buffer_load_dwordx4 v134, s[64:67], s52 offen lds
	s_mov_b32 m0, s35
	s_add_i32 s82, s82, 0x200080
	buffer_load_dwordx4 v136, s[64:67], s52 offen lds
	s_mov_b32 m0, s37
	s_nop 0
	buffer_load_dwordx4 v134, s[64:67], s82 offen lds
	s_mov_b32 m0, s44
	s_nop 0
	buffer_load_dwordx4 v136, s[64:67], s82 offen lds
	s_mov_b32 m0, s14
	s_nop 0
	buffer_load_dwordx4 v131, s[60:63], s73 offen lds
	s_mov_b32 m0, s36
	s_nop 0
	buffer_load_dwordx4 v135, s[60:63], s73 offen lds
	s_waitcnt vmcnt(8)
	s_waitcnt lgkmcnt(0)
	s_setprio 1
	s_barrier
	v_mfma_f32_16x16x32_bf16 v[94:97], v[142:145], v[194:197], v[94:97]
	v_mfma_f32_16x16x32_bf16 v[86:89], v[142:145], v[202:205], v[86:89]
	v_mfma_f32_16x16x32_bf16 v[78:81], v[142:145], v[232:235], v[78:81]
	v_mfma_f32_16x16x32_bf16 v[70:73], v[142:145], v[240:243], v[70:73]
	v_mfma_f32_16x16x32_bf16 v[90:93], v[170:173], v[194:197], v[90:93]
	v_mfma_f32_16x16x32_bf16 v[82:85], v[170:173], v[202:205], v[82:85]
	v_mfma_f32_16x16x32_bf16 v[74:77], v[170:173], v[232:235], v[74:77]
	v_mfma_f32_16x16x32_bf16 v[66:69], v[170:173], v[240:243], v[66:69]
	v_mfma_f32_16x16x32_bf16 v[94:97], v[154:157], v[198:201], v[94:97]
	v_mfma_f32_16x16x32_bf16 v[86:89], v[154:157], v[228:231], v[86:89]
	v_mfma_f32_16x16x32_bf16 v[78:81], v[154:157], v[236:239], v[78:81]
	v_mfma_f32_16x16x32_bf16 v[70:73], v[154:157], v[244:247], v[70:73]
	v_mfma_f32_16x16x32_bf16 v[90:93], v[174:177], v[198:201], v[90:93]
	v_mfma_f32_16x16x32_bf16 v[82:85], v[174:177], v[228:231], v[82:85]
	v_mfma_f32_16x16x32_bf16 v[74:77], v[174:177], v[236:239], v[74:77]
	v_mfma_f32_16x16x32_bf16 v[66:69], v[174:177], v[244:247], v[66:69]
	v_mfma_f32_16x16x32_bf16 v[30:33], v[178:181], v[194:197], v[30:33]
	v_mfma_f32_16x16x32_bf16 v[22:25], v[178:181], v[202:205], v[22:25]
	v_mfma_f32_16x16x32_bf16 v[14:17], v[178:181], v[232:235], v[14:17]
	v_mfma_f32_16x16x32_bf16 v[6:9], v[178:181], v[240:243], v[6:9]
	v_mfma_f32_16x16x32_bf16 v[26:29], v[186:189], v[194:197], v[26:29]
	v_mfma_f32_16x16x32_bf16 v[18:21], v[186:189], v[202:205], v[18:21]
	v_mfma_f32_16x16x32_bf16 v[10:13], v[186:189], v[232:235], v[10:13]
	v_mfma_f32_16x16x32_bf16 v[2:5], v[186:189], v[240:243], v[2:5]
	v_mfma_f32_16x16x32_bf16 v[30:33], v[182:185], v[198:201], v[30:33]
	v_mfma_f32_16x16x32_bf16 v[22:25], v[182:185], v[228:231], v[22:25]
	v_mfma_f32_16x16x32_bf16 v[14:17], v[182:185], v[236:239], v[14:17]
	v_mfma_f32_16x16x32_bf16 v[6:9], v[182:185], v[244:247], v[6:9]
	v_mfma_f32_16x16x32_bf16 v[26:29], v[190:193], v[198:201], v[26:29]
	v_mfma_f32_16x16x32_bf16 v[18:21], v[190:193], v[228:231], v[18:21]
	v_mfma_f32_16x16x32_bf16 v[10:13], v[190:193], v[236:239], v[10:13]
	v_mfma_f32_16x16x32_bf16 v[2:5], v[190:193], v[244:247], v[2:5]
	s_barrier
	s_setprio 0
	s_add_i32 s72, s72, 2
	s_addk_i32 s30, 0x100
	s_addk_i32 s31, 0x100
	s_cmpk_gt_u32 s72, 0x7d
	s_cbranch_scc0 .LBB0_1193
	s_and_b64 vcc, exec, s[42:43]
	s_cbranch_vccz .LBB0_1196
	s_barrier

.LBB0_1222:
	s_lshl_b32 s14, s82, 22
	s_and_b64 s[8:9], s[44:45], exec
	s_cselect_b32 s8, s14, s19
	s_lshl_b32 s46, s84, 22
	s_and_b64 s[26:27], s[44:45], exec
	s_cselect_b32 s9, s46, s22
	s_add_i32 s19, s19, 0x200080
	s_addk_i32 s22, 0x100
	s_mov_b32 s26, -2
	v_add_u32_e32 v141, 0x10000, v139
	ds_read_b128 v[142:145], v141
	ds_read_b128 v[154:157], v141 offset:1024
	ds_read_b128 v[170:173], v141 offset:2048
	ds_read_b128 v[174:177], v141 offset:3072
	v_add_u32_e32 v141, 0x14000, v139
	ds_read_b128 v[178:181], v141
	ds_read_b128 v[182:185], v141 offset:1024
	ds_read_b128 v[186:189], v141 offset:2048
	ds_read_b128 v[190:193], v141 offset:3072
	s_add_i32 s27, s19, 0xffe00080
	s_cmpk_eq_i32 s26, 0x7c
	s_cselect_b32 s52, s8, s27
	s_cselect_b32 s47, s9, s22
	s_or_b32 s27, s52, 0x80
	s_mov_b32 m0, s71
	ds_read_b128 v[194:197], v140
	ds_read_b128 v[198:201], v140 offset:1024
	ds_read_b128 v[202:205], v140 offset:2048
	ds_read_b128 v[228:231], v140 offset:3072
	ds_read_b128 v[232:235], v140 offset:4096
	ds_read_b128 v[236:239], v140 offset:5120
	ds_read_b128 v[240:243], v140 offset:6144
	ds_read_b128 v[244:247], v140 offset:7168
	buffer_load_dwordx4 v131, s[60:63], s19 offen lds
	s_mov_b32 m0, s72
	s_nop 0
	buffer_load_dwordx4 v135, s[60:63], s19 offen lds
	s_waitcnt vmcnt(8)
	s_waitcnt lgkmcnt(0)
	s_setprio 1
	s_barrier
	v_mfma_f32_16x16x32_bf16 v[126:129], v[142:145], v[194:197], 0
	v_mfma_f32_16x16x32_bf16 v[118:121], v[142:145], v[202:205], 0
	v_mfma_f32_16x16x32_bf16 v[110:113], v[142:145], v[232:235], 0
	v_mfma_f32_16x16x32_bf16 v[102:105], v[142:145], v[240:243], 0
	v_mfma_f32_16x16x32_bf16 v[122:125], v[170:173], v[194:197], 0
	v_mfma_f32_16x16x32_bf16 v[114:117], v[170:173], v[202:205], 0
	v_mfma_f32_16x16x32_bf16 v[106:109], v[170:173], v[232:235], 0
	v_mfma_f32_16x16x32_bf16 v[98:101], v[170:173], v[240:243], 0
	v_mfma_f32_16x16x32_bf16 v[126:129], v[154:157], v[198:201], v[126:129]
	v_mfma_f32_16x16x32_bf16 v[118:121], v[154:157], v[228:231], v[118:121]
	v_mfma_f32_16x16x32_bf16 v[110:113], v[154:157], v[236:239], v[110:113]
	v_mfma_f32_16x16x32_bf16 v[102:105], v[154:157], v[244:247], v[102:105]
	v_mfma_f32_16x16x32_bf16 v[122:125], v[174:177], v[198:201], v[122:125]
	v_mfma_f32_16x16x32_bf16 v[114:117], v[174:177], v[228:231], v[114:117]
	v_mfma_f32_16x16x32_bf16 v[106:109], v[174:177], v[236:239], v[106:109]
	v_mfma_f32_16x16x32_bf16 v[98:101], v[174:177], v[244:247], v[98:101]
	v_mfma_f32_16x16x32_bf16 v[62:65], v[178:181], v[194:197], 0
	v_mfma_f32_16x16x32_bf16 v[54:57], v[178:181], v[202:205], 0
	v_mfma_f32_16x16x32_bf16 v[46:49], v[178:181], v[232:235], 0
	v_mfma_f32_16x16x32_bf16 v[38:41], v[178:181], v[240:243], 0
	v_mfma_f32_16x16x32_bf16 v[58:61], v[186:189], v[194:197], 0
	v_mfma_f32_16x16x32_bf16 v[50:53], v[186:189], v[202:205], 0
	v_mfma_f32_16x16x32_bf16 v[42:45], v[186:189], v[232:235], 0
	v_mfma_f32_16x16x32_bf16 v[34:37], v[186:189], v[240:243], 0
	v_mfma_f32_16x16x32_bf16 v[62:65], v[182:185], v[198:201], v[62:65]
	v_mfma_f32_16x16x32_bf16 v[54:57], v[182:185], v[228:231], v[54:57]
	v_mfma_f32_16x16x32_bf16 v[46:49], v[182:185], v[236:239], v[46:49]
	v_mfma_f32_16x16x32_bf16 v[38:41], v[182:185], v[244:247], v[38:41]
	v_mfma_f32_16x16x32_bf16 v[58:61], v[190:193], v[198:201], v[58:61]
	v_mfma_f32_16x16x32_bf16 v[50:53], v[190:193], v[228:231], v[50:53]
	v_mfma_f32_16x16x32_bf16 v[42:45], v[190:193], v[236:239], v[42:45]
	v_mfma_f32_16x16x32_bf16 v[34:37], v[190:193], v[244:247], v[34:37]
	s_barrier
	s_setprio 0
	s_mov_b32 m0, s2
	s_mov_b32 s66, s62
	s_mov_b32 s67, s63
	ds_read_b128 v[194:197], v140 offset:16384
	ds_read_b128 v[198:201], v140 offset:17408
	ds_read_b128 v[202:205], v140 offset:18432
	ds_read_b128 v[228:231], v140 offset:19456
	ds_read_b128 v[232:235], v140 offset:20480
	ds_read_b128 v[236:239], v140 offset:21504
	ds_read_b128 v[240:243], v140 offset:22528
	ds_read_b128 v[244:247], v140 offset:23552
	buffer_load_dwordx4 v134, s[64:67], s47 offen lds
	s_mov_b32 m0, s21
	s_add_i32 s53, s47, 0x200000
	buffer_load_dwordx4 v136, s[64:67], s47 offen lds
	s_mov_b32 m0, s23
	s_nop 0
	buffer_load_dwordx4 v134, s[64:67], s53 offen lds
	s_mov_b32 m0, s24
	s_nop 0
	buffer_load_dwordx4 v136, s[64:67], s53 offen lds
	s_mov_b32 m0, s16
	s_nop 0
	buffer_load_dwordx4 v131, s[60:63], s52 offen lds
	s_mov_b32 m0, s25
	s_nop 0
	buffer_load_dwordx4 v135, s[60:63], s52 offen lds
	s_waitcnt vmcnt(8)
	s_waitcnt lgkmcnt(0)
	s_setprio 1
	s_barrier
	v_mfma_f32_16x16x32_bf16 v[94:97], v[142:145], v[194:197], 0
	v_mfma_f32_16x16x32_bf16 v[86:89], v[142:145], v[202:205], 0
	v_mfma_f32_16x16x32_bf16 v[78:81], v[142:145], v[232:235], 0
	v_mfma_f32_16x16x32_bf16 v[70:73], v[142:145], v[240:243], 0
	v_mfma_f32_16x16x32_bf16 v[90:93], v[170:173], v[194:197], 0
	v_mfma_f32_16x16x32_bf16 v[82:85], v[170:173], v[202:205], 0
	v_mfma_f32_16x16x32_bf16 v[74:77], v[170:173], v[232:235], 0
	v_mfma_f32_16x16x32_bf16 v[66:69], v[170:173], v[240:243], 0
	v_mfma_f32_16x16x32_bf16 v[94:97], v[154:157], v[198:201], v[94:97]
	v_mfma_f32_16x16x32_bf16 v[86:89], v[154:157], v[228:231], v[86:89]
	v_mfma_f32_16x16x32_bf16 v[78:81], v[154:157], v[236:239], v[78:81]
	v_mfma_f32_16x16x32_bf16 v[70:73], v[154:157], v[244:247], v[70:73]
	v_mfma_f32_16x16x32_bf16 v[90:93], v[174:177], v[198:201], v[90:93]
	v_mfma_f32_16x16x32_bf16 v[82:85], v[174:177], v[228:231], v[82:85]
	v_mfma_f32_16x16x32_bf16 v[74:77], v[174:177], v[236:239], v[74:77]
	v_mfma_f32_16x16x32_bf16 v[66:69], v[174:177], v[244:247], v[66:69]
	v_mfma_f32_16x16x32_bf16 v[30:33], v[178:181], v[194:197], 0
	v_mfma_f32_16x16x32_bf16 v[22:25], v[178:181], v[202:205], 0
	v_mfma_f32_16x16x32_bf16 v[14:17], v[178:181], v[232:235], 0
	v_mfma_f32_16x16x32_bf16 v[6:9], v[178:181], v[240:243], 0
	v_mfma_f32_16x16x32_bf16 v[26:29], v[186:189], v[194:197], 0
	v_mfma_f32_16x16x32_bf16 v[18:21], v[186:189], v[202:205], 0
	v_mfma_f32_16x16x32_bf16 v[10:13], v[186:189], v[232:235], 0
	v_mfma_f32_16x16x32_bf16 v[2:5], v[186:189], v[240:243], 0
	v_mfma_f32_16x16x32_bf16 v[30:33], v[182:185], v[198:201], v[30:33]
	v_mfma_f32_16x16x32_bf16 v[22:25], v[182:185], v[228:231], v[22:25]
	v_mfma_f32_16x16x32_bf16 v[14:17], v[182:185], v[236:239], v[14:17]
	v_mfma_f32_16x16x32_bf16 v[6:9], v[182:185], v[244:247], v[6:9]
	v_mfma_f32_16x16x32_bf16 v[26:29], v[190:193], v[198:201], v[26:29]
	v_mfma_f32_16x16x32_bf16 v[18:21], v[190:193], v[228:231], v[18:21]
	v_mfma_f32_16x16x32_bf16 v[10:13], v[190:193], v[236:239], v[10:13]
	v_mfma_f32_16x16x32_bf16 v[2:5], v[190:193], v[244:247], v[2:5]
	s_barrier
	s_setprio 0
	v_add_u32_e32 v141, 0x18000, v139
	ds_read_b128 v[142:145], v141
	ds_read_b128 v[154:157], v141 offset:1024
	ds_read_b128 v[170:173], v141 offset:2048
	ds_read_b128 v[174:177], v141 offset:3072
	v_add_u32_e32 v141, 0x1c000, v139
	ds_read_b128 v[178:181], v141
	ds_read_b128 v[182:185], v141 offset:1024
	ds_read_b128 v[186:189], v141 offset:2048
	ds_read_b128 v[190:193], v141 offset:3072
	s_add_i32 s52, s52, 0x200000
	s_mov_b32 m0, s30
	ds_read_b128 v[194:197], v140 offset:32768
	ds_read_b128 v[198:201], v140 offset:33792
	ds_read_b128 v[202:205], v140 offset:34816
	ds_read_b128 v[228:231], v140 offset:35840
	ds_read_b128 v[232:235], v140 offset:36864
	ds_read_b128 v[236:239], v140 offset:37888
	ds_read_b128 v[240:243], v140 offset:38912
	ds_read_b128 v[244:247], v140 offset:39936
	buffer_load_dwordx4 v131, s[60:63], s52 offen lds
	s_mov_b32 m0, s31
	s_nop 0
	buffer_load_dwordx4 v135, s[60:63], s52 offen lds
	s_waitcnt vmcnt(8)
	s_waitcnt lgkmcnt(0)
	s_setprio 1
	s_barrier
	v_mfma_f32_16x16x32_bf16 v[126:129], v[142:145], v[194:197], v[126:129]
	v_mfma_f32_16x16x32_bf16 v[118:121], v[142:145], v[202:205], v[118:121]
	v_mfma_f32_16x16x32_bf16 v[110:113], v[142:145], v[232:235], v[110:113]
	v_mfma_f32_16x16x32_bf16 v[102:105], v[142:145], v[240:243], v[102:105]
	v_mfma_f32_16x16x32_bf16 v[122:125], v[170:173], v[194:197], v[122:125]
	v_mfma_f32_16x16x32_bf16 v[114:117], v[170:173], v[202:205], v[114:117]
	v_mfma_f32_16x16x32_bf16 v[106:109], v[170:173], v[232:235], v[106:109]
	v_mfma_f32_16x16x32_bf16 v[98:101], v[170:173], v[240:243], v[98:101]
	v_mfma_f32_16x16x32_bf16 v[126:129], v[154:157], v[198:201], v[126:129]
	v_mfma_f32_16x16x32_bf16 v[118:121], v[154:157], v[228:231], v[118:121]
	v_mfma_f32_16x16x32_bf16 v[110:113], v[154:157], v[236:239], v[110:113]
	v_mfma_f32_16x16x32_bf16 v[102:105], v[154:157], v[244:247], v[102:105]
	v_mfma_f32_16x16x32_bf16 v[122:125], v[174:177], v[198:201], v[122:125]
	v_mfma_f32_16x16x32_bf16 v[114:117], v[174:177], v[228:231], v[114:117]
	v_mfma_f32_16x16x32_bf16 v[106:109], v[174:177], v[236:239], v[106:109]
	v_mfma_f32_16x16x32_bf16 v[98:101], v[174:177], v[244:247], v[98:101]
	v_mfma_f32_16x16x32_bf16 v[62:65], v[178:181], v[194:197], v[62:65]
	v_mfma_f32_16x16x32_bf16 v[54:57], v[178:181], v[202:205], v[54:57]
	v_mfma_f32_16x16x32_bf16 v[46:49], v[178:181], v[232:235], v[46:49]
	v_mfma_f32_16x16x32_bf16 v[38:41], v[178:181], v[240:243], v[38:41]
	v_mfma_f32_16x16x32_bf16 v[58:61], v[186:189], v[194:197], v[58:61]
	v_mfma_f32_16x16x32_bf16 v[50:53], v[186:189], v[202:205], v[50:53]
	v_mfma_f32_16x16x32_bf16 v[42:45], v[186:189], v[232:235], v[42:45]
	v_mfma_f32_16x16x32_bf16 v[34:37], v[186:189], v[240:243], v[34:37]
	v_mfma_f32_16x16x32_bf16 v[62:65], v[182:185], v[198:201], v[62:65]
	v_mfma_f32_16x16x32_bf16 v[54:57], v[182:185], v[228:231], v[54:57]
	v_mfma_f32_16x16x32_bf16 v[46:49], v[182:185], v[236:239], v[46:49]
	v_mfma_f32_16x16x32_bf16 v[38:41], v[182:185], v[244:247], v[38:41]
	v_mfma_f32_16x16x32_bf16 v[58:61], v[190:193], v[198:201], v[58:61]
	v_mfma_f32_16x16x32_bf16 v[50:53], v[190:193], v[228:231], v[50:53]
	v_mfma_f32_16x16x32_bf16 v[42:45], v[190:193], v[236:239], v[42:45]
	v_mfma_f32_16x16x32_bf16 v[34:37], v[190:193], v[244:247], v[34:37]
	s_barrier
	s_setprio 0
	s_mov_b32 m0, s33
	s_or_b32 s52, s47, 0x80
	ds_read_b128 v[194:197], v140 offset:49152
	ds_read_b128 v[198:201], v140 offset:50176
	ds_read_b128 v[202:205], v140 offset:51200
	ds_read_b128 v[228:231], v140 offset:52224
	ds_read_b128 v[232:235], v140 offset:53248
	ds_read_b128 v[236:239], v140 offset:54272
	ds_read_b128 v[240:243], v140 offset:55296
	ds_read_b128 v[244:247], v140 offset:56320
	buffer_load_dwordx4 v134, s[64:67], s52 offen lds
	s_mov_b32 m0, s34
	s_add_i32 s47, s47, 0x200080
	buffer_load_dwordx4 v136, s[64:67], s52 offen lds
	s_mov_b32 m0, s37
	s_nop 0
	buffer_load_dwordx4 v134, s[64:67], s47 offen lds
	s_mov_b32 m0, s68
	s_nop 0
	buffer_load_dwordx4 v136, s[64:67], s47 offen lds
	s_mov_b32 m0, s35
	s_nop 0
	buffer_load_dwordx4 v131, s[60:63], s27 offen lds
	s_mov_b32 m0, s36
	s_nop 0
	buffer_load_dwordx4 v135, s[60:63], s27 offen lds
	s_waitcnt vmcnt(8)
	s_waitcnt lgkmcnt(0)
	s_setprio 1
	s_barrier
	v_mfma_f32_16x16x32_bf16 v[94:97], v[142:145], v[194:197], v[94:97]
	v_mfma_f32_16x16x32_bf16 v[86:89], v[142:145], v[202:205], v[86:89]
	v_mfma_f32_16x16x32_bf16 v[78:81], v[142:145], v[232:235], v[78:81]
	v_mfma_f32_16x16x32_bf16 v[70:73], v[142:145], v[240:243], v[70:73]
	v_mfma_f32_16x16x32_bf16 v[90:93], v[170:173], v[194:197], v[90:93]
	v_mfma_f32_16x16x32_bf16 v[82:85], v[170:173], v[202:205], v[82:85]
	v_mfma_f32_16x16x32_bf16 v[74:77], v[170:173], v[232:235], v[74:77]
	v_mfma_f32_16x16x32_bf16 v[66:69], v[170:173], v[240:243], v[66:69]
	v_mfma_f32_16x16x32_bf16 v[94:97], v[154:157], v[198:201], v[94:97]
	v_mfma_f32_16x16x32_bf16 v[86:89], v[154:157], v[228:231], v[86:89]
	v_mfma_f32_16x16x32_bf16 v[78:81], v[154:157], v[236:239], v[78:81]
	v_mfma_f32_16x16x32_bf16 v[70:73], v[154:157], v[244:247], v[70:73]
	v_mfma_f32_16x16x32_bf16 v[90:93], v[174:177], v[198:201], v[90:93]
	v_mfma_f32_16x16x32_bf16 v[82:85], v[174:177], v[228:231], v[82:85]
	v_mfma_f32_16x16x32_bf16 v[74:77], v[174:177], v[236:239], v[74:77]
	v_mfma_f32_16x16x32_bf16 v[66:69], v[174:177], v[244:247], v[66:69]
	v_mfma_f32_16x16x32_bf16 v[30:33], v[178:181], v[194:197], v[30:33]
	v_mfma_f32_16x16x32_bf16 v[22:25], v[178:181], v[202:205], v[22:25]
	v_mfma_f32_16x16x32_bf16 v[14:17], v[178:181], v[232:235], v[14:17]
	v_mfma_f32_16x16x32_bf16 v[6:9], v[178:181], v[240:243], v[6:9]
	v_mfma_f32_16x16x32_bf16 v[26:29], v[186:189], v[194:197], v[26:29]
	v_mfma_f32_16x16x32_bf16 v[18:21], v[186:189], v[202:205], v[18:21]
	v_mfma_f32_16x16x32_bf16 v[10:13], v[186:189], v[232:235], v[10:13]
	v_mfma_f32_16x16x32_bf16 v[2:5], v[186:189], v[240:243], v[2:5]
	v_mfma_f32_16x16x32_bf16 v[30:33], v[182:185], v[198:201], v[30:33]
	v_mfma_f32_16x16x32_bf16 v[22:25], v[182:185], v[228:231], v[22:25]
	v_mfma_f32_16x16x32_bf16 v[14:17], v[182:185], v[236:239], v[14:17]
	v_mfma_f32_16x16x32_bf16 v[6:9], v[182:185], v[244:247], v[6:9]
	v_mfma_f32_16x16x32_bf16 v[26:29], v[190:193], v[198:201], v[26:29]
	v_mfma_f32_16x16x32_bf16 v[18:21], v[190:193], v[228:231], v[18:21]
	v_mfma_f32_16x16x32_bf16 v[10:13], v[190:193], v[236:239], v[10:13]
	v_mfma_f32_16x16x32_bf16 v[2:5], v[190:193], v[244:247], v[2:5]
	s_barrier
	s_setprio 0
	s_add_i32 s26, s26, 2
	s_addk_i32 s19, 0x100
	s_addk_i32 s22, 0x100
	s_cmpk_gt_u32 s26, 0x7d
.LBB0_1223:
	v_add_u32_e32 v141, 0x10000, v139
	ds_read_b128 v[142:145], v141
	ds_read_b128 v[154:157], v141 offset:1024
	ds_read_b128 v[170:173], v141 offset:2048
	ds_read_b128 v[174:177], v141 offset:3072
	v_add_u32_e32 v141, 0x14000, v139
	ds_read_b128 v[178:181], v141
	ds_read_b128 v[182:185], v141 offset:1024
	ds_read_b128 v[186:189], v141 offset:2048
	ds_read_b128 v[190:193], v141 offset:3072
	s_add_i32 s27, s19, 0xffe00080
	s_cmpk_eq_i32 s26, 0x7c
	s_cselect_b32 s52, s8, s27
	s_cselect_b32 s47, s9, s22
	s_or_b32 s27, s52, 0x80
	s_mov_b32 m0, s71
	ds_read_b128 v[194:197], v140
	ds_read_b128 v[198:201], v140 offset:1024
	ds_read_b128 v[202:205], v140 offset:2048
	ds_read_b128 v[228:231], v140 offset:3072
	ds_read_b128 v[232:235], v140 offset:4096
	ds_read_b128 v[236:239], v140 offset:5120
	ds_read_b128 v[240:243], v140 offset:6144
	ds_read_b128 v[244:247], v140 offset:7168
	buffer_load_dwordx4 v131, s[60:63], s19 offen lds
	s_mov_b32 m0, s72
	s_nop 0
	buffer_load_dwordx4 v135, s[60:63], s19 offen lds
	s_waitcnt vmcnt(8)
	s_waitcnt lgkmcnt(0)
	s_setprio 1
	s_barrier
	v_mfma_f32_16x16x32_bf16 v[126:129], v[142:145], v[194:197], v[126:129]
	v_mfma_f32_16x16x32_bf16 v[118:121], v[142:145], v[202:205], v[118:121]
	v_mfma_f32_16x16x32_bf16 v[110:113], v[142:145], v[232:235], v[110:113]
	v_mfma_f32_16x16x32_bf16 v[102:105], v[142:145], v[240:243], v[102:105]
	v_mfma_f32_16x16x32_bf16 v[122:125], v[170:173], v[194:197], v[122:125]
	v_mfma_f32_16x16x32_bf16 v[114:117], v[170:173], v[202:205], v[114:117]
	v_mfma_f32_16x16x32_bf16 v[106:109], v[170:173], v[232:235], v[106:109]
	v_mfma_f32_16x16x32_bf16 v[98:101], v[170:173], v[240:243], v[98:101]
	v_mfma_f32_16x16x32_bf16 v[126:129], v[154:157], v[198:201], v[126:129]
	v_mfma_f32_16x16x32_bf16 v[118:121], v[154:157], v[228:231], v[118:121]
	v_mfma_f32_16x16x32_bf16 v[110:113], v[154:157], v[236:239], v[110:113]
	v_mfma_f32_16x16x32_bf16 v[102:105], v[154:157], v[244:247], v[102:105]
	v_mfma_f32_16x16x32_bf16 v[122:125], v[174:177], v[198:201], v[122:125]
	v_mfma_f32_16x16x32_bf16 v[114:117], v[174:177], v[228:231], v[114:117]
	v_mfma_f32_16x16x32_bf16 v[106:109], v[174:177], v[236:239], v[106:109]
	v_mfma_f32_16x16x32_bf16 v[98:101], v[174:177], v[244:247], v[98:101]
	v_mfma_f32_16x16x32_bf16 v[62:65], v[178:181], v[194:197], v[62:65]
	v_mfma_f32_16x16x32_bf16 v[54:57], v[178:181], v[202:205], v[54:57]
	v_mfma_f32_16x16x32_bf16 v[46:49], v[178:181], v[232:235], v[46:49]
	v_mfma_f32_16x16x32_bf16 v[38:41], v[178:181], v[240:243], v[38:41]
	v_mfma_f32_16x16x32_bf16 v[58:61], v[186:189], v[194:197], v[58:61]
	v_mfma_f32_16x16x32_bf16 v[50:53], v[186:189], v[202:205], v[50:53]
	v_mfma_f32_16x16x32_bf16 v[42:45], v[186:189], v[232:235], v[42:45]
	v_mfma_f32_16x16x32_bf16 v[34:37], v[186:189], v[240:243], v[34:37]
	v_mfma_f32_16x16x32_bf16 v[62:65], v[182:185], v[198:201], v[62:65]
	v_mfma_f32_16x16x32_bf16 v[54:57], v[182:185], v[228:231], v[54:57]
	v_mfma_f32_16x16x32_bf16 v[46:49], v[182:185], v[236:239], v[46:49]
	v_mfma_f32_16x16x32_bf16 v[38:41], v[182:185], v[244:247], v[38:41]
	v_mfma_f32_16x16x32_bf16 v[58:61], v[190:193], v[198:201], v[58:61]
	v_mfma_f32_16x16x32_bf16 v[50:53], v[190:193], v[228:231], v[50:53]
	v_mfma_f32_16x16x32_bf16 v[42:45], v[190:193], v[236:239], v[42:45]
	v_mfma_f32_16x16x32_bf16 v[34:37], v[190:193], v[244:247], v[34:37]
	s_barrier
	s_setprio 0
	s_mov_b32 m0, s2
	s_mov_b32 s66, s62
	s_mov_b32 s67, s63
	ds_read_b128 v[194:197], v140 offset:16384
	ds_read_b128 v[198:201], v140 offset:17408
	ds_read_b128 v[202:205], v140 offset:18432
	ds_read_b128 v[228:231], v140 offset:19456
	ds_read_b128 v[232:235], v140 offset:20480
	ds_read_b128 v[236:239], v140 offset:21504
	ds_read_b128 v[240:243], v140 offset:22528
	ds_read_b128 v[244:247], v140 offset:23552
	buffer_load_dwordx4 v134, s[64:67], s47 offen lds
	s_mov_b32 m0, s21
	s_add_i32 s53, s47, 0x200000
	buffer_load_dwordx4 v136, s[64:67], s47 offen lds
	s_mov_b32 m0, s23
	s_nop 0
	buffer_load_dwordx4 v134, s[64:67], s53 offen lds
	s_mov_b32 m0, s24
	s_nop 0
	buffer_load_dwordx4 v136, s[64:67], s53 offen lds
	s_mov_b32 m0, s16
	s_nop 0
	buffer_load_dwordx4 v131, s[60:63], s52 offen lds
	s_mov_b32 m0, s25
	s_nop 0
	buffer_load_dwordx4 v135, s[60:63], s52 offen lds
	s_waitcnt vmcnt(8)
	s_waitcnt lgkmcnt(0)
	s_setprio 1
	s_barrier
	v_mfma_f32_16x16x32_bf16 v[94:97], v[142:145], v[194:197], v[94:97]
	v_mfma_f32_16x16x32_bf16 v[86:89], v[142:145], v[202:205], v[86:89]
	v_mfma_f32_16x16x32_bf16 v[78:81], v[142:145], v[232:235], v[78:81]
	v_mfma_f32_16x16x32_bf16 v[70:73], v[142:145], v[240:243], v[70:73]
	v_mfma_f32_16x16x32_bf16 v[90:93], v[170:173], v[194:197], v[90:93]
	v_mfma_f32_16x16x32_bf16 v[82:85], v[170:173], v[202:205], v[82:85]
	v_mfma_f32_16x16x32_bf16 v[74:77], v[170:173], v[232:235], v[74:77]
	v_mfma_f32_16x16x32_bf16 v[66:69], v[170:173], v[240:243], v[66:69]
	v_mfma_f32_16x16x32_bf16 v[94:97], v[154:157], v[198:201], v[94:97]
	v_mfma_f32_16x16x32_bf16 v[86:89], v[154:157], v[228:231], v[86:89]
	v_mfma_f32_16x16x32_bf16 v[78:81], v[154:157], v[236:239], v[78:81]
	v_mfma_f32_16x16x32_bf16 v[70:73], v[154:157], v[244:247], v[70:73]
	v_mfma_f32_16x16x32_bf16 v[90:93], v[174:177], v[198:201], v[90:93]
	v_mfma_f32_16x16x32_bf16 v[82:85], v[174:177], v[228:231], v[82:85]
	v_mfma_f32_16x16x32_bf16 v[74:77], v[174:177], v[236:239], v[74:77]
	v_mfma_f32_16x16x32_bf16 v[66:69], v[174:177], v[244:247], v[66:69]
	v_mfma_f32_16x16x32_bf16 v[30:33], v[178:181], v[194:197], v[30:33]
	v_mfma_f32_16x16x32_bf16 v[22:25], v[178:181], v[202:205], v[22:25]
	v_mfma_f32_16x16x32_bf16 v[14:17], v[178:181], v[232:235], v[14:17]
	v_mfma_f32_16x16x32_bf16 v[6:9], v[178:181], v[240:243], v[6:9]
	v_mfma_f32_16x16x32_bf16 v[26:29], v[186:189], v[194:197], v[26:29]
	v_mfma_f32_16x16x32_bf16 v[18:21], v[186:189], v[202:205], v[18:21]
	v_mfma_f32_16x16x32_bf16 v[10:13], v[186:189], v[232:235], v[10:13]
	v_mfma_f32_16x16x32_bf16 v[2:5], v[186:189], v[240:243], v[2:5]
	v_mfma_f32_16x16x32_bf16 v[30:33], v[182:185], v[198:201], v[30:33]
	v_mfma_f32_16x16x32_bf16 v[22:25], v[182:185], v[228:231], v[22:25]
	v_mfma_f32_16x16x32_bf16 v[14:17], v[182:185], v[236:239], v[14:17]
	v_mfma_f32_16x16x32_bf16 v[6:9], v[182:185], v[244:247], v[6:9]
	v_mfma_f32_16x16x32_bf16 v[26:29], v[190:193], v[198:201], v[26:29]
	v_mfma_f32_16x16x32_bf16 v[18:21], v[190:193], v[228:231], v[18:21]
	v_mfma_f32_16x16x32_bf16 v[10:13], v[190:193], v[236:239], v[10:13]
	v_mfma_f32_16x16x32_bf16 v[2:5], v[190:193], v[244:247], v[2:5]
	s_barrier
	s_setprio 0
	v_add_u32_e32 v141, 0x18000, v139
	ds_read_b128 v[142:145], v141
	ds_read_b128 v[154:157], v141 offset:1024
	ds_read_b128 v[170:173], v141 offset:2048
	ds_read_b128 v[174:177], v141 offset:3072
	v_add_u32_e32 v141, 0x1c000, v139
	ds_read_b128 v[178:181], v141
	ds_read_b128 v[182:185], v141 offset:1024
	ds_read_b128 v[186:189], v141 offset:2048
	ds_read_b128 v[190:193], v141 offset:3072
	s_add_i32 s52, s52, 0x200000
	s_mov_b32 m0, s30
	ds_read_b128 v[194:197], v140 offset:32768
	ds_read_b128 v[198:201], v140 offset:33792
	ds_read_b128 v[202:205], v140 offset:34816
	ds_read_b128 v[228:231], v140 offset:35840
	ds_read_b128 v[232:235], v140 offset:36864
	ds_read_b128 v[236:239], v140 offset:37888
	ds_read_b128 v[240:243], v140 offset:38912
	ds_read_b128 v[244:247], v140 offset:39936
	buffer_load_dwordx4 v131, s[60:63], s52 offen lds
	s_mov_b32 m0, s31
	s_nop 0
	buffer_load_dwordx4 v135, s[60:63], s52 offen lds
	s_waitcnt vmcnt(8)
	s_waitcnt lgkmcnt(0)
	s_setprio 1
	s_barrier
	v_mfma_f32_16x16x32_bf16 v[126:129], v[142:145], v[194:197], v[126:129]
	v_mfma_f32_16x16x32_bf16 v[118:121], v[142:145], v[202:205], v[118:121]
	v_mfma_f32_16x16x32_bf16 v[110:113], v[142:145], v[232:235], v[110:113]
	v_mfma_f32_16x16x32_bf16 v[102:105], v[142:145], v[240:243], v[102:105]
	v_mfma_f32_16x16x32_bf16 v[122:125], v[170:173], v[194:197], v[122:125]
	v_mfma_f32_16x16x32_bf16 v[114:117], v[170:173], v[202:205], v[114:117]
	v_mfma_f32_16x16x32_bf16 v[106:109], v[170:173], v[232:235], v[106:109]
	v_mfma_f32_16x16x32_bf16 v[98:101], v[170:173], v[240:243], v[98:101]
	v_mfma_f32_16x16x32_bf16 v[126:129], v[154:157], v[198:201], v[126:129]
	v_mfma_f32_16x16x32_bf16 v[118:121], v[154:157], v[228:231], v[118:121]
	v_mfma_f32_16x16x32_bf16 v[110:113], v[154:157], v[236:239], v[110:113]
	v_mfma_f32_16x16x32_bf16 v[102:105], v[154:157], v[244:247], v[102:105]
	v_mfma_f32_16x16x32_bf16 v[122:125], v[174:177], v[198:201], v[122:125]
	v_mfma_f32_16x16x32_bf16 v[114:117], v[174:177], v[228:231], v[114:117]
	v_mfma_f32_16x16x32_bf16 v[106:109], v[174:177], v[236:239], v[106:109]
	v_mfma_f32_16x16x32_bf16 v[98:101], v[174:177], v[244:247], v[98:101]
	v_mfma_f32_16x16x32_bf16 v[62:65], v[178:181], v[194:197], v[62:65]
	v_mfma_f32_16x16x32_bf16 v[54:57], v[178:181], v[202:205], v[54:57]
	v_mfma_f32_16x16x32_bf16 v[46:49], v[178:181], v[232:235], v[46:49]
	v_mfma_f32_16x16x32_bf16 v[38:41], v[178:181], v[240:243], v[38:41]
	v_mfma_f32_16x16x32_bf16 v[58:61], v[186:189], v[194:197], v[58:61]
	v_mfma_f32_16x16x32_bf16 v[50:53], v[186:189], v[202:205], v[50:53]
	v_mfma_f32_16x16x32_bf16 v[42:45], v[186:189], v[232:235], v[42:45]
	v_mfma_f32_16x16x32_bf16 v[34:37], v[186:189], v[240:243], v[34:37]
	v_mfma_f32_16x16x32_bf16 v[62:65], v[182:185], v[198:201], v[62:65]
	v_mfma_f32_16x16x32_bf16 v[54:57], v[182:185], v[228:231], v[54:57]
	v_mfma_f32_16x16x32_bf16 v[46:49], v[182:185], v[236:239], v[46:49]
	v_mfma_f32_16x16x32_bf16 v[38:41], v[182:185], v[244:247], v[38:41]
	v_mfma_f32_16x16x32_bf16 v[58:61], v[190:193], v[198:201], v[58:61]
	v_mfma_f32_16x16x32_bf16 v[50:53], v[190:193], v[228:231], v[50:53]
	v_mfma_f32_16x16x32_bf16 v[42:45], v[190:193], v[236:239], v[42:45]
	v_mfma_f32_16x16x32_bf16 v[34:37], v[190:193], v[244:247], v[34:37]
	s_barrier
	s_setprio 0
	s_mov_b32 m0, s33
	s_or_b32 s52, s47, 0x80
	ds_read_b128 v[194:197], v140 offset:49152
	ds_read_b128 v[198:201], v140 offset:50176
	ds_read_b128 v[202:205], v140 offset:51200
	ds_read_b128 v[228:231], v140 offset:52224
	ds_read_b128 v[232:235], v140 offset:53248
	ds_read_b128 v[236:239], v140 offset:54272
	ds_read_b128 v[240:243], v140 offset:55296
	ds_read_b128 v[244:247], v140 offset:56320
	buffer_load_dwordx4 v134, s[64:67], s52 offen lds
	s_mov_b32 m0, s34
	s_add_i32 s47, s47, 0x200080
	buffer_load_dwordx4 v136, s[64:67], s52 offen lds
	s_mov_b32 m0, s37
	s_nop 0
	buffer_load_dwordx4 v134, s[64:67], s47 offen lds
	s_mov_b32 m0, s68
	s_nop 0
	buffer_load_dwordx4 v136, s[64:67], s47 offen lds
	s_mov_b32 m0, s35
	s_nop 0
	buffer_load_dwordx4 v131, s[60:63], s27 offen lds
	s_mov_b32 m0, s36
	s_nop 0
	buffer_load_dwordx4 v135, s[60:63], s27 offen lds
	s_waitcnt vmcnt(8)
	s_waitcnt lgkmcnt(0)
	s_setprio 1
	s_barrier
	v_mfma_f32_16x16x32_bf16 v[94:97], v[142:145], v[194:197], v[94:97]
	v_mfma_f32_16x16x32_bf16 v[86:89], v[142:145], v[202:205], v[86:89]
	v_mfma_f32_16x16x32_bf16 v[78:81], v[142:145], v[232:235], v[78:81]
	v_mfma_f32_16x16x32_bf16 v[70:73], v[142:145], v[240:243], v[70:73]
	v_mfma_f32_16x16x32_bf16 v[90:93], v[170:173], v[194:197], v[90:93]
	v_mfma_f32_16x16x32_bf16 v[82:85], v[170:173], v[202:205], v[82:85]
	v_mfma_f32_16x16x32_bf16 v[74:77], v[170:173], v[232:235], v[74:77]
	v_mfma_f32_16x16x32_bf16 v[66:69], v[170:173], v[240:243], v[66:69]
	v_mfma_f32_16x16x32_bf16 v[94:97], v[154:157], v[198:201], v[94:97]
	v_mfma_f32_16x16x32_bf16 v[86:89], v[154:157], v[228:231], v[86:89]
	v_mfma_f32_16x16x32_bf16 v[78:81], v[154:157], v[236:239], v[78:81]
	v_mfma_f32_16x16x32_bf16 v[70:73], v[154:157], v[244:247], v[70:73]
	v_mfma_f32_16x16x32_bf16 v[90:93], v[174:177], v[198:201], v[90:93]
	v_mfma_f32_16x16x32_bf16 v[82:85], v[174:177], v[228:231], v[82:85]
	v_mfma_f32_16x16x32_bf16 v[74:77], v[174:177], v[236:239], v[74:77]
	v_mfma_f32_16x16x32_bf16 v[66:69], v[174:177], v[244:247], v[66:69]
	v_mfma_f32_16x16x32_bf16 v[30:33], v[178:181], v[194:197], v[30:33]
	v_mfma_f32_16x16x32_bf16 v[22:25], v[178:181], v[202:205], v[22:25]
	v_mfma_f32_16x16x32_bf16 v[14:17], v[178:181], v[232:235], v[14:17]
	v_mfma_f32_16x16x32_bf16 v[6:9], v[178:181], v[240:243], v[6:9]
	v_mfma_f32_16x16x32_bf16 v[26:29], v[186:189], v[194:197], v[26:29]
	v_mfma_f32_16x16x32_bf16 v[18:21], v[186:189], v[202:205], v[18:21]
	v_mfma_f32_16x16x32_bf16 v[10:13], v[186:189], v[232:235], v[10:13]
	v_mfma_f32_16x16x32_bf16 v[2:5], v[186:189], v[240:243], v[2:5]
	v_mfma_f32_16x16x32_bf16 v[30:33], v[182:185], v[198:201], v[30:33]
	v_mfma_f32_16x16x32_bf16 v[22:25], v[182:185], v[228:231], v[22:25]
	v_mfma_f32_16x16x32_bf16 v[14:17], v[182:185], v[236:239], v[14:17]
	v_mfma_f32_16x16x32_bf16 v[6:9], v[182:185], v[244:247], v[6:9]
	v_mfma_f32_16x16x32_bf16 v[26:29], v[190:193], v[198:201], v[26:29]
	v_mfma_f32_16x16x32_bf16 v[18:21], v[190:193], v[228:231], v[18:21]
	v_mfma_f32_16x16x32_bf16 v[10:13], v[190:193], v[236:239], v[10:13]
	v_mfma_f32_16x16x32_bf16 v[2:5], v[190:193], v[244:247], v[2:5]
	s_barrier
	s_setprio 0
	s_add_i32 s26, s26, 2
	s_addk_i32 s19, 0x100
	s_addk_i32 s22, 0x100
	s_cmpk_gt_u32 s26, 0x7d
	s_cbranch_scc0 .LBB0_1223
	s_and_b64 vcc, exec, s[42:43]
	s_cbranch_vccz .LBB0_1226
	s_barrier

.LBB0_1252:
	s_lshl_b32 s12, s73, 20
	s_and_b64 s[8:9], s[40:41], exec
	s_cselect_b32 s8, s12, s26
	s_lshl_b32 s22, s82, 20
	s_and_b64 s[70:71], s[40:41], exec
	s_cselect_b32 s9, s22, s27
	s_add_i32 s26, s26, 0x80080
	s_addk_i32 s27, 0x100
	s_mov_b32 s83, -2
	v_add_u32_e32 v141, 0x10000, v139
	ds_read_b128 v[142:145], v141
	ds_read_b128 v[154:157], v141 offset:1024
	ds_read_b128 v[170:173], v141 offset:2048
	ds_read_b128 v[174:177], v141 offset:3072
	v_add_u32_e32 v141, 0x14000, v139
	ds_read_b128 v[178:181], v141
	ds_read_b128 v[182:185], v141 offset:1024
	ds_read_b128 v[186:189], v141 offset:2048
	ds_read_b128 v[190:193], v141 offset:3072
	s_add_i32 s52, s26, 0xfff80080
	s_cmp_eq_u32 s83, 28
	s_cselect_b32 s52, s8, s52
	s_cselect_b32 s85, s9, s27
	s_or_b32 s84, s52, 0x80
	s_mov_b32 m0, s72
	ds_read_b128 v[194:197], v140
	ds_read_b128 v[198:201], v140 offset:1024
	ds_read_b128 v[202:205], v140 offset:2048
	ds_read_b128 v[228:231], v140 offset:3072
	ds_read_b128 v[232:235], v140 offset:4096
	ds_read_b128 v[236:239], v140 offset:5120
	ds_read_b128 v[240:243], v140 offset:6144
	ds_read_b128 v[244:247], v140 offset:7168
	buffer_load_dwordx4 v131, s[60:63], s26 offen lds
	s_mov_b32 m0, s46
	s_nop 0
	buffer_load_dwordx4 v135, s[60:63], s26 offen lds
	s_waitcnt vmcnt(8)
	s_waitcnt lgkmcnt(0)
	s_setprio 1
	s_barrier
	v_mfma_f32_16x16x32_bf16 v[126:129], v[142:145], v[194:197], 0
	v_mfma_f32_16x16x32_bf16 v[118:121], v[142:145], v[202:205], 0
	v_mfma_f32_16x16x32_bf16 v[110:113], v[142:145], v[232:235], 0
	v_mfma_f32_16x16x32_bf16 v[102:105], v[142:145], v[240:243], 0
	v_mfma_f32_16x16x32_bf16 v[122:125], v[170:173], v[194:197], 0
	v_mfma_f32_16x16x32_bf16 v[114:117], v[170:173], v[202:205], 0
	v_mfma_f32_16x16x32_bf16 v[106:109], v[170:173], v[232:235], 0
	v_mfma_f32_16x16x32_bf16 v[98:101], v[170:173], v[240:243], 0
	v_mfma_f32_16x16x32_bf16 v[126:129], v[154:157], v[198:201], v[126:129]
	v_mfma_f32_16x16x32_bf16 v[118:121], v[154:157], v[228:231], v[118:121]
	v_mfma_f32_16x16x32_bf16 v[110:113], v[154:157], v[236:239], v[110:113]
	v_mfma_f32_16x16x32_bf16 v[102:105], v[154:157], v[244:247], v[102:105]
	v_mfma_f32_16x16x32_bf16 v[122:125], v[174:177], v[198:201], v[122:125]
	v_mfma_f32_16x16x32_bf16 v[114:117], v[174:177], v[228:231], v[114:117]
	v_mfma_f32_16x16x32_bf16 v[106:109], v[174:177], v[236:239], v[106:109]
	v_mfma_f32_16x16x32_bf16 v[98:101], v[174:177], v[244:247], v[98:101]
	v_mfma_f32_16x16x32_bf16 v[62:65], v[178:181], v[194:197], 0
	v_mfma_f32_16x16x32_bf16 v[54:57], v[178:181], v[202:205], 0
	v_mfma_f32_16x16x32_bf16 v[46:49], v[178:181], v[232:235], 0
	v_mfma_f32_16x16x32_bf16 v[38:41], v[178:181], v[240:243], 0
	v_mfma_f32_16x16x32_bf16 v[58:61], v[186:189], v[194:197], 0
	v_mfma_f32_16x16x32_bf16 v[50:53], v[186:189], v[202:205], 0
	v_mfma_f32_16x16x32_bf16 v[42:45], v[186:189], v[232:235], 0
	v_mfma_f32_16x16x32_bf16 v[34:37], v[186:189], v[240:243], 0
	v_mfma_f32_16x16x32_bf16 v[62:65], v[182:185], v[198:201], v[62:65]
	v_mfma_f32_16x16x32_bf16 v[54:57], v[182:185], v[228:231], v[54:57]
	v_mfma_f32_16x16x32_bf16 v[46:49], v[182:185], v[236:239], v[46:49]
	v_mfma_f32_16x16x32_bf16 v[38:41], v[182:185], v[244:247], v[38:41]
	v_mfma_f32_16x16x32_bf16 v[58:61], v[190:193], v[198:201], v[58:61]
	v_mfma_f32_16x16x32_bf16 v[50:53], v[190:193], v[228:231], v[50:53]
	v_mfma_f32_16x16x32_bf16 v[42:45], v[190:193], v[236:239], v[42:45]
	v_mfma_f32_16x16x32_bf16 v[34:37], v[190:193], v[244:247], v[34:37]
	s_barrier
	s_setprio 0
	s_mov_b32 m0, s21
	s_mov_b32 s70, s62
	s_mov_b32 s71, s63
	ds_read_b128 v[194:197], v140 offset:16384
	ds_read_b128 v[198:201], v140 offset:17408
	ds_read_b128 v[202:205], v140 offset:18432
	ds_read_b128 v[228:231], v140 offset:19456
	ds_read_b128 v[232:235], v140 offset:20480
	ds_read_b128 v[236:239], v140 offset:21504
	ds_read_b128 v[240:243], v140 offset:22528
	ds_read_b128 v[244:247], v140 offset:23552
	buffer_load_dwordx4 v134, s[68:71], s85 offen lds
	s_mov_b32 m0, s23
	s_add_i32 s53, s85, 0x80000
	buffer_load_dwordx4 v136, s[68:71], s85 offen lds
	s_mov_b32 m0, s24
	s_nop 0
	buffer_load_dwordx4 v134, s[68:71], s53 offen lds
	s_mov_b32 m0, s25
	s_nop 0
	buffer_load_dwordx4 v136, s[68:71], s53 offen lds
	s_mov_b32 m0, s16
	s_nop 0
	buffer_load_dwordx4 v131, s[60:63], s52 offen lds
	s_mov_b32 m0, s30
	s_nop 0
	buffer_load_dwordx4 v135, s[60:63], s52 offen lds
	s_waitcnt vmcnt(8)
	s_waitcnt lgkmcnt(0)
	s_setprio 1
	s_barrier
	v_mfma_f32_16x16x32_bf16 v[94:97], v[142:145], v[194:197], 0
	v_mfma_f32_16x16x32_bf16 v[86:89], v[142:145], v[202:205], 0
	v_mfma_f32_16x16x32_bf16 v[78:81], v[142:145], v[232:235], 0
	v_mfma_f32_16x16x32_bf16 v[70:73], v[142:145], v[240:243], 0
	v_mfma_f32_16x16x32_bf16 v[90:93], v[170:173], v[194:197], 0
	v_mfma_f32_16x16x32_bf16 v[82:85], v[170:173], v[202:205], 0
	v_mfma_f32_16x16x32_bf16 v[74:77], v[170:173], v[232:235], 0
	v_mfma_f32_16x16x32_bf16 v[66:69], v[170:173], v[240:243], 0
	v_mfma_f32_16x16x32_bf16 v[94:97], v[154:157], v[198:201], v[94:97]
	v_mfma_f32_16x16x32_bf16 v[86:89], v[154:157], v[228:231], v[86:89]
	v_mfma_f32_16x16x32_bf16 v[78:81], v[154:157], v[236:239], v[78:81]
	v_mfma_f32_16x16x32_bf16 v[70:73], v[154:157], v[244:247], v[70:73]
	v_mfma_f32_16x16x32_bf16 v[90:93], v[174:177], v[198:201], v[90:93]
	v_mfma_f32_16x16x32_bf16 v[82:85], v[174:177], v[228:231], v[82:85]
	v_mfma_f32_16x16x32_bf16 v[74:77], v[174:177], v[236:239], v[74:77]
	v_mfma_f32_16x16x32_bf16 v[66:69], v[174:177], v[244:247], v[66:69]
	v_mfma_f32_16x16x32_bf16 v[30:33], v[178:181], v[194:197], 0
	v_mfma_f32_16x16x32_bf16 v[22:25], v[178:181], v[202:205], 0
	v_mfma_f32_16x16x32_bf16 v[14:17], v[178:181], v[232:235], 0
	v_mfma_f32_16x16x32_bf16 v[6:9], v[178:181], v[240:243], 0
	v_mfma_f32_16x16x32_bf16 v[26:29], v[186:189], v[194:197], 0
	v_mfma_f32_16x16x32_bf16 v[18:21], v[186:189], v[202:205], 0
	v_mfma_f32_16x16x32_bf16 v[10:13], v[186:189], v[232:235], 0
	v_mfma_f32_16x16x32_bf16 v[2:5], v[186:189], v[240:243], 0
	v_mfma_f32_16x16x32_bf16 v[30:33], v[182:185], v[198:201], v[30:33]
	v_mfma_f32_16x16x32_bf16 v[22:25], v[182:185], v[228:231], v[22:25]
	v_mfma_f32_16x16x32_bf16 v[14:17], v[182:185], v[236:239], v[14:17]
	v_mfma_f32_16x16x32_bf16 v[6:9], v[182:185], v[244:247], v[6:9]
	v_mfma_f32_16x16x32_bf16 v[26:29], v[190:193], v[198:201], v[26:29]
	v_mfma_f32_16x16x32_bf16 v[18:21], v[190:193], v[228:231], v[18:21]
	v_mfma_f32_16x16x32_bf16 v[10:13], v[190:193], v[236:239], v[10:13]
	v_mfma_f32_16x16x32_bf16 v[2:5], v[190:193], v[244:247], v[2:5]
	s_barrier
	s_setprio 0
	v_add_u32_e32 v141, 0x18000, v139
	ds_read_b128 v[142:145], v141
	ds_read_b128 v[154:157], v141 offset:1024
	ds_read_b128 v[170:173], v141 offset:2048
	ds_read_b128 v[174:177], v141 offset:3072
	v_add_u32_e32 v141, 0x1c000, v139
	ds_read_b128 v[178:181], v141
	ds_read_b128 v[182:185], v141 offset:1024
	ds_read_b128 v[186:189], v141 offset:2048
	ds_read_b128 v[190:193], v141 offset:3072
	s_add_i32 s52, s52, 0x80000
	s_mov_b32 m0, s31
	ds_read_b128 v[194:197], v140 offset:32768
	ds_read_b128 v[198:201], v140 offset:33792
	ds_read_b128 v[202:205], v140 offset:34816
	ds_read_b128 v[228:231], v140 offset:35840
	ds_read_b128 v[232:235], v140 offset:36864
	ds_read_b128 v[236:239], v140 offset:37888
	ds_read_b128 v[240:243], v140 offset:38912
	ds_read_b128 v[244:247], v140 offset:39936
	buffer_load_dwordx4 v131, s[60:63], s52 offen lds
	s_mov_b32 m0, s33
	s_nop 0
	buffer_load_dwordx4 v135, s[60:63], s52 offen lds
	s_waitcnt vmcnt(8)
	s_waitcnt lgkmcnt(0)
	s_setprio 1
	s_barrier
	v_mfma_f32_16x16x32_bf16 v[126:129], v[142:145], v[194:197], v[126:129]
	v_mfma_f32_16x16x32_bf16 v[118:121], v[142:145], v[202:205], v[118:121]
	v_mfma_f32_16x16x32_bf16 v[110:113], v[142:145], v[232:235], v[110:113]
	v_mfma_f32_16x16x32_bf16 v[102:105], v[142:145], v[240:243], v[102:105]
	v_mfma_f32_16x16x32_bf16 v[122:125], v[170:173], v[194:197], v[122:125]
	v_mfma_f32_16x16x32_bf16 v[114:117], v[170:173], v[202:205], v[114:117]
	v_mfma_f32_16x16x32_bf16 v[106:109], v[170:173], v[232:235], v[106:109]
	v_mfma_f32_16x16x32_bf16 v[98:101], v[170:173], v[240:243], v[98:101]
	v_mfma_f32_16x16x32_bf16 v[126:129], v[154:157], v[198:201], v[126:129]
	v_mfma_f32_16x16x32_bf16 v[118:121], v[154:157], v[228:231], v[118:121]
	v_mfma_f32_16x16x32_bf16 v[110:113], v[154:157], v[236:239], v[110:113]
	v_mfma_f32_16x16x32_bf16 v[102:105], v[154:157], v[244:247], v[102:105]
	v_mfma_f32_16x16x32_bf16 v[122:125], v[174:177], v[198:201], v[122:125]
	v_mfma_f32_16x16x32_bf16 v[114:117], v[174:177], v[228:231], v[114:117]
	v_mfma_f32_16x16x32_bf16 v[106:109], v[174:177], v[236:239], v[106:109]
	v_mfma_f32_16x16x32_bf16 v[98:101], v[174:177], v[244:247], v[98:101]
	v_mfma_f32_16x16x32_bf16 v[62:65], v[178:181], v[194:197], v[62:65]
	v_mfma_f32_16x16x32_bf16 v[54:57], v[178:181], v[202:205], v[54:57]
	v_mfma_f32_16x16x32_bf16 v[46:49], v[178:181], v[232:235], v[46:49]
	v_mfma_f32_16x16x32_bf16 v[38:41], v[178:181], v[240:243], v[38:41]
	v_mfma_f32_16x16x32_bf16 v[58:61], v[186:189], v[194:197], v[58:61]
	v_mfma_f32_16x16x32_bf16 v[50:53], v[186:189], v[202:205], v[50:53]
	v_mfma_f32_16x16x32_bf16 v[42:45], v[186:189], v[232:235], v[42:45]
	v_mfma_f32_16x16x32_bf16 v[34:37], v[186:189], v[240:243], v[34:37]
	v_mfma_f32_16x16x32_bf16 v[62:65], v[182:185], v[198:201], v[62:65]
	v_mfma_f32_16x16x32_bf16 v[54:57], v[182:185], v[228:231], v[54:57]
	v_mfma_f32_16x16x32_bf16 v[46:49], v[182:185], v[236:239], v[46:49]
	v_mfma_f32_16x16x32_bf16 v[38:41], v[182:185], v[244:247], v[38:41]
	v_mfma_f32_16x16x32_bf16 v[58:61], v[190:193], v[198:201], v[58:61]
	v_mfma_f32_16x16x32_bf16 v[50:53], v[190:193], v[228:231], v[50:53]
	v_mfma_f32_16x16x32_bf16 v[42:45], v[190:193], v[236:239], v[42:45]
	v_mfma_f32_16x16x32_bf16 v[34:37], v[190:193], v[244:247], v[34:37]
	s_barrier
	s_setprio 0
	s_mov_b32 m0, s34
	s_or_b32 s52, s85, 0x80
	ds_read_b128 v[194:197], v140 offset:49152
	ds_read_b128 v[198:201], v140 offset:50176
	ds_read_b128 v[202:205], v140 offset:51200
	ds_read_b128 v[228:231], v140 offset:52224
	ds_read_b128 v[232:235], v140 offset:53248
	ds_read_b128 v[236:239], v140 offset:54272
	ds_read_b128 v[240:243], v140 offset:55296
	ds_read_b128 v[244:247], v140 offset:56320
	buffer_load_dwordx4 v134, s[68:71], s52 offen lds
	s_mov_b32 m0, s35
	s_add_i32 s85, s85, 0x80080
	buffer_load_dwordx4 v136, s[68:71], s52 offen lds
	s_mov_b32 m0, s37
	s_nop 0
	buffer_load_dwordx4 v134, s[68:71], s85 offen lds
	s_mov_b32 m0, s65
	s_nop 0
	buffer_load_dwordx4 v136, s[68:71], s85 offen lds
	s_mov_b32 m0, s14
	s_nop 0
	buffer_load_dwordx4 v131, s[60:63], s84 offen lds
	s_mov_b32 m0, s36
	s_nop 0
	buffer_load_dwordx4 v135, s[60:63], s84 offen lds
	s_waitcnt vmcnt(8)
	s_waitcnt lgkmcnt(0)
	s_setprio 1
	s_barrier
	v_mfma_f32_16x16x32_bf16 v[94:97], v[142:145], v[194:197], v[94:97]
	v_mfma_f32_16x16x32_bf16 v[86:89], v[142:145], v[202:205], v[86:89]
	v_mfma_f32_16x16x32_bf16 v[78:81], v[142:145], v[232:235], v[78:81]
	v_mfma_f32_16x16x32_bf16 v[70:73], v[142:145], v[240:243], v[70:73]
	v_mfma_f32_16x16x32_bf16 v[90:93], v[170:173], v[194:197], v[90:93]
	v_mfma_f32_16x16x32_bf16 v[82:85], v[170:173], v[202:205], v[82:85]
	v_mfma_f32_16x16x32_bf16 v[74:77], v[170:173], v[232:235], v[74:77]
	v_mfma_f32_16x16x32_bf16 v[66:69], v[170:173], v[240:243], v[66:69]
	v_mfma_f32_16x16x32_bf16 v[94:97], v[154:157], v[198:201], v[94:97]
	v_mfma_f32_16x16x32_bf16 v[86:89], v[154:157], v[228:231], v[86:89]
	v_mfma_f32_16x16x32_bf16 v[78:81], v[154:157], v[236:239], v[78:81]
	v_mfma_f32_16x16x32_bf16 v[70:73], v[154:157], v[244:247], v[70:73]
	v_mfma_f32_16x16x32_bf16 v[90:93], v[174:177], v[198:201], v[90:93]
	v_mfma_f32_16x16x32_bf16 v[82:85], v[174:177], v[228:231], v[82:85]
	v_mfma_f32_16x16x32_bf16 v[74:77], v[174:177], v[236:239], v[74:77]
	v_mfma_f32_16x16x32_bf16 v[66:69], v[174:177], v[244:247], v[66:69]
	v_mfma_f32_16x16x32_bf16 v[30:33], v[178:181], v[194:197], v[30:33]
	v_mfma_f32_16x16x32_bf16 v[22:25], v[178:181], v[202:205], v[22:25]
	v_mfma_f32_16x16x32_bf16 v[14:17], v[178:181], v[232:235], v[14:17]
	v_mfma_f32_16x16x32_bf16 v[6:9], v[178:181], v[240:243], v[6:9]
	v_mfma_f32_16x16x32_bf16 v[26:29], v[186:189], v[194:197], v[26:29]
	v_mfma_f32_16x16x32_bf16 v[18:21], v[186:189], v[202:205], v[18:21]
	v_mfma_f32_16x16x32_bf16 v[10:13], v[186:189], v[232:235], v[10:13]
	v_mfma_f32_16x16x32_bf16 v[2:5], v[186:189], v[240:243], v[2:5]
	v_mfma_f32_16x16x32_bf16 v[30:33], v[182:185], v[198:201], v[30:33]
	v_mfma_f32_16x16x32_bf16 v[22:25], v[182:185], v[228:231], v[22:25]
	v_mfma_f32_16x16x32_bf16 v[14:17], v[182:185], v[236:239], v[14:17]
	v_mfma_f32_16x16x32_bf16 v[6:9], v[182:185], v[244:247], v[6:9]
	v_mfma_f32_16x16x32_bf16 v[26:29], v[190:193], v[198:201], v[26:29]
	v_mfma_f32_16x16x32_bf16 v[18:21], v[190:193], v[228:231], v[18:21]
	v_mfma_f32_16x16x32_bf16 v[10:13], v[190:193], v[236:239], v[10:13]
	v_mfma_f32_16x16x32_bf16 v[2:5], v[190:193], v[244:247], v[2:5]
	s_barrier
	s_setprio 0
	s_add_i32 s83, s83, 2
	s_addk_i32 s26, 0x100
	s_addk_i32 s27, 0x100
	s_cmp_gt_u32 s83, 29
.LBB0_1253:
	v_add_u32_e32 v141, 0x10000, v139
	ds_read_b128 v[142:145], v141
	ds_read_b128 v[154:157], v141 offset:1024
	ds_read_b128 v[170:173], v141 offset:2048
	ds_read_b128 v[174:177], v141 offset:3072
	v_add_u32_e32 v141, 0x14000, v139
	ds_read_b128 v[178:181], v141
	ds_read_b128 v[182:185], v141 offset:1024
	ds_read_b128 v[186:189], v141 offset:2048
	ds_read_b128 v[190:193], v141 offset:3072
	s_add_i32 s52, s26, 0xfff80080
	s_cmp_eq_u32 s83, 28
	s_cselect_b32 s52, s8, s52
	s_cselect_b32 s85, s9, s27
	s_or_b32 s84, s52, 0x80
	s_mov_b32 m0, s72
	ds_read_b128 v[194:197], v140
	ds_read_b128 v[198:201], v140 offset:1024
	ds_read_b128 v[202:205], v140 offset:2048
	ds_read_b128 v[228:231], v140 offset:3072
	ds_read_b128 v[232:235], v140 offset:4096
	ds_read_b128 v[236:239], v140 offset:5120
	ds_read_b128 v[240:243], v140 offset:6144
	ds_read_b128 v[244:247], v140 offset:7168
	buffer_load_dwordx4 v131, s[60:63], s26 offen lds
	s_mov_b32 m0, s46
	s_nop 0
	buffer_load_dwordx4 v135, s[60:63], s26 offen lds
	s_waitcnt vmcnt(8)
	s_waitcnt lgkmcnt(0)
	s_setprio 1
	s_barrier
	v_mfma_f32_16x16x32_bf16 v[126:129], v[142:145], v[194:197], v[126:129]
	v_mfma_f32_16x16x32_bf16 v[118:121], v[142:145], v[202:205], v[118:121]
	v_mfma_f32_16x16x32_bf16 v[110:113], v[142:145], v[232:235], v[110:113]
	v_mfma_f32_16x16x32_bf16 v[102:105], v[142:145], v[240:243], v[102:105]
	v_mfma_f32_16x16x32_bf16 v[122:125], v[170:173], v[194:197], v[122:125]
	v_mfma_f32_16x16x32_bf16 v[114:117], v[170:173], v[202:205], v[114:117]
	v_mfma_f32_16x16x32_bf16 v[106:109], v[170:173], v[232:235], v[106:109]
	v_mfma_f32_16x16x32_bf16 v[98:101], v[170:173], v[240:243], v[98:101]
	v_mfma_f32_16x16x32_bf16 v[126:129], v[154:157], v[198:201], v[126:129]
	v_mfma_f32_16x16x32_bf16 v[118:121], v[154:157], v[228:231], v[118:121]
	v_mfma_f32_16x16x32_bf16 v[110:113], v[154:157], v[236:239], v[110:113]
	v_mfma_f32_16x16x32_bf16 v[102:105], v[154:157], v[244:247], v[102:105]
	v_mfma_f32_16x16x32_bf16 v[122:125], v[174:177], v[198:201], v[122:125]
	v_mfma_f32_16x16x32_bf16 v[114:117], v[174:177], v[228:231], v[114:117]
	v_mfma_f32_16x16x32_bf16 v[106:109], v[174:177], v[236:239], v[106:109]
	v_mfma_f32_16x16x32_bf16 v[98:101], v[174:177], v[244:247], v[98:101]
	v_mfma_f32_16x16x32_bf16 v[62:65], v[178:181], v[194:197], v[62:65]
	v_mfma_f32_16x16x32_bf16 v[54:57], v[178:181], v[202:205], v[54:57]
	v_mfma_f32_16x16x32_bf16 v[46:49], v[178:181], v[232:235], v[46:49]
	v_mfma_f32_16x16x32_bf16 v[38:41], v[178:181], v[240:243], v[38:41]
	v_mfma_f32_16x16x32_bf16 v[58:61], v[186:189], v[194:197], v[58:61]
	v_mfma_f32_16x16x32_bf16 v[50:53], v[186:189], v[202:205], v[50:53]
	v_mfma_f32_16x16x32_bf16 v[42:45], v[186:189], v[232:235], v[42:45]
	v_mfma_f32_16x16x32_bf16 v[34:37], v[186:189], v[240:243], v[34:37]
	v_mfma_f32_16x16x32_bf16 v[62:65], v[182:185], v[198:201], v[62:65]
	v_mfma_f32_16x16x32_bf16 v[54:57], v[182:185], v[228:231], v[54:57]
	v_mfma_f32_16x16x32_bf16 v[46:49], v[182:185], v[236:239], v[46:49]
	v_mfma_f32_16x16x32_bf16 v[38:41], v[182:185], v[244:247], v[38:41]
	v_mfma_f32_16x16x32_bf16 v[58:61], v[190:193], v[198:201], v[58:61]
	v_mfma_f32_16x16x32_bf16 v[50:53], v[190:193], v[228:231], v[50:53]
	v_mfma_f32_16x16x32_bf16 v[42:45], v[190:193], v[236:239], v[42:45]
	v_mfma_f32_16x16x32_bf16 v[34:37], v[190:193], v[244:247], v[34:37]
	s_barrier
	s_setprio 0
	s_mov_b32 m0, s21
	s_mov_b32 s70, s62
	s_mov_b32 s71, s63
	ds_read_b128 v[194:197], v140 offset:16384
	ds_read_b128 v[198:201], v140 offset:17408
	ds_read_b128 v[202:205], v140 offset:18432
	ds_read_b128 v[228:231], v140 offset:19456
	ds_read_b128 v[232:235], v140 offset:20480
	ds_read_b128 v[236:239], v140 offset:21504
	ds_read_b128 v[240:243], v140 offset:22528
	ds_read_b128 v[244:247], v140 offset:23552
	buffer_load_dwordx4 v134, s[68:71], s85 offen lds
	s_mov_b32 m0, s23
	s_add_i32 s53, s85, 0x80000
	buffer_load_dwordx4 v136, s[68:71], s85 offen lds
	s_mov_b32 m0, s24
	s_nop 0
	buffer_load_dwordx4 v134, s[68:71], s53 offen lds
	s_mov_b32 m0, s25
	s_nop 0
	buffer_load_dwordx4 v136, s[68:71], s53 offen lds
	s_mov_b32 m0, s16
	s_nop 0
	buffer_load_dwordx4 v131, s[60:63], s52 offen lds
	s_mov_b32 m0, s30
	s_nop 0
	buffer_load_dwordx4 v135, s[60:63], s52 offen lds
	s_waitcnt vmcnt(8)
	s_waitcnt lgkmcnt(0)
	s_setprio 1
	s_barrier
	v_mfma_f32_16x16x32_bf16 v[94:97], v[142:145], v[194:197], v[94:97]
	v_mfma_f32_16x16x32_bf16 v[86:89], v[142:145], v[202:205], v[86:89]
	v_mfma_f32_16x16x32_bf16 v[78:81], v[142:145], v[232:235], v[78:81]
	v_mfma_f32_16x16x32_bf16 v[70:73], v[142:145], v[240:243], v[70:73]
	v_mfma_f32_16x16x32_bf16 v[90:93], v[170:173], v[194:197], v[90:93]
	v_mfma_f32_16x16x32_bf16 v[82:85], v[170:173], v[202:205], v[82:85]
	v_mfma_f32_16x16x32_bf16 v[74:77], v[170:173], v[232:235], v[74:77]
	v_mfma_f32_16x16x32_bf16 v[66:69], v[170:173], v[240:243], v[66:69]
	v_mfma_f32_16x16x32_bf16 v[94:97], v[154:157], v[198:201], v[94:97]
	v_mfma_f32_16x16x32_bf16 v[86:89], v[154:157], v[228:231], v[86:89]
	v_mfma_f32_16x16x32_bf16 v[78:81], v[154:157], v[236:239], v[78:81]
	v_mfma_f32_16x16x32_bf16 v[70:73], v[154:157], v[244:247], v[70:73]
	v_mfma_f32_16x16x32_bf16 v[90:93], v[174:177], v[198:201], v[90:93]
	v_mfma_f32_16x16x32_bf16 v[82:85], v[174:177], v[228:231], v[82:85]
	v_mfma_f32_16x16x32_bf16 v[74:77], v[174:177], v[236:239], v[74:77]
	v_mfma_f32_16x16x32_bf16 v[66:69], v[174:177], v[244:247], v[66:69]
	v_mfma_f32_16x16x32_bf16 v[30:33], v[178:181], v[194:197], v[30:33]
	v_mfma_f32_16x16x32_bf16 v[22:25], v[178:181], v[202:205], v[22:25]
	v_mfma_f32_16x16x32_bf16 v[14:17], v[178:181], v[232:235], v[14:17]
	v_mfma_f32_16x16x32_bf16 v[6:9], v[178:181], v[240:243], v[6:9]
	v_mfma_f32_16x16x32_bf16 v[26:29], v[186:189], v[194:197], v[26:29]
	v_mfma_f32_16x16x32_bf16 v[18:21], v[186:189], v[202:205], v[18:21]
	v_mfma_f32_16x16x32_bf16 v[10:13], v[186:189], v[232:235], v[10:13]
	v_mfma_f32_16x16x32_bf16 v[2:5], v[186:189], v[240:243], v[2:5]
	v_mfma_f32_16x16x32_bf16 v[30:33], v[182:185], v[198:201], v[30:33]
	v_mfma_f32_16x16x32_bf16 v[22:25], v[182:185], v[228:231], v[22:25]
	v_mfma_f32_16x16x32_bf16 v[14:17], v[182:185], v[236:239], v[14:17]
	v_mfma_f32_16x16x32_bf16 v[6:9], v[182:185], v[244:247], v[6:9]
	v_mfma_f32_16x16x32_bf16 v[26:29], v[190:193], v[198:201], v[26:29]
	v_mfma_f32_16x16x32_bf16 v[18:21], v[190:193], v[228:231], v[18:21]
	v_mfma_f32_16x16x32_bf16 v[10:13], v[190:193], v[236:239], v[10:13]
	v_mfma_f32_16x16x32_bf16 v[2:5], v[190:193], v[244:247], v[2:5]
	s_barrier
	s_setprio 0
	v_add_u32_e32 v141, 0x18000, v139
	ds_read_b128 v[142:145], v141
	ds_read_b128 v[154:157], v141 offset:1024
	ds_read_b128 v[170:173], v141 offset:2048
	ds_read_b128 v[174:177], v141 offset:3072
	v_add_u32_e32 v141, 0x1c000, v139
	ds_read_b128 v[178:181], v141
	ds_read_b128 v[182:185], v141 offset:1024
	ds_read_b128 v[186:189], v141 offset:2048
	ds_read_b128 v[190:193], v141 offset:3072
	s_add_i32 s52, s52, 0x80000
	s_mov_b32 m0, s31
	ds_read_b128 v[194:197], v140 offset:32768
	ds_read_b128 v[198:201], v140 offset:33792
	ds_read_b128 v[202:205], v140 offset:34816
	ds_read_b128 v[228:231], v140 offset:35840
	ds_read_b128 v[232:235], v140 offset:36864
	ds_read_b128 v[236:239], v140 offset:37888
	ds_read_b128 v[240:243], v140 offset:38912
	ds_read_b128 v[244:247], v140 offset:39936
	buffer_load_dwordx4 v131, s[60:63], s52 offen lds
	s_mov_b32 m0, s33
	s_nop 0
	buffer_load_dwordx4 v135, s[60:63], s52 offen lds
	s_waitcnt vmcnt(8)
	s_waitcnt lgkmcnt(0)
	s_setprio 1
	s_barrier
	v_mfma_f32_16x16x32_bf16 v[126:129], v[142:145], v[194:197], v[126:129]
	v_mfma_f32_16x16x32_bf16 v[118:121], v[142:145], v[202:205], v[118:121]
	v_mfma_f32_16x16x32_bf16 v[110:113], v[142:145], v[232:235], v[110:113]
	v_mfma_f32_16x16x32_bf16 v[102:105], v[142:145], v[240:243], v[102:105]
	v_mfma_f32_16x16x32_bf16 v[122:125], v[170:173], v[194:197], v[122:125]
	v_mfma_f32_16x16x32_bf16 v[114:117], v[170:173], v[202:205], v[114:117]
	v_mfma_f32_16x16x32_bf16 v[106:109], v[170:173], v[232:235], v[106:109]
	v_mfma_f32_16x16x32_bf16 v[98:101], v[170:173], v[240:243], v[98:101]
	v_mfma_f32_16x16x32_bf16 v[126:129], v[154:157], v[198:201], v[126:129]
	v_mfma_f32_16x16x32_bf16 v[118:121], v[154:157], v[228:231], v[118:121]
	v_mfma_f32_16x16x32_bf16 v[110:113], v[154:157], v[236:239], v[110:113]
	v_mfma_f32_16x16x32_bf16 v[102:105], v[154:157], v[244:247], v[102:105]
	v_mfma_f32_16x16x32_bf16 v[122:125], v[174:177], v[198:201], v[122:125]
	v_mfma_f32_16x16x32_bf16 v[114:117], v[174:177], v[228:231], v[114:117]
	v_mfma_f32_16x16x32_bf16 v[106:109], v[174:177], v[236:239], v[106:109]
	v_mfma_f32_16x16x32_bf16 v[98:101], v[174:177], v[244:247], v[98:101]
	v_mfma_f32_16x16x32_bf16 v[62:65], v[178:181], v[194:197], v[62:65]
	v_mfma_f32_16x16x32_bf16 v[54:57], v[178:181], v[202:205], v[54:57]
	v_mfma_f32_16x16x32_bf16 v[46:49], v[178:181], v[232:235], v[46:49]
	v_mfma_f32_16x16x32_bf16 v[38:41], v[178:181], v[240:243], v[38:41]
	v_mfma_f32_16x16x32_bf16 v[58:61], v[186:189], v[194:197], v[58:61]
	v_mfma_f32_16x16x32_bf16 v[50:53], v[186:189], v[202:205], v[50:53]
	v_mfma_f32_16x16x32_bf16 v[42:45], v[186:189], v[232:235], v[42:45]
	v_mfma_f32_16x16x32_bf16 v[34:37], v[186:189], v[240:243], v[34:37]
	v_mfma_f32_16x16x32_bf16 v[62:65], v[182:185], v[198:201], v[62:65]
	v_mfma_f32_16x16x32_bf16 v[54:57], v[182:185], v[228:231], v[54:57]
	v_mfma_f32_16x16x32_bf16 v[46:49], v[182:185], v[236:239], v[46:49]
	v_mfma_f32_16x16x32_bf16 v[38:41], v[182:185], v[244:247], v[38:41]
	v_mfma_f32_16x16x32_bf16 v[58:61], v[190:193], v[198:201], v[58:61]
	v_mfma_f32_16x16x32_bf16 v[50:53], v[190:193], v[228:231], v[50:53]
	v_mfma_f32_16x16x32_bf16 v[42:45], v[190:193], v[236:239], v[42:45]
	v_mfma_f32_16x16x32_bf16 v[34:37], v[190:193], v[244:247], v[34:37]
	s_barrier
	s_setprio 0
	s_mov_b32 m0, s34
	s_or_b32 s52, s85, 0x80
	ds_read_b128 v[194:197], v140 offset:49152
	ds_read_b128 v[198:201], v140 offset:50176
	ds_read_b128 v[202:205], v140 offset:51200
	ds_read_b128 v[228:231], v140 offset:52224
	ds_read_b128 v[232:235], v140 offset:53248
	ds_read_b128 v[236:239], v140 offset:54272
	ds_read_b128 v[240:243], v140 offset:55296
	ds_read_b128 v[244:247], v140 offset:56320
	buffer_load_dwordx4 v134, s[68:71], s52 offen lds
	s_mov_b32 m0, s35
	s_add_i32 s85, s85, 0x80080
	buffer_load_dwordx4 v136, s[68:71], s52 offen lds
	s_mov_b32 m0, s37
	s_nop 0
	buffer_load_dwordx4 v134, s[68:71], s85 offen lds
	s_mov_b32 m0, s65
	s_nop 0
	buffer_load_dwordx4 v136, s[68:71], s85 offen lds
	s_mov_b32 m0, s14
	s_nop 0
	buffer_load_dwordx4 v131, s[60:63], s84 offen lds
	s_mov_b32 m0, s36
	s_nop 0
	buffer_load_dwordx4 v135, s[60:63], s84 offen lds
	s_waitcnt vmcnt(8)
	s_waitcnt lgkmcnt(0)
	s_setprio 1
	s_barrier
	v_mfma_f32_16x16x32_bf16 v[94:97], v[142:145], v[194:197], v[94:97]
	v_mfma_f32_16x16x32_bf16 v[86:89], v[142:145], v[202:205], v[86:89]
	v_mfma_f32_16x16x32_bf16 v[78:81], v[142:145], v[232:235], v[78:81]
	v_mfma_f32_16x16x32_bf16 v[70:73], v[142:145], v[240:243], v[70:73]
	v_mfma_f32_16x16x32_bf16 v[90:93], v[170:173], v[194:197], v[90:93]
	v_mfma_f32_16x16x32_bf16 v[82:85], v[170:173], v[202:205], v[82:85]
	v_mfma_f32_16x16x32_bf16 v[74:77], v[170:173], v[232:235], v[74:77]
	v_mfma_f32_16x16x32_bf16 v[66:69], v[170:173], v[240:243], v[66:69]
	v_mfma_f32_16x16x32_bf16 v[94:97], v[154:157], v[198:201], v[94:97]
	v_mfma_f32_16x16x32_bf16 v[86:89], v[154:157], v[228:231], v[86:89]
	v_mfma_f32_16x16x32_bf16 v[78:81], v[154:157], v[236:239], v[78:81]
	v_mfma_f32_16x16x32_bf16 v[70:73], v[154:157], v[244:247], v[70:73]
	v_mfma_f32_16x16x32_bf16 v[90:93], v[174:177], v[198:201], v[90:93]
	v_mfma_f32_16x16x32_bf16 v[82:85], v[174:177], v[228:231], v[82:85]
	v_mfma_f32_16x16x32_bf16 v[74:77], v[174:177], v[236:239], v[74:77]
	v_mfma_f32_16x16x32_bf16 v[66:69], v[174:177], v[244:247], v[66:69]
	v_mfma_f32_16x16x32_bf16 v[30:33], v[178:181], v[194:197], v[30:33]
	v_mfma_f32_16x16x32_bf16 v[22:25], v[178:181], v[202:205], v[22:25]
	v_mfma_f32_16x16x32_bf16 v[14:17], v[178:181], v[232:235], v[14:17]
	v_mfma_f32_16x16x32_bf16 v[6:9], v[178:181], v[240:243], v[6:9]
	v_mfma_f32_16x16x32_bf16 v[26:29], v[186:189], v[194:197], v[26:29]
	v_mfma_f32_16x16x32_bf16 v[18:21], v[186:189], v[202:205], v[18:21]
	v_mfma_f32_16x16x32_bf16 v[10:13], v[186:189], v[232:235], v[10:13]
	v_mfma_f32_16x16x32_bf16 v[2:5], v[186:189], v[240:243], v[2:5]
	v_mfma_f32_16x16x32_bf16 v[30:33], v[182:185], v[198:201], v[30:33]
	v_mfma_f32_16x16x32_bf16 v[22:25], v[182:185], v[228:231], v[22:25]
	v_mfma_f32_16x16x32_bf16 v[14:17], v[182:185], v[236:239], v[14:17]
	v_mfma_f32_16x16x32_bf16 v[6:9], v[182:185], v[244:247], v[6:9]
	v_mfma_f32_16x16x32_bf16 v[26:29], v[190:193], v[198:201], v[26:29]
	v_mfma_f32_16x16x32_bf16 v[18:21], v[190:193], v[228:231], v[18:21]
	v_mfma_f32_16x16x32_bf16 v[10:13], v[190:193], v[236:239], v[10:13]
	v_mfma_f32_16x16x32_bf16 v[2:5], v[190:193], v[244:247], v[2:5]
	s_barrier
	s_setprio 0
	s_add_i32 s83, s83, 2
	s_addk_i32 s26, 0x100
	s_addk_i32 s27, 0x100
	s_cmp_gt_u32 s83, 29
	s_cbranch_scc0 .LBB0_1253
	s_and_b64 vcc, exec, s[44:45]
	s_cbranch_vccz .LBB0_1256
	s_barrier

.LBB0_1282:
	s_lshl_b32 s46, s85, 20
	s_and_b64 s[8:9], s[40:41], exec
	s_cselect_b32 s8, s46, s19
	s_lshl_b32 s47, s14, 20
	s_and_b64 s[26:27], s[40:41], exec
	s_cselect_b32 s9, s47, s22
	s_add_i32 s19, s19, 0x80080
	s_addk_i32 s22, 0x100
	s_mov_b32 s26, -2
	v_add_u32_e32 v141, 0x10000, v139
	ds_read_b128 v[142:145], v141
	ds_read_b128 v[154:157], v141 offset:1024
	ds_read_b128 v[170:173], v141 offset:2048
	ds_read_b128 v[174:177], v141 offset:3072
	v_add_u32_e32 v141, 0x14000, v139
	ds_read_b128 v[178:181], v141
	ds_read_b128 v[182:185], v141 offset:1024
	ds_read_b128 v[186:189], v141 offset:2048
	ds_read_b128 v[190:193], v141 offset:3072
	s_add_i32 s27, s19, 0xfff80080
	s_cmp_eq_u32 s26, 28
	s_cselect_b32 s52, s8, s27
	s_cselect_b32 s83, s9, s22
	s_or_b32 s27, s52, 0x80
	s_mov_b32 m0, s73
	ds_read_b128 v[194:197], v140
	ds_read_b128 v[198:201], v140 offset:1024
	ds_read_b128 v[202:205], v140 offset:2048
	ds_read_b128 v[228:231], v140 offset:3072
	ds_read_b128 v[232:235], v140 offset:4096
	ds_read_b128 v[236:239], v140 offset:5120
	ds_read_b128 v[240:243], v140 offset:6144
	ds_read_b128 v[244:247], v140 offset:7168
	buffer_load_dwordx4 v131, s[60:63], s19 offen lds
	s_mov_b32 m0, s82
	s_nop 0
	buffer_load_dwordx4 v135, s[60:63], s19 offen lds
	s_waitcnt vmcnt(8)
	s_waitcnt lgkmcnt(0)
	s_setprio 1
	s_barrier
	v_mfma_f32_16x16x32_bf16 v[126:129], v[142:145], v[194:197], 0
	v_mfma_f32_16x16x32_bf16 v[118:121], v[142:145], v[202:205], 0
	v_mfma_f32_16x16x32_bf16 v[110:113], v[142:145], v[232:235], 0
	v_mfma_f32_16x16x32_bf16 v[102:105], v[142:145], v[240:243], 0
	v_mfma_f32_16x16x32_bf16 v[122:125], v[170:173], v[194:197], 0
	v_mfma_f32_16x16x32_bf16 v[114:117], v[170:173], v[202:205], 0
	v_mfma_f32_16x16x32_bf16 v[106:109], v[170:173], v[232:235], 0
	v_mfma_f32_16x16x32_bf16 v[98:101], v[170:173], v[240:243], 0
	v_mfma_f32_16x16x32_bf16 v[126:129], v[154:157], v[198:201], v[126:129]
	v_mfma_f32_16x16x32_bf16 v[118:121], v[154:157], v[228:231], v[118:121]
	v_mfma_f32_16x16x32_bf16 v[110:113], v[154:157], v[236:239], v[110:113]
	v_mfma_f32_16x16x32_bf16 v[102:105], v[154:157], v[244:247], v[102:105]
	v_mfma_f32_16x16x32_bf16 v[122:125], v[174:177], v[198:201], v[122:125]
	v_mfma_f32_16x16x32_bf16 v[114:117], v[174:177], v[228:231], v[114:117]
	v_mfma_f32_16x16x32_bf16 v[106:109], v[174:177], v[236:239], v[106:109]
	v_mfma_f32_16x16x32_bf16 v[98:101], v[174:177], v[244:247], v[98:101]
	v_mfma_f32_16x16x32_bf16 v[62:65], v[178:181], v[194:197], 0
	v_mfma_f32_16x16x32_bf16 v[54:57], v[178:181], v[202:205], 0
	v_mfma_f32_16x16x32_bf16 v[46:49], v[178:181], v[232:235], 0
	v_mfma_f32_16x16x32_bf16 v[38:41], v[178:181], v[240:243], 0
	v_mfma_f32_16x16x32_bf16 v[58:61], v[186:189], v[194:197], 0
	v_mfma_f32_16x16x32_bf16 v[50:53], v[186:189], v[202:205], 0
	v_mfma_f32_16x16x32_bf16 v[42:45], v[186:189], v[232:235], 0
	v_mfma_f32_16x16x32_bf16 v[34:37], v[186:189], v[240:243], 0
	v_mfma_f32_16x16x32_bf16 v[62:65], v[182:185], v[198:201], v[62:65]
	v_mfma_f32_16x16x32_bf16 v[54:57], v[182:185], v[228:231], v[54:57]
	v_mfma_f32_16x16x32_bf16 v[46:49], v[182:185], v[236:239], v[46:49]
	v_mfma_f32_16x16x32_bf16 v[38:41], v[182:185], v[244:247], v[38:41]
	v_mfma_f32_16x16x32_bf16 v[58:61], v[190:193], v[198:201], v[58:61]
	v_mfma_f32_16x16x32_bf16 v[50:53], v[190:193], v[228:231], v[50:53]
	v_mfma_f32_16x16x32_bf16 v[42:45], v[190:193], v[236:239], v[42:45]
	v_mfma_f32_16x16x32_bf16 v[34:37], v[190:193], v[244:247], v[34:37]
	s_barrier
	s_setprio 0
	s_mov_b32 m0, s21
	s_mov_b32 s70, s62
	s_mov_b32 s71, s63
	ds_read_b128 v[194:197], v140 offset:16384
	ds_read_b128 v[198:201], v140 offset:17408
	ds_read_b128 v[202:205], v140 offset:18432
	ds_read_b128 v[228:231], v140 offset:19456
	ds_read_b128 v[232:235], v140 offset:20480
	ds_read_b128 v[236:239], v140 offset:21504
	ds_read_b128 v[240:243], v140 offset:22528
	ds_read_b128 v[244:247], v140 offset:23552
	buffer_load_dwordx4 v134, s[68:71], s83 offen lds
	s_mov_b32 m0, s23
	s_add_i32 s53, s83, 0x80000
	buffer_load_dwordx4 v136, s[68:71], s83 offen lds
	s_mov_b32 m0, s24
	s_nop 0
	buffer_load_dwordx4 v134, s[68:71], s53 offen lds
	s_mov_b32 m0, s25
	s_nop 0
	buffer_load_dwordx4 v136, s[68:71], s53 offen lds
	s_mov_b32 m0, s2
	s_nop 0
	buffer_load_dwordx4 v131, s[60:63], s52 offen lds
	s_mov_b32 m0, s30
	s_nop 0
	buffer_load_dwordx4 v135, s[60:63], s52 offen lds
	s_waitcnt vmcnt(8)
	s_waitcnt lgkmcnt(0)
	s_setprio 1
	s_barrier
	v_mfma_f32_16x16x32_bf16 v[94:97], v[142:145], v[194:197], 0
	v_mfma_f32_16x16x32_bf16 v[86:89], v[142:145], v[202:205], 0
	v_mfma_f32_16x16x32_bf16 v[78:81], v[142:145], v[232:235], 0
	v_mfma_f32_16x16x32_bf16 v[70:73], v[142:145], v[240:243], 0
	v_mfma_f32_16x16x32_bf16 v[90:93], v[170:173], v[194:197], 0
	v_mfma_f32_16x16x32_bf16 v[82:85], v[170:173], v[202:205], 0
	v_mfma_f32_16x16x32_bf16 v[74:77], v[170:173], v[232:235], 0
	v_mfma_f32_16x16x32_bf16 v[66:69], v[170:173], v[240:243], 0
	v_mfma_f32_16x16x32_bf16 v[94:97], v[154:157], v[198:201], v[94:97]
	v_mfma_f32_16x16x32_bf16 v[86:89], v[154:157], v[228:231], v[86:89]
	v_mfma_f32_16x16x32_bf16 v[78:81], v[154:157], v[236:239], v[78:81]
	v_mfma_f32_16x16x32_bf16 v[70:73], v[154:157], v[244:247], v[70:73]
	v_mfma_f32_16x16x32_bf16 v[90:93], v[174:177], v[198:201], v[90:93]
	v_mfma_f32_16x16x32_bf16 v[82:85], v[174:177], v[228:231], v[82:85]
	v_mfma_f32_16x16x32_bf16 v[74:77], v[174:177], v[236:239], v[74:77]
	v_mfma_f32_16x16x32_bf16 v[66:69], v[174:177], v[244:247], v[66:69]
	v_mfma_f32_16x16x32_bf16 v[30:33], v[178:181], v[194:197], 0
	v_mfma_f32_16x16x32_bf16 v[22:25], v[178:181], v[202:205], 0
	v_mfma_f32_16x16x32_bf16 v[14:17], v[178:181], v[232:235], 0
	v_mfma_f32_16x16x32_bf16 v[6:9], v[178:181], v[240:243], 0
	v_mfma_f32_16x16x32_bf16 v[26:29], v[186:189], v[194:197], 0
	v_mfma_f32_16x16x32_bf16 v[18:21], v[186:189], v[202:205], 0
	v_mfma_f32_16x16x32_bf16 v[10:13], v[186:189], v[232:235], 0
	v_mfma_f32_16x16x32_bf16 v[2:5], v[186:189], v[240:243], 0
	v_mfma_f32_16x16x32_bf16 v[30:33], v[182:185], v[198:201], v[30:33]
	v_mfma_f32_16x16x32_bf16 v[22:25], v[182:185], v[228:231], v[22:25]
	v_mfma_f32_16x16x32_bf16 v[14:17], v[182:185], v[236:239], v[14:17]
	v_mfma_f32_16x16x32_bf16 v[6:9], v[182:185], v[244:247], v[6:9]
	v_mfma_f32_16x16x32_bf16 v[26:29], v[190:193], v[198:201], v[26:29]
	v_mfma_f32_16x16x32_bf16 v[18:21], v[190:193], v[228:231], v[18:21]
	v_mfma_f32_16x16x32_bf16 v[10:13], v[190:193], v[236:239], v[10:13]
	v_mfma_f32_16x16x32_bf16 v[2:5], v[190:193], v[244:247], v[2:5]
	s_barrier
	s_setprio 0
	v_add_u32_e32 v141, 0x18000, v139
	ds_read_b128 v[142:145], v141
	ds_read_b128 v[154:157], v141 offset:1024
	ds_read_b128 v[170:173], v141 offset:2048
	ds_read_b128 v[174:177], v141 offset:3072
	v_add_u32_e32 v141, 0x1c000, v139
	ds_read_b128 v[178:181], v141
	ds_read_b128 v[182:185], v141 offset:1024
	ds_read_b128 v[186:189], v141 offset:2048
	ds_read_b128 v[190:193], v141 offset:3072
	s_add_i32 s52, s52, 0x80000
	s_mov_b32 m0, s31
	ds_read_b128 v[194:197], v140 offset:32768
	ds_read_b128 v[198:201], v140 offset:33792
	ds_read_b128 v[202:205], v140 offset:34816
	ds_read_b128 v[228:231], v140 offset:35840
	ds_read_b128 v[232:235], v140 offset:36864
	ds_read_b128 v[236:239], v140 offset:37888
	ds_read_b128 v[240:243], v140 offset:38912
	ds_read_b128 v[244:247], v140 offset:39936
	buffer_load_dwordx4 v131, s[60:63], s52 offen lds
	s_mov_b32 m0, s33
	s_nop 0
	buffer_load_dwordx4 v135, s[60:63], s52 offen lds
	s_waitcnt vmcnt(8)
	s_waitcnt lgkmcnt(0)
	s_setprio 1
	s_barrier
	v_mfma_f32_16x16x32_bf16 v[126:129], v[142:145], v[194:197], v[126:129]
	v_mfma_f32_16x16x32_bf16 v[118:121], v[142:145], v[202:205], v[118:121]
	v_mfma_f32_16x16x32_bf16 v[110:113], v[142:145], v[232:235], v[110:113]
	v_mfma_f32_16x16x32_bf16 v[102:105], v[142:145], v[240:243], v[102:105]
	v_mfma_f32_16x16x32_bf16 v[122:125], v[170:173], v[194:197], v[122:125]
	v_mfma_f32_16x16x32_bf16 v[114:117], v[170:173], v[202:205], v[114:117]
	v_mfma_f32_16x16x32_bf16 v[106:109], v[170:173], v[232:235], v[106:109]
	v_mfma_f32_16x16x32_bf16 v[98:101], v[170:173], v[240:243], v[98:101]
	v_mfma_f32_16x16x32_bf16 v[126:129], v[154:157], v[198:201], v[126:129]
	v_mfma_f32_16x16x32_bf16 v[118:121], v[154:157], v[228:231], v[118:121]
	v_mfma_f32_16x16x32_bf16 v[110:113], v[154:157], v[236:239], v[110:113]
	v_mfma_f32_16x16x32_bf16 v[102:105], v[154:157], v[244:247], v[102:105]
	v_mfma_f32_16x16x32_bf16 v[122:125], v[174:177], v[198:201], v[122:125]
	v_mfma_f32_16x16x32_bf16 v[114:117], v[174:177], v[228:231], v[114:117]
	v_mfma_f32_16x16x32_bf16 v[106:109], v[174:177], v[236:239], v[106:109]
	v_mfma_f32_16x16x32_bf16 v[98:101], v[174:177], v[244:247], v[98:101]
	v_mfma_f32_16x16x32_bf16 v[62:65], v[178:181], v[194:197], v[62:65]
	v_mfma_f32_16x16x32_bf16 v[54:57], v[178:181], v[202:205], v[54:57]
	v_mfma_f32_16x16x32_bf16 v[46:49], v[178:181], v[232:235], v[46:49]
	v_mfma_f32_16x16x32_bf16 v[38:41], v[178:181], v[240:243], v[38:41]
	v_mfma_f32_16x16x32_bf16 v[58:61], v[186:189], v[194:197], v[58:61]
	v_mfma_f32_16x16x32_bf16 v[50:53], v[186:189], v[202:205], v[50:53]
	v_mfma_f32_16x16x32_bf16 v[42:45], v[186:189], v[232:235], v[42:45]
	v_mfma_f32_16x16x32_bf16 v[34:37], v[186:189], v[240:243], v[34:37]
	v_mfma_f32_16x16x32_bf16 v[62:65], v[182:185], v[198:201], v[62:65]
	v_mfma_f32_16x16x32_bf16 v[54:57], v[182:185], v[228:231], v[54:57]
	v_mfma_f32_16x16x32_bf16 v[46:49], v[182:185], v[236:239], v[46:49]
	v_mfma_f32_16x16x32_bf16 v[38:41], v[182:185], v[244:247], v[38:41]
	v_mfma_f32_16x16x32_bf16 v[58:61], v[190:193], v[198:201], v[58:61]
	v_mfma_f32_16x16x32_bf16 v[50:53], v[190:193], v[228:231], v[50:53]
	v_mfma_f32_16x16x32_bf16 v[42:45], v[190:193], v[236:239], v[42:45]
	v_mfma_f32_16x16x32_bf16 v[34:37], v[190:193], v[244:247], v[34:37]
	s_barrier
	s_setprio 0
	s_mov_b32 m0, s34
	s_or_b32 s52, s83, 0x80
	ds_read_b128 v[194:197], v140 offset:49152
	ds_read_b128 v[198:201], v140 offset:50176
	ds_read_b128 v[202:205], v140 offset:51200
	ds_read_b128 v[228:231], v140 offset:52224
	ds_read_b128 v[232:235], v140 offset:53248
	ds_read_b128 v[236:239], v140 offset:54272
	ds_read_b128 v[240:243], v140 offset:55296
	ds_read_b128 v[244:247], v140 offset:56320
	buffer_load_dwordx4 v134, s[68:71], s52 offen lds
	s_mov_b32 m0, s35
	s_add_i32 s83, s83, 0x80080
	buffer_load_dwordx4 v136, s[68:71], s52 offen lds
	s_mov_b32 m0, s65
	s_nop 0
	buffer_load_dwordx4 v134, s[68:71], s83 offen lds
	s_mov_b32 m0, s66
	s_nop 0
	buffer_load_dwordx4 v136, s[68:71], s83 offen lds
	s_mov_b32 m0, s36
	s_nop 0
	buffer_load_dwordx4 v131, s[60:63], s27 offen lds
	s_mov_b32 m0, s37
	s_nop 0
	buffer_load_dwordx4 v135, s[60:63], s27 offen lds
	s_waitcnt vmcnt(8)
	s_waitcnt lgkmcnt(0)
	s_setprio 1
	s_barrier
	v_mfma_f32_16x16x32_bf16 v[94:97], v[142:145], v[194:197], v[94:97]
	v_mfma_f32_16x16x32_bf16 v[86:89], v[142:145], v[202:205], v[86:89]
	v_mfma_f32_16x16x32_bf16 v[78:81], v[142:145], v[232:235], v[78:81]
	v_mfma_f32_16x16x32_bf16 v[70:73], v[142:145], v[240:243], v[70:73]
	v_mfma_f32_16x16x32_bf16 v[90:93], v[170:173], v[194:197], v[90:93]
	v_mfma_f32_16x16x32_bf16 v[82:85], v[170:173], v[202:205], v[82:85]
	v_mfma_f32_16x16x32_bf16 v[74:77], v[170:173], v[232:235], v[74:77]
	v_mfma_f32_16x16x32_bf16 v[66:69], v[170:173], v[240:243], v[66:69]
	v_mfma_f32_16x16x32_bf16 v[94:97], v[154:157], v[198:201], v[94:97]
	v_mfma_f32_16x16x32_bf16 v[86:89], v[154:157], v[228:231], v[86:89]
	v_mfma_f32_16x16x32_bf16 v[78:81], v[154:157], v[236:239], v[78:81]
	v_mfma_f32_16x16x32_bf16 v[70:73], v[154:157], v[244:247], v[70:73]
	v_mfma_f32_16x16x32_bf16 v[90:93], v[174:177], v[198:201], v[90:93]
	v_mfma_f32_16x16x32_bf16 v[82:85], v[174:177], v[228:231], v[82:85]
	v_mfma_f32_16x16x32_bf16 v[74:77], v[174:177], v[236:239], v[74:77]
	v_mfma_f32_16x16x32_bf16 v[66:69], v[174:177], v[244:247], v[66:69]
	v_mfma_f32_16x16x32_bf16 v[30:33], v[178:181], v[194:197], v[30:33]
	v_mfma_f32_16x16x32_bf16 v[22:25], v[178:181], v[202:205], v[22:25]
	v_mfma_f32_16x16x32_bf16 v[14:17], v[178:181], v[232:235], v[14:17]
	v_mfma_f32_16x16x32_bf16 v[6:9], v[178:181], v[240:243], v[6:9]
	v_mfma_f32_16x16x32_bf16 v[26:29], v[186:189], v[194:197], v[26:29]
	v_mfma_f32_16x16x32_bf16 v[18:21], v[186:189], v[202:205], v[18:21]
	v_mfma_f32_16x16x32_bf16 v[10:13], v[186:189], v[232:235], v[10:13]
	v_mfma_f32_16x16x32_bf16 v[2:5], v[186:189], v[240:243], v[2:5]
	v_mfma_f32_16x16x32_bf16 v[30:33], v[182:185], v[198:201], v[30:33]
	v_mfma_f32_16x16x32_bf16 v[22:25], v[182:185], v[228:231], v[22:25]
	v_mfma_f32_16x16x32_bf16 v[14:17], v[182:185], v[236:239], v[14:17]
	v_mfma_f32_16x16x32_bf16 v[6:9], v[182:185], v[244:247], v[6:9]
	v_mfma_f32_16x16x32_bf16 v[26:29], v[190:193], v[198:201], v[26:29]
	v_mfma_f32_16x16x32_bf16 v[18:21], v[190:193], v[228:231], v[18:21]
	v_mfma_f32_16x16x32_bf16 v[10:13], v[190:193], v[236:239], v[10:13]
	v_mfma_f32_16x16x32_bf16 v[2:5], v[190:193], v[244:247], v[2:5]
	s_barrier
	s_setprio 0
	s_add_i32 s26, s26, 2
	s_addk_i32 s19, 0x100
	s_addk_i32 s22, 0x100
	s_cmp_gt_u32 s26, 29
.LBB0_1283:
	v_add_u32_e32 v141, 0x10000, v139
	ds_read_b128 v[142:145], v141
	ds_read_b128 v[154:157], v141 offset:1024
	ds_read_b128 v[170:173], v141 offset:2048
	ds_read_b128 v[174:177], v141 offset:3072
	v_add_u32_e32 v141, 0x14000, v139
	ds_read_b128 v[178:181], v141
	ds_read_b128 v[182:185], v141 offset:1024
	ds_read_b128 v[186:189], v141 offset:2048
	ds_read_b128 v[190:193], v141 offset:3072
	s_add_i32 s27, s19, 0xfff80080
	s_cmp_eq_u32 s26, 28
	s_cselect_b32 s52, s8, s27
	s_cselect_b32 s83, s9, s22
	s_or_b32 s27, s52, 0x80
	s_mov_b32 m0, s73
	ds_read_b128 v[194:197], v140
	ds_read_b128 v[198:201], v140 offset:1024
	ds_read_b128 v[202:205], v140 offset:2048
	ds_read_b128 v[228:231], v140 offset:3072
	ds_read_b128 v[232:235], v140 offset:4096
	ds_read_b128 v[236:239], v140 offset:5120
	ds_read_b128 v[240:243], v140 offset:6144
	ds_read_b128 v[244:247], v140 offset:7168
	buffer_load_dwordx4 v131, s[60:63], s19 offen lds
	s_mov_b32 m0, s82
	s_nop 0
	buffer_load_dwordx4 v135, s[60:63], s19 offen lds
	s_waitcnt vmcnt(8)
	s_waitcnt lgkmcnt(0)
	s_setprio 1
	s_barrier
	v_mfma_f32_16x16x32_bf16 v[126:129], v[142:145], v[194:197], v[126:129]
	v_mfma_f32_16x16x32_bf16 v[118:121], v[142:145], v[202:205], v[118:121]
	v_mfma_f32_16x16x32_bf16 v[110:113], v[142:145], v[232:235], v[110:113]
	v_mfma_f32_16x16x32_bf16 v[102:105], v[142:145], v[240:243], v[102:105]
	v_mfma_f32_16x16x32_bf16 v[122:125], v[170:173], v[194:197], v[122:125]
	v_mfma_f32_16x16x32_bf16 v[114:117], v[170:173], v[202:205], v[114:117]
	v_mfma_f32_16x16x32_bf16 v[106:109], v[170:173], v[232:235], v[106:109]
	v_mfma_f32_16x16x32_bf16 v[98:101], v[170:173], v[240:243], v[98:101]
	v_mfma_f32_16x16x32_bf16 v[126:129], v[154:157], v[198:201], v[126:129]
	v_mfma_f32_16x16x32_bf16 v[118:121], v[154:157], v[228:231], v[118:121]
	v_mfma_f32_16x16x32_bf16 v[110:113], v[154:157], v[236:239], v[110:113]
	v_mfma_f32_16x16x32_bf16 v[102:105], v[154:157], v[244:247], v[102:105]
	v_mfma_f32_16x16x32_bf16 v[122:125], v[174:177], v[198:201], v[122:125]
	v_mfma_f32_16x16x32_bf16 v[114:117], v[174:177], v[228:231], v[114:117]
	v_mfma_f32_16x16x32_bf16 v[106:109], v[174:177], v[236:239], v[106:109]
	v_mfma_f32_16x16x32_bf16 v[98:101], v[174:177], v[244:247], v[98:101]
	v_mfma_f32_16x16x32_bf16 v[62:65], v[178:181], v[194:197], v[62:65]
	v_mfma_f32_16x16x32_bf16 v[54:57], v[178:181], v[202:205], v[54:57]
	v_mfma_f32_16x16x32_bf16 v[46:49], v[178:181], v[232:235], v[46:49]
	v_mfma_f32_16x16x32_bf16 v[38:41], v[178:181], v[240:243], v[38:41]
	v_mfma_f32_16x16x32_bf16 v[58:61], v[186:189], v[194:197], v[58:61]
	v_mfma_f32_16x16x32_bf16 v[50:53], v[186:189], v[202:205], v[50:53]
	v_mfma_f32_16x16x32_bf16 v[42:45], v[186:189], v[232:235], v[42:45]
	v_mfma_f32_16x16x32_bf16 v[34:37], v[186:189], v[240:243], v[34:37]
	v_mfma_f32_16x16x32_bf16 v[62:65], v[182:185], v[198:201], v[62:65]
	v_mfma_f32_16x16x32_bf16 v[54:57], v[182:185], v[228:231], v[54:57]
	v_mfma_f32_16x16x32_bf16 v[46:49], v[182:185], v[236:239], v[46:49]
	v_mfma_f32_16x16x32_bf16 v[38:41], v[182:185], v[244:247], v[38:41]
	v_mfma_f32_16x16x32_bf16 v[58:61], v[190:193], v[198:201], v[58:61]
	v_mfma_f32_16x16x32_bf16 v[50:53], v[190:193], v[228:231], v[50:53]
	v_mfma_f32_16x16x32_bf16 v[42:45], v[190:193], v[236:239], v[42:45]
	v_mfma_f32_16x16x32_bf16 v[34:37], v[190:193], v[244:247], v[34:37]
	s_barrier
	s_setprio 0
	s_mov_b32 m0, s21
	s_mov_b32 s70, s62
	s_mov_b32 s71, s63
	ds_read_b128 v[194:197], v140 offset:16384
	ds_read_b128 v[198:201], v140 offset:17408
	ds_read_b128 v[202:205], v140 offset:18432
	ds_read_b128 v[228:231], v140 offset:19456
	ds_read_b128 v[232:235], v140 offset:20480
	ds_read_b128 v[236:239], v140 offset:21504
	ds_read_b128 v[240:243], v140 offset:22528
	ds_read_b128 v[244:247], v140 offset:23552
	buffer_load_dwordx4 v134, s[68:71], s83 offen lds
	s_mov_b32 m0, s23
	s_add_i32 s53, s83, 0x80000
	buffer_load_dwordx4 v136, s[68:71], s83 offen lds
	s_mov_b32 m0, s24
	s_nop 0
	buffer_load_dwordx4 v134, s[68:71], s53 offen lds
	s_mov_b32 m0, s25
	s_nop 0
	buffer_load_dwordx4 v136, s[68:71], s53 offen lds
	s_mov_b32 m0, s2
	s_nop 0
	buffer_load_dwordx4 v131, s[60:63], s52 offen lds
	s_mov_b32 m0, s30
	s_nop 0
	buffer_load_dwordx4 v135, s[60:63], s52 offen lds
	s_waitcnt vmcnt(8)
	s_waitcnt lgkmcnt(0)
	s_setprio 1
	s_barrier
	v_mfma_f32_16x16x32_bf16 v[94:97], v[142:145], v[194:197], v[94:97]
	v_mfma_f32_16x16x32_bf16 v[86:89], v[142:145], v[202:205], v[86:89]
	v_mfma_f32_16x16x32_bf16 v[78:81], v[142:145], v[232:235], v[78:81]
	v_mfma_f32_16x16x32_bf16 v[70:73], v[142:145], v[240:243], v[70:73]
	v_mfma_f32_16x16x32_bf16 v[90:93], v[170:173], v[194:197], v[90:93]
	v_mfma_f32_16x16x32_bf16 v[82:85], v[170:173], v[202:205], v[82:85]
	v_mfma_f32_16x16x32_bf16 v[74:77], v[170:173], v[232:235], v[74:77]
	v_mfma_f32_16x16x32_bf16 v[66:69], v[170:173], v[240:243], v[66:69]
	v_mfma_f32_16x16x32_bf16 v[94:97], v[154:157], v[198:201], v[94:97]
	v_mfma_f32_16x16x32_bf16 v[86:89], v[154:157], v[228:231], v[86:89]
	v_mfma_f32_16x16x32_bf16 v[78:81], v[154:157], v[236:239], v[78:81]
	v_mfma_f32_16x16x32_bf16 v[70:73], v[154:157], v[244:247], v[70:73]
	v_mfma_f32_16x16x32_bf16 v[90:93], v[174:177], v[198:201], v[90:93]
	v_mfma_f32_16x16x32_bf16 v[82:85], v[174:177], v[228:231], v[82:85]
	v_mfma_f32_16x16x32_bf16 v[74:77], v[174:177], v[236:239], v[74:77]
	v_mfma_f32_16x16x32_bf16 v[66:69], v[174:177], v[244:247], v[66:69]
	v_mfma_f32_16x16x32_bf16 v[30:33], v[178:181], v[194:197], v[30:33]
	v_mfma_f32_16x16x32_bf16 v[22:25], v[178:181], v[202:205], v[22:25]
	v_mfma_f32_16x16x32_bf16 v[14:17], v[178:181], v[232:235], v[14:17]
	v_mfma_f32_16x16x32_bf16 v[6:9], v[178:181], v[240:243], v[6:9]
	v_mfma_f32_16x16x32_bf16 v[26:29], v[186:189], v[194:197], v[26:29]
	v_mfma_f32_16x16x32_bf16 v[18:21], v[186:189], v[202:205], v[18:21]
	v_mfma_f32_16x16x32_bf16 v[10:13], v[186:189], v[232:235], v[10:13]
	v_mfma_f32_16x16x32_bf16 v[2:5], v[186:189], v[240:243], v[2:5]
	v_mfma_f32_16x16x32_bf16 v[30:33], v[182:185], v[198:201], v[30:33]
	v_mfma_f32_16x16x32_bf16 v[22:25], v[182:185], v[228:231], v[22:25]
	v_mfma_f32_16x16x32_bf16 v[14:17], v[182:185], v[236:239], v[14:17]
	v_mfma_f32_16x16x32_bf16 v[6:9], v[182:185], v[244:247], v[6:9]
	v_mfma_f32_16x16x32_bf16 v[26:29], v[190:193], v[198:201], v[26:29]
	v_mfma_f32_16x16x32_bf16 v[18:21], v[190:193], v[228:231], v[18:21]
	v_mfma_f32_16x16x32_bf16 v[10:13], v[190:193], v[236:239], v[10:13]
	v_mfma_f32_16x16x32_bf16 v[2:5], v[190:193], v[244:247], v[2:5]
	s_barrier
	s_setprio 0
	v_add_u32_e32 v141, 0x18000, v139
	ds_read_b128 v[142:145], v141
	ds_read_b128 v[154:157], v141 offset:1024
	ds_read_b128 v[170:173], v141 offset:2048
	ds_read_b128 v[174:177], v141 offset:3072
	v_add_u32_e32 v141, 0x1c000, v139
	ds_read_b128 v[178:181], v141
	ds_read_b128 v[182:185], v141 offset:1024
	ds_read_b128 v[186:189], v141 offset:2048
	ds_read_b128 v[190:193], v141 offset:3072
	s_add_i32 s52, s52, 0x80000
	s_mov_b32 m0, s31
	ds_read_b128 v[194:197], v140 offset:32768
	ds_read_b128 v[198:201], v140 offset:33792
	ds_read_b128 v[202:205], v140 offset:34816
	ds_read_b128 v[228:231], v140 offset:35840
	ds_read_b128 v[232:235], v140 offset:36864
	ds_read_b128 v[236:239], v140 offset:37888
	ds_read_b128 v[240:243], v140 offset:38912
	ds_read_b128 v[244:247], v140 offset:39936
	buffer_load_dwordx4 v131, s[60:63], s52 offen lds
	s_mov_b32 m0, s33
	s_nop 0
	buffer_load_dwordx4 v135, s[60:63], s52 offen lds
	s_waitcnt vmcnt(8)
	s_waitcnt lgkmcnt(0)
	s_setprio 1
	s_barrier
	v_mfma_f32_16x16x32_bf16 v[126:129], v[142:145], v[194:197], v[126:129]
	v_mfma_f32_16x16x32_bf16 v[118:121], v[142:145], v[202:205], v[118:121]
	v_mfma_f32_16x16x32_bf16 v[110:113], v[142:145], v[232:235], v[110:113]
	v_mfma_f32_16x16x32_bf16 v[102:105], v[142:145], v[240:243], v[102:105]
	v_mfma_f32_16x16x32_bf16 v[122:125], v[170:173], v[194:197], v[122:125]
	v_mfma_f32_16x16x32_bf16 v[114:117], v[170:173], v[202:205], v[114:117]
	v_mfma_f32_16x16x32_bf16 v[106:109], v[170:173], v[232:235], v[106:109]
	v_mfma_f32_16x16x32_bf16 v[98:101], v[170:173], v[240:243], v[98:101]
	v_mfma_f32_16x16x32_bf16 v[126:129], v[154:157], v[198:201], v[126:129]
	v_mfma_f32_16x16x32_bf16 v[118:121], v[154:157], v[228:231], v[118:121]
	v_mfma_f32_16x16x32_bf16 v[110:113], v[154:157], v[236:239], v[110:113]
	v_mfma_f32_16x16x32_bf16 v[102:105], v[154:157], v[244:247], v[102:105]
	v_mfma_f32_16x16x32_bf16 v[122:125], v[174:177], v[198:201], v[122:125]
	v_mfma_f32_16x16x32_bf16 v[114:117], v[174:177], v[228:231], v[114:117]
	v_mfma_f32_16x16x32_bf16 v[106:109], v[174:177], v[236:239], v[106:109]
	v_mfma_f32_16x16x32_bf16 v[98:101], v[174:177], v[244:247], v[98:101]
	v_mfma_f32_16x16x32_bf16 v[62:65], v[178:181], v[194:197], v[62:65]
	v_mfma_f32_16x16x32_bf16 v[54:57], v[178:181], v[202:205], v[54:57]
	v_mfma_f32_16x16x32_bf16 v[46:49], v[178:181], v[232:235], v[46:49]
	v_mfma_f32_16x16x32_bf16 v[38:41], v[178:181], v[240:243], v[38:41]
	v_mfma_f32_16x16x32_bf16 v[58:61], v[186:189], v[194:197], v[58:61]
	v_mfma_f32_16x16x32_bf16 v[50:53], v[186:189], v[202:205], v[50:53]
	v_mfma_f32_16x16x32_bf16 v[42:45], v[186:189], v[232:235], v[42:45]
	v_mfma_f32_16x16x32_bf16 v[34:37], v[186:189], v[240:243], v[34:37]
	v_mfma_f32_16x16x32_bf16 v[62:65], v[182:185], v[198:201], v[62:65]
	v_mfma_f32_16x16x32_bf16 v[54:57], v[182:185], v[228:231], v[54:57]
	v_mfma_f32_16x16x32_bf16 v[46:49], v[182:185], v[236:239], v[46:49]
	v_mfma_f32_16x16x32_bf16 v[38:41], v[182:185], v[244:247], v[38:41]
	v_mfma_f32_16x16x32_bf16 v[58:61], v[190:193], v[198:201], v[58:61]
	v_mfma_f32_16x16x32_bf16 v[50:53], v[190:193], v[228:231], v[50:53]
	v_mfma_f32_16x16x32_bf16 v[42:45], v[190:193], v[236:239], v[42:45]
	v_mfma_f32_16x16x32_bf16 v[34:37], v[190:193], v[244:247], v[34:37]
	s_barrier
	s_setprio 0
	s_mov_b32 m0, s34
	s_or_b32 s52, s83, 0x80
	ds_read_b128 v[194:197], v140 offset:49152
	ds_read_b128 v[198:201], v140 offset:50176
	ds_read_b128 v[202:205], v140 offset:51200
	ds_read_b128 v[228:231], v140 offset:52224
	ds_read_b128 v[232:235], v140 offset:53248
	ds_read_b128 v[236:239], v140 offset:54272
	ds_read_b128 v[240:243], v140 offset:55296
	ds_read_b128 v[244:247], v140 offset:56320
	buffer_load_dwordx4 v134, s[68:71], s52 offen lds
	s_mov_b32 m0, s35
	s_add_i32 s83, s83, 0x80080
	buffer_load_dwordx4 v136, s[68:71], s52 offen lds
	s_mov_b32 m0, s65
	s_nop 0
	buffer_load_dwordx4 v134, s[68:71], s83 offen lds
	s_mov_b32 m0, s66
	s_nop 0
	buffer_load_dwordx4 v136, s[68:71], s83 offen lds
	s_mov_b32 m0, s36
	s_nop 0
	buffer_load_dwordx4 v131, s[60:63], s27 offen lds
	s_mov_b32 m0, s37
	s_nop 0
	buffer_load_dwordx4 v135, s[60:63], s27 offen lds
	s_waitcnt vmcnt(8)
	s_waitcnt lgkmcnt(0)
	s_setprio 1
	s_barrier
	v_mfma_f32_16x16x32_bf16 v[94:97], v[142:145], v[194:197], v[94:97]
	v_mfma_f32_16x16x32_bf16 v[86:89], v[142:145], v[202:205], v[86:89]
	v_mfma_f32_16x16x32_bf16 v[78:81], v[142:145], v[232:235], v[78:81]
	v_mfma_f32_16x16x32_bf16 v[70:73], v[142:145], v[240:243], v[70:73]
	v_mfma_f32_16x16x32_bf16 v[90:93], v[170:173], v[194:197], v[90:93]
	v_mfma_f32_16x16x32_bf16 v[82:85], v[170:173], v[202:205], v[82:85]
	v_mfma_f32_16x16x32_bf16 v[74:77], v[170:173], v[232:235], v[74:77]
	v_mfma_f32_16x16x32_bf16 v[66:69], v[170:173], v[240:243], v[66:69]
	v_mfma_f32_16x16x32_bf16 v[94:97], v[154:157], v[198:201], v[94:97]
	v_mfma_f32_16x16x32_bf16 v[86:89], v[154:157], v[228:231], v[86:89]
	v_mfma_f32_16x16x32_bf16 v[78:81], v[154:157], v[236:239], v[78:81]
	v_mfma_f32_16x16x32_bf16 v[70:73], v[154:157], v[244:247], v[70:73]
	v_mfma_f32_16x16x32_bf16 v[90:93], v[174:177], v[198:201], v[90:93]
	v_mfma_f32_16x16x32_bf16 v[82:85], v[174:177], v[228:231], v[82:85]
	v_mfma_f32_16x16x32_bf16 v[74:77], v[174:177], v[236:239], v[74:77]
	v_mfma_f32_16x16x32_bf16 v[66:69], v[174:177], v[244:247], v[66:69]
	v_mfma_f32_16x16x32_bf16 v[30:33], v[178:181], v[194:197], v[30:33]
	v_mfma_f32_16x16x32_bf16 v[22:25], v[178:181], v[202:205], v[22:25]
	v_mfma_f32_16x16x32_bf16 v[14:17], v[178:181], v[232:235], v[14:17]
	v_mfma_f32_16x16x32_bf16 v[6:9], v[178:181], v[240:243], v[6:9]
	v_mfma_f32_16x16x32_bf16 v[26:29], v[186:189], v[194:197], v[26:29]
	v_mfma_f32_16x16x32_bf16 v[18:21], v[186:189], v[202:205], v[18:21]
	v_mfma_f32_16x16x32_bf16 v[10:13], v[186:189], v[232:235], v[10:13]
	v_mfma_f32_16x16x32_bf16 v[2:5], v[186:189], v[240:243], v[2:5]
	v_mfma_f32_16x16x32_bf16 v[30:33], v[182:185], v[198:201], v[30:33]
	v_mfma_f32_16x16x32_bf16 v[22:25], v[182:185], v[228:231], v[22:25]
	v_mfma_f32_16x16x32_bf16 v[14:17], v[182:185], v[236:239], v[14:17]
	v_mfma_f32_16x16x32_bf16 v[6:9], v[182:185], v[244:247], v[6:9]
	v_mfma_f32_16x16x32_bf16 v[26:29], v[190:193], v[198:201], v[26:29]
	v_mfma_f32_16x16x32_bf16 v[18:21], v[190:193], v[228:231], v[18:21]
	v_mfma_f32_16x16x32_bf16 v[10:13], v[190:193], v[236:239], v[10:13]
	v_mfma_f32_16x16x32_bf16 v[2:5], v[190:193], v[244:247], v[2:5]
	s_barrier
	s_setprio 0
	s_add_i32 s26, s26, 2
	s_addk_i32 s19, 0x100
	s_addk_i32 s22, 0x100
	s_cmp_gt_u32 s26, 29
	s_cbranch_scc0 .LBB0_1283
	s_and_b64 vcc, exec, s[44:45]
	s_cbranch_vccz .LBB0_1286
	s_barrier

.LBB0_1588:
	s_lshl_b32 s85, s84, 20
	s_and_b64 s[8:9], s[42:43], exec
	s_cselect_b32 s8, s85, s13
	s_lshl_b32 s48, s73, 20
	s_and_b64 s[22:23], s[42:43], exec
	s_cselect_b32 s9, s48, s21
	s_add_i32 s13, s13, 0x80080
	s_addk_i32 s21, 0x100
	s_mov_b32 s22, -2
	s_waitcnt lgkmcnt(0)
	v_add_u32_e32 v170, 0x10000, v140
	v_add_u32_e32 v186, 0x14000, v140
	ds_read_b128 v[132:135], v170
	ds_read_b128 v[142:145], v170 offset:1024
	ds_read_b128 v[154:157], v170 offset:2048
	ds_read_b128 v[170:173], v170 offset:3072
	ds_read_b128 v[174:177], v186
	ds_read_b128 v[178:181], v186 offset:1024
	ds_read_b128 v[182:185], v186 offset:2048
	ds_read_b128 v[186:189], v186 offset:3072
	s_add_i32 s23, s13, 0xfff80080
	s_cmp_eq_u32 s22, 28
	s_cselect_b32 s27, s8, s23
	s_cselect_b32 s26, s9, s21
	s_or_b32 s23, s27, 0x80
	s_mov_b32 m0, s70
	ds_read_b128 v[190:193], v141
	ds_read_b128 v[194:197], v141 offset:1024
	ds_read_b128 v[198:201], v141 offset:2048
	ds_read_b128 v[202:205], v141 offset:3072
	ds_read_b128 v[228:231], v141 offset:4096
	ds_read_b128 v[232:235], v141 offset:5120
	ds_read_b128 v[236:239], v141 offset:6144
	ds_read_b128 v[240:243], v141 offset:7168
	buffer_load_dwordx4 v136, s[60:63], s13 offen lds
	s_mov_b32 m0, s72
	s_nop 0
	buffer_load_dwordx4 v138, s[60:63], s13 offen lds
	s_waitcnt vmcnt(8)
	s_waitcnt lgkmcnt(0)
	s_setprio 1
	s_barrier
	v_mfma_f32_16x16x32_bf16 v[126:129], v[132:135], v[190:193], 0
	v_mfma_f32_16x16x32_bf16 v[118:121], v[132:135], v[198:201], 0
	v_mfma_f32_16x16x32_bf16 v[94:97], v[132:135], v[228:231], 0
	v_mfma_f32_16x16x32_bf16 v[78:81], v[132:135], v[236:239], 0
	v_mfma_f32_16x16x32_bf16 v[106:109], v[154:157], v[190:193], 0
	v_mfma_f32_16x16x32_bf16 v[114:117], v[154:157], v[198:201], 0
	v_mfma_f32_16x16x32_bf16 v[90:93], v[154:157], v[228:231], 0
	v_mfma_f32_16x16x32_bf16 v[74:77], v[154:157], v[236:239], 0
	v_mfma_f32_16x16x32_bf16 v[126:129], v[142:145], v[194:197], v[126:129]
	v_mfma_f32_16x16x32_bf16 v[118:121], v[142:145], v[202:205], v[118:121]
	v_mfma_f32_16x16x32_bf16 v[94:97], v[142:145], v[232:235], v[94:97]
	v_mfma_f32_16x16x32_bf16 v[78:81], v[142:145], v[240:243], v[78:81]
	v_mfma_f32_16x16x32_bf16 v[106:109], v[170:173], v[194:197], v[106:109]
	v_mfma_f32_16x16x32_bf16 v[114:117], v[170:173], v[202:205], v[114:117]
	v_mfma_f32_16x16x32_bf16 v[90:93], v[170:173], v[232:235], v[90:93]
	v_mfma_f32_16x16x32_bf16 v[74:77], v[170:173], v[240:243], v[74:77]
	v_mfma_f32_16x16x32_bf16 v[122:125], v[174:177], v[190:193], 0
	v_mfma_f32_16x16x32_bf16 v[102:105], v[174:177], v[198:201], 0
	v_mfma_f32_16x16x32_bf16 v[86:89], v[174:177], v[228:231], 0
	v_mfma_f32_16x16x32_bf16 v[70:73], v[174:177], v[236:239], 0
	v_mfma_f32_16x16x32_bf16 v[110:113], v[182:185], v[190:193], 0
	v_mfma_f32_16x16x32_bf16 v[98:101], v[182:185], v[198:201], 0
	v_mfma_f32_16x16x32_bf16 v[82:85], v[182:185], v[228:231], 0
	v_mfma_f32_16x16x32_bf16 v[66:69], v[182:185], v[236:239], 0
	v_mfma_f32_16x16x32_bf16 v[122:125], v[178:181], v[194:197], v[122:125]
	v_mfma_f32_16x16x32_bf16 v[102:105], v[178:181], v[202:205], v[102:105]
	v_mfma_f32_16x16x32_bf16 v[86:89], v[178:181], v[232:235], v[86:89]
	v_mfma_f32_16x16x32_bf16 v[70:73], v[178:181], v[240:243], v[70:73]
	v_mfma_f32_16x16x32_bf16 v[110:113], v[186:189], v[194:197], v[110:113]
	v_mfma_f32_16x16x32_bf16 v[98:101], v[186:189], v[202:205], v[98:101]
	v_mfma_f32_16x16x32_bf16 v[82:85], v[186:189], v[232:235], v[82:85]
	v_mfma_f32_16x16x32_bf16 v[66:69], v[186:189], v[240:243], v[66:69]
	s_barrier
	s_setprio 0
	s_mov_b32 m0, s15
	s_mov_b32 s46, s62
	s_mov_b32 s47, s63
	ds_read_b128 v[190:193], v141 offset:16384
	ds_read_b128 v[194:197], v141 offset:17408
	ds_read_b128 v[198:201], v141 offset:18432
	ds_read_b128 v[202:205], v141 offset:19456
	ds_read_b128 v[228:231], v141 offset:20480
	ds_read_b128 v[232:235], v141 offset:21504
	ds_read_b128 v[236:239], v141 offset:22528
	ds_read_b128 v[240:243], v141 offset:23552
	buffer_load_dwordx4 v137, s[44:47], s26 offen lds
	s_mov_b32 m0, s16
	s_add_i32 s49, s26, 0x80000
	buffer_load_dwordx4 v139, s[44:47], s26 offen lds
	s_mov_b32 m0, s18
	s_nop 0
	buffer_load_dwordx4 v137, s[44:47], s49 offen lds
	s_mov_b32 m0, s19
	s_nop 0
	buffer_load_dwordx4 v139, s[44:47], s49 offen lds
	s_mov_b32 m0, s14
	s_nop 0
	buffer_load_dwordx4 v136, s[60:63], s27 offen lds
	s_mov_b32 m0, s24
	s_nop 0
	buffer_load_dwordx4 v138, s[60:63], s27 offen lds
	s_waitcnt vmcnt(8)
	s_waitcnt lgkmcnt(0)
	s_setprio 1
	s_barrier
	v_mfma_f32_16x16x32_bf16 v[62:65], v[132:135], v[190:193], 0
	v_mfma_f32_16x16x32_bf16 v[46:49], v[132:135], v[198:201], 0
	v_mfma_f32_16x16x32_bf16 v[30:33], v[132:135], v[228:231], 0
	v_mfma_f32_16x16x32_bf16 v[14:17], v[132:135], v[236:239], 0
	v_mfma_f32_16x16x32_bf16 v[58:61], v[154:157], v[190:193], 0
	v_mfma_f32_16x16x32_bf16 v[42:45], v[154:157], v[198:201], 0
	v_mfma_f32_16x16x32_bf16 v[26:29], v[154:157], v[228:231], 0
	v_mfma_f32_16x16x32_bf16 v[10:13], v[154:157], v[236:239], 0
	v_mfma_f32_16x16x32_bf16 v[62:65], v[142:145], v[194:197], v[62:65]
	v_mfma_f32_16x16x32_bf16 v[46:49], v[142:145], v[202:205], v[46:49]
	v_mfma_f32_16x16x32_bf16 v[30:33], v[142:145], v[232:235], v[30:33]
	v_mfma_f32_16x16x32_bf16 v[14:17], v[142:145], v[240:243], v[14:17]
	v_mfma_f32_16x16x32_bf16 v[58:61], v[170:173], v[194:197], v[58:61]
	v_mfma_f32_16x16x32_bf16 v[42:45], v[170:173], v[202:205], v[42:45]
	v_mfma_f32_16x16x32_bf16 v[26:29], v[170:173], v[232:235], v[26:29]
	v_mfma_f32_16x16x32_bf16 v[10:13], v[170:173], v[240:243], v[10:13]
	v_mfma_f32_16x16x32_bf16 v[54:57], v[174:177], v[190:193], 0
	v_mfma_f32_16x16x32_bf16 v[38:41], v[174:177], v[198:201], 0
	v_mfma_f32_16x16x32_bf16 v[22:25], v[174:177], v[228:231], 0
	v_mfma_f32_16x16x32_bf16 v[6:9], v[174:177], v[236:239], 0
	v_mfma_f32_16x16x32_bf16 v[50:53], v[182:185], v[190:193], 0
	v_mfma_f32_16x16x32_bf16 v[34:37], v[182:185], v[198:201], 0
	v_mfma_f32_16x16x32_bf16 v[18:21], v[182:185], v[228:231], 0
	v_mfma_f32_16x16x32_bf16 v[2:5], v[182:185], v[236:239], 0
	v_mfma_f32_16x16x32_bf16 v[54:57], v[178:181], v[194:197], v[54:57]
	v_mfma_f32_16x16x32_bf16 v[38:41], v[178:181], v[202:205], v[38:41]
	v_mfma_f32_16x16x32_bf16 v[22:25], v[178:181], v[232:235], v[22:25]
	v_mfma_f32_16x16x32_bf16 v[6:9], v[178:181], v[240:243], v[6:9]
	v_mfma_f32_16x16x32_bf16 v[50:53], v[186:189], v[194:197], v[50:53]
	v_mfma_f32_16x16x32_bf16 v[34:37], v[186:189], v[202:205], v[34:37]
	v_mfma_f32_16x16x32_bf16 v[18:21], v[186:189], v[232:235], v[18:21]
	v_mfma_f32_16x16x32_bf16 v[2:5], v[186:189], v[240:243], v[2:5]
	s_barrier
	s_setprio 0
	v_add_u32_e32 v170, 0x18000, v140
	v_add_u32_e32 v186, 0x1c000, v140
	ds_read_b128 v[132:135], v170
	ds_read_b128 v[142:145], v170 offset:1024
	ds_read_b128 v[154:157], v170 offset:2048
	ds_read_b128 v[170:173], v170 offset:3072
	ds_read_b128 v[174:177], v186
	ds_read_b128 v[178:181], v186 offset:1024
	ds_read_b128 v[182:185], v186 offset:2048
	ds_read_b128 v[186:189], v186 offset:3072
	s_add_i32 s27, s27, 0x80000
	s_mov_b32 m0, s25
	ds_read_b128 v[190:193], v141 offset:32768
	ds_read_b128 v[194:197], v141 offset:33792
	ds_read_b128 v[198:201], v141 offset:34816
	ds_read_b128 v[202:205], v141 offset:35840
	ds_read_b128 v[228:231], v141 offset:36864
	ds_read_b128 v[232:235], v141 offset:37888
	ds_read_b128 v[236:239], v141 offset:38912
	ds_read_b128 v[240:243], v141 offset:39936
	buffer_load_dwordx4 v136, s[60:63], s27 offen lds
	s_mov_b32 m0, s30
	s_nop 0
	buffer_load_dwordx4 v138, s[60:63], s27 offen lds
	s_waitcnt vmcnt(8)
	s_waitcnt lgkmcnt(0)
	s_setprio 1
	s_barrier
	v_mfma_f32_16x16x32_bf16 v[126:129], v[132:135], v[190:193], v[126:129]
	v_mfma_f32_16x16x32_bf16 v[118:121], v[132:135], v[198:201], v[118:121]
	v_mfma_f32_16x16x32_bf16 v[94:97], v[132:135], v[228:231], v[94:97]
	v_mfma_f32_16x16x32_bf16 v[78:81], v[132:135], v[236:239], v[78:81]
	v_mfma_f32_16x16x32_bf16 v[106:109], v[154:157], v[190:193], v[106:109]
	v_mfma_f32_16x16x32_bf16 v[114:117], v[154:157], v[198:201], v[114:117]
	v_mfma_f32_16x16x32_bf16 v[90:93], v[154:157], v[228:231], v[90:93]
	v_mfma_f32_16x16x32_bf16 v[74:77], v[154:157], v[236:239], v[74:77]
	v_mfma_f32_16x16x32_bf16 v[126:129], v[142:145], v[194:197], v[126:129]
	v_mfma_f32_16x16x32_bf16 v[118:121], v[142:145], v[202:205], v[118:121]
	v_mfma_f32_16x16x32_bf16 v[94:97], v[142:145], v[232:235], v[94:97]
	v_mfma_f32_16x16x32_bf16 v[78:81], v[142:145], v[240:243], v[78:81]
	v_mfma_f32_16x16x32_bf16 v[106:109], v[170:173], v[194:197], v[106:109]
	v_mfma_f32_16x16x32_bf16 v[114:117], v[170:173], v[202:205], v[114:117]
	v_mfma_f32_16x16x32_bf16 v[90:93], v[170:173], v[232:235], v[90:93]
	v_mfma_f32_16x16x32_bf16 v[74:77], v[170:173], v[240:243], v[74:77]
	v_mfma_f32_16x16x32_bf16 v[122:125], v[174:177], v[190:193], v[122:125]
	v_mfma_f32_16x16x32_bf16 v[102:105], v[174:177], v[198:201], v[102:105]
	v_mfma_f32_16x16x32_bf16 v[86:89], v[174:177], v[228:231], v[86:89]
	v_mfma_f32_16x16x32_bf16 v[70:73], v[174:177], v[236:239], v[70:73]
	v_mfma_f32_16x16x32_bf16 v[110:113], v[182:185], v[190:193], v[110:113]
	v_mfma_f32_16x16x32_bf16 v[98:101], v[182:185], v[198:201], v[98:101]
	v_mfma_f32_16x16x32_bf16 v[82:85], v[182:185], v[228:231], v[82:85]
	v_mfma_f32_16x16x32_bf16 v[66:69], v[182:185], v[236:239], v[66:69]
	v_mfma_f32_16x16x32_bf16 v[122:125], v[178:181], v[194:197], v[122:125]
	v_mfma_f32_16x16x32_bf16 v[102:105], v[178:181], v[202:205], v[102:105]
	v_mfma_f32_16x16x32_bf16 v[86:89], v[178:181], v[232:235], v[86:89]
	v_mfma_f32_16x16x32_bf16 v[70:73], v[178:181], v[240:243], v[70:73]
	v_mfma_f32_16x16x32_bf16 v[110:113], v[186:189], v[194:197], v[110:113]
	v_mfma_f32_16x16x32_bf16 v[98:101], v[186:189], v[202:205], v[98:101]
	v_mfma_f32_16x16x32_bf16 v[82:85], v[186:189], v[232:235], v[82:85]
	v_mfma_f32_16x16x32_bf16 v[66:69], v[186:189], v[240:243], v[66:69]
	s_barrier
	s_setprio 0
	s_mov_b32 m0, s36
	s_or_b32 s27, s26, 0x80
	ds_read_b128 v[190:193], v141 offset:49152
	ds_read_b128 v[194:197], v141 offset:50176
	ds_read_b128 v[198:201], v141 offset:51200
	ds_read_b128 v[202:205], v141 offset:52224
	ds_read_b128 v[228:231], v141 offset:53248
	ds_read_b128 v[232:235], v141 offset:54272
	ds_read_b128 v[236:239], v141 offset:55296
	ds_read_b128 v[240:243], v141 offset:56320
	buffer_load_dwordx4 v137, s[44:47], s27 offen lds
	s_mov_b32 m0, s37
	s_add_i32 s26, s26, 0x80080
	buffer_load_dwordx4 v139, s[44:47], s27 offen lds
	s_mov_b32 m0, s68
	s_nop 0
	buffer_load_dwordx4 v137, s[44:47], s26 offen lds
	s_mov_b32 m0, s69
	s_nop 0
	buffer_load_dwordx4 v139, s[44:47], s26 offen lds
	s_mov_b32 m0, s66
	s_nop 0
	buffer_load_dwordx4 v136, s[60:63], s23 offen lds
	s_mov_b32 m0, s67
	s_nop 0
	buffer_load_dwordx4 v138, s[60:63], s23 offen lds
	s_waitcnt vmcnt(8)
	s_waitcnt lgkmcnt(0)
	s_setprio 1
	s_barrier
	v_mfma_f32_16x16x32_bf16 v[62:65], v[132:135], v[190:193], v[62:65]
	v_mfma_f32_16x16x32_bf16 v[46:49], v[132:135], v[198:201], v[46:49]
	v_mfma_f32_16x16x32_bf16 v[30:33], v[132:135], v[228:231], v[30:33]
	v_mfma_f32_16x16x32_bf16 v[14:17], v[132:135], v[236:239], v[14:17]
	v_mfma_f32_16x16x32_bf16 v[58:61], v[154:157], v[190:193], v[58:61]
	v_mfma_f32_16x16x32_bf16 v[42:45], v[154:157], v[198:201], v[42:45]
	v_mfma_f32_16x16x32_bf16 v[26:29], v[154:157], v[228:231], v[26:29]
	v_mfma_f32_16x16x32_bf16 v[10:13], v[154:157], v[236:239], v[10:13]
	v_mfma_f32_16x16x32_bf16 v[62:65], v[142:145], v[194:197], v[62:65]
	v_mfma_f32_16x16x32_bf16 v[46:49], v[142:145], v[202:205], v[46:49]
	v_mfma_f32_16x16x32_bf16 v[30:33], v[142:145], v[232:235], v[30:33]
	v_mfma_f32_16x16x32_bf16 v[14:17], v[142:145], v[240:243], v[14:17]
	v_mfma_f32_16x16x32_bf16 v[58:61], v[170:173], v[194:197], v[58:61]
	v_mfma_f32_16x16x32_bf16 v[42:45], v[170:173], v[202:205], v[42:45]
	v_mfma_f32_16x16x32_bf16 v[26:29], v[170:173], v[232:235], v[26:29]
	v_mfma_f32_16x16x32_bf16 v[10:13], v[170:173], v[240:243], v[10:13]
	v_mfma_f32_16x16x32_bf16 v[54:57], v[174:177], v[190:193], v[54:57]
	v_mfma_f32_16x16x32_bf16 v[38:41], v[174:177], v[198:201], v[38:41]
	v_mfma_f32_16x16x32_bf16 v[22:25], v[174:177], v[228:231], v[22:25]
	v_mfma_f32_16x16x32_bf16 v[6:9], v[174:177], v[236:239], v[6:9]
	v_mfma_f32_16x16x32_bf16 v[50:53], v[182:185], v[190:193], v[50:53]
	v_mfma_f32_16x16x32_bf16 v[34:37], v[182:185], v[198:201], v[34:37]
	v_mfma_f32_16x16x32_bf16 v[18:21], v[182:185], v[228:231], v[18:21]
	v_mfma_f32_16x16x32_bf16 v[2:5], v[182:185], v[236:239], v[2:5]
	v_mfma_f32_16x16x32_bf16 v[54:57], v[178:181], v[194:197], v[54:57]
	v_mfma_f32_16x16x32_bf16 v[38:41], v[178:181], v[202:205], v[38:41]
	v_mfma_f32_16x16x32_bf16 v[22:25], v[178:181], v[232:235], v[22:25]
	v_mfma_f32_16x16x32_bf16 v[6:9], v[178:181], v[240:243], v[6:9]
	v_mfma_f32_16x16x32_bf16 v[50:53], v[186:189], v[194:197], v[50:53]
	v_mfma_f32_16x16x32_bf16 v[34:37], v[186:189], v[202:205], v[34:37]
	v_mfma_f32_16x16x32_bf16 v[18:21], v[186:189], v[232:235], v[18:21]
	v_mfma_f32_16x16x32_bf16 v[2:5], v[186:189], v[240:243], v[2:5]
	s_barrier
	s_setprio 0
	s_add_i32 s22, s22, 2
	s_addk_i32 s13, 0x100
	s_addk_i32 s21, 0x100
	s_cmp_gt_u32 s22, 29
.LBB0_1589:
	v_add_u32_e32 v170, 0x10000, v140
	v_add_u32_e32 v186, 0x14000, v140
	ds_read_b128 v[132:135], v170
	ds_read_b128 v[142:145], v170 offset:1024
	ds_read_b128 v[154:157], v170 offset:2048
	ds_read_b128 v[170:173], v170 offset:3072
	ds_read_b128 v[174:177], v186
	ds_read_b128 v[178:181], v186 offset:1024
	ds_read_b128 v[182:185], v186 offset:2048
	ds_read_b128 v[186:189], v186 offset:3072
	s_add_i32 s23, s13, 0xfff80080
	s_cmp_eq_u32 s22, 28
	s_cselect_b32 s27, s8, s23
	s_cselect_b32 s26, s9, s21
	s_or_b32 s23, s27, 0x80
	s_mov_b32 m0, s70
	ds_read_b128 v[190:193], v141
	ds_read_b128 v[194:197], v141 offset:1024
	ds_read_b128 v[198:201], v141 offset:2048
	ds_read_b128 v[202:205], v141 offset:3072
	ds_read_b128 v[228:231], v141 offset:4096
	ds_read_b128 v[232:235], v141 offset:5120
	ds_read_b128 v[236:239], v141 offset:6144
	ds_read_b128 v[240:243], v141 offset:7168
	buffer_load_dwordx4 v136, s[60:63], s13 offen lds
	s_mov_b32 m0, s72
	s_nop 0
	buffer_load_dwordx4 v138, s[60:63], s13 offen lds
	s_waitcnt vmcnt(8)
	s_waitcnt lgkmcnt(0)
	s_setprio 1
	s_barrier
	v_mfma_f32_16x16x32_bf16 v[126:129], v[132:135], v[190:193], v[126:129]
	v_mfma_f32_16x16x32_bf16 v[118:121], v[132:135], v[198:201], v[118:121]
	v_mfma_f32_16x16x32_bf16 v[94:97], v[132:135], v[228:231], v[94:97]
	v_mfma_f32_16x16x32_bf16 v[78:81], v[132:135], v[236:239], v[78:81]
	v_mfma_f32_16x16x32_bf16 v[106:109], v[154:157], v[190:193], v[106:109]
	v_mfma_f32_16x16x32_bf16 v[114:117], v[154:157], v[198:201], v[114:117]
	v_mfma_f32_16x16x32_bf16 v[90:93], v[154:157], v[228:231], v[90:93]
	v_mfma_f32_16x16x32_bf16 v[74:77], v[154:157], v[236:239], v[74:77]
	v_mfma_f32_16x16x32_bf16 v[126:129], v[142:145], v[194:197], v[126:129]
	v_mfma_f32_16x16x32_bf16 v[118:121], v[142:145], v[202:205], v[118:121]
	v_mfma_f32_16x16x32_bf16 v[94:97], v[142:145], v[232:235], v[94:97]
	v_mfma_f32_16x16x32_bf16 v[78:81], v[142:145], v[240:243], v[78:81]
	v_mfma_f32_16x16x32_bf16 v[106:109], v[170:173], v[194:197], v[106:109]
	v_mfma_f32_16x16x32_bf16 v[114:117], v[170:173], v[202:205], v[114:117]
	v_mfma_f32_16x16x32_bf16 v[90:93], v[170:173], v[232:235], v[90:93]
	v_mfma_f32_16x16x32_bf16 v[74:77], v[170:173], v[240:243], v[74:77]
	v_mfma_f32_16x16x32_bf16 v[122:125], v[174:177], v[190:193], v[122:125]
	v_mfma_f32_16x16x32_bf16 v[102:105], v[174:177], v[198:201], v[102:105]
	v_mfma_f32_16x16x32_bf16 v[86:89], v[174:177], v[228:231], v[86:89]
	v_mfma_f32_16x16x32_bf16 v[70:73], v[174:177], v[236:239], v[70:73]
	v_mfma_f32_16x16x32_bf16 v[110:113], v[182:185], v[190:193], v[110:113]
	v_mfma_f32_16x16x32_bf16 v[98:101], v[182:185], v[198:201], v[98:101]
	v_mfma_f32_16x16x32_bf16 v[82:85], v[182:185], v[228:231], v[82:85]
	v_mfma_f32_16x16x32_bf16 v[66:69], v[182:185], v[236:239], v[66:69]
	v_mfma_f32_16x16x32_bf16 v[122:125], v[178:181], v[194:197], v[122:125]
	v_mfma_f32_16x16x32_bf16 v[102:105], v[178:181], v[202:205], v[102:105]
	v_mfma_f32_16x16x32_bf16 v[86:89], v[178:181], v[232:235], v[86:89]
	v_mfma_f32_16x16x32_bf16 v[70:73], v[178:181], v[240:243], v[70:73]
	v_mfma_f32_16x16x32_bf16 v[110:113], v[186:189], v[194:197], v[110:113]
	v_mfma_f32_16x16x32_bf16 v[98:101], v[186:189], v[202:205], v[98:101]
	v_mfma_f32_16x16x32_bf16 v[82:85], v[186:189], v[232:235], v[82:85]
	v_mfma_f32_16x16x32_bf16 v[66:69], v[186:189], v[240:243], v[66:69]
	s_barrier
	s_setprio 0
	s_mov_b32 m0, s15
	s_mov_b32 s46, s62
	s_mov_b32 s47, s63
	ds_read_b128 v[190:193], v141 offset:16384
	ds_read_b128 v[194:197], v141 offset:17408
	ds_read_b128 v[198:201], v141 offset:18432
	ds_read_b128 v[202:205], v141 offset:19456
	ds_read_b128 v[228:231], v141 offset:20480
	ds_read_b128 v[232:235], v141 offset:21504
	ds_read_b128 v[236:239], v141 offset:22528
	ds_read_b128 v[240:243], v141 offset:23552
	buffer_load_dwordx4 v137, s[44:47], s26 offen lds
	s_mov_b32 m0, s16
	s_add_i32 s49, s26, 0x80000
	buffer_load_dwordx4 v139, s[44:47], s26 offen lds
	s_mov_b32 m0, s18
	s_nop 0
	buffer_load_dwordx4 v137, s[44:47], s49 offen lds
	s_mov_b32 m0, s19
	s_nop 0
	buffer_load_dwordx4 v139, s[44:47], s49 offen lds
	s_mov_b32 m0, s14
	s_nop 0
	buffer_load_dwordx4 v136, s[60:63], s27 offen lds
	s_mov_b32 m0, s24
	s_nop 0
	buffer_load_dwordx4 v138, s[60:63], s27 offen lds
	s_waitcnt vmcnt(8)
	s_waitcnt lgkmcnt(0)
	s_setprio 1
	s_barrier
	v_mfma_f32_16x16x32_bf16 v[62:65], v[132:135], v[190:193], v[62:65]
	v_mfma_f32_16x16x32_bf16 v[46:49], v[132:135], v[198:201], v[46:49]
	v_mfma_f32_16x16x32_bf16 v[30:33], v[132:135], v[228:231], v[30:33]
	v_mfma_f32_16x16x32_bf16 v[14:17], v[132:135], v[236:239], v[14:17]
	v_mfma_f32_16x16x32_bf16 v[58:61], v[154:157], v[190:193], v[58:61]
	v_mfma_f32_16x16x32_bf16 v[42:45], v[154:157], v[198:201], v[42:45]
	v_mfma_f32_16x16x32_bf16 v[26:29], v[154:157], v[228:231], v[26:29]
	v_mfma_f32_16x16x32_bf16 v[10:13], v[154:157], v[236:239], v[10:13]
	v_mfma_f32_16x16x32_bf16 v[62:65], v[142:145], v[194:197], v[62:65]
	v_mfma_f32_16x16x32_bf16 v[46:49], v[142:145], v[202:205], v[46:49]
	v_mfma_f32_16x16x32_bf16 v[30:33], v[142:145], v[232:235], v[30:33]
	v_mfma_f32_16x16x32_bf16 v[14:17], v[142:145], v[240:243], v[14:17]
	v_mfma_f32_16x16x32_bf16 v[58:61], v[170:173], v[194:197], v[58:61]
	v_mfma_f32_16x16x32_bf16 v[42:45], v[170:173], v[202:205], v[42:45]
	v_mfma_f32_16x16x32_bf16 v[26:29], v[170:173], v[232:235], v[26:29]
	v_mfma_f32_16x16x32_bf16 v[10:13], v[170:173], v[240:243], v[10:13]
	v_mfma_f32_16x16x32_bf16 v[54:57], v[174:177], v[190:193], v[54:57]
	v_mfma_f32_16x16x32_bf16 v[38:41], v[174:177], v[198:201], v[38:41]
	v_mfma_f32_16x16x32_bf16 v[22:25], v[174:177], v[228:231], v[22:25]
	v_mfma_f32_16x16x32_bf16 v[6:9], v[174:177], v[236:239], v[6:9]
	v_mfma_f32_16x16x32_bf16 v[50:53], v[182:185], v[190:193], v[50:53]
	v_mfma_f32_16x16x32_bf16 v[34:37], v[182:185], v[198:201], v[34:37]
	v_mfma_f32_16x16x32_bf16 v[18:21], v[182:185], v[228:231], v[18:21]
	v_mfma_f32_16x16x32_bf16 v[2:5], v[182:185], v[236:239], v[2:5]
	v_mfma_f32_16x16x32_bf16 v[54:57], v[178:181], v[194:197], v[54:57]
	v_mfma_f32_16x16x32_bf16 v[38:41], v[178:181], v[202:205], v[38:41]
	v_mfma_f32_16x16x32_bf16 v[22:25], v[178:181], v[232:235], v[22:25]
	v_mfma_f32_16x16x32_bf16 v[6:9], v[178:181], v[240:243], v[6:9]
	v_mfma_f32_16x16x32_bf16 v[50:53], v[186:189], v[194:197], v[50:53]
	v_mfma_f32_16x16x32_bf16 v[34:37], v[186:189], v[202:205], v[34:37]
	v_mfma_f32_16x16x32_bf16 v[18:21], v[186:189], v[232:235], v[18:21]
	v_mfma_f32_16x16x32_bf16 v[2:5], v[186:189], v[240:243], v[2:5]
	s_barrier
	s_setprio 0
	v_add_u32_e32 v170, 0x18000, v140
	v_add_u32_e32 v186, 0x1c000, v140
	ds_read_b128 v[132:135], v170
	ds_read_b128 v[142:145], v170 offset:1024
	ds_read_b128 v[154:157], v170 offset:2048
	ds_read_b128 v[170:173], v170 offset:3072
	ds_read_b128 v[174:177], v186
	ds_read_b128 v[178:181], v186 offset:1024
	ds_read_b128 v[182:185], v186 offset:2048
	ds_read_b128 v[186:189], v186 offset:3072
	s_add_i32 s27, s27, 0x80000
	s_mov_b32 m0, s25
	ds_read_b128 v[190:193], v141 offset:32768
	ds_read_b128 v[194:197], v141 offset:33792
	ds_read_b128 v[198:201], v141 offset:34816
	ds_read_b128 v[202:205], v141 offset:35840
	ds_read_b128 v[228:231], v141 offset:36864
	ds_read_b128 v[232:235], v141 offset:37888
	ds_read_b128 v[236:239], v141 offset:38912
	ds_read_b128 v[240:243], v141 offset:39936
	buffer_load_dwordx4 v136, s[60:63], s27 offen lds
	s_mov_b32 m0, s30
	s_nop 0
	buffer_load_dwordx4 v138, s[60:63], s27 offen lds
	s_waitcnt vmcnt(8)
	s_waitcnt lgkmcnt(0)
	s_setprio 1
	s_barrier
	v_mfma_f32_16x16x32_bf16 v[126:129], v[132:135], v[190:193], v[126:129]
	v_mfma_f32_16x16x32_bf16 v[118:121], v[132:135], v[198:201], v[118:121]
	v_mfma_f32_16x16x32_bf16 v[94:97], v[132:135], v[228:231], v[94:97]
	v_mfma_f32_16x16x32_bf16 v[78:81], v[132:135], v[236:239], v[78:81]
	v_mfma_f32_16x16x32_bf16 v[106:109], v[154:157], v[190:193], v[106:109]
	v_mfma_f32_16x16x32_bf16 v[114:117], v[154:157], v[198:201], v[114:117]
	v_mfma_f32_16x16x32_bf16 v[90:93], v[154:157], v[228:231], v[90:93]
	v_mfma_f32_16x16x32_bf16 v[74:77], v[154:157], v[236:239], v[74:77]
	v_mfma_f32_16x16x32_bf16 v[126:129], v[142:145], v[194:197], v[126:129]
	v_mfma_f32_16x16x32_bf16 v[118:121], v[142:145], v[202:205], v[118:121]
	v_mfma_f32_16x16x32_bf16 v[94:97], v[142:145], v[232:235], v[94:97]
	v_mfma_f32_16x16x32_bf16 v[78:81], v[142:145], v[240:243], v[78:81]
	v_mfma_f32_16x16x32_bf16 v[106:109], v[170:173], v[194:197], v[106:109]
	v_mfma_f32_16x16x32_bf16 v[114:117], v[170:173], v[202:205], v[114:117]
	v_mfma_f32_16x16x32_bf16 v[90:93], v[170:173], v[232:235], v[90:93]
	v_mfma_f32_16x16x32_bf16 v[74:77], v[170:173], v[240:243], v[74:77]
	v_mfma_f32_16x16x32_bf16 v[122:125], v[174:177], v[190:193], v[122:125]
	v_mfma_f32_16x16x32_bf16 v[102:105], v[174:177], v[198:201], v[102:105]
	v_mfma_f32_16x16x32_bf16 v[86:89], v[174:177], v[228:231], v[86:89]
	v_mfma_f32_16x16x32_bf16 v[70:73], v[174:177], v[236:239], v[70:73]
	v_mfma_f32_16x16x32_bf16 v[110:113], v[182:185], v[190:193], v[110:113]
	v_mfma_f32_16x16x32_bf16 v[98:101], v[182:185], v[198:201], v[98:101]
	v_mfma_f32_16x16x32_bf16 v[82:85], v[182:185], v[228:231], v[82:85]
	v_mfma_f32_16x16x32_bf16 v[66:69], v[182:185], v[236:239], v[66:69]
	v_mfma_f32_16x16x32_bf16 v[122:125], v[178:181], v[194:197], v[122:125]
	v_mfma_f32_16x16x32_bf16 v[102:105], v[178:181], v[202:205], v[102:105]
	v_mfma_f32_16x16x32_bf16 v[86:89], v[178:181], v[232:235], v[86:89]
	v_mfma_f32_16x16x32_bf16 v[70:73], v[178:181], v[240:243], v[70:73]
	v_mfma_f32_16x16x32_bf16 v[110:113], v[186:189], v[194:197], v[110:113]
	v_mfma_f32_16x16x32_bf16 v[98:101], v[186:189], v[202:205], v[98:101]
	v_mfma_f32_16x16x32_bf16 v[82:85], v[186:189], v[232:235], v[82:85]
	v_mfma_f32_16x16x32_bf16 v[66:69], v[186:189], v[240:243], v[66:69]
	s_barrier
	s_setprio 0
	s_mov_b32 m0, s36
	s_or_b32 s27, s26, 0x80
	ds_read_b128 v[190:193], v141 offset:49152
	ds_read_b128 v[194:197], v141 offset:50176
	ds_read_b128 v[198:201], v141 offset:51200
	ds_read_b128 v[202:205], v141 offset:52224
	ds_read_b128 v[228:231], v141 offset:53248
	ds_read_b128 v[232:235], v141 offset:54272
	ds_read_b128 v[236:239], v141 offset:55296
	ds_read_b128 v[240:243], v141 offset:56320
	buffer_load_dwordx4 v137, s[44:47], s27 offen lds
	s_mov_b32 m0, s37
	s_add_i32 s26, s26, 0x80080
	buffer_load_dwordx4 v139, s[44:47], s27 offen lds
	s_mov_b32 m0, s68
	s_nop 0
	buffer_load_dwordx4 v137, s[44:47], s26 offen lds
	s_mov_b32 m0, s69
	s_nop 0
	buffer_load_dwordx4 v139, s[44:47], s26 offen lds
	s_mov_b32 m0, s66
	s_nop 0
	buffer_load_dwordx4 v136, s[60:63], s23 offen lds
	s_mov_b32 m0, s67
	s_nop 0
	buffer_load_dwordx4 v138, s[60:63], s23 offen lds
	s_waitcnt vmcnt(8)
	s_waitcnt lgkmcnt(0)
	s_setprio 1
	s_barrier
	v_mfma_f32_16x16x32_bf16 v[62:65], v[132:135], v[190:193], v[62:65]
	v_mfma_f32_16x16x32_bf16 v[46:49], v[132:135], v[198:201], v[46:49]
	v_mfma_f32_16x16x32_bf16 v[30:33], v[132:135], v[228:231], v[30:33]
	v_mfma_f32_16x16x32_bf16 v[14:17], v[132:135], v[236:239], v[14:17]
	v_mfma_f32_16x16x32_bf16 v[58:61], v[154:157], v[190:193], v[58:61]
	v_mfma_f32_16x16x32_bf16 v[42:45], v[154:157], v[198:201], v[42:45]
	v_mfma_f32_16x16x32_bf16 v[26:29], v[154:157], v[228:231], v[26:29]
	v_mfma_f32_16x16x32_bf16 v[10:13], v[154:157], v[236:239], v[10:13]
	v_mfma_f32_16x16x32_bf16 v[62:65], v[142:145], v[194:197], v[62:65]
	v_mfma_f32_16x16x32_bf16 v[46:49], v[142:145], v[202:205], v[46:49]
	v_mfma_f32_16x16x32_bf16 v[30:33], v[142:145], v[232:235], v[30:33]
	v_mfma_f32_16x16x32_bf16 v[14:17], v[142:145], v[240:243], v[14:17]
	v_mfma_f32_16x16x32_bf16 v[58:61], v[170:173], v[194:197], v[58:61]
	v_mfma_f32_16x16x32_bf16 v[42:45], v[170:173], v[202:205], v[42:45]
	v_mfma_f32_16x16x32_bf16 v[26:29], v[170:173], v[232:235], v[26:29]
	v_mfma_f32_16x16x32_bf16 v[10:13], v[170:173], v[240:243], v[10:13]
	v_mfma_f32_16x16x32_bf16 v[54:57], v[174:177], v[190:193], v[54:57]
	v_mfma_f32_16x16x32_bf16 v[38:41], v[174:177], v[198:201], v[38:41]
	v_mfma_f32_16x16x32_bf16 v[22:25], v[174:177], v[228:231], v[22:25]
	v_mfma_f32_16x16x32_bf16 v[6:9], v[174:177], v[236:239], v[6:9]
	v_mfma_f32_16x16x32_bf16 v[50:53], v[182:185], v[190:193], v[50:53]
	v_mfma_f32_16x16x32_bf16 v[34:37], v[182:185], v[198:201], v[34:37]
	v_mfma_f32_16x16x32_bf16 v[18:21], v[182:185], v[228:231], v[18:21]
	v_mfma_f32_16x16x32_bf16 v[2:5], v[182:185], v[236:239], v[2:5]
	v_mfma_f32_16x16x32_bf16 v[54:57], v[178:181], v[194:197], v[54:57]
	v_mfma_f32_16x16x32_bf16 v[38:41], v[178:181], v[202:205], v[38:41]
	v_mfma_f32_16x16x32_bf16 v[22:25], v[178:181], v[232:235], v[22:25]
	v_mfma_f32_16x16x32_bf16 v[6:9], v[178:181], v[240:243], v[6:9]
	v_mfma_f32_16x16x32_bf16 v[50:53], v[186:189], v[194:197], v[50:53]
	v_mfma_f32_16x16x32_bf16 v[34:37], v[186:189], v[202:205], v[34:37]
	v_mfma_f32_16x16x32_bf16 v[18:21], v[186:189], v[232:235], v[18:21]
	v_mfma_f32_16x16x32_bf16 v[2:5], v[186:189], v[240:243], v[2:5]
	s_barrier
	s_setprio 0
	s_add_i32 s22, s22, 2
	s_addk_i32 s13, 0x100
	s_addk_i32 s21, 0x100
	s_cmp_gt_u32 s22, 29
	s_cbranch_scc0 .LBB0_1589
	s_and_b64 vcc, exec, s[64:65]
	s_cbranch_vccz .LBB0_1592
	s_barrier

.LBB0_1879:
	s_lshl_b32 s18, s91, 20
	s_and_b64 s[8:9], s[48:49], exec
	s_cselect_b32 s8, s18, s95
	s_lshl_b32 s19, s92, 20
	s_and_b64 s[42:43], s[48:49], exec
	s_cselect_b32 s9, s19, s94
	s_add_i32 vcc_lo, s95, 0x80080
	s_add_i32 vcc_hi, s94, 0x100
	s_mov_b32 s94, -2
	v_add_u32_e32 v139, 0x10000, v136
	ds_read_b128 v[140:143], v139
	ds_read_b128 v[154:157], v139 offset:1024
	ds_read_b128 v[170:173], v139 offset:2048
	ds_read_b128 v[174:177], v139 offset:3072
	v_add_u32_e32 v139, 0x14000, v136
	ds_read_b128 v[178:181], v139
	ds_read_b128 v[182:185], v139 offset:1024
	ds_read_b128 v[186:189], v139 offset:2048
	ds_read_b128 v[190:193], v139 offset:3072
	s_add_i32 s42, vcc_lo, 0xfff80080
	s_cmp_eq_u32 s94, 28
	s_cselect_b32 s52, s8, s42
	s_cselect_b32 s96, s9, vcc_hi
	s_or_b32 s95, s52, 0x80
	s_mov_b32 m0, s72
	ds_read_b128 v[194:197], v137
	ds_read_b128 v[198:201], v137 offset:1024
	ds_read_b128 v[202:205], v137 offset:2048
	ds_read_b128 v[228:231], v137 offset:3072
	ds_read_b128 v[232:235], v137 offset:4096
	ds_read_b128 v[236:239], v137 offset:5120
	ds_read_b128 v[240:243], v137 offset:6144
	ds_read_b128 v[244:247], v137 offset:7168
	buffer_load_dwordx4 v132, s[60:63], vcc_lo offen lds
	s_mov_b32 m0, s47
	s_nop 0
	buffer_load_dwordx4 v134, s[60:63], vcc_lo offen lds
	s_waitcnt vmcnt(8)
	s_waitcnt lgkmcnt(0)
	s_setprio 1
	s_barrier
	v_mfma_f32_16x16x32_bf16 v[114:117], v[140:143], v[194:197], 0
	v_mfma_f32_16x16x32_bf16 v[106:109], v[140:143], v[202:205], 0
	v_mfma_f32_16x16x32_bf16 v[94:97], v[140:143], v[232:235], 0
	v_mfma_f32_16x16x32_bf16 v[78:81], v[140:143], v[240:243], 0
	v_mfma_f32_16x16x32_bf16 v[110:113], v[170:173], v[194:197], 0
	v_mfma_f32_16x16x32_bf16 v[102:105], v[170:173], v[202:205], 0
	v_mfma_f32_16x16x32_bf16 v[86:89], v[170:173], v[232:235], 0
	v_mfma_f32_16x16x32_bf16 v[70:73], v[170:173], v[240:243], 0
	v_mfma_f32_16x16x32_bf16 v[114:117], v[154:157], v[198:201], v[114:117]
	v_mfma_f32_16x16x32_bf16 v[106:109], v[154:157], v[228:231], v[106:109]
	v_mfma_f32_16x16x32_bf16 v[94:97], v[154:157], v[236:239], v[94:97]
	v_mfma_f32_16x16x32_bf16 v[78:81], v[154:157], v[244:247], v[78:81]
	v_mfma_f32_16x16x32_bf16 v[110:113], v[174:177], v[198:201], v[110:113]
	v_mfma_f32_16x16x32_bf16 v[102:105], v[174:177], v[228:231], v[102:105]
	v_mfma_f32_16x16x32_bf16 v[86:89], v[174:177], v[236:239], v[86:89]
	v_mfma_f32_16x16x32_bf16 v[70:73], v[174:177], v[244:247], v[70:73]
	v_mfma_f32_16x16x32_bf16 v[126:129], v[178:181], v[194:197], 0
	v_mfma_f32_16x16x32_bf16 v[118:121], v[178:181], v[202:205], 0
	v_mfma_f32_16x16x32_bf16 v[90:93], v[178:181], v[232:235], 0
	v_mfma_f32_16x16x32_bf16 v[74:77], v[178:181], v[240:243], 0
	v_mfma_f32_16x16x32_bf16 v[122:125], v[186:189], v[194:197], 0
	v_mfma_f32_16x16x32_bf16 v[98:101], v[186:189], v[202:205], 0
	v_mfma_f32_16x16x32_bf16 v[82:85], v[186:189], v[232:235], 0
	v_mfma_f32_16x16x32_bf16 v[66:69], v[186:189], v[240:243], 0
	v_mfma_f32_16x16x32_bf16 v[126:129], v[182:185], v[198:201], v[126:129]
	v_mfma_f32_16x16x32_bf16 v[118:121], v[182:185], v[228:231], v[118:121]
	v_mfma_f32_16x16x32_bf16 v[90:93], v[182:185], v[236:239], v[90:93]
	v_mfma_f32_16x16x32_bf16 v[74:77], v[182:185], v[244:247], v[74:77]
	v_mfma_f32_16x16x32_bf16 v[122:125], v[190:193], v[198:201], v[122:125]
	v_mfma_f32_16x16x32_bf16 v[98:101], v[190:193], v[228:231], v[98:101]
	v_mfma_f32_16x16x32_bf16 v[82:85], v[190:193], v[236:239], v[82:85]
	v_mfma_f32_16x16x32_bf16 v[66:69], v[190:193], v[244:247], v[66:69]
	s_barrier
	s_setprio 0
	s_mov_b32 m0, s13
	s_mov_b32 s42, s62
	s_mov_b32 s43, s63
	ds_read_b128 v[194:197], v137 offset:16384
	ds_read_b128 v[198:201], v137 offset:17408
	ds_read_b128 v[202:205], v137 offset:18432
	ds_read_b128 v[228:231], v137 offset:19456
	ds_read_b128 v[232:235], v137 offset:20480
	ds_read_b128 v[236:239], v137 offset:21504
	ds_read_b128 v[240:243], v137 offset:22528
	ds_read_b128 v[244:247], v137 offset:23552
	buffer_load_dwordx4 v133, s[40:43], s96 offen lds
	s_mov_b32 m0, s14
	s_add_i32 s53, s96, 0x80000
	buffer_load_dwordx4 v135, s[40:43], s96 offen lds
	s_mov_b32 m0, s15
	s_nop 0
	buffer_load_dwordx4 v133, s[40:43], s53 offen lds
	s_mov_b32 m0, s16
	s_nop 0
	buffer_load_dwordx4 v135, s[40:43], s53 offen lds
	s_mov_b32 m0, s2
	s_nop 0
	buffer_load_dwordx4 v132, s[60:63], s52 offen lds
	s_mov_b32 m0, s21
	s_nop 0
	buffer_load_dwordx4 v134, s[60:63], s52 offen lds
	s_waitcnt vmcnt(8)
	s_waitcnt lgkmcnt(0)
	s_setprio 1
	s_barrier
	v_mfma_f32_16x16x32_bf16 v[62:65], v[140:143], v[194:197], 0
	v_mfma_f32_16x16x32_bf16 v[46:49], v[140:143], v[202:205], 0
	v_mfma_f32_16x16x32_bf16 v[30:33], v[140:143], v[232:235], 0
	v_mfma_f32_16x16x32_bf16 v[14:17], v[140:143], v[240:243], 0
	v_mfma_f32_16x16x32_bf16 v[54:57], v[170:173], v[194:197], 0
	v_mfma_f32_16x16x32_bf16 v[38:41], v[170:173], v[202:205], 0
	v_mfma_f32_16x16x32_bf16 v[22:25], v[170:173], v[232:235], 0
	v_mfma_f32_16x16x32_bf16 v[6:9], v[170:173], v[240:243], 0
	v_mfma_f32_16x16x32_bf16 v[62:65], v[154:157], v[198:201], v[62:65]
	v_mfma_f32_16x16x32_bf16 v[46:49], v[154:157], v[228:231], v[46:49]
	v_mfma_f32_16x16x32_bf16 v[30:33], v[154:157], v[236:239], v[30:33]
	v_mfma_f32_16x16x32_bf16 v[14:17], v[154:157], v[244:247], v[14:17]
	v_mfma_f32_16x16x32_bf16 v[54:57], v[174:177], v[198:201], v[54:57]
	v_mfma_f32_16x16x32_bf16 v[38:41], v[174:177], v[228:231], v[38:41]
	v_mfma_f32_16x16x32_bf16 v[22:25], v[174:177], v[236:239], v[22:25]
	v_mfma_f32_16x16x32_bf16 v[6:9], v[174:177], v[244:247], v[6:9]
	v_mfma_f32_16x16x32_bf16 v[58:61], v[178:181], v[194:197], 0
	v_mfma_f32_16x16x32_bf16 v[42:45], v[178:181], v[202:205], 0
	v_mfma_f32_16x16x32_bf16 v[26:29], v[178:181], v[232:235], 0
	v_mfma_f32_16x16x32_bf16 v[10:13], v[178:181], v[240:243], 0
	v_mfma_f32_16x16x32_bf16 v[50:53], v[186:189], v[194:197], 0
	v_mfma_f32_16x16x32_bf16 v[34:37], v[186:189], v[202:205], 0
	v_mfma_f32_16x16x32_bf16 v[18:21], v[186:189], v[232:235], 0
	v_mfma_f32_16x16x32_bf16 v[2:5], v[186:189], v[240:243], 0
	v_mfma_f32_16x16x32_bf16 v[58:61], v[182:185], v[198:201], v[58:61]
	v_mfma_f32_16x16x32_bf16 v[42:45], v[182:185], v[228:231], v[42:45]
	v_mfma_f32_16x16x32_bf16 v[26:29], v[182:185], v[236:239], v[26:29]
	v_mfma_f32_16x16x32_bf16 v[10:13], v[182:185], v[244:247], v[10:13]
	v_mfma_f32_16x16x32_bf16 v[50:53], v[190:193], v[198:201], v[50:53]
	v_mfma_f32_16x16x32_bf16 v[34:37], v[190:193], v[228:231], v[34:37]
	v_mfma_f32_16x16x32_bf16 v[18:21], v[190:193], v[236:239], v[18:21]
	v_mfma_f32_16x16x32_bf16 v[2:5], v[190:193], v[244:247], v[2:5]
	s_barrier
	s_setprio 0
	v_add_u32_e32 v139, 0x18000, v136
	ds_read_b128 v[140:143], v139
	ds_read_b128 v[154:157], v139 offset:1024
	ds_read_b128 v[170:173], v139 offset:2048
	ds_read_b128 v[174:177], v139 offset:3072
	v_add_u32_e32 v139, 0x1c000, v136
	ds_read_b128 v[178:181], v139
	ds_read_b128 v[182:185], v139 offset:1024
	ds_read_b128 v[186:189], v139 offset:2048
	ds_read_b128 v[190:193], v139 offset:3072
	s_add_i32 s52, s52, 0x80000
	s_mov_b32 m0, s23
	ds_read_b128 v[194:197], v137 offset:32768
	ds_read_b128 v[198:201], v137 offset:33792
	ds_read_b128 v[202:205], v137 offset:34816
	ds_read_b128 v[228:231], v137 offset:35840
	ds_read_b128 v[232:235], v137 offset:36864
	ds_read_b128 v[236:239], v137 offset:37888
	ds_read_b128 v[240:243], v137 offset:38912
	ds_read_b128 v[244:247], v137 offset:39936
	buffer_load_dwordx4 v132, s[60:63], s52 offen lds
	s_mov_b32 m0, s24
	s_nop 0
	buffer_load_dwordx4 v134, s[60:63], s52 offen lds
	s_waitcnt vmcnt(8)
	s_waitcnt lgkmcnt(0)
	s_setprio 1
	s_barrier
	v_mfma_f32_16x16x32_bf16 v[114:117], v[140:143], v[194:197], v[114:117]
	v_mfma_f32_16x16x32_bf16 v[106:109], v[140:143], v[202:205], v[106:109]
	v_mfma_f32_16x16x32_bf16 v[94:97], v[140:143], v[232:235], v[94:97]
	v_mfma_f32_16x16x32_bf16 v[78:81], v[140:143], v[240:243], v[78:81]
	v_mfma_f32_16x16x32_bf16 v[110:113], v[170:173], v[194:197], v[110:113]
	v_mfma_f32_16x16x32_bf16 v[102:105], v[170:173], v[202:205], v[102:105]
	v_mfma_f32_16x16x32_bf16 v[86:89], v[170:173], v[232:235], v[86:89]
	v_mfma_f32_16x16x32_bf16 v[70:73], v[170:173], v[240:243], v[70:73]
	v_mfma_f32_16x16x32_bf16 v[114:117], v[154:157], v[198:201], v[114:117]
	v_mfma_f32_16x16x32_bf16 v[106:109], v[154:157], v[228:231], v[106:109]
	v_mfma_f32_16x16x32_bf16 v[94:97], v[154:157], v[236:239], v[94:97]
	v_mfma_f32_16x16x32_bf16 v[78:81], v[154:157], v[244:247], v[78:81]
	v_mfma_f32_16x16x32_bf16 v[110:113], v[174:177], v[198:201], v[110:113]
	v_mfma_f32_16x16x32_bf16 v[102:105], v[174:177], v[228:231], v[102:105]
	v_mfma_f32_16x16x32_bf16 v[86:89], v[174:177], v[236:239], v[86:89]
	v_mfma_f32_16x16x32_bf16 v[70:73], v[174:177], v[244:247], v[70:73]
	v_mfma_f32_16x16x32_bf16 v[126:129], v[178:181], v[194:197], v[126:129]
	v_mfma_f32_16x16x32_bf16 v[118:121], v[178:181], v[202:205], v[118:121]
	v_mfma_f32_16x16x32_bf16 v[90:93], v[178:181], v[232:235], v[90:93]
	v_mfma_f32_16x16x32_bf16 v[74:77], v[178:181], v[240:243], v[74:77]
	v_mfma_f32_16x16x32_bf16 v[122:125], v[186:189], v[194:197], v[122:125]
	v_mfma_f32_16x16x32_bf16 v[98:101], v[186:189], v[202:205], v[98:101]
	v_mfma_f32_16x16x32_bf16 v[82:85], v[186:189], v[232:235], v[82:85]
	v_mfma_f32_16x16x32_bf16 v[66:69], v[186:189], v[240:243], v[66:69]
	v_mfma_f32_16x16x32_bf16 v[126:129], v[182:185], v[198:201], v[126:129]
	v_mfma_f32_16x16x32_bf16 v[118:121], v[182:185], v[228:231], v[118:121]
	v_mfma_f32_16x16x32_bf16 v[90:93], v[182:185], v[236:239], v[90:93]
	v_mfma_f32_16x16x32_bf16 v[74:77], v[182:185], v[244:247], v[74:77]
	v_mfma_f32_16x16x32_bf16 v[122:125], v[190:193], v[198:201], v[122:125]
	v_mfma_f32_16x16x32_bf16 v[98:101], v[190:193], v[228:231], v[98:101]
	v_mfma_f32_16x16x32_bf16 v[82:85], v[190:193], v[236:239], v[82:85]
	v_mfma_f32_16x16x32_bf16 v[66:69], v[190:193], v[244:247], v[66:69]
	s_barrier
	s_setprio 0
	s_mov_b32 m0, s31
	s_or_b32 s52, s96, 0x80
	ds_read_b128 v[194:197], v137 offset:49152
	ds_read_b128 v[198:201], v137 offset:50176
	ds_read_b128 v[202:205], v137 offset:51200
	ds_read_b128 v[228:231], v137 offset:52224
	ds_read_b128 v[232:235], v137 offset:53248
	ds_read_b128 v[236:239], v137 offset:54272
	ds_read_b128 v[240:243], v137 offset:55296
	ds_read_b128 v[244:247], v137 offset:56320
	buffer_load_dwordx4 v133, s[40:43], s52 offen lds
	s_mov_b32 m0, s33
	s_add_i32 s96, s96, 0x80080
	buffer_load_dwordx4 v135, s[40:43], s52 offen lds
	s_mov_b32 m0, s36
	s_nop 0
	buffer_load_dwordx4 v133, s[40:43], s96 offen lds
	s_mov_b32 m0, s37
	s_nop 0
	buffer_load_dwordx4 v135, s[40:43], s96 offen lds
	s_mov_b32 m0, s34
	s_nop 0
	buffer_load_dwordx4 v132, s[60:63], s95 offen lds
	s_mov_b32 m0, s35
	s_nop 0
	buffer_load_dwordx4 v134, s[60:63], s95 offen lds
	s_waitcnt vmcnt(8)
	s_waitcnt lgkmcnt(0)
	s_setprio 1
	s_barrier
	v_mfma_f32_16x16x32_bf16 v[62:65], v[140:143], v[194:197], v[62:65]
	v_mfma_f32_16x16x32_bf16 v[46:49], v[140:143], v[202:205], v[46:49]
	v_mfma_f32_16x16x32_bf16 v[30:33], v[140:143], v[232:235], v[30:33]
	v_mfma_f32_16x16x32_bf16 v[14:17], v[140:143], v[240:243], v[14:17]
	v_mfma_f32_16x16x32_bf16 v[54:57], v[170:173], v[194:197], v[54:57]
	v_mfma_f32_16x16x32_bf16 v[38:41], v[170:173], v[202:205], v[38:41]
	v_mfma_f32_16x16x32_bf16 v[22:25], v[170:173], v[232:235], v[22:25]
	v_mfma_f32_16x16x32_bf16 v[6:9], v[170:173], v[240:243], v[6:9]
	v_mfma_f32_16x16x32_bf16 v[62:65], v[154:157], v[198:201], v[62:65]
	v_mfma_f32_16x16x32_bf16 v[46:49], v[154:157], v[228:231], v[46:49]
	v_mfma_f32_16x16x32_bf16 v[30:33], v[154:157], v[236:239], v[30:33]
	v_mfma_f32_16x16x32_bf16 v[14:17], v[154:157], v[244:247], v[14:17]
	v_mfma_f32_16x16x32_bf16 v[54:57], v[174:177], v[198:201], v[54:57]
	v_mfma_f32_16x16x32_bf16 v[38:41], v[174:177], v[228:231], v[38:41]
	v_mfma_f32_16x16x32_bf16 v[22:25], v[174:177], v[236:239], v[22:25]
	v_mfma_f32_16x16x32_bf16 v[6:9], v[174:177], v[244:247], v[6:9]
	v_mfma_f32_16x16x32_bf16 v[58:61], v[178:181], v[194:197], v[58:61]
	v_mfma_f32_16x16x32_bf16 v[42:45], v[178:181], v[202:205], v[42:45]
	v_mfma_f32_16x16x32_bf16 v[26:29], v[178:181], v[232:235], v[26:29]
	v_mfma_f32_16x16x32_bf16 v[10:13], v[178:181], v[240:243], v[10:13]
	v_mfma_f32_16x16x32_bf16 v[50:53], v[186:189], v[194:197], v[50:53]
	v_mfma_f32_16x16x32_bf16 v[34:37], v[186:189], v[202:205], v[34:37]
	v_mfma_f32_16x16x32_bf16 v[18:21], v[186:189], v[232:235], v[18:21]
	v_mfma_f32_16x16x32_bf16 v[2:5], v[186:189], v[240:243], v[2:5]
	v_mfma_f32_16x16x32_bf16 v[58:61], v[182:185], v[198:201], v[58:61]
	v_mfma_f32_16x16x32_bf16 v[42:45], v[182:185], v[228:231], v[42:45]
	v_mfma_f32_16x16x32_bf16 v[26:29], v[182:185], v[236:239], v[26:29]
	v_mfma_f32_16x16x32_bf16 v[10:13], v[182:185], v[244:247], v[10:13]
	v_mfma_f32_16x16x32_bf16 v[50:53], v[190:193], v[198:201], v[50:53]
	v_mfma_f32_16x16x32_bf16 v[34:37], v[190:193], v[228:231], v[34:37]
	v_mfma_f32_16x16x32_bf16 v[18:21], v[190:193], v[236:239], v[18:21]
	v_mfma_f32_16x16x32_bf16 v[2:5], v[190:193], v[244:247], v[2:5]
	s_barrier
	s_setprio 0
	s_add_i32 s94, s94, 2
	s_addk_i32 vcc_lo, 0x100
	s_addk_i32 vcc_hi, 0x100
	s_cmp_gt_u32 s94, 29
.LBB0_1880:
	v_add_u32_e32 v139, 0x10000, v136
	ds_read_b128 v[140:143], v139
	ds_read_b128 v[154:157], v139 offset:1024
	ds_read_b128 v[170:173], v139 offset:2048
	ds_read_b128 v[174:177], v139 offset:3072
	v_add_u32_e32 v139, 0x14000, v136
	ds_read_b128 v[178:181], v139
	ds_read_b128 v[182:185], v139 offset:1024
	ds_read_b128 v[186:189], v139 offset:2048
	ds_read_b128 v[190:193], v139 offset:3072
	s_add_i32 s42, vcc_lo, 0xfff80080
	s_cmp_eq_u32 s94, 28
	s_cselect_b32 s52, s8, s42
	s_cselect_b32 s96, s9, vcc_hi
	s_or_b32 s95, s52, 0x80
	s_mov_b32 m0, s72
	ds_read_b128 v[194:197], v137
	ds_read_b128 v[198:201], v137 offset:1024
	ds_read_b128 v[202:205], v137 offset:2048
	ds_read_b128 v[228:231], v137 offset:3072
	ds_read_b128 v[232:235], v137 offset:4096
	ds_read_b128 v[236:239], v137 offset:5120
	ds_read_b128 v[240:243], v137 offset:6144
	ds_read_b128 v[244:247], v137 offset:7168
	buffer_load_dwordx4 v132, s[60:63], vcc_lo offen lds
	s_mov_b32 m0, s47
	s_nop 0
	buffer_load_dwordx4 v134, s[60:63], vcc_lo offen lds
	s_waitcnt vmcnt(8)
	s_waitcnt lgkmcnt(0)
	s_setprio 1
	s_barrier
	v_mfma_f32_16x16x32_bf16 v[114:117], v[140:143], v[194:197], v[114:117]
	v_mfma_f32_16x16x32_bf16 v[106:109], v[140:143], v[202:205], v[106:109]
	v_mfma_f32_16x16x32_bf16 v[94:97], v[140:143], v[232:235], v[94:97]
	v_mfma_f32_16x16x32_bf16 v[78:81], v[140:143], v[240:243], v[78:81]
	v_mfma_f32_16x16x32_bf16 v[110:113], v[170:173], v[194:197], v[110:113]
	v_mfma_f32_16x16x32_bf16 v[102:105], v[170:173], v[202:205], v[102:105]
	v_mfma_f32_16x16x32_bf16 v[86:89], v[170:173], v[232:235], v[86:89]
	v_mfma_f32_16x16x32_bf16 v[70:73], v[170:173], v[240:243], v[70:73]
	v_mfma_f32_16x16x32_bf16 v[114:117], v[154:157], v[198:201], v[114:117]
	v_mfma_f32_16x16x32_bf16 v[106:109], v[154:157], v[228:231], v[106:109]
	v_mfma_f32_16x16x32_bf16 v[94:97], v[154:157], v[236:239], v[94:97]
	v_mfma_f32_16x16x32_bf16 v[78:81], v[154:157], v[244:247], v[78:81]
	v_mfma_f32_16x16x32_bf16 v[110:113], v[174:177], v[198:201], v[110:113]
	v_mfma_f32_16x16x32_bf16 v[102:105], v[174:177], v[228:231], v[102:105]
	v_mfma_f32_16x16x32_bf16 v[86:89], v[174:177], v[236:239], v[86:89]
	v_mfma_f32_16x16x32_bf16 v[70:73], v[174:177], v[244:247], v[70:73]
	v_mfma_f32_16x16x32_bf16 v[126:129], v[178:181], v[194:197], v[126:129]
	v_mfma_f32_16x16x32_bf16 v[118:121], v[178:181], v[202:205], v[118:121]
	v_mfma_f32_16x16x32_bf16 v[90:93], v[178:181], v[232:235], v[90:93]
	v_mfma_f32_16x16x32_bf16 v[74:77], v[178:181], v[240:243], v[74:77]
	v_mfma_f32_16x16x32_bf16 v[122:125], v[186:189], v[194:197], v[122:125]
	v_mfma_f32_16x16x32_bf16 v[98:101], v[186:189], v[202:205], v[98:101]
	v_mfma_f32_16x16x32_bf16 v[82:85], v[186:189], v[232:235], v[82:85]
	v_mfma_f32_16x16x32_bf16 v[66:69], v[186:189], v[240:243], v[66:69]
	v_mfma_f32_16x16x32_bf16 v[126:129], v[182:185], v[198:201], v[126:129]
	v_mfma_f32_16x16x32_bf16 v[118:121], v[182:185], v[228:231], v[118:121]
	v_mfma_f32_16x16x32_bf16 v[90:93], v[182:185], v[236:239], v[90:93]
	v_mfma_f32_16x16x32_bf16 v[74:77], v[182:185], v[244:247], v[74:77]
	v_mfma_f32_16x16x32_bf16 v[122:125], v[190:193], v[198:201], v[122:125]
	v_mfma_f32_16x16x32_bf16 v[98:101], v[190:193], v[228:231], v[98:101]
	v_mfma_f32_16x16x32_bf16 v[82:85], v[190:193], v[236:239], v[82:85]
	v_mfma_f32_16x16x32_bf16 v[66:69], v[190:193], v[244:247], v[66:69]
	s_barrier
	s_setprio 0
	s_mov_b32 m0, s13
	s_mov_b32 s42, s62
	s_mov_b32 s43, s63
	ds_read_b128 v[194:197], v137 offset:16384
	ds_read_b128 v[198:201], v137 offset:17408
	ds_read_b128 v[202:205], v137 offset:18432
	ds_read_b128 v[228:231], v137 offset:19456
	ds_read_b128 v[232:235], v137 offset:20480
	ds_read_b128 v[236:239], v137 offset:21504
	ds_read_b128 v[240:243], v137 offset:22528
	ds_read_b128 v[244:247], v137 offset:23552
	buffer_load_dwordx4 v133, s[40:43], s96 offen lds
	s_mov_b32 m0, s14
	s_add_i32 s53, s96, 0x80000
	buffer_load_dwordx4 v135, s[40:43], s96 offen lds
	s_mov_b32 m0, s15
	s_nop 0
	buffer_load_dwordx4 v133, s[40:43], s53 offen lds
	s_mov_b32 m0, s16
	s_nop 0
	buffer_load_dwordx4 v135, s[40:43], s53 offen lds
	s_mov_b32 m0, s2
	s_nop 0
	buffer_load_dwordx4 v132, s[60:63], s52 offen lds
	s_mov_b32 m0, s21
	s_nop 0
	buffer_load_dwordx4 v134, s[60:63], s52 offen lds
	s_waitcnt vmcnt(8)
	s_waitcnt lgkmcnt(0)
	s_setprio 1
	s_barrier
	v_mfma_f32_16x16x32_bf16 v[62:65], v[140:143], v[194:197], v[62:65]
	v_mfma_f32_16x16x32_bf16 v[46:49], v[140:143], v[202:205], v[46:49]
	v_mfma_f32_16x16x32_bf16 v[30:33], v[140:143], v[232:235], v[30:33]
	v_mfma_f32_16x16x32_bf16 v[14:17], v[140:143], v[240:243], v[14:17]
	v_mfma_f32_16x16x32_bf16 v[54:57], v[170:173], v[194:197], v[54:57]
	v_mfma_f32_16x16x32_bf16 v[38:41], v[170:173], v[202:205], v[38:41]
	v_mfma_f32_16x16x32_bf16 v[22:25], v[170:173], v[232:235], v[22:25]
	v_mfma_f32_16x16x32_bf16 v[6:9], v[170:173], v[240:243], v[6:9]
	v_mfma_f32_16x16x32_bf16 v[62:65], v[154:157], v[198:201], v[62:65]
	v_mfma_f32_16x16x32_bf16 v[46:49], v[154:157], v[228:231], v[46:49]
	v_mfma_f32_16x16x32_bf16 v[30:33], v[154:157], v[236:239], v[30:33]
	v_mfma_f32_16x16x32_bf16 v[14:17], v[154:157], v[244:247], v[14:17]
	v_mfma_f32_16x16x32_bf16 v[54:57], v[174:177], v[198:201], v[54:57]
	v_mfma_f32_16x16x32_bf16 v[38:41], v[174:177], v[228:231], v[38:41]
	v_mfma_f32_16x16x32_bf16 v[22:25], v[174:177], v[236:239], v[22:25]
	v_mfma_f32_16x16x32_bf16 v[6:9], v[174:177], v[244:247], v[6:9]
	v_mfma_f32_16x16x32_bf16 v[58:61], v[178:181], v[194:197], v[58:61]
	v_mfma_f32_16x16x32_bf16 v[42:45], v[178:181], v[202:205], v[42:45]
	v_mfma_f32_16x16x32_bf16 v[26:29], v[178:181], v[232:235], v[26:29]
	v_mfma_f32_16x16x32_bf16 v[10:13], v[178:181], v[240:243], v[10:13]
	v_mfma_f32_16x16x32_bf16 v[50:53], v[186:189], v[194:197], v[50:53]
	v_mfma_f32_16x16x32_bf16 v[34:37], v[186:189], v[202:205], v[34:37]
	v_mfma_f32_16x16x32_bf16 v[18:21], v[186:189], v[232:235], v[18:21]
	v_mfma_f32_16x16x32_bf16 v[2:5], v[186:189], v[240:243], v[2:5]
	v_mfma_f32_16x16x32_bf16 v[58:61], v[182:185], v[198:201], v[58:61]
	v_mfma_f32_16x16x32_bf16 v[42:45], v[182:185], v[228:231], v[42:45]
	v_mfma_f32_16x16x32_bf16 v[26:29], v[182:185], v[236:239], v[26:29]
	v_mfma_f32_16x16x32_bf16 v[10:13], v[182:185], v[244:247], v[10:13]
	v_mfma_f32_16x16x32_bf16 v[50:53], v[190:193], v[198:201], v[50:53]
	v_mfma_f32_16x16x32_bf16 v[34:37], v[190:193], v[228:231], v[34:37]
	v_mfma_f32_16x16x32_bf16 v[18:21], v[190:193], v[236:239], v[18:21]
	v_mfma_f32_16x16x32_bf16 v[2:5], v[190:193], v[244:247], v[2:5]
	s_barrier
	s_setprio 0
	v_add_u32_e32 v139, 0x18000, v136
	ds_read_b128 v[140:143], v139
	ds_read_b128 v[154:157], v139 offset:1024
	ds_read_b128 v[170:173], v139 offset:2048
	ds_read_b128 v[174:177], v139 offset:3072
	v_add_u32_e32 v139, 0x1c000, v136
	ds_read_b128 v[178:181], v139
	ds_read_b128 v[182:185], v139 offset:1024
	ds_read_b128 v[186:189], v139 offset:2048
	ds_read_b128 v[190:193], v139 offset:3072
	s_add_i32 s52, s52, 0x80000
	s_mov_b32 m0, s23
	ds_read_b128 v[194:197], v137 offset:32768
	ds_read_b128 v[198:201], v137 offset:33792
	ds_read_b128 v[202:205], v137 offset:34816
	ds_read_b128 v[228:231], v137 offset:35840
	ds_read_b128 v[232:235], v137 offset:36864
	ds_read_b128 v[236:239], v137 offset:37888
	ds_read_b128 v[240:243], v137 offset:38912
	ds_read_b128 v[244:247], v137 offset:39936
	buffer_load_dwordx4 v132, s[60:63], s52 offen lds
	s_mov_b32 m0, s24
	s_nop 0
	buffer_load_dwordx4 v134, s[60:63], s52 offen lds
	s_waitcnt vmcnt(8)
	s_waitcnt lgkmcnt(0)
	s_setprio 1
	s_barrier
	v_mfma_f32_16x16x32_bf16 v[114:117], v[140:143], v[194:197], v[114:117]
	v_mfma_f32_16x16x32_bf16 v[106:109], v[140:143], v[202:205], v[106:109]
	v_mfma_f32_16x16x32_bf16 v[94:97], v[140:143], v[232:235], v[94:97]
	v_mfma_f32_16x16x32_bf16 v[78:81], v[140:143], v[240:243], v[78:81]
	v_mfma_f32_16x16x32_bf16 v[110:113], v[170:173], v[194:197], v[110:113]
	v_mfma_f32_16x16x32_bf16 v[102:105], v[170:173], v[202:205], v[102:105]
	v_mfma_f32_16x16x32_bf16 v[86:89], v[170:173], v[232:235], v[86:89]
	v_mfma_f32_16x16x32_bf16 v[70:73], v[170:173], v[240:243], v[70:73]
	v_mfma_f32_16x16x32_bf16 v[114:117], v[154:157], v[198:201], v[114:117]
	v_mfma_f32_16x16x32_bf16 v[106:109], v[154:157], v[228:231], v[106:109]
	v_mfma_f32_16x16x32_bf16 v[94:97], v[154:157], v[236:239], v[94:97]
	v_mfma_f32_16x16x32_bf16 v[78:81], v[154:157], v[244:247], v[78:81]
	v_mfma_f32_16x16x32_bf16 v[110:113], v[174:177], v[198:201], v[110:113]
	v_mfma_f32_16x16x32_bf16 v[102:105], v[174:177], v[228:231], v[102:105]
	v_mfma_f32_16x16x32_bf16 v[86:89], v[174:177], v[236:239], v[86:89]
	v_mfma_f32_16x16x32_bf16 v[70:73], v[174:177], v[244:247], v[70:73]
	v_mfma_f32_16x16x32_bf16 v[126:129], v[178:181], v[194:197], v[126:129]
	v_mfma_f32_16x16x32_bf16 v[118:121], v[178:181], v[202:205], v[118:121]
	v_mfma_f32_16x16x32_bf16 v[90:93], v[178:181], v[232:235], v[90:93]
	v_mfma_f32_16x16x32_bf16 v[74:77], v[178:181], v[240:243], v[74:77]
	v_mfma_f32_16x16x32_bf16 v[122:125], v[186:189], v[194:197], v[122:125]
	v_mfma_f32_16x16x32_bf16 v[98:101], v[186:189], v[202:205], v[98:101]
	v_mfma_f32_16x16x32_bf16 v[82:85], v[186:189], v[232:235], v[82:85]
	v_mfma_f32_16x16x32_bf16 v[66:69], v[186:189], v[240:243], v[66:69]
	v_mfma_f32_16x16x32_bf16 v[126:129], v[182:185], v[198:201], v[126:129]
	v_mfma_f32_16x16x32_bf16 v[118:121], v[182:185], v[228:231], v[118:121]
	v_mfma_f32_16x16x32_bf16 v[90:93], v[182:185], v[236:239], v[90:93]
	v_mfma_f32_16x16x32_bf16 v[74:77], v[182:185], v[244:247], v[74:77]
	v_mfma_f32_16x16x32_bf16 v[122:125], v[190:193], v[198:201], v[122:125]
	v_mfma_f32_16x16x32_bf16 v[98:101], v[190:193], v[228:231], v[98:101]
	v_mfma_f32_16x16x32_bf16 v[82:85], v[190:193], v[236:239], v[82:85]
	v_mfma_f32_16x16x32_bf16 v[66:69], v[190:193], v[244:247], v[66:69]
	s_barrier
	s_setprio 0
	s_mov_b32 m0, s31
	s_or_b32 s52, s96, 0x80
	ds_read_b128 v[194:197], v137 offset:49152
	ds_read_b128 v[198:201], v137 offset:50176
	ds_read_b128 v[202:205], v137 offset:51200
	ds_read_b128 v[228:231], v137 offset:52224
	ds_read_b128 v[232:235], v137 offset:53248
	ds_read_b128 v[236:239], v137 offset:54272
	ds_read_b128 v[240:243], v137 offset:55296
	ds_read_b128 v[244:247], v137 offset:56320
	buffer_load_dwordx4 v133, s[40:43], s52 offen lds
	s_mov_b32 m0, s33
	s_add_i32 s96, s96, 0x80080
	buffer_load_dwordx4 v135, s[40:43], s52 offen lds
	s_mov_b32 m0, s36
	s_nop 0
	buffer_load_dwordx4 v133, s[40:43], s96 offen lds
	s_mov_b32 m0, s37
	s_nop 0
	buffer_load_dwordx4 v135, s[40:43], s96 offen lds
	s_mov_b32 m0, s34
	s_nop 0
	buffer_load_dwordx4 v132, s[60:63], s95 offen lds
	s_mov_b32 m0, s35
	s_nop 0
	buffer_load_dwordx4 v134, s[60:63], s95 offen lds
	s_waitcnt vmcnt(8)
	s_waitcnt lgkmcnt(0)
	s_setprio 1
	s_barrier
	v_mfma_f32_16x16x32_bf16 v[62:65], v[140:143], v[194:197], v[62:65]
	v_mfma_f32_16x16x32_bf16 v[46:49], v[140:143], v[202:205], v[46:49]
	v_mfma_f32_16x16x32_bf16 v[30:33], v[140:143], v[232:235], v[30:33]
	v_mfma_f32_16x16x32_bf16 v[14:17], v[140:143], v[240:243], v[14:17]
	v_mfma_f32_16x16x32_bf16 v[54:57], v[170:173], v[194:197], v[54:57]
	v_mfma_f32_16x16x32_bf16 v[38:41], v[170:173], v[202:205], v[38:41]
	v_mfma_f32_16x16x32_bf16 v[22:25], v[170:173], v[232:235], v[22:25]
	v_mfma_f32_16x16x32_bf16 v[6:9], v[170:173], v[240:243], v[6:9]
	v_mfma_f32_16x16x32_bf16 v[62:65], v[154:157], v[198:201], v[62:65]
	v_mfma_f32_16x16x32_bf16 v[46:49], v[154:157], v[228:231], v[46:49]
	v_mfma_f32_16x16x32_bf16 v[30:33], v[154:157], v[236:239], v[30:33]
	v_mfma_f32_16x16x32_bf16 v[14:17], v[154:157], v[244:247], v[14:17]
	v_mfma_f32_16x16x32_bf16 v[54:57], v[174:177], v[198:201], v[54:57]
	v_mfma_f32_16x16x32_bf16 v[38:41], v[174:177], v[228:231], v[38:41]
	v_mfma_f32_16x16x32_bf16 v[22:25], v[174:177], v[236:239], v[22:25]
	v_mfma_f32_16x16x32_bf16 v[6:9], v[174:177], v[244:247], v[6:9]
	v_mfma_f32_16x16x32_bf16 v[58:61], v[178:181], v[194:197], v[58:61]
	v_mfma_f32_16x16x32_bf16 v[42:45], v[178:181], v[202:205], v[42:45]
	v_mfma_f32_16x16x32_bf16 v[26:29], v[178:181], v[232:235], v[26:29]
	v_mfma_f32_16x16x32_bf16 v[10:13], v[178:181], v[240:243], v[10:13]
	v_mfma_f32_16x16x32_bf16 v[50:53], v[186:189], v[194:197], v[50:53]
	v_mfma_f32_16x16x32_bf16 v[34:37], v[186:189], v[202:205], v[34:37]
	v_mfma_f32_16x16x32_bf16 v[18:21], v[186:189], v[232:235], v[18:21]
	v_mfma_f32_16x16x32_bf16 v[2:5], v[186:189], v[240:243], v[2:5]
	v_mfma_f32_16x16x32_bf16 v[58:61], v[182:185], v[198:201], v[58:61]
	v_mfma_f32_16x16x32_bf16 v[42:45], v[182:185], v[228:231], v[42:45]
	v_mfma_f32_16x16x32_bf16 v[26:29], v[182:185], v[236:239], v[26:29]
	v_mfma_f32_16x16x32_bf16 v[10:13], v[182:185], v[244:247], v[10:13]
	v_mfma_f32_16x16x32_bf16 v[50:53], v[190:193], v[198:201], v[50:53]
	v_mfma_f32_16x16x32_bf16 v[34:37], v[190:193], v[228:231], v[34:37]
	v_mfma_f32_16x16x32_bf16 v[18:21], v[190:193], v[236:239], v[18:21]
	v_mfma_f32_16x16x32_bf16 v[2:5], v[190:193], v[244:247], v[2:5]
	s_barrier
	s_setprio 0
	s_add_i32 s94, s94, 2
	s_addk_i32 vcc_lo, 0x100
	s_addk_i32 vcc_hi, 0x100
	s_cmp_gt_u32 s94, 29
	s_cbranch_scc0 .LBB0_1880
	s_and_b64 vcc, exec, s[64:65]
	s_cbranch_vccz .LBB0_1883
	s_barrier

.LBB0_2155:
	s_mul_i32 s49, s48, 0x2c0000
	s_and_b64 s[8:9], s[42:43], exec
	s_mul_i32 s23, s15, 0x2c0000
	s_cselect_b32 s8, s49, s21
	s_cselect_b32 s9, s23, s13
	s_addk_i32 s13, 0x100
	s_add_i32 s21, s21, 0xc000
	s_mov_b32 s22, -2
	s_waitcnt lgkmcnt(0)
	v_add_u32_e32 v170, 0x10000, v140
	v_add_u32_e32 v186, 0x14000, v140
	ds_read_b128 v[132:135], v170
	ds_read_b128 v[142:145], v170 offset:1024
	ds_read_b128 v[154:157], v170 offset:2048
	ds_read_b128 v[170:173], v170 offset:3072
	ds_read_b128 v[174:177], v186
	ds_read_b128 v[178:181], v186 offset:1024
	ds_read_b128 v[182:185], v186 offset:2048
	ds_read_b128 v[186:189], v186 offset:3072
	s_add_i32 s26, s21, 0x4000
	s_cmpk_eq_i32 s22, 0x54
	s_cselect_b32 s52, s8, s26
	s_cselect_b32 s27, s9, s13
	s_or_b32 s26, s52, 0x8000
	s_mov_b32 m0, s84
	ds_read_b128 v[190:193], v141
	ds_read_b128 v[194:197], v141 offset:1024
	ds_read_b128 v[198:201], v141 offset:2048
	ds_read_b128 v[202:205], v141 offset:3072
	ds_read_b128 v[228:231], v141 offset:4096
	ds_read_b128 v[232:235], v141 offset:5120
	ds_read_b128 v[236:239], v141 offset:6144
	ds_read_b128 v[240:243], v141 offset:7168
	buffer_load_dwordx4 v136, s[60:63], s21 offen lds
	s_mov_b32 m0, s16
	s_nop 0
	buffer_load_dwordx4 v138, s[60:63], s21 offen lds
	s_waitcnt vmcnt(8)
	s_waitcnt lgkmcnt(0)
	s_setprio 1
	s_barrier
	v_mfma_f32_16x16x32_bf16 v[126:129], v[132:135], v[190:193], 0
	v_mfma_f32_16x16x32_bf16 v[118:121], v[132:135], v[198:201], 0
	v_mfma_f32_16x16x32_bf16 v[94:97], v[132:135], v[228:231], 0
	v_mfma_f32_16x16x32_bf16 v[78:81], v[132:135], v[236:239], 0
	v_mfma_f32_16x16x32_bf16 v[106:109], v[154:157], v[190:193], 0
	v_mfma_f32_16x16x32_bf16 v[114:117], v[154:157], v[198:201], 0
	v_mfma_f32_16x16x32_bf16 v[90:93], v[154:157], v[228:231], 0
	v_mfma_f32_16x16x32_bf16 v[74:77], v[154:157], v[236:239], 0
	v_mfma_f32_16x16x32_bf16 v[126:129], v[142:145], v[194:197], v[126:129]
	v_mfma_f32_16x16x32_bf16 v[118:121], v[142:145], v[202:205], v[118:121]
	v_mfma_f32_16x16x32_bf16 v[94:97], v[142:145], v[232:235], v[94:97]
	v_mfma_f32_16x16x32_bf16 v[78:81], v[142:145], v[240:243], v[78:81]
	v_mfma_f32_16x16x32_bf16 v[106:109], v[170:173], v[194:197], v[106:109]
	v_mfma_f32_16x16x32_bf16 v[114:117], v[170:173], v[202:205], v[114:117]
	v_mfma_f32_16x16x32_bf16 v[90:93], v[170:173], v[232:235], v[90:93]
	v_mfma_f32_16x16x32_bf16 v[74:77], v[170:173], v[240:243], v[74:77]
	v_mfma_f32_16x16x32_bf16 v[122:125], v[174:177], v[190:193], 0
	v_mfma_f32_16x16x32_bf16 v[102:105], v[174:177], v[198:201], 0
	v_mfma_f32_16x16x32_bf16 v[86:89], v[174:177], v[228:231], 0
	v_mfma_f32_16x16x32_bf16 v[70:73], v[174:177], v[236:239], 0
	v_mfma_f32_16x16x32_bf16 v[110:113], v[182:185], v[190:193], 0
	v_mfma_f32_16x16x32_bf16 v[98:101], v[182:185], v[198:201], 0
	v_mfma_f32_16x16x32_bf16 v[82:85], v[182:185], v[228:231], 0
	v_mfma_f32_16x16x32_bf16 v[66:69], v[182:185], v[236:239], 0
	v_mfma_f32_16x16x32_bf16 v[122:125], v[178:181], v[194:197], v[122:125]
	v_mfma_f32_16x16x32_bf16 v[102:105], v[178:181], v[202:205], v[102:105]
	v_mfma_f32_16x16x32_bf16 v[86:89], v[178:181], v[232:235], v[86:89]
	v_mfma_f32_16x16x32_bf16 v[70:73], v[178:181], v[240:243], v[70:73]
	v_mfma_f32_16x16x32_bf16 v[110:113], v[186:189], v[194:197], v[110:113]
	v_mfma_f32_16x16x32_bf16 v[98:101], v[186:189], v[202:205], v[98:101]
	v_mfma_f32_16x16x32_bf16 v[82:85], v[186:189], v[232:235], v[82:85]
	v_mfma_f32_16x16x32_bf16 v[66:69], v[186:189], v[240:243], v[66:69]
	s_barrier
	s_setprio 0
	s_mov_b32 m0, s18
	s_mov_b32 s46, s62
	s_mov_b32 s47, s63
	ds_read_b128 v[190:193], v141 offset:16384
	ds_read_b128 v[194:197], v141 offset:17408
	ds_read_b128 v[198:201], v141 offset:18432
	ds_read_b128 v[202:205], v141 offset:19456
	ds_read_b128 v[228:231], v141 offset:20480
	ds_read_b128 v[232:235], v141 offset:21504
	ds_read_b128 v[236:239], v141 offset:22528
	ds_read_b128 v[240:243], v141 offset:23552
	buffer_load_dwordx4 v137, s[44:47], s27 offen lds
	s_mov_b32 m0, s19
	s_add_i32 s53, s27, 0x160000
	buffer_load_dwordx4 v139, s[44:47], s27 offen lds
	s_mov_b32 m0, s24
	s_nop 0
	buffer_load_dwordx4 v137, s[44:47], s53 offen lds
	s_mov_b32 m0, s25
	s_nop 0
	buffer_load_dwordx4 v139, s[44:47], s53 offen lds
	s_mov_b32 m0, s14
	s_nop 0
	buffer_load_dwordx4 v136, s[60:63], s52 offen lds
	s_mov_b32 m0, s30
	s_nop 0
	buffer_load_dwordx4 v138, s[60:63], s52 offen lds
	s_waitcnt vmcnt(8)
	s_waitcnt lgkmcnt(0)
	s_setprio 1
	s_barrier
	v_mfma_f32_16x16x32_bf16 v[62:65], v[132:135], v[190:193], 0
	v_mfma_f32_16x16x32_bf16 v[46:49], v[132:135], v[198:201], 0
	v_mfma_f32_16x16x32_bf16 v[30:33], v[132:135], v[228:231], 0
	v_mfma_f32_16x16x32_bf16 v[14:17], v[132:135], v[236:239], 0
	v_mfma_f32_16x16x32_bf16 v[58:61], v[154:157], v[190:193], 0
	v_mfma_f32_16x16x32_bf16 v[42:45], v[154:157], v[198:201], 0
	v_mfma_f32_16x16x32_bf16 v[26:29], v[154:157], v[228:231], 0
	v_mfma_f32_16x16x32_bf16 v[10:13], v[154:157], v[236:239], 0
	v_mfma_f32_16x16x32_bf16 v[62:65], v[142:145], v[194:197], v[62:65]
	v_mfma_f32_16x16x32_bf16 v[46:49], v[142:145], v[202:205], v[46:49]
	v_mfma_f32_16x16x32_bf16 v[30:33], v[142:145], v[232:235], v[30:33]
	v_mfma_f32_16x16x32_bf16 v[14:17], v[142:145], v[240:243], v[14:17]
	v_mfma_f32_16x16x32_bf16 v[58:61], v[170:173], v[194:197], v[58:61]
	v_mfma_f32_16x16x32_bf16 v[42:45], v[170:173], v[202:205], v[42:45]
	v_mfma_f32_16x16x32_bf16 v[26:29], v[170:173], v[232:235], v[26:29]
	v_mfma_f32_16x16x32_bf16 v[10:13], v[170:173], v[240:243], v[10:13]
	v_mfma_f32_16x16x32_bf16 v[54:57], v[174:177], v[190:193], 0
	v_mfma_f32_16x16x32_bf16 v[38:41], v[174:177], v[198:201], 0
	v_mfma_f32_16x16x32_bf16 v[22:25], v[174:177], v[228:231], 0
	v_mfma_f32_16x16x32_bf16 v[6:9], v[174:177], v[236:239], 0
	v_mfma_f32_16x16x32_bf16 v[50:53], v[182:185], v[190:193], 0
	v_mfma_f32_16x16x32_bf16 v[34:37], v[182:185], v[198:201], 0
	v_mfma_f32_16x16x32_bf16 v[18:21], v[182:185], v[228:231], 0
	v_mfma_f32_16x16x32_bf16 v[2:5], v[182:185], v[236:239], 0
	v_mfma_f32_16x16x32_bf16 v[54:57], v[178:181], v[194:197], v[54:57]
	v_mfma_f32_16x16x32_bf16 v[38:41], v[178:181], v[202:205], v[38:41]
	v_mfma_f32_16x16x32_bf16 v[22:25], v[178:181], v[232:235], v[22:25]
	v_mfma_f32_16x16x32_bf16 v[6:9], v[178:181], v[240:243], v[6:9]
	v_mfma_f32_16x16x32_bf16 v[50:53], v[186:189], v[194:197], v[50:53]
	v_mfma_f32_16x16x32_bf16 v[34:37], v[186:189], v[202:205], v[34:37]
	v_mfma_f32_16x16x32_bf16 v[18:21], v[186:189], v[232:235], v[18:21]
	v_mfma_f32_16x16x32_bf16 v[2:5], v[186:189], v[240:243], v[2:5]
	s_barrier
	s_setprio 0
	v_add_u32_e32 v170, 0x18000, v140
	v_add_u32_e32 v186, 0x1c000, v140
	ds_read_b128 v[132:135], v170
	ds_read_b128 v[142:145], v170 offset:1024
	ds_read_b128 v[154:157], v170 offset:2048
	ds_read_b128 v[170:173], v170 offset:3072
	ds_read_b128 v[174:177], v186
	ds_read_b128 v[178:181], v186 offset:1024
	ds_read_b128 v[182:185], v186 offset:2048
	ds_read_b128 v[186:189], v186 offset:3072
	s_bitset1_b32 s52, 14
	s_mov_b32 m0, s31
	ds_read_b128 v[190:193], v141 offset:32768
	ds_read_b128 v[194:197], v141 offset:33792
	ds_read_b128 v[198:201], v141 offset:34816
	ds_read_b128 v[202:205], v141 offset:35840
	ds_read_b128 v[228:231], v141 offset:36864
	ds_read_b128 v[232:235], v141 offset:37888
	ds_read_b128 v[236:239], v141 offset:38912
	ds_read_b128 v[240:243], v141 offset:39936
	buffer_load_dwordx4 v136, s[60:63], s52 offen lds
	s_mov_b32 m0, s33
	s_nop 0
	buffer_load_dwordx4 v138, s[60:63], s52 offen lds
	s_waitcnt vmcnt(8)
	s_waitcnt lgkmcnt(0)
	s_setprio 1
	s_barrier
	v_mfma_f32_16x16x32_bf16 v[126:129], v[132:135], v[190:193], v[126:129]
	v_mfma_f32_16x16x32_bf16 v[118:121], v[132:135], v[198:201], v[118:121]
	v_mfma_f32_16x16x32_bf16 v[94:97], v[132:135], v[228:231], v[94:97]
	v_mfma_f32_16x16x32_bf16 v[78:81], v[132:135], v[236:239], v[78:81]
	v_mfma_f32_16x16x32_bf16 v[106:109], v[154:157], v[190:193], v[106:109]
	v_mfma_f32_16x16x32_bf16 v[114:117], v[154:157], v[198:201], v[114:117]
	v_mfma_f32_16x16x32_bf16 v[90:93], v[154:157], v[228:231], v[90:93]
	v_mfma_f32_16x16x32_bf16 v[74:77], v[154:157], v[236:239], v[74:77]
	v_mfma_f32_16x16x32_bf16 v[126:129], v[142:145], v[194:197], v[126:129]
	v_mfma_f32_16x16x32_bf16 v[118:121], v[142:145], v[202:205], v[118:121]
	v_mfma_f32_16x16x32_bf16 v[94:97], v[142:145], v[232:235], v[94:97]
	v_mfma_f32_16x16x32_bf16 v[78:81], v[142:145], v[240:243], v[78:81]
	v_mfma_f32_16x16x32_bf16 v[106:109], v[170:173], v[194:197], v[106:109]
	v_mfma_f32_16x16x32_bf16 v[114:117], v[170:173], v[202:205], v[114:117]
	v_mfma_f32_16x16x32_bf16 v[90:93], v[170:173], v[232:235], v[90:93]
	v_mfma_f32_16x16x32_bf16 v[74:77], v[170:173], v[240:243], v[74:77]
	v_mfma_f32_16x16x32_bf16 v[122:125], v[174:177], v[190:193], v[122:125]
	v_mfma_f32_16x16x32_bf16 v[102:105], v[174:177], v[198:201], v[102:105]
	v_mfma_f32_16x16x32_bf16 v[86:89], v[174:177], v[228:231], v[86:89]
	v_mfma_f32_16x16x32_bf16 v[70:73], v[174:177], v[236:239], v[70:73]
	v_mfma_f32_16x16x32_bf16 v[110:113], v[182:185], v[190:193], v[110:113]
	v_mfma_f32_16x16x32_bf16 v[98:101], v[182:185], v[198:201], v[98:101]
	v_mfma_f32_16x16x32_bf16 v[82:85], v[182:185], v[228:231], v[82:85]
	v_mfma_f32_16x16x32_bf16 v[66:69], v[182:185], v[236:239], v[66:69]
	v_mfma_f32_16x16x32_bf16 v[122:125], v[178:181], v[194:197], v[122:125]
	v_mfma_f32_16x16x32_bf16 v[102:105], v[178:181], v[202:205], v[102:105]
	v_mfma_f32_16x16x32_bf16 v[86:89], v[178:181], v[232:235], v[86:89]
	v_mfma_f32_16x16x32_bf16 v[70:73], v[178:181], v[240:243], v[70:73]
	v_mfma_f32_16x16x32_bf16 v[110:113], v[186:189], v[194:197], v[110:113]
	v_mfma_f32_16x16x32_bf16 v[98:101], v[186:189], v[202:205], v[98:101]
	v_mfma_f32_16x16x32_bf16 v[82:85], v[186:189], v[232:235], v[82:85]
	v_mfma_f32_16x16x32_bf16 v[66:69], v[186:189], v[240:243], v[66:69]
	s_barrier
	s_setprio 0
	s_mov_b32 m0, s68
	s_or_b32 s52, s27, 0x80
	ds_read_b128 v[190:193], v141 offset:49152
	ds_read_b128 v[194:197], v141 offset:50176
	ds_read_b128 v[198:201], v141 offset:51200
	ds_read_b128 v[202:205], v141 offset:52224
	ds_read_b128 v[228:231], v141 offset:53248
	ds_read_b128 v[232:235], v141 offset:54272
	ds_read_b128 v[236:239], v141 offset:55296
	ds_read_b128 v[240:243], v141 offset:56320
	buffer_load_dwordx4 v137, s[44:47], s52 offen lds
	s_mov_b32 m0, s69
	s_add_i32 s27, s27, 0x160080
	buffer_load_dwordx4 v139, s[44:47], s52 offen lds
	s_mov_b32 m0, s72
	s_nop 0
	buffer_load_dwordx4 v137, s[44:47], s27 offen lds
	s_mov_b32 m0, s73
	s_nop 0
	buffer_load_dwordx4 v139, s[44:47], s27 offen lds
	s_mov_b32 m0, s70
	s_nop 0
	buffer_load_dwordx4 v136, s[60:63], s26 offen lds
	s_mov_b32 m0, s71
	s_nop 0
	buffer_load_dwordx4 v138, s[60:63], s26 offen lds
	s_waitcnt vmcnt(8)
	s_waitcnt lgkmcnt(0)
	s_setprio 1
	s_barrier
	v_mfma_f32_16x16x32_bf16 v[62:65], v[132:135], v[190:193], v[62:65]
	v_mfma_f32_16x16x32_bf16 v[46:49], v[132:135], v[198:201], v[46:49]
	v_mfma_f32_16x16x32_bf16 v[30:33], v[132:135], v[228:231], v[30:33]
	v_mfma_f32_16x16x32_bf16 v[14:17], v[132:135], v[236:239], v[14:17]
	v_mfma_f32_16x16x32_bf16 v[58:61], v[154:157], v[190:193], v[58:61]
	v_mfma_f32_16x16x32_bf16 v[42:45], v[154:157], v[198:201], v[42:45]
	v_mfma_f32_16x16x32_bf16 v[26:29], v[154:157], v[228:231], v[26:29]
	v_mfma_f32_16x16x32_bf16 v[10:13], v[154:157], v[236:239], v[10:13]
	v_mfma_f32_16x16x32_bf16 v[62:65], v[142:145], v[194:197], v[62:65]
	v_mfma_f32_16x16x32_bf16 v[46:49], v[142:145], v[202:205], v[46:49]
	v_mfma_f32_16x16x32_bf16 v[30:33], v[142:145], v[232:235], v[30:33]
	v_mfma_f32_16x16x32_bf16 v[14:17], v[142:145], v[240:243], v[14:17]
	v_mfma_f32_16x16x32_bf16 v[58:61], v[170:173], v[194:197], v[58:61]
	v_mfma_f32_16x16x32_bf16 v[42:45], v[170:173], v[202:205], v[42:45]
	v_mfma_f32_16x16x32_bf16 v[26:29], v[170:173], v[232:235], v[26:29]
	v_mfma_f32_16x16x32_bf16 v[10:13], v[170:173], v[240:243], v[10:13]
	v_mfma_f32_16x16x32_bf16 v[54:57], v[174:177], v[190:193], v[54:57]
	v_mfma_f32_16x16x32_bf16 v[38:41], v[174:177], v[198:201], v[38:41]
	v_mfma_f32_16x16x32_bf16 v[22:25], v[174:177], v[228:231], v[22:25]
	v_mfma_f32_16x16x32_bf16 v[6:9], v[174:177], v[236:239], v[6:9]
	v_mfma_f32_16x16x32_bf16 v[50:53], v[182:185], v[190:193], v[50:53]
	v_mfma_f32_16x16x32_bf16 v[34:37], v[182:185], v[198:201], v[34:37]
	v_mfma_f32_16x16x32_bf16 v[18:21], v[182:185], v[228:231], v[18:21]
	v_mfma_f32_16x16x32_bf16 v[2:5], v[182:185], v[236:239], v[2:5]
	v_mfma_f32_16x16x32_bf16 v[54:57], v[178:181], v[194:197], v[54:57]
	v_mfma_f32_16x16x32_bf16 v[38:41], v[178:181], v[202:205], v[38:41]
	v_mfma_f32_16x16x32_bf16 v[22:25], v[178:181], v[232:235], v[22:25]
	v_mfma_f32_16x16x32_bf16 v[6:9], v[178:181], v[240:243], v[6:9]
	v_mfma_f32_16x16x32_bf16 v[50:53], v[186:189], v[194:197], v[50:53]
	v_mfma_f32_16x16x32_bf16 v[34:37], v[186:189], v[202:205], v[34:37]
	v_mfma_f32_16x16x32_bf16 v[18:21], v[186:189], v[232:235], v[18:21]
	v_mfma_f32_16x16x32_bf16 v[2:5], v[186:189], v[240:243], v[2:5]
	s_barrier
	s_setprio 0
	s_addk_i32 s13, 0x100
	s_add_i32 s22, s22, 2
	s_add_i32 s21, s21, 0x10000
	s_cmpk_gt_u32 s22, 0x55
.LBB0_2156:
	v_add_u32_e32 v170, 0x10000, v140
	v_add_u32_e32 v186, 0x14000, v140
	ds_read_b128 v[132:135], v170
	ds_read_b128 v[142:145], v170 offset:1024
	ds_read_b128 v[154:157], v170 offset:2048
	ds_read_b128 v[170:173], v170 offset:3072
	ds_read_b128 v[174:177], v186
	ds_read_b128 v[178:181], v186 offset:1024
	ds_read_b128 v[182:185], v186 offset:2048
	ds_read_b128 v[186:189], v186 offset:3072
	s_add_i32 s26, s21, 0x4000
	s_cmpk_eq_i32 s22, 0x54
	s_cselect_b32 s52, s8, s26
	s_cselect_b32 s27, s9, s13
	s_or_b32 s26, s52, 0x8000
	s_mov_b32 m0, s84
	ds_read_b128 v[190:193], v141
	ds_read_b128 v[194:197], v141 offset:1024
	ds_read_b128 v[198:201], v141 offset:2048
	ds_read_b128 v[202:205], v141 offset:3072
	ds_read_b128 v[228:231], v141 offset:4096
	ds_read_b128 v[232:235], v141 offset:5120
	ds_read_b128 v[236:239], v141 offset:6144
	ds_read_b128 v[240:243], v141 offset:7168
	buffer_load_dwordx4 v136, s[60:63], s21 offen lds
	s_mov_b32 m0, s16
	s_nop 0
	buffer_load_dwordx4 v138, s[60:63], s21 offen lds
	s_waitcnt vmcnt(8)
	s_waitcnt lgkmcnt(0)
	s_setprio 1
	s_barrier
	v_mfma_f32_16x16x32_bf16 v[126:129], v[132:135], v[190:193], v[126:129]
	v_mfma_f32_16x16x32_bf16 v[118:121], v[132:135], v[198:201], v[118:121]
	v_mfma_f32_16x16x32_bf16 v[94:97], v[132:135], v[228:231], v[94:97]
	v_mfma_f32_16x16x32_bf16 v[78:81], v[132:135], v[236:239], v[78:81]
	v_mfma_f32_16x16x32_bf16 v[106:109], v[154:157], v[190:193], v[106:109]
	v_mfma_f32_16x16x32_bf16 v[114:117], v[154:157], v[198:201], v[114:117]
	v_mfma_f32_16x16x32_bf16 v[90:93], v[154:157], v[228:231], v[90:93]
	v_mfma_f32_16x16x32_bf16 v[74:77], v[154:157], v[236:239], v[74:77]
	v_mfma_f32_16x16x32_bf16 v[126:129], v[142:145], v[194:197], v[126:129]
	v_mfma_f32_16x16x32_bf16 v[118:121], v[142:145], v[202:205], v[118:121]
	v_mfma_f32_16x16x32_bf16 v[94:97], v[142:145], v[232:235], v[94:97]
	v_mfma_f32_16x16x32_bf16 v[78:81], v[142:145], v[240:243], v[78:81]
	v_mfma_f32_16x16x32_bf16 v[106:109], v[170:173], v[194:197], v[106:109]
	v_mfma_f32_16x16x32_bf16 v[114:117], v[170:173], v[202:205], v[114:117]
	v_mfma_f32_16x16x32_bf16 v[90:93], v[170:173], v[232:235], v[90:93]
	v_mfma_f32_16x16x32_bf16 v[74:77], v[170:173], v[240:243], v[74:77]
	v_mfma_f32_16x16x32_bf16 v[122:125], v[174:177], v[190:193], v[122:125]
	v_mfma_f32_16x16x32_bf16 v[102:105], v[174:177], v[198:201], v[102:105]
	v_mfma_f32_16x16x32_bf16 v[86:89], v[174:177], v[228:231], v[86:89]
	v_mfma_f32_16x16x32_bf16 v[70:73], v[174:177], v[236:239], v[70:73]
	v_mfma_f32_16x16x32_bf16 v[110:113], v[182:185], v[190:193], v[110:113]
	v_mfma_f32_16x16x32_bf16 v[98:101], v[182:185], v[198:201], v[98:101]
	v_mfma_f32_16x16x32_bf16 v[82:85], v[182:185], v[228:231], v[82:85]
	v_mfma_f32_16x16x32_bf16 v[66:69], v[182:185], v[236:239], v[66:69]
	v_mfma_f32_16x16x32_bf16 v[122:125], v[178:181], v[194:197], v[122:125]
	v_mfma_f32_16x16x32_bf16 v[102:105], v[178:181], v[202:205], v[102:105]
	v_mfma_f32_16x16x32_bf16 v[86:89], v[178:181], v[232:235], v[86:89]
	v_mfma_f32_16x16x32_bf16 v[70:73], v[178:181], v[240:243], v[70:73]
	v_mfma_f32_16x16x32_bf16 v[110:113], v[186:189], v[194:197], v[110:113]
	v_mfma_f32_16x16x32_bf16 v[98:101], v[186:189], v[202:205], v[98:101]
	v_mfma_f32_16x16x32_bf16 v[82:85], v[186:189], v[232:235], v[82:85]
	v_mfma_f32_16x16x32_bf16 v[66:69], v[186:189], v[240:243], v[66:69]
	s_barrier
	s_setprio 0
	s_mov_b32 m0, s18
	s_mov_b32 s46, s62
	s_mov_b32 s47, s63
	ds_read_b128 v[190:193], v141 offset:16384
	ds_read_b128 v[194:197], v141 offset:17408
	ds_read_b128 v[198:201], v141 offset:18432
	ds_read_b128 v[202:205], v141 offset:19456
	ds_read_b128 v[228:231], v141 offset:20480
	ds_read_b128 v[232:235], v141 offset:21504
	ds_read_b128 v[236:239], v141 offset:22528
	ds_read_b128 v[240:243], v141 offset:23552
	buffer_load_dwordx4 v137, s[44:47], s27 offen lds
	s_mov_b32 m0, s19
	s_add_i32 s53, s27, 0x160000
	buffer_load_dwordx4 v139, s[44:47], s27 offen lds
	s_mov_b32 m0, s24
	s_nop 0
	buffer_load_dwordx4 v137, s[44:47], s53 offen lds
	s_mov_b32 m0, s25
	s_nop 0
	buffer_load_dwordx4 v139, s[44:47], s53 offen lds
	s_mov_b32 m0, s14
	s_nop 0
	buffer_load_dwordx4 v136, s[60:63], s52 offen lds
	s_mov_b32 m0, s30
	s_nop 0
	buffer_load_dwordx4 v138, s[60:63], s52 offen lds
	s_waitcnt vmcnt(8)
	s_waitcnt lgkmcnt(0)
	s_setprio 1
	s_barrier
	v_mfma_f32_16x16x32_bf16 v[62:65], v[132:135], v[190:193], v[62:65]
	v_mfma_f32_16x16x32_bf16 v[46:49], v[132:135], v[198:201], v[46:49]
	v_mfma_f32_16x16x32_bf16 v[30:33], v[132:135], v[228:231], v[30:33]
	v_mfma_f32_16x16x32_bf16 v[14:17], v[132:135], v[236:239], v[14:17]
	v_mfma_f32_16x16x32_bf16 v[58:61], v[154:157], v[190:193], v[58:61]
	v_mfma_f32_16x16x32_bf16 v[42:45], v[154:157], v[198:201], v[42:45]
	v_mfma_f32_16x16x32_bf16 v[26:29], v[154:157], v[228:231], v[26:29]
	v_mfma_f32_16x16x32_bf16 v[10:13], v[154:157], v[236:239], v[10:13]
	v_mfma_f32_16x16x32_bf16 v[62:65], v[142:145], v[194:197], v[62:65]
	v_mfma_f32_16x16x32_bf16 v[46:49], v[142:145], v[202:205], v[46:49]
	v_mfma_f32_16x16x32_bf16 v[30:33], v[142:145], v[232:235], v[30:33]
	v_mfma_f32_16x16x32_bf16 v[14:17], v[142:145], v[240:243], v[14:17]
	v_mfma_f32_16x16x32_bf16 v[58:61], v[170:173], v[194:197], v[58:61]
	v_mfma_f32_16x16x32_bf16 v[42:45], v[170:173], v[202:205], v[42:45]
	v_mfma_f32_16x16x32_bf16 v[26:29], v[170:173], v[232:235], v[26:29]
	v_mfma_f32_16x16x32_bf16 v[10:13], v[170:173], v[240:243], v[10:13]
	v_mfma_f32_16x16x32_bf16 v[54:57], v[174:177], v[190:193], v[54:57]
	v_mfma_f32_16x16x32_bf16 v[38:41], v[174:177], v[198:201], v[38:41]
	v_mfma_f32_16x16x32_bf16 v[22:25], v[174:177], v[228:231], v[22:25]
	v_mfma_f32_16x16x32_bf16 v[6:9], v[174:177], v[236:239], v[6:9]
	v_mfma_f32_16x16x32_bf16 v[50:53], v[182:185], v[190:193], v[50:53]
	v_mfma_f32_16x16x32_bf16 v[34:37], v[182:185], v[198:201], v[34:37]
	v_mfma_f32_16x16x32_bf16 v[18:21], v[182:185], v[228:231], v[18:21]
	v_mfma_f32_16x16x32_bf16 v[2:5], v[182:185], v[236:239], v[2:5]
	v_mfma_f32_16x16x32_bf16 v[54:57], v[178:181], v[194:197], v[54:57]
	v_mfma_f32_16x16x32_bf16 v[38:41], v[178:181], v[202:205], v[38:41]
	v_mfma_f32_16x16x32_bf16 v[22:25], v[178:181], v[232:235], v[22:25]
	v_mfma_f32_16x16x32_bf16 v[6:9], v[178:181], v[240:243], v[6:9]
	v_mfma_f32_16x16x32_bf16 v[50:53], v[186:189], v[194:197], v[50:53]
	v_mfma_f32_16x16x32_bf16 v[34:37], v[186:189], v[202:205], v[34:37]
	v_mfma_f32_16x16x32_bf16 v[18:21], v[186:189], v[232:235], v[18:21]
	v_mfma_f32_16x16x32_bf16 v[2:5], v[186:189], v[240:243], v[2:5]
	s_barrier
	s_setprio 0
	v_add_u32_e32 v170, 0x18000, v140
	v_add_u32_e32 v186, 0x1c000, v140
	ds_read_b128 v[132:135], v170
	ds_read_b128 v[142:145], v170 offset:1024
	ds_read_b128 v[154:157], v170 offset:2048
	ds_read_b128 v[170:173], v170 offset:3072
	ds_read_b128 v[174:177], v186
	ds_read_b128 v[178:181], v186 offset:1024
	ds_read_b128 v[182:185], v186 offset:2048
	ds_read_b128 v[186:189], v186 offset:3072
	s_bitset1_b32 s52, 14
	s_mov_b32 m0, s31
	ds_read_b128 v[190:193], v141 offset:32768
	ds_read_b128 v[194:197], v141 offset:33792
	ds_read_b128 v[198:201], v141 offset:34816
	ds_read_b128 v[202:205], v141 offset:35840
	ds_read_b128 v[228:231], v141 offset:36864
	ds_read_b128 v[232:235], v141 offset:37888
	ds_read_b128 v[236:239], v141 offset:38912
	ds_read_b128 v[240:243], v141 offset:39936
	buffer_load_dwordx4 v136, s[60:63], s52 offen lds
	s_mov_b32 m0, s33
	s_nop 0
	buffer_load_dwordx4 v138, s[60:63], s52 offen lds
	s_waitcnt vmcnt(8)
	s_waitcnt lgkmcnt(0)
	s_setprio 1
	s_barrier
	v_mfma_f32_16x16x32_bf16 v[126:129], v[132:135], v[190:193], v[126:129]
	v_mfma_f32_16x16x32_bf16 v[118:121], v[132:135], v[198:201], v[118:121]
	v_mfma_f32_16x16x32_bf16 v[94:97], v[132:135], v[228:231], v[94:97]
	v_mfma_f32_16x16x32_bf16 v[78:81], v[132:135], v[236:239], v[78:81]
	v_mfma_f32_16x16x32_bf16 v[106:109], v[154:157], v[190:193], v[106:109]
	v_mfma_f32_16x16x32_bf16 v[114:117], v[154:157], v[198:201], v[114:117]
	v_mfma_f32_16x16x32_bf16 v[90:93], v[154:157], v[228:231], v[90:93]
	v_mfma_f32_16x16x32_bf16 v[74:77], v[154:157], v[236:239], v[74:77]
	v_mfma_f32_16x16x32_bf16 v[126:129], v[142:145], v[194:197], v[126:129]
	v_mfma_f32_16x16x32_bf16 v[118:121], v[142:145], v[202:205], v[118:121]
	v_mfma_f32_16x16x32_bf16 v[94:97], v[142:145], v[232:235], v[94:97]
	v_mfma_f32_16x16x32_bf16 v[78:81], v[142:145], v[240:243], v[78:81]
	v_mfma_f32_16x16x32_bf16 v[106:109], v[170:173], v[194:197], v[106:109]
	v_mfma_f32_16x16x32_bf16 v[114:117], v[170:173], v[202:205], v[114:117]
	v_mfma_f32_16x16x32_bf16 v[90:93], v[170:173], v[232:235], v[90:93]
	v_mfma_f32_16x16x32_bf16 v[74:77], v[170:173], v[240:243], v[74:77]
	v_mfma_f32_16x16x32_bf16 v[122:125], v[174:177], v[190:193], v[122:125]
	v_mfma_f32_16x16x32_bf16 v[102:105], v[174:177], v[198:201], v[102:105]
	v_mfma_f32_16x16x32_bf16 v[86:89], v[174:177], v[228:231], v[86:89]
	v_mfma_f32_16x16x32_bf16 v[70:73], v[174:177], v[236:239], v[70:73]
	v_mfma_f32_16x16x32_bf16 v[110:113], v[182:185], v[190:193], v[110:113]
	v_mfma_f32_16x16x32_bf16 v[98:101], v[182:185], v[198:201], v[98:101]
	v_mfma_f32_16x16x32_bf16 v[82:85], v[182:185], v[228:231], v[82:85]
	v_mfma_f32_16x16x32_bf16 v[66:69], v[182:185], v[236:239], v[66:69]
	v_mfma_f32_16x16x32_bf16 v[122:125], v[178:181], v[194:197], v[122:125]
	v_mfma_f32_16x16x32_bf16 v[102:105], v[178:181], v[202:205], v[102:105]
	v_mfma_f32_16x16x32_bf16 v[86:89], v[178:181], v[232:235], v[86:89]
	v_mfma_f32_16x16x32_bf16 v[70:73], v[178:181], v[240:243], v[70:73]
	v_mfma_f32_16x16x32_bf16 v[110:113], v[186:189], v[194:197], v[110:113]
	v_mfma_f32_16x16x32_bf16 v[98:101], v[186:189], v[202:205], v[98:101]
	v_mfma_f32_16x16x32_bf16 v[82:85], v[186:189], v[232:235], v[82:85]
	v_mfma_f32_16x16x32_bf16 v[66:69], v[186:189], v[240:243], v[66:69]
	s_barrier
	s_setprio 0
	s_mov_b32 m0, s68
	s_or_b32 s52, s27, 0x80
	ds_read_b128 v[190:193], v141 offset:49152
	ds_read_b128 v[194:197], v141 offset:50176
	ds_read_b128 v[198:201], v141 offset:51200
	ds_read_b128 v[202:205], v141 offset:52224
	ds_read_b128 v[228:231], v141 offset:53248
	ds_read_b128 v[232:235], v141 offset:54272
	ds_read_b128 v[236:239], v141 offset:55296
	ds_read_b128 v[240:243], v141 offset:56320
	buffer_load_dwordx4 v137, s[44:47], s52 offen lds
	s_mov_b32 m0, s69
	s_add_i32 s27, s27, 0x160080
	buffer_load_dwordx4 v139, s[44:47], s52 offen lds
	s_mov_b32 m0, s72
	s_nop 0
	buffer_load_dwordx4 v137, s[44:47], s27 offen lds
	s_mov_b32 m0, s73
	s_nop 0
	buffer_load_dwordx4 v139, s[44:47], s27 offen lds
	s_mov_b32 m0, s70
	s_nop 0
	buffer_load_dwordx4 v136, s[60:63], s26 offen lds
	s_mov_b32 m0, s71
	s_nop 0
	buffer_load_dwordx4 v138, s[60:63], s26 offen lds
	s_waitcnt vmcnt(8)
	s_waitcnt lgkmcnt(0)
	s_setprio 1
	s_barrier
	v_mfma_f32_16x16x32_bf16 v[62:65], v[132:135], v[190:193], v[62:65]
	v_mfma_f32_16x16x32_bf16 v[46:49], v[132:135], v[198:201], v[46:49]
	v_mfma_f32_16x16x32_bf16 v[30:33], v[132:135], v[228:231], v[30:33]
	v_mfma_f32_16x16x32_bf16 v[14:17], v[132:135], v[236:239], v[14:17]
	v_mfma_f32_16x16x32_bf16 v[58:61], v[154:157], v[190:193], v[58:61]
	v_mfma_f32_16x16x32_bf16 v[42:45], v[154:157], v[198:201], v[42:45]
	v_mfma_f32_16x16x32_bf16 v[26:29], v[154:157], v[228:231], v[26:29]
	v_mfma_f32_16x16x32_bf16 v[10:13], v[154:157], v[236:239], v[10:13]
	v_mfma_f32_16x16x32_bf16 v[62:65], v[142:145], v[194:197], v[62:65]
	v_mfma_f32_16x16x32_bf16 v[46:49], v[142:145], v[202:205], v[46:49]
	v_mfma_f32_16x16x32_bf16 v[30:33], v[142:145], v[232:235], v[30:33]
	v_mfma_f32_16x16x32_bf16 v[14:17], v[142:145], v[240:243], v[14:17]
	v_mfma_f32_16x16x32_bf16 v[58:61], v[170:173], v[194:197], v[58:61]
	v_mfma_f32_16x16x32_bf16 v[42:45], v[170:173], v[202:205], v[42:45]
	v_mfma_f32_16x16x32_bf16 v[26:29], v[170:173], v[232:235], v[26:29]
	v_mfma_f32_16x16x32_bf16 v[10:13], v[170:173], v[240:243], v[10:13]
	v_mfma_f32_16x16x32_bf16 v[54:57], v[174:177], v[190:193], v[54:57]
	v_mfma_f32_16x16x32_bf16 v[38:41], v[174:177], v[198:201], v[38:41]
	v_mfma_f32_16x16x32_bf16 v[22:25], v[174:177], v[228:231], v[22:25]
	v_mfma_f32_16x16x32_bf16 v[6:9], v[174:177], v[236:239], v[6:9]
	v_mfma_f32_16x16x32_bf16 v[50:53], v[182:185], v[190:193], v[50:53]
	v_mfma_f32_16x16x32_bf16 v[34:37], v[182:185], v[198:201], v[34:37]
	v_mfma_f32_16x16x32_bf16 v[18:21], v[182:185], v[228:231], v[18:21]
	v_mfma_f32_16x16x32_bf16 v[2:5], v[182:185], v[236:239], v[2:5]
	v_mfma_f32_16x16x32_bf16 v[54:57], v[178:181], v[194:197], v[54:57]
	v_mfma_f32_16x16x32_bf16 v[38:41], v[178:181], v[202:205], v[38:41]
	v_mfma_f32_16x16x32_bf16 v[22:25], v[178:181], v[232:235], v[22:25]
	v_mfma_f32_16x16x32_bf16 v[6:9], v[178:181], v[240:243], v[6:9]
	v_mfma_f32_16x16x32_bf16 v[50:53], v[186:189], v[194:197], v[50:53]
	v_mfma_f32_16x16x32_bf16 v[34:37], v[186:189], v[202:205], v[34:37]
	v_mfma_f32_16x16x32_bf16 v[18:21], v[186:189], v[232:235], v[18:21]
	v_mfma_f32_16x16x32_bf16 v[2:5], v[186:189], v[240:243], v[2:5]
	s_barrier
	s_setprio 0
	s_addk_i32 s13, 0x100
	s_add_i32 s22, s22, 2
	s_add_i32 s21, s21, 0x10000
	s_cmpk_gt_u32 s22, 0x55
	s_cbranch_scc0 .LBB0_2156
	s_and_b64 vcc, exec, s[66:67]
	s_cbranch_vccz .LBB0_2159
	s_barrier

.LBB0_2173:
	v_mov_b32_e32 v125, 0
	s_mul_i32 s69, s68, s12
	s_mul_i32 s70, s67, s12
	s_andn2_b64 vcc, exec, s[34:35]
	v_mov_b32_e32 v124, v125
	v_mov_b32_e32 v123, v125
	v_mov_b32_e32 v122, v125
	v_mov_b32_e32 v129, v125
	v_mov_b32_e32 v128, v125
	v_mov_b32_e32 v127, v125
	v_mov_b32_e32 v126, v125
	v_mov_b32_e32 v113, v125
	v_mov_b32_e32 v112, v125
	v_mov_b32_e32 v111, v125
	v_mov_b32_e32 v110, v125
	v_mov_b32_e32 v109, v125
	v_mov_b32_e32 v108, v125
	v_mov_b32_e32 v107, v125
	v_mov_b32_e32 v106, v125
	v_mov_b32_e32 v97, v125
	v_mov_b32_e32 v96, v125
	v_mov_b32_e32 v95, v125
	v_mov_b32_e32 v94, v125
	v_mov_b32_e32 v93, v125
	v_mov_b32_e32 v92, v125
	v_mov_b32_e32 v91, v125
	v_mov_b32_e32 v90, v125
	v_mov_b32_e32 v81, v125
	v_mov_b32_e32 v80, v125
	v_mov_b32_e32 v79, v125
	v_mov_b32_e32 v78, v125
	v_mov_b32_e32 v77, v125
	v_mov_b32_e32 v76, v125
	v_mov_b32_e32 v75, v125
	v_mov_b32_e32 v74, v125
	v_mov_b32_e32 v121, v125
	v_mov_b32_e32 v120, v125
	v_mov_b32_e32 v119, v125
	v_mov_b32_e32 v118, v125
	v_mov_b32_e32 v117, v125
	v_mov_b32_e32 v116, v125
	v_mov_b32_e32 v115, v125
	v_mov_b32_e32 v114, v125
	v_mov_b32_e32 v105, v125
	v_mov_b32_e32 v104, v125
	v_mov_b32_e32 v103, v125
	v_mov_b32_e32 v102, v125
	v_mov_b32_e32 v101, v125
	v_mov_b32_e32 v100, v125
	v_mov_b32_e32 v99, v125
	v_mov_b32_e32 v98, v125
	v_mov_b32_e32 v89, v125
	v_mov_b32_e32 v88, v125
	v_mov_b32_e32 v87, v125
	v_mov_b32_e32 v86, v125
	v_mov_b32_e32 v85, v125
	v_mov_b32_e32 v84, v125
	v_mov_b32_e32 v83, v125
	v_mov_b32_e32 v82, v125
	v_mov_b32_e32 v73, v125
	v_mov_b32_e32 v72, v125
	v_mov_b32_e32 v71, v125
	v_mov_b32_e32 v70, v125
	v_mov_b32_e32 v69, v125
	v_mov_b32_e32 v68, v125
	v_mov_b32_e32 v67, v125
	v_mov_b32_e32 v66, v125
	v_mov_b32_e32 v65, v125
	v_mov_b32_e32 v64, v125
	v_mov_b32_e32 v63, v125
	v_mov_b32_e32 v62, v125
	v_mov_b32_e32 v61, v125
	v_mov_b32_e32 v60, v125
	v_mov_b32_e32 v59, v125
	v_mov_b32_e32 v58, v125
	v_mov_b32_e32 v49, v125
	v_mov_b32_e32 v48, v125
	v_mov_b32_e32 v47, v125
	v_mov_b32_e32 v46, v125
	v_mov_b32_e32 v45, v125
	v_mov_b32_e32 v44, v125
	v_mov_b32_e32 v43, v125
	v_mov_b32_e32 v42, v125
	v_mov_b32_e32 v33, v125
	v_mov_b32_e32 v32, v125
	v_mov_b32_e32 v31, v125
	v_mov_b32_e32 v30, v125
	v_mov_b32_e32 v29, v125
	v_mov_b32_e32 v28, v125
	v_mov_b32_e32 v27, v125
	v_mov_b32_e32 v26, v125
	v_mov_b32_e32 v17, v125
	v_mov_b32_e32 v16, v125
	v_mov_b32_e32 v15, v125
	v_mov_b32_e32 v14, v125
	v_mov_b32_e32 v13, v125
	v_mov_b32_e32 v12, v125
	v_mov_b32_e32 v11, v125
	v_mov_b32_e32 v10, v125
	v_mov_b32_e32 v57, v125
	v_mov_b32_e32 v56, v125
	v_mov_b32_e32 v55, v125
	v_mov_b32_e32 v54, v125
	v_mov_b32_e32 v53, v125
	v_mov_b32_e32 v52, v125
	v_mov_b32_e32 v51, v125
	v_mov_b32_e32 v50, v125
	v_mov_b32_e32 v41, v125
	v_mov_b32_e32 v40, v125
	v_mov_b32_e32 v39, v125
	v_mov_b32_e32 v38, v125
	v_mov_b32_e32 v37, v125
	v_mov_b32_e32 v36, v125
	v_mov_b32_e32 v35, v125
	v_mov_b32_e32 v34, v125
	v_mov_b32_e32 v25, v125
	v_mov_b32_e32 v24, v125
	v_mov_b32_e32 v23, v125
	v_mov_b32_e32 v22, v125
	v_mov_b32_e32 v21, v125
	v_mov_b32_e32 v20, v125
	v_mov_b32_e32 v19, v125
	v_mov_b32_e32 v18, v125
	v_mov_b32_e32 v9, v125
	v_mov_b32_e32 v8, v125
	v_mov_b32_e32 v7, v125
	v_mov_b32_e32 v6, v125
	v_mov_b32_e32 v5, v125
	v_mov_b32_e32 v4, v125
	v_mov_b32_e32 v3, v125
	v_mov_b32_e32 v2, v125
	s_cbranch_vccnz .LBB0_2177
	s_and_b64 s[8:9], s[40:41], exec
	s_cselect_b32 s8, s69, s73
	s_cselect_b32 s9, s70, s82
	s_addk_i32 s73, 0x80
	s_addk_i32 s82, 0x100
	s_mov_b32 s83, 0
	v_add_u32_e32 v144, 0x10000, v134
	ds_read_b128 v[136:139], v144
	ds_read_b128 v[140:143], v144 offset:1024
	ds_read_b128 v[154:157], v144 offset:2048
	ds_read_b128 v[170:173], v144 offset:3072
	v_add_u32_e32 v144, 0x14000, v134
	ds_read_b128 v[174:177], v144
	ds_read_b128 v[178:181], v144 offset:1024
	ds_read_b128 v[182:185], v144 offset:2048
	ds_read_b128 v[186:189], v144 offset:3072
	s_add_i32 s46, s73, 0x80
	s_cmp_eq_u32 s49, s83
	s_cselect_b32 s52, s8, s46
	s_cselect_b32 s85, s9, s82
	s_add_i32 s84, s52, 0x80
	s_add_i32 s46, s2, s73
	s_mov_b32 m0, s64
	ds_read_b128 v[190:193], v135
	ds_read_b128 v[194:197], v135 offset:1024
	ds_read_b128 v[198:201], v135 offset:2048
	ds_read_b128 v[202:205], v135 offset:3072
	ds_read_b128 v[228:231], v135 offset:4096
	ds_read_b128 v[232:235], v135 offset:5120
	ds_read_b128 v[236:239], v135 offset:6144
	ds_read_b128 v[240:243], v135 offset:7168
	buffer_load_dwordx4 v130, s[60:63], s46 offen lds
	s_mov_b32 m0, s65
	s_nop 0
	buffer_load_dwordx4 v132, s[60:63], s46 offen lds
	s_waitcnt vmcnt(8)
	s_waitcnt lgkmcnt(0)
	s_setprio 1
	s_barrier
	v_mfma_f32_16x16x32_bf16 v[122:125], v[136:139], v[190:193], 0
	v_mfma_f32_16x16x32_bf16 v[110:113], v[136:139], v[198:201], 0
	v_mfma_f32_16x16x32_bf16 v[94:97], v[136:139], v[228:231], 0
	v_mfma_f32_16x16x32_bf16 v[78:81], v[136:139], v[236:239], 0
	v_mfma_f32_16x16x32_bf16 v[126:129], v[154:157], v[190:193], 0
	v_mfma_f32_16x16x32_bf16 v[106:109], v[154:157], v[198:201], 0
	v_mfma_f32_16x16x32_bf16 v[90:93], v[154:157], v[228:231], 0
	v_mfma_f32_16x16x32_bf16 v[74:77], v[154:157], v[236:239], 0
	v_mfma_f32_16x16x32_bf16 v[122:125], v[140:143], v[194:197], v[122:125]
	v_mfma_f32_16x16x32_bf16 v[110:113], v[140:143], v[202:205], v[110:113]
	v_mfma_f32_16x16x32_bf16 v[94:97], v[140:143], v[232:235], v[94:97]
	v_mfma_f32_16x16x32_bf16 v[78:81], v[140:143], v[240:243], v[78:81]
	v_mfma_f32_16x16x32_bf16 v[126:129], v[170:173], v[194:197], v[126:129]
	v_mfma_f32_16x16x32_bf16 v[106:109], v[170:173], v[202:205], v[106:109]
	v_mfma_f32_16x16x32_bf16 v[90:93], v[170:173], v[232:235], v[90:93]
	v_mfma_f32_16x16x32_bf16 v[74:77], v[170:173], v[240:243], v[74:77]
	v_mfma_f32_16x16x32_bf16 v[118:121], v[174:177], v[190:193], 0
	v_mfma_f32_16x16x32_bf16 v[102:105], v[174:177], v[198:201], 0
	v_mfma_f32_16x16x32_bf16 v[86:89], v[174:177], v[228:231], 0
	v_mfma_f32_16x16x32_bf16 v[70:73], v[174:177], v[236:239], 0
	v_mfma_f32_16x16x32_bf16 v[114:117], v[182:185], v[190:193], 0
	v_mfma_f32_16x16x32_bf16 v[98:101], v[182:185], v[198:201], 0
	v_mfma_f32_16x16x32_bf16 v[82:85], v[182:185], v[228:231], 0
	v_mfma_f32_16x16x32_bf16 v[66:69], v[182:185], v[236:239], 0
	v_mfma_f32_16x16x32_bf16 v[118:121], v[178:181], v[194:197], v[118:121]
	v_mfma_f32_16x16x32_bf16 v[102:105], v[178:181], v[202:205], v[102:105]
	v_mfma_f32_16x16x32_bf16 v[86:89], v[178:181], v[232:235], v[86:89]
	v_mfma_f32_16x16x32_bf16 v[70:73], v[178:181], v[240:243], v[70:73]
	v_mfma_f32_16x16x32_bf16 v[114:117], v[186:189], v[194:197], v[114:117]
	v_mfma_f32_16x16x32_bf16 v[98:101], v[186:189], v[202:205], v[98:101]
	v_mfma_f32_16x16x32_bf16 v[82:85], v[186:189], v[232:235], v[82:85]
	v_mfma_f32_16x16x32_bf16 v[66:69], v[186:189], v[240:243], v[66:69]
	s_barrier
	s_setprio 0
	s_mov_b32 m0, s14
	s_mov_b32 s46, s62
	s_mov_b32 s47, s63
	ds_read_b128 v[190:193], v135 offset:16384
	ds_read_b128 v[194:197], v135 offset:17408
	ds_read_b128 v[198:201], v135 offset:18432
	ds_read_b128 v[202:205], v135 offset:19456
	ds_read_b128 v[228:231], v135 offset:20480
	ds_read_b128 v[232:235], v135 offset:21504
	ds_read_b128 v[236:239], v135 offset:22528
	ds_read_b128 v[240:243], v135 offset:23552
	buffer_load_dwordx4 v131, s[44:47], s85 offen lds
	s_mov_b32 m0, s15
	s_add_i32 s53, s85, s2
	buffer_load_dwordx4 v133, s[44:47], s85 offen lds
	s_mov_b32 m0, s16
	s_nop 0
	buffer_load_dwordx4 v131, s[44:47], s53 offen lds
	s_mov_b32 m0, s18
	s_nop 0
	buffer_load_dwordx4 v133, s[44:47], s53 offen lds
	s_mov_b32 m0, s13
	s_nop 0
	buffer_load_dwordx4 v130, s[60:63], s52 offen lds
	s_mov_b32 m0, s19
	s_nop 0
	buffer_load_dwordx4 v132, s[60:63], s52 offen lds
	s_waitcnt vmcnt(8)
	s_waitcnt lgkmcnt(0)
	s_setprio 1
	s_barrier
	v_mfma_f32_16x16x32_bf16 v[62:65], v[136:139], v[190:193], 0
	v_mfma_f32_16x16x32_bf16 v[46:49], v[136:139], v[198:201], 0
	v_mfma_f32_16x16x32_bf16 v[30:33], v[136:139], v[228:231], 0
	v_mfma_f32_16x16x32_bf16 v[14:17], v[136:139], v[236:239], 0
	v_mfma_f32_16x16x32_bf16 v[58:61], v[154:157], v[190:193], 0
	v_mfma_f32_16x16x32_bf16 v[42:45], v[154:157], v[198:201], 0
	v_mfma_f32_16x16x32_bf16 v[26:29], v[154:157], v[228:231], 0
	v_mfma_f32_16x16x32_bf16 v[10:13], v[154:157], v[236:239], 0
	v_mfma_f32_16x16x32_bf16 v[62:65], v[140:143], v[194:197], v[62:65]
	v_mfma_f32_16x16x32_bf16 v[46:49], v[140:143], v[202:205], v[46:49]
	v_mfma_f32_16x16x32_bf16 v[30:33], v[140:143], v[232:235], v[30:33]
	v_mfma_f32_16x16x32_bf16 v[14:17], v[140:143], v[240:243], v[14:17]
	v_mfma_f32_16x16x32_bf16 v[58:61], v[170:173], v[194:197], v[58:61]
	v_mfma_f32_16x16x32_bf16 v[42:45], v[170:173], v[202:205], v[42:45]
	v_mfma_f32_16x16x32_bf16 v[26:29], v[170:173], v[232:235], v[26:29]
	v_mfma_f32_16x16x32_bf16 v[10:13], v[170:173], v[240:243], v[10:13]
	v_mfma_f32_16x16x32_bf16 v[54:57], v[174:177], v[190:193], 0
	v_mfma_f32_16x16x32_bf16 v[38:41], v[174:177], v[198:201], 0
	v_mfma_f32_16x16x32_bf16 v[22:25], v[174:177], v[228:231], 0
	v_mfma_f32_16x16x32_bf16 v[6:9], v[174:177], v[236:239], 0
	v_mfma_f32_16x16x32_bf16 v[50:53], v[182:185], v[190:193], 0
	v_mfma_f32_16x16x32_bf16 v[34:37], v[182:185], v[198:201], 0
	v_mfma_f32_16x16x32_bf16 v[18:21], v[182:185], v[228:231], 0
	v_mfma_f32_16x16x32_bf16 v[2:5], v[182:185], v[236:239], 0
	v_mfma_f32_16x16x32_bf16 v[54:57], v[178:181], v[194:197], v[54:57]
	v_mfma_f32_16x16x32_bf16 v[38:41], v[178:181], v[202:205], v[38:41]
	v_mfma_f32_16x16x32_bf16 v[22:25], v[178:181], v[232:235], v[22:25]
	v_mfma_f32_16x16x32_bf16 v[6:9], v[178:181], v[240:243], v[6:9]
	v_mfma_f32_16x16x32_bf16 v[50:53], v[186:189], v[194:197], v[50:53]
	v_mfma_f32_16x16x32_bf16 v[34:37], v[186:189], v[202:205], v[34:37]
	v_mfma_f32_16x16x32_bf16 v[18:21], v[186:189], v[232:235], v[18:21]
	v_mfma_f32_16x16x32_bf16 v[2:5], v[186:189], v[240:243], v[2:5]
	s_barrier
	s_setprio 0
	v_add_u32_e32 v144, 0x18000, v134
	ds_read_b128 v[136:139], v144
	ds_read_b128 v[140:143], v144 offset:1024
	ds_read_b128 v[154:157], v144 offset:2048
	ds_read_b128 v[170:173], v144 offset:3072
	v_add_u32_e32 v144, 0x1c000, v134
	ds_read_b128 v[174:177], v144
	ds_read_b128 v[178:181], v144 offset:1024
	ds_read_b128 v[182:185], v144 offset:2048
	ds_read_b128 v[186:189], v144 offset:3072
	s_add_i32 s52, s52, s2
	s_mov_b32 m0, s21
	ds_read_b128 v[190:193], v135 offset:32768
	ds_read_b128 v[194:197], v135 offset:33792
	ds_read_b128 v[198:201], v135 offset:34816
	ds_read_b128 v[202:205], v135 offset:35840
	ds_read_b128 v[228:231], v135 offset:36864
	ds_read_b128 v[232:235], v135 offset:37888
	ds_read_b128 v[236:239], v135 offset:38912
	ds_read_b128 v[240:243], v135 offset:39936
	buffer_load_dwordx4 v130, s[60:63], s52 offen lds
	s_mov_b32 m0, s22
	s_nop 0
	buffer_load_dwordx4 v132, s[60:63], s52 offen lds
	s_waitcnt vmcnt(8)
	s_waitcnt lgkmcnt(0)
	s_setprio 1
	s_barrier
	v_mfma_f32_16x16x32_bf16 v[122:125], v[136:139], v[190:193], v[122:125]
	v_mfma_f32_16x16x32_bf16 v[110:113], v[136:139], v[198:201], v[110:113]
	v_mfma_f32_16x16x32_bf16 v[94:97], v[136:139], v[228:231], v[94:97]
	v_mfma_f32_16x16x32_bf16 v[78:81], v[136:139], v[236:239], v[78:81]
	v_mfma_f32_16x16x32_bf16 v[126:129], v[154:157], v[190:193], v[126:129]
	v_mfma_f32_16x16x32_bf16 v[106:109], v[154:157], v[198:201], v[106:109]
	v_mfma_f32_16x16x32_bf16 v[90:93], v[154:157], v[228:231], v[90:93]
	v_mfma_f32_16x16x32_bf16 v[74:77], v[154:157], v[236:239], v[74:77]
	v_mfma_f32_16x16x32_bf16 v[122:125], v[140:143], v[194:197], v[122:125]
	v_mfma_f32_16x16x32_bf16 v[110:113], v[140:143], v[202:205], v[110:113]
	v_mfma_f32_16x16x32_bf16 v[94:97], v[140:143], v[232:235], v[94:97]
	v_mfma_f32_16x16x32_bf16 v[78:81], v[140:143], v[240:243], v[78:81]
	v_mfma_f32_16x16x32_bf16 v[126:129], v[170:173], v[194:197], v[126:129]
	v_mfma_f32_16x16x32_bf16 v[106:109], v[170:173], v[202:205], v[106:109]
	v_mfma_f32_16x16x32_bf16 v[90:93], v[170:173], v[232:235], v[90:93]
	v_mfma_f32_16x16x32_bf16 v[74:77], v[170:173], v[240:243], v[74:77]
	v_mfma_f32_16x16x32_bf16 v[118:121], v[174:177], v[190:193], v[118:121]
	v_mfma_f32_16x16x32_bf16 v[102:105], v[174:177], v[198:201], v[102:105]
	v_mfma_f32_16x16x32_bf16 v[86:89], v[174:177], v[228:231], v[86:89]
	v_mfma_f32_16x16x32_bf16 v[70:73], v[174:177], v[236:239], v[70:73]
	v_mfma_f32_16x16x32_bf16 v[114:117], v[182:185], v[190:193], v[114:117]
	v_mfma_f32_16x16x32_bf16 v[98:101], v[182:185], v[198:201], v[98:101]
	v_mfma_f32_16x16x32_bf16 v[82:85], v[182:185], v[228:231], v[82:85]
	v_mfma_f32_16x16x32_bf16 v[66:69], v[182:185], v[236:239], v[66:69]
	v_mfma_f32_16x16x32_bf16 v[118:121], v[178:181], v[194:197], v[118:121]
	v_mfma_f32_16x16x32_bf16 v[102:105], v[178:181], v[202:205], v[102:105]
	v_mfma_f32_16x16x32_bf16 v[86:89], v[178:181], v[232:235], v[86:89]
	v_mfma_f32_16x16x32_bf16 v[70:73], v[178:181], v[240:243], v[70:73]
	v_mfma_f32_16x16x32_bf16 v[114:117], v[186:189], v[194:197], v[114:117]
	v_mfma_f32_16x16x32_bf16 v[98:101], v[186:189], v[202:205], v[98:101]
	v_mfma_f32_16x16x32_bf16 v[82:85], v[186:189], v[232:235], v[82:85]
	v_mfma_f32_16x16x32_bf16 v[66:69], v[186:189], v[240:243], v[66:69]
	s_barrier
	s_setprio 0
	s_mov_b32 m0, s33
	s_add_i32 s52, s85, 0x80
	ds_read_b128 v[190:193], v135 offset:49152
	ds_read_b128 v[194:197], v135 offset:50176
	ds_read_b128 v[198:201], v135 offset:51200
	ds_read_b128 v[202:205], v135 offset:52224
	ds_read_b128 v[228:231], v135 offset:53248
	ds_read_b128 v[232:235], v135 offset:54272
	ds_read_b128 v[236:239], v135 offset:55296
	ds_read_b128 v[240:243], v135 offset:56320
	buffer_load_dwordx4 v131, s[44:47], s52 offen lds
	s_mov_b32 m0, s36
	s_nop 0
	buffer_load_dwordx4 v133, s[44:47], s52 offen lds
	s_add_i32 s52, s52, s2
	s_mov_b32 m0, s43
	s_nop 0
	buffer_load_dwordx4 v131, s[44:47], s52 offen lds
	s_mov_b32 m0, s48
	s_nop 0
	buffer_load_dwordx4 v133, s[44:47], s52 offen lds
	s_mov_b32 m0, s37
	s_nop 0
	buffer_load_dwordx4 v130, s[60:63], s84 offen lds
	s_mov_b32 m0, s42
	s_nop 0
	buffer_load_dwordx4 v132, s[60:63], s84 offen lds
	s_waitcnt vmcnt(8)
	s_waitcnt lgkmcnt(0)
	s_setprio 1
	s_barrier
	v_mfma_f32_16x16x32_bf16 v[62:65], v[136:139], v[190:193], v[62:65]
	v_mfma_f32_16x16x32_bf16 v[46:49], v[136:139], v[198:201], v[46:49]
	v_mfma_f32_16x16x32_bf16 v[30:33], v[136:139], v[228:231], v[30:33]
	v_mfma_f32_16x16x32_bf16 v[14:17], v[136:139], v[236:239], v[14:17]
	v_mfma_f32_16x16x32_bf16 v[58:61], v[154:157], v[190:193], v[58:61]
	v_mfma_f32_16x16x32_bf16 v[42:45], v[154:157], v[198:201], v[42:45]
	v_mfma_f32_16x16x32_bf16 v[26:29], v[154:157], v[228:231], v[26:29]
	v_mfma_f32_16x16x32_bf16 v[10:13], v[154:157], v[236:239], v[10:13]
	v_mfma_f32_16x16x32_bf16 v[62:65], v[140:143], v[194:197], v[62:65]
	v_mfma_f32_16x16x32_bf16 v[46:49], v[140:143], v[202:205], v[46:49]
	v_mfma_f32_16x16x32_bf16 v[30:33], v[140:143], v[232:235], v[30:33]
	v_mfma_f32_16x16x32_bf16 v[14:17], v[140:143], v[240:243], v[14:17]
	v_mfma_f32_16x16x32_bf16 v[58:61], v[170:173], v[194:197], v[58:61]
	v_mfma_f32_16x16x32_bf16 v[42:45], v[170:173], v[202:205], v[42:45]
	v_mfma_f32_16x16x32_bf16 v[26:29], v[170:173], v[232:235], v[26:29]
	v_mfma_f32_16x16x32_bf16 v[10:13], v[170:173], v[240:243], v[10:13]
	v_mfma_f32_16x16x32_bf16 v[54:57], v[174:177], v[190:193], v[54:57]
	v_mfma_f32_16x16x32_bf16 v[38:41], v[174:177], v[198:201], v[38:41]
	v_mfma_f32_16x16x32_bf16 v[22:25], v[174:177], v[228:231], v[22:25]
	v_mfma_f32_16x16x32_bf16 v[6:9], v[174:177], v[236:239], v[6:9]
	v_mfma_f32_16x16x32_bf16 v[50:53], v[182:185], v[190:193], v[50:53]
	v_mfma_f32_16x16x32_bf16 v[34:37], v[182:185], v[198:201], v[34:37]
	v_mfma_f32_16x16x32_bf16 v[18:21], v[182:185], v[228:231], v[18:21]
	v_mfma_f32_16x16x32_bf16 v[2:5], v[182:185], v[236:239], v[2:5]
	v_mfma_f32_16x16x32_bf16 v[54:57], v[178:181], v[194:197], v[54:57]
	v_mfma_f32_16x16x32_bf16 v[38:41], v[178:181], v[202:205], v[38:41]
	v_mfma_f32_16x16x32_bf16 v[22:25], v[178:181], v[232:235], v[22:25]
	v_mfma_f32_16x16x32_bf16 v[6:9], v[178:181], v[240:243], v[6:9]
	v_mfma_f32_16x16x32_bf16 v[50:53], v[186:189], v[194:197], v[50:53]
	v_mfma_f32_16x16x32_bf16 v[34:37], v[186:189], v[202:205], v[34:37]
	v_mfma_f32_16x16x32_bf16 v[18:21], v[186:189], v[232:235], v[18:21]
	v_mfma_f32_16x16x32_bf16 v[2:5], v[186:189], v[240:243], v[2:5]
	s_barrier
	s_setprio 0
	s_add_i32 s83, s83, 2
	s_addk_i32 s73, 0x100
	s_addk_i32 s82, 0x100
	s_cmp_ge_i32 s83, s23
.LBB0_2175:
	v_add_u32_e32 v144, 0x10000, v134
	ds_read_b128 v[136:139], v144
	ds_read_b128 v[140:143], v144 offset:1024
	ds_read_b128 v[154:157], v144 offset:2048
	ds_read_b128 v[170:173], v144 offset:3072
	v_add_u32_e32 v144, 0x14000, v134
	ds_read_b128 v[174:177], v144
	ds_read_b128 v[178:181], v144 offset:1024
	ds_read_b128 v[182:185], v144 offset:2048
	ds_read_b128 v[186:189], v144 offset:3072
	s_add_i32 s46, s73, 0x80
	s_cmp_eq_u32 s49, s83
	s_cselect_b32 s52, s8, s46
	s_cselect_b32 s85, s9, s82
	s_add_i32 s84, s52, 0x80
	s_add_i32 s46, s2, s73
	s_mov_b32 m0, s64
	ds_read_b128 v[190:193], v135
	ds_read_b128 v[194:197], v135 offset:1024
	ds_read_b128 v[198:201], v135 offset:2048
	ds_read_b128 v[202:205], v135 offset:3072
	ds_read_b128 v[228:231], v135 offset:4096
	ds_read_b128 v[232:235], v135 offset:5120
	ds_read_b128 v[236:239], v135 offset:6144
	ds_read_b128 v[240:243], v135 offset:7168
	buffer_load_dwordx4 v130, s[60:63], s46 offen lds
	s_mov_b32 m0, s65
	s_nop 0
	buffer_load_dwordx4 v132, s[60:63], s46 offen lds
	s_waitcnt vmcnt(8)
	s_waitcnt lgkmcnt(0)
	s_setprio 1
	s_barrier
	v_mfma_f32_16x16x32_bf16 v[122:125], v[136:139], v[190:193], v[122:125]
	v_mfma_f32_16x16x32_bf16 v[110:113], v[136:139], v[198:201], v[110:113]
	v_mfma_f32_16x16x32_bf16 v[94:97], v[136:139], v[228:231], v[94:97]
	v_mfma_f32_16x16x32_bf16 v[78:81], v[136:139], v[236:239], v[78:81]
	v_mfma_f32_16x16x32_bf16 v[126:129], v[154:157], v[190:193], v[126:129]
	v_mfma_f32_16x16x32_bf16 v[106:109], v[154:157], v[198:201], v[106:109]
	v_mfma_f32_16x16x32_bf16 v[90:93], v[154:157], v[228:231], v[90:93]
	v_mfma_f32_16x16x32_bf16 v[74:77], v[154:157], v[236:239], v[74:77]
	v_mfma_f32_16x16x32_bf16 v[122:125], v[140:143], v[194:197], v[122:125]
	v_mfma_f32_16x16x32_bf16 v[110:113], v[140:143], v[202:205], v[110:113]
	v_mfma_f32_16x16x32_bf16 v[94:97], v[140:143], v[232:235], v[94:97]
	v_mfma_f32_16x16x32_bf16 v[78:81], v[140:143], v[240:243], v[78:81]
	v_mfma_f32_16x16x32_bf16 v[126:129], v[170:173], v[194:197], v[126:129]
	v_mfma_f32_16x16x32_bf16 v[106:109], v[170:173], v[202:205], v[106:109]
	v_mfma_f32_16x16x32_bf16 v[90:93], v[170:173], v[232:235], v[90:93]
	v_mfma_f32_16x16x32_bf16 v[74:77], v[170:173], v[240:243], v[74:77]
	v_mfma_f32_16x16x32_bf16 v[118:121], v[174:177], v[190:193], v[118:121]
	v_mfma_f32_16x16x32_bf16 v[102:105], v[174:177], v[198:201], v[102:105]
	v_mfma_f32_16x16x32_bf16 v[86:89], v[174:177], v[228:231], v[86:89]
	v_mfma_f32_16x16x32_bf16 v[70:73], v[174:177], v[236:239], v[70:73]
	v_mfma_f32_16x16x32_bf16 v[114:117], v[182:185], v[190:193], v[114:117]
	v_mfma_f32_16x16x32_bf16 v[98:101], v[182:185], v[198:201], v[98:101]
	v_mfma_f32_16x16x32_bf16 v[82:85], v[182:185], v[228:231], v[82:85]
	v_mfma_f32_16x16x32_bf16 v[66:69], v[182:185], v[236:239], v[66:69]
	v_mfma_f32_16x16x32_bf16 v[118:121], v[178:181], v[194:197], v[118:121]
	v_mfma_f32_16x16x32_bf16 v[102:105], v[178:181], v[202:205], v[102:105]
	v_mfma_f32_16x16x32_bf16 v[86:89], v[178:181], v[232:235], v[86:89]
	v_mfma_f32_16x16x32_bf16 v[70:73], v[178:181], v[240:243], v[70:73]
	v_mfma_f32_16x16x32_bf16 v[114:117], v[186:189], v[194:197], v[114:117]
	v_mfma_f32_16x16x32_bf16 v[98:101], v[186:189], v[202:205], v[98:101]
	v_mfma_f32_16x16x32_bf16 v[82:85], v[186:189], v[232:235], v[82:85]
	v_mfma_f32_16x16x32_bf16 v[66:69], v[186:189], v[240:243], v[66:69]
	s_barrier
	s_setprio 0
	s_mov_b32 m0, s14
	s_mov_b32 s46, s62
	s_mov_b32 s47, s63
	ds_read_b128 v[190:193], v135 offset:16384
	ds_read_b128 v[194:197], v135 offset:17408
	ds_read_b128 v[198:201], v135 offset:18432
	ds_read_b128 v[202:205], v135 offset:19456
	ds_read_b128 v[228:231], v135 offset:20480
	ds_read_b128 v[232:235], v135 offset:21504
	ds_read_b128 v[236:239], v135 offset:22528
	ds_read_b128 v[240:243], v135 offset:23552
	buffer_load_dwordx4 v131, s[44:47], s85 offen lds
	s_mov_b32 m0, s15
	s_add_i32 s53, s85, s2
	buffer_load_dwordx4 v133, s[44:47], s85 offen lds
	s_mov_b32 m0, s16
	s_nop 0
	buffer_load_dwordx4 v131, s[44:47], s53 offen lds
	s_mov_b32 m0, s18
	s_nop 0
	buffer_load_dwordx4 v133, s[44:47], s53 offen lds
	s_mov_b32 m0, s13
	s_nop 0
	buffer_load_dwordx4 v130, s[60:63], s52 offen lds
	s_mov_b32 m0, s19
	s_nop 0
	buffer_load_dwordx4 v132, s[60:63], s52 offen lds
	s_waitcnt vmcnt(8)
	s_waitcnt lgkmcnt(0)
	s_setprio 1
	s_barrier
	v_mfma_f32_16x16x32_bf16 v[62:65], v[136:139], v[190:193], v[62:65]
	v_mfma_f32_16x16x32_bf16 v[46:49], v[136:139], v[198:201], v[46:49]
	v_mfma_f32_16x16x32_bf16 v[30:33], v[136:139], v[228:231], v[30:33]
	v_mfma_f32_16x16x32_bf16 v[14:17], v[136:139], v[236:239], v[14:17]
	v_mfma_f32_16x16x32_bf16 v[58:61], v[154:157], v[190:193], v[58:61]
	v_mfma_f32_16x16x32_bf16 v[42:45], v[154:157], v[198:201], v[42:45]
	v_mfma_f32_16x16x32_bf16 v[26:29], v[154:157], v[228:231], v[26:29]
	v_mfma_f32_16x16x32_bf16 v[10:13], v[154:157], v[236:239], v[10:13]
	v_mfma_f32_16x16x32_bf16 v[62:65], v[140:143], v[194:197], v[62:65]
	v_mfma_f32_16x16x32_bf16 v[46:49], v[140:143], v[202:205], v[46:49]
	v_mfma_f32_16x16x32_bf16 v[30:33], v[140:143], v[232:235], v[30:33]
	v_mfma_f32_16x16x32_bf16 v[14:17], v[140:143], v[240:243], v[14:17]
	v_mfma_f32_16x16x32_bf16 v[58:61], v[170:173], v[194:197], v[58:61]
	v_mfma_f32_16x16x32_bf16 v[42:45], v[170:173], v[202:205], v[42:45]
	v_mfma_f32_16x16x32_bf16 v[26:29], v[170:173], v[232:235], v[26:29]
	v_mfma_f32_16x16x32_bf16 v[10:13], v[170:173], v[240:243], v[10:13]
	v_mfma_f32_16x16x32_bf16 v[54:57], v[174:177], v[190:193], v[54:57]
	v_mfma_f32_16x16x32_bf16 v[38:41], v[174:177], v[198:201], v[38:41]
	v_mfma_f32_16x16x32_bf16 v[22:25], v[174:177], v[228:231], v[22:25]
	v_mfma_f32_16x16x32_bf16 v[6:9], v[174:177], v[236:239], v[6:9]
	v_mfma_f32_16x16x32_bf16 v[50:53], v[182:185], v[190:193], v[50:53]
	v_mfma_f32_16x16x32_bf16 v[34:37], v[182:185], v[198:201], v[34:37]
	v_mfma_f32_16x16x32_bf16 v[18:21], v[182:185], v[228:231], v[18:21]
	v_mfma_f32_16x16x32_bf16 v[2:5], v[182:185], v[236:239], v[2:5]
	v_mfma_f32_16x16x32_bf16 v[54:57], v[178:181], v[194:197], v[54:57]
	v_mfma_f32_16x16x32_bf16 v[38:41], v[178:181], v[202:205], v[38:41]
	v_mfma_f32_16x16x32_bf16 v[22:25], v[178:181], v[232:235], v[22:25]
	v_mfma_f32_16x16x32_bf16 v[6:9], v[178:181], v[240:243], v[6:9]
	v_mfma_f32_16x16x32_bf16 v[50:53], v[186:189], v[194:197], v[50:53]
	v_mfma_f32_16x16x32_bf16 v[34:37], v[186:189], v[202:205], v[34:37]
	v_mfma_f32_16x16x32_bf16 v[18:21], v[186:189], v[232:235], v[18:21]
	v_mfma_f32_16x16x32_bf16 v[2:5], v[186:189], v[240:243], v[2:5]
	s_barrier
	s_setprio 0
	v_add_u32_e32 v144, 0x18000, v134
	ds_read_b128 v[136:139], v144
	ds_read_b128 v[140:143], v144 offset:1024
	ds_read_b128 v[154:157], v144 offset:2048
	ds_read_b128 v[170:173], v144 offset:3072
	v_add_u32_e32 v144, 0x1c000, v134
	ds_read_b128 v[174:177], v144
	ds_read_b128 v[178:181], v144 offset:1024
	ds_read_b128 v[182:185], v144 offset:2048
	ds_read_b128 v[186:189], v144 offset:3072
	s_add_i32 s52, s52, s2
	s_mov_b32 m0, s21
	ds_read_b128 v[190:193], v135 offset:32768
	ds_read_b128 v[194:197], v135 offset:33792
	ds_read_b128 v[198:201], v135 offset:34816
	ds_read_b128 v[202:205], v135 offset:35840
	ds_read_b128 v[228:231], v135 offset:36864
	ds_read_b128 v[232:235], v135 offset:37888
	ds_read_b128 v[236:239], v135 offset:38912
	ds_read_b128 v[240:243], v135 offset:39936
	buffer_load_dwordx4 v130, s[60:63], s52 offen lds
	s_mov_b32 m0, s22
	s_nop 0
	buffer_load_dwordx4 v132, s[60:63], s52 offen lds
	s_waitcnt vmcnt(8)
	s_waitcnt lgkmcnt(0)
	s_setprio 1
	s_barrier
	v_mfma_f32_16x16x32_bf16 v[122:125], v[136:139], v[190:193], v[122:125]
	v_mfma_f32_16x16x32_bf16 v[110:113], v[136:139], v[198:201], v[110:113]
	v_mfma_f32_16x16x32_bf16 v[94:97], v[136:139], v[228:231], v[94:97]
	v_mfma_f32_16x16x32_bf16 v[78:81], v[136:139], v[236:239], v[78:81]
	v_mfma_f32_16x16x32_bf16 v[126:129], v[154:157], v[190:193], v[126:129]
	v_mfma_f32_16x16x32_bf16 v[106:109], v[154:157], v[198:201], v[106:109]
	v_mfma_f32_16x16x32_bf16 v[90:93], v[154:157], v[228:231], v[90:93]
	v_mfma_f32_16x16x32_bf16 v[74:77], v[154:157], v[236:239], v[74:77]
	v_mfma_f32_16x16x32_bf16 v[122:125], v[140:143], v[194:197], v[122:125]
	v_mfma_f32_16x16x32_bf16 v[110:113], v[140:143], v[202:205], v[110:113]
	v_mfma_f32_16x16x32_bf16 v[94:97], v[140:143], v[232:235], v[94:97]
	v_mfma_f32_16x16x32_bf16 v[78:81], v[140:143], v[240:243], v[78:81]
	v_mfma_f32_16x16x32_bf16 v[126:129], v[170:173], v[194:197], v[126:129]
	v_mfma_f32_16x16x32_bf16 v[106:109], v[170:173], v[202:205], v[106:109]
	v_mfma_f32_16x16x32_bf16 v[90:93], v[170:173], v[232:235], v[90:93]
	v_mfma_f32_16x16x32_bf16 v[74:77], v[170:173], v[240:243], v[74:77]
	v_mfma_f32_16x16x32_bf16 v[118:121], v[174:177], v[190:193], v[118:121]
	v_mfma_f32_16x16x32_bf16 v[102:105], v[174:177], v[198:201], v[102:105]
	v_mfma_f32_16x16x32_bf16 v[86:89], v[174:177], v[228:231], v[86:89]
	v_mfma_f32_16x16x32_bf16 v[70:73], v[174:177], v[236:239], v[70:73]
	v_mfma_f32_16x16x32_bf16 v[114:117], v[182:185], v[190:193], v[114:117]
	v_mfma_f32_16x16x32_bf16 v[98:101], v[182:185], v[198:201], v[98:101]
	v_mfma_f32_16x16x32_bf16 v[82:85], v[182:185], v[228:231], v[82:85]
	v_mfma_f32_16x16x32_bf16 v[66:69], v[182:185], v[236:239], v[66:69]
	v_mfma_f32_16x16x32_bf16 v[118:121], v[178:181], v[194:197], v[118:121]
	v_mfma_f32_16x16x32_bf16 v[102:105], v[178:181], v[202:205], v[102:105]
	v_mfma_f32_16x16x32_bf16 v[86:89], v[178:181], v[232:235], v[86:89]
	v_mfma_f32_16x16x32_bf16 v[70:73], v[178:181], v[240:243], v[70:73]
	v_mfma_f32_16x16x32_bf16 v[114:117], v[186:189], v[194:197], v[114:117]
	v_mfma_f32_16x16x32_bf16 v[98:101], v[186:189], v[202:205], v[98:101]
	v_mfma_f32_16x16x32_bf16 v[82:85], v[186:189], v[232:235], v[82:85]
	v_mfma_f32_16x16x32_bf16 v[66:69], v[186:189], v[240:243], v[66:69]
	s_barrier
	s_setprio 0
	s_mov_b32 m0, s33
	s_add_i32 s52, s85, 0x80
	ds_read_b128 v[190:193], v135 offset:49152
	ds_read_b128 v[194:197], v135 offset:50176
	ds_read_b128 v[198:201], v135 offset:51200
	ds_read_b128 v[202:205], v135 offset:52224
	ds_read_b128 v[228:231], v135 offset:53248
	ds_read_b128 v[232:235], v135 offset:54272
	ds_read_b128 v[236:239], v135 offset:55296
	ds_read_b128 v[240:243], v135 offset:56320
	buffer_load_dwordx4 v131, s[44:47], s52 offen lds
	s_mov_b32 m0, s36
	s_nop 0
	buffer_load_dwordx4 v133, s[44:47], s52 offen lds
	s_add_i32 s52, s52, s2
	s_mov_b32 m0, s43
	s_nop 0
	buffer_load_dwordx4 v131, s[44:47], s52 offen lds
	s_mov_b32 m0, s48
	s_nop 0
	buffer_load_dwordx4 v133, s[44:47], s52 offen lds
	s_mov_b32 m0, s37
	s_nop 0
	buffer_load_dwordx4 v130, s[60:63], s84 offen lds
	s_mov_b32 m0, s42
	s_nop 0
	buffer_load_dwordx4 v132, s[60:63], s84 offen lds
	s_waitcnt vmcnt(8)
	s_waitcnt lgkmcnt(0)
	s_setprio 1
	s_barrier
	v_mfma_f32_16x16x32_bf16 v[62:65], v[136:139], v[190:193], v[62:65]
	v_mfma_f32_16x16x32_bf16 v[46:49], v[136:139], v[198:201], v[46:49]
	v_mfma_f32_16x16x32_bf16 v[30:33], v[136:139], v[228:231], v[30:33]
	v_mfma_f32_16x16x32_bf16 v[14:17], v[136:139], v[236:239], v[14:17]
	v_mfma_f32_16x16x32_bf16 v[58:61], v[154:157], v[190:193], v[58:61]
	v_mfma_f32_16x16x32_bf16 v[42:45], v[154:157], v[198:201], v[42:45]
	v_mfma_f32_16x16x32_bf16 v[26:29], v[154:157], v[228:231], v[26:29]
	v_mfma_f32_16x16x32_bf16 v[10:13], v[154:157], v[236:239], v[10:13]
	v_mfma_f32_16x16x32_bf16 v[62:65], v[140:143], v[194:197], v[62:65]
	v_mfma_f32_16x16x32_bf16 v[46:49], v[140:143], v[202:205], v[46:49]
	v_mfma_f32_16x16x32_bf16 v[30:33], v[140:143], v[232:235], v[30:33]
	v_mfma_f32_16x16x32_bf16 v[14:17], v[140:143], v[240:243], v[14:17]
	v_mfma_f32_16x16x32_bf16 v[58:61], v[170:173], v[194:197], v[58:61]
	v_mfma_f32_16x16x32_bf16 v[42:45], v[170:173], v[202:205], v[42:45]
	v_mfma_f32_16x16x32_bf16 v[26:29], v[170:173], v[232:235], v[26:29]
	v_mfma_f32_16x16x32_bf16 v[10:13], v[170:173], v[240:243], v[10:13]
	v_mfma_f32_16x16x32_bf16 v[54:57], v[174:177], v[190:193], v[54:57]
	v_mfma_f32_16x16x32_bf16 v[38:41], v[174:177], v[198:201], v[38:41]
	v_mfma_f32_16x16x32_bf16 v[22:25], v[174:177], v[228:231], v[22:25]
	v_mfma_f32_16x16x32_bf16 v[6:9], v[174:177], v[236:239], v[6:9]
	v_mfma_f32_16x16x32_bf16 v[50:53], v[182:185], v[190:193], v[50:53]
	v_mfma_f32_16x16x32_bf16 v[34:37], v[182:185], v[198:201], v[34:37]
	v_mfma_f32_16x16x32_bf16 v[18:21], v[182:185], v[228:231], v[18:21]
	v_mfma_f32_16x16x32_bf16 v[2:5], v[182:185], v[236:239], v[2:5]
	v_mfma_f32_16x16x32_bf16 v[54:57], v[178:181], v[194:197], v[54:57]
	v_mfma_f32_16x16x32_bf16 v[38:41], v[178:181], v[202:205], v[38:41]
	v_mfma_f32_16x16x32_bf16 v[22:25], v[178:181], v[232:235], v[22:25]
	v_mfma_f32_16x16x32_bf16 v[6:9], v[178:181], v[240:243], v[6:9]
	v_mfma_f32_16x16x32_bf16 v[50:53], v[186:189], v[194:197], v[50:53]
	v_mfma_f32_16x16x32_bf16 v[34:37], v[186:189], v[202:205], v[34:37]
	v_mfma_f32_16x16x32_bf16 v[18:21], v[186:189], v[232:235], v[18:21]
	v_mfma_f32_16x16x32_bf16 v[2:5], v[186:189], v[240:243], v[2:5]
	s_barrier
	s_setprio 0
	s_add_i32 s83, s83, 2
	s_addk_i32 s73, 0x100
	s_addk_i32 s82, 0x100
	s_cmp_ge_i32 s83, s23
	s_cbranch_scc0 .LBB0_2175
	v_readlane_b32 s83, v252, 30

.LBB0_2449:
	s_lshl_b32 s73, s72, 20
	s_and_b64 s[8:9], s[40:41], exec
	s_cselect_b32 s8, s73, s13
	s_lshl_b32 s84, s71, 20
	s_and_b64 s[24:25], s[40:41], exec
	s_cselect_b32 s9, s84, s21
	s_add_i32 s13, s13, 0x80080
	s_addk_i32 s21, 0x100
	s_mov_b32 s22, -2
	s_waitcnt lgkmcnt(0)
	v_add_u32_e32 v142, 0x10000, v188
	v_add_u32_e32 v182, 0x14000, v188
	ds_read_b128 v[130:133], v142
	ds_read_b128 v[134:137], v142 offset:1024
	ds_read_b128 v[138:141], v142 offset:2048
	ds_read_b128 v[142:145], v142 offset:3072
	ds_read_b128 v[154:157], v182
	ds_read_b128 v[174:177], v182 offset:1024
	ds_read_b128 v[178:181], v182 offset:2048
	ds_read_b128 v[190:193], v182 offset:3072
	s_add_i32 s24, s13, 0xfff80080
	s_cmp_eq_u32 s22, 28
	s_cselect_b32 s52, s8, s24
	s_cselect_b32 s25, s9, s21
	s_or_b32 s24, s52, 0x80
	s_mov_b32 m0, s68
	ds_read_b128 v[194:197], v189
	ds_read_b128 v[198:201], v189 offset:1024
	ds_read_b128 v[202:205], v189 offset:2048
	ds_read_b128 v[228:231], v189 offset:3072
	ds_read_b128 v[232:235], v189 offset:4096
	ds_read_b128 v[236:239], v189 offset:5120
	ds_read_b128 v[240:243], v189 offset:6144
	ds_read_b128 v[244:247], v189 offset:7168
	buffer_load_dwordx4 v184, s[60:63], s13 offen lds
	s_mov_b32 m0, s70
	s_nop 0
	buffer_load_dwordx4 v186, s[60:63], s13 offen lds
	s_waitcnt vmcnt(8)
	s_waitcnt lgkmcnt(0)
	s_setprio 1
	s_barrier
	v_mfma_f32_16x16x32_bf16 v[126:129], v[130:133], v[194:197], 0
	v_mfma_f32_16x16x32_bf16 v[110:113], v[130:133], v[202:205], 0
	v_mfma_f32_16x16x32_bf16 v[94:97], v[130:133], v[232:235], 0
	v_mfma_f32_16x16x32_bf16 v[78:81], v[130:133], v[240:243], 0
	v_mfma_f32_16x16x32_bf16 v[122:125], v[138:141], v[194:197], 0
	v_mfma_f32_16x16x32_bf16 v[106:109], v[138:141], v[202:205], 0
	v_mfma_f32_16x16x32_bf16 v[90:93], v[138:141], v[232:235], 0
	v_mfma_f32_16x16x32_bf16 v[74:77], v[138:141], v[240:243], 0
	v_mfma_f32_16x16x32_bf16 v[126:129], v[134:137], v[198:201], v[126:129]
	v_mfma_f32_16x16x32_bf16 v[110:113], v[134:137], v[228:231], v[110:113]
	v_mfma_f32_16x16x32_bf16 v[94:97], v[134:137], v[236:239], v[94:97]
	v_mfma_f32_16x16x32_bf16 v[78:81], v[134:137], v[244:247], v[78:81]
	v_mfma_f32_16x16x32_bf16 v[122:125], v[142:145], v[198:201], v[122:125]
	v_mfma_f32_16x16x32_bf16 v[106:109], v[142:145], v[228:231], v[106:109]
	v_mfma_f32_16x16x32_bf16 v[90:93], v[142:145], v[236:239], v[90:93]
	v_mfma_f32_16x16x32_bf16 v[74:77], v[142:145], v[244:247], v[74:77]
	v_mfma_f32_16x16x32_bf16 v[118:121], v[154:157], v[194:197], 0
	v_mfma_f32_16x16x32_bf16 v[102:105], v[154:157], v[202:205], 0
	v_mfma_f32_16x16x32_bf16 v[86:89], v[154:157], v[232:235], 0
	v_mfma_f32_16x16x32_bf16 v[70:73], v[154:157], v[240:243], 0
	v_mfma_f32_16x16x32_bf16 v[114:117], v[178:181], v[194:197], 0
	v_mfma_f32_16x16x32_bf16 v[98:101], v[178:181], v[202:205], 0
	v_mfma_f32_16x16x32_bf16 v[82:85], v[178:181], v[232:235], 0
	v_mfma_f32_16x16x32_bf16 v[66:69], v[178:181], v[240:243], 0
	v_mfma_f32_16x16x32_bf16 v[118:121], v[174:177], v[198:201], v[118:121]
	v_mfma_f32_16x16x32_bf16 v[102:105], v[174:177], v[228:231], v[102:105]
	v_mfma_f32_16x16x32_bf16 v[86:89], v[174:177], v[236:239], v[86:89]
	v_mfma_f32_16x16x32_bf16 v[70:73], v[174:177], v[244:247], v[70:73]
	v_mfma_f32_16x16x32_bf16 v[114:117], v[190:193], v[198:201], v[114:117]
	v_mfma_f32_16x16x32_bf16 v[98:101], v[190:193], v[228:231], v[98:101]
	v_mfma_f32_16x16x32_bf16 v[82:85], v[190:193], v[236:239], v[82:85]
	v_mfma_f32_16x16x32_bf16 v[66:69], v[190:193], v[244:247], v[66:69]
	s_barrier
	s_setprio 0
	s_mov_b32 m0, s16
	s_mov_b32 s46, s62
	s_mov_b32 s47, s63
	ds_read_b128 v[194:197], v189 offset:16384
	ds_read_b128 v[198:201], v189 offset:17408
	ds_read_b128 v[202:205], v189 offset:18432
	ds_read_b128 v[228:231], v189 offset:19456
	ds_read_b128 v[232:235], v189 offset:20480
	ds_read_b128 v[236:239], v189 offset:21504
	ds_read_b128 v[240:243], v189 offset:22528
	ds_read_b128 v[244:247], v189 offset:23552
	buffer_load_dwordx4 v185, s[44:47], s25 offen lds
	s_mov_b32 m0, s18
	s_add_i32 s53, s25, 0x80000
	buffer_load_dwordx4 v187, s[44:47], s25 offen lds
	s_mov_b32 m0, s19
	s_nop 0
	buffer_load_dwordx4 v185, s[44:47], s53 offen lds
	s_mov_b32 m0, s23
	s_nop 0
	buffer_load_dwordx4 v187, s[44:47], s53 offen lds
	s_mov_b32 m0, s15
	s_nop 0
	buffer_load_dwordx4 v184, s[60:63], s52 offen lds
	s_mov_b32 m0, s26
	s_nop 0
	buffer_load_dwordx4 v186, s[60:63], s52 offen lds
	s_waitcnt vmcnt(8)
	s_waitcnt lgkmcnt(0)
	s_setprio 1
	s_barrier
	v_mfma_f32_16x16x32_bf16 v[62:65], v[130:133], v[194:197], 0
	v_mfma_f32_16x16x32_bf16 v[46:49], v[130:133], v[202:205], 0
	v_mfma_f32_16x16x32_bf16 v[30:33], v[130:133], v[232:235], 0
	v_mfma_f32_16x16x32_bf16 v[14:17], v[130:133], v[240:243], 0
	v_mfma_f32_16x16x32_bf16 v[58:61], v[138:141], v[194:197], 0
	v_mfma_f32_16x16x32_bf16 v[42:45], v[138:141], v[202:205], 0
	v_mfma_f32_16x16x32_bf16 v[26:29], v[138:141], v[232:235], 0
	v_mfma_f32_16x16x32_bf16 v[10:13], v[138:141], v[240:243], 0
	v_mfma_f32_16x16x32_bf16 v[62:65], v[134:137], v[198:201], v[62:65]
	v_mfma_f32_16x16x32_bf16 v[46:49], v[134:137], v[228:231], v[46:49]
	v_mfma_f32_16x16x32_bf16 v[30:33], v[134:137], v[236:239], v[30:33]
	v_mfma_f32_16x16x32_bf16 v[14:17], v[134:137], v[244:247], v[14:17]
	v_mfma_f32_16x16x32_bf16 v[58:61], v[142:145], v[198:201], v[58:61]
	v_mfma_f32_16x16x32_bf16 v[42:45], v[142:145], v[228:231], v[42:45]
	v_mfma_f32_16x16x32_bf16 v[26:29], v[142:145], v[236:239], v[26:29]
	v_mfma_f32_16x16x32_bf16 v[10:13], v[142:145], v[244:247], v[10:13]
	v_mfma_f32_16x16x32_bf16 v[54:57], v[154:157], v[194:197], 0
	v_mfma_f32_16x16x32_bf16 v[38:41], v[154:157], v[202:205], 0
	v_mfma_f32_16x16x32_bf16 v[22:25], v[154:157], v[232:235], 0
	v_mfma_f32_16x16x32_bf16 v[6:9], v[154:157], v[240:243], 0
	v_mfma_f32_16x16x32_bf16 v[50:53], v[178:181], v[194:197], 0
	v_mfma_f32_16x16x32_bf16 v[34:37], v[178:181], v[202:205], 0
	v_mfma_f32_16x16x32_bf16 v[18:21], v[178:181], v[232:235], 0
	v_mfma_f32_16x16x32_bf16 v[2:5], v[178:181], v[240:243], 0
	v_mfma_f32_16x16x32_bf16 v[54:57], v[174:177], v[198:201], v[54:57]
	v_mfma_f32_16x16x32_bf16 v[38:41], v[174:177], v[228:231], v[38:41]
	v_mfma_f32_16x16x32_bf16 v[22:25], v[174:177], v[236:239], v[22:25]
	v_mfma_f32_16x16x32_bf16 v[6:9], v[174:177], v[244:247], v[6:9]
	v_mfma_f32_16x16x32_bf16 v[50:53], v[190:193], v[198:201], v[50:53]
	v_mfma_f32_16x16x32_bf16 v[34:37], v[190:193], v[228:231], v[34:37]
	v_mfma_f32_16x16x32_bf16 v[18:21], v[190:193], v[236:239], v[18:21]
	v_mfma_f32_16x16x32_bf16 v[2:5], v[190:193], v[244:247], v[2:5]
	s_barrier
	s_setprio 0
	v_add_u32_e32 v142, 0x18000, v188
	v_add_u32_e32 v182, 0x1c000, v188
	ds_read_b128 v[130:133], v142
	ds_read_b128 v[134:137], v142 offset:1024
	ds_read_b128 v[138:141], v142 offset:2048
	ds_read_b128 v[142:145], v142 offset:3072
	ds_read_b128 v[154:157], v182
	ds_read_b128 v[174:177], v182 offset:1024
	ds_read_b128 v[178:181], v182 offset:2048
	ds_read_b128 v[190:193], v182 offset:3072
	s_add_i32 s52, s52, 0x80000
	s_mov_b32 m0, s27
	ds_read_b128 v[194:197], v189 offset:32768
	ds_read_b128 v[198:201], v189 offset:33792
	ds_read_b128 v[202:205], v189 offset:34816
	ds_read_b128 v[228:231], v189 offset:35840
	ds_read_b128 v[232:235], v189 offset:36864
	ds_read_b128 v[236:239], v189 offset:37888
	ds_read_b128 v[240:243], v189 offset:38912
	ds_read_b128 v[244:247], v189 offset:39936
	buffer_load_dwordx4 v184, s[60:63], s52 offen lds
	s_mov_b32 m0, s30
	s_nop 0
	buffer_load_dwordx4 v186, s[60:63], s52 offen lds
	s_waitcnt vmcnt(8)
	s_waitcnt lgkmcnt(0)
	s_setprio 1
	s_barrier
	v_mfma_f32_16x16x32_bf16 v[126:129], v[130:133], v[194:197], v[126:129]
	v_mfma_f32_16x16x32_bf16 v[110:113], v[130:133], v[202:205], v[110:113]
	v_mfma_f32_16x16x32_bf16 v[94:97], v[130:133], v[232:235], v[94:97]
	v_mfma_f32_16x16x32_bf16 v[78:81], v[130:133], v[240:243], v[78:81]
	v_mfma_f32_16x16x32_bf16 v[122:125], v[138:141], v[194:197], v[122:125]
	v_mfma_f32_16x16x32_bf16 v[106:109], v[138:141], v[202:205], v[106:109]
	v_mfma_f32_16x16x32_bf16 v[90:93], v[138:141], v[232:235], v[90:93]
	v_mfma_f32_16x16x32_bf16 v[74:77], v[138:141], v[240:243], v[74:77]
	v_mfma_f32_16x16x32_bf16 v[126:129], v[134:137], v[198:201], v[126:129]
	v_mfma_f32_16x16x32_bf16 v[110:113], v[134:137], v[228:231], v[110:113]
	v_mfma_f32_16x16x32_bf16 v[94:97], v[134:137], v[236:239], v[94:97]
	v_mfma_f32_16x16x32_bf16 v[78:81], v[134:137], v[244:247], v[78:81]
	v_mfma_f32_16x16x32_bf16 v[122:125], v[142:145], v[198:201], v[122:125]
	v_mfma_f32_16x16x32_bf16 v[106:109], v[142:145], v[228:231], v[106:109]
	v_mfma_f32_16x16x32_bf16 v[90:93], v[142:145], v[236:239], v[90:93]
	v_mfma_f32_16x16x32_bf16 v[74:77], v[142:145], v[244:247], v[74:77]
	v_mfma_f32_16x16x32_bf16 v[118:121], v[154:157], v[194:197], v[118:121]
	v_mfma_f32_16x16x32_bf16 v[102:105], v[154:157], v[202:205], v[102:105]
	v_mfma_f32_16x16x32_bf16 v[86:89], v[154:157], v[232:235], v[86:89]
	v_mfma_f32_16x16x32_bf16 v[70:73], v[154:157], v[240:243], v[70:73]
	v_mfma_f32_16x16x32_bf16 v[114:117], v[178:181], v[194:197], v[114:117]
	v_mfma_f32_16x16x32_bf16 v[98:101], v[178:181], v[202:205], v[98:101]
	v_mfma_f32_16x16x32_bf16 v[82:85], v[178:181], v[232:235], v[82:85]
	v_mfma_f32_16x16x32_bf16 v[66:69], v[178:181], v[240:243], v[66:69]
	v_mfma_f32_16x16x32_bf16 v[118:121], v[174:177], v[198:201], v[118:121]
	v_mfma_f32_16x16x32_bf16 v[102:105], v[174:177], v[228:231], v[102:105]
	v_mfma_f32_16x16x32_bf16 v[86:89], v[174:177], v[236:239], v[86:89]
	v_mfma_f32_16x16x32_bf16 v[70:73], v[174:177], v[244:247], v[70:73]
	v_mfma_f32_16x16x32_bf16 v[114:117], v[190:193], v[198:201], v[114:117]
	v_mfma_f32_16x16x32_bf16 v[98:101], v[190:193], v[228:231], v[98:101]
	v_mfma_f32_16x16x32_bf16 v[82:85], v[190:193], v[236:239], v[82:85]
	v_mfma_f32_16x16x32_bf16 v[66:69], v[190:193], v[244:247], v[66:69]
	s_barrier
	s_setprio 0
	s_mov_b32 m0, s36
	s_or_b32 s52, s25, 0x80
	ds_read_b128 v[194:197], v189 offset:49152
	ds_read_b128 v[198:201], v189 offset:50176
	ds_read_b128 v[202:205], v189 offset:51200
	ds_read_b128 v[228:231], v189 offset:52224
	ds_read_b128 v[232:235], v189 offset:53248
	ds_read_b128 v[236:239], v189 offset:54272
	ds_read_b128 v[240:243], v189 offset:55296
	ds_read_b128 v[244:247], v189 offset:56320
	buffer_load_dwordx4 v185, s[44:47], s52 offen lds
	s_mov_b32 m0, s37
	s_add_i32 s25, s25, 0x80080
	buffer_load_dwordx4 v187, s[44:47], s52 offen lds
	s_mov_b32 m0, s66
	s_nop 0
	buffer_load_dwordx4 v185, s[44:47], s25 offen lds
	s_mov_b32 m0, s67
	s_nop 0
	buffer_load_dwordx4 v187, s[44:47], s25 offen lds
	s_mov_b32 m0, s48
	s_nop 0
	buffer_load_dwordx4 v184, s[60:63], s24 offen lds
	s_mov_b32 m0, s49
	s_nop 0
	buffer_load_dwordx4 v186, s[60:63], s24 offen lds
	s_waitcnt vmcnt(8)
	s_waitcnt lgkmcnt(0)
	s_setprio 1
	s_barrier
	v_mfma_f32_16x16x32_bf16 v[62:65], v[130:133], v[194:197], v[62:65]
	v_mfma_f32_16x16x32_bf16 v[46:49], v[130:133], v[202:205], v[46:49]
	v_mfma_f32_16x16x32_bf16 v[30:33], v[130:133], v[232:235], v[30:33]
	v_mfma_f32_16x16x32_bf16 v[14:17], v[130:133], v[240:243], v[14:17]
	v_mfma_f32_16x16x32_bf16 v[58:61], v[138:141], v[194:197], v[58:61]
	v_mfma_f32_16x16x32_bf16 v[42:45], v[138:141], v[202:205], v[42:45]
	v_mfma_f32_16x16x32_bf16 v[26:29], v[138:141], v[232:235], v[26:29]
	v_mfma_f32_16x16x32_bf16 v[10:13], v[138:141], v[240:243], v[10:13]
	v_mfma_f32_16x16x32_bf16 v[62:65], v[134:137], v[198:201], v[62:65]
	v_mfma_f32_16x16x32_bf16 v[46:49], v[134:137], v[228:231], v[46:49]
	v_mfma_f32_16x16x32_bf16 v[30:33], v[134:137], v[236:239], v[30:33]
	v_mfma_f32_16x16x32_bf16 v[14:17], v[134:137], v[244:247], v[14:17]
	v_mfma_f32_16x16x32_bf16 v[58:61], v[142:145], v[198:201], v[58:61]
	v_mfma_f32_16x16x32_bf16 v[42:45], v[142:145], v[228:231], v[42:45]
	v_mfma_f32_16x16x32_bf16 v[26:29], v[142:145], v[236:239], v[26:29]
	v_mfma_f32_16x16x32_bf16 v[10:13], v[142:145], v[244:247], v[10:13]
	v_mfma_f32_16x16x32_bf16 v[54:57], v[154:157], v[194:197], v[54:57]
	v_mfma_f32_16x16x32_bf16 v[38:41], v[154:157], v[202:205], v[38:41]
	v_mfma_f32_16x16x32_bf16 v[22:25], v[154:157], v[232:235], v[22:25]
	v_mfma_f32_16x16x32_bf16 v[6:9], v[154:157], v[240:243], v[6:9]
	v_mfma_f32_16x16x32_bf16 v[50:53], v[178:181], v[194:197], v[50:53]
	v_mfma_f32_16x16x32_bf16 v[34:37], v[178:181], v[202:205], v[34:37]
	v_mfma_f32_16x16x32_bf16 v[18:21], v[178:181], v[232:235], v[18:21]
	v_mfma_f32_16x16x32_bf16 v[2:5], v[178:181], v[240:243], v[2:5]
	v_mfma_f32_16x16x32_bf16 v[54:57], v[174:177], v[198:201], v[54:57]
	v_mfma_f32_16x16x32_bf16 v[38:41], v[174:177], v[228:231], v[38:41]
	v_mfma_f32_16x16x32_bf16 v[22:25], v[174:177], v[236:239], v[22:25]
	v_mfma_f32_16x16x32_bf16 v[6:9], v[174:177], v[244:247], v[6:9]
	v_mfma_f32_16x16x32_bf16 v[50:53], v[190:193], v[198:201], v[50:53]
	v_mfma_f32_16x16x32_bf16 v[34:37], v[190:193], v[228:231], v[34:37]
	v_mfma_f32_16x16x32_bf16 v[18:21], v[190:193], v[236:239], v[18:21]
	v_mfma_f32_16x16x32_bf16 v[2:5], v[190:193], v[244:247], v[2:5]
	s_barrier
	s_setprio 0
	s_add_i32 s22, s22, 2
	s_addk_i32 s13, 0x100
	s_addk_i32 s21, 0x100
	s_cmp_gt_u32 s22, 29
.LBB0_2450:
	v_add_u32_e32 v142, 0x10000, v188
	v_add_u32_e32 v182, 0x14000, v188
	ds_read_b128 v[130:133], v142
	ds_read_b128 v[134:137], v142 offset:1024
	ds_read_b128 v[138:141], v142 offset:2048
	ds_read_b128 v[142:145], v142 offset:3072
	ds_read_b128 v[154:157], v182
	ds_read_b128 v[174:177], v182 offset:1024
	ds_read_b128 v[178:181], v182 offset:2048
	ds_read_b128 v[190:193], v182 offset:3072
	s_add_i32 s24, s13, 0xfff80080
	s_cmp_eq_u32 s22, 28
	s_cselect_b32 s52, s8, s24
	s_cselect_b32 s25, s9, s21
	s_or_b32 s24, s52, 0x80
	s_mov_b32 m0, s68
	ds_read_b128 v[194:197], v189
	ds_read_b128 v[198:201], v189 offset:1024
	ds_read_b128 v[202:205], v189 offset:2048
	ds_read_b128 v[228:231], v189 offset:3072
	ds_read_b128 v[232:235], v189 offset:4096
	ds_read_b128 v[236:239], v189 offset:5120
	ds_read_b128 v[240:243], v189 offset:6144
	ds_read_b128 v[244:247], v189 offset:7168
	buffer_load_dwordx4 v184, s[60:63], s13 offen lds
	s_mov_b32 m0, s70
	s_nop 0
	buffer_load_dwordx4 v186, s[60:63], s13 offen lds
	s_waitcnt vmcnt(8)
	s_waitcnt lgkmcnt(0)
	s_setprio 1
	s_barrier
	v_mfma_f32_16x16x32_bf16 v[126:129], v[130:133], v[194:197], v[126:129]
	v_mfma_f32_16x16x32_bf16 v[110:113], v[130:133], v[202:205], v[110:113]
	v_mfma_f32_16x16x32_bf16 v[94:97], v[130:133], v[232:235], v[94:97]
	v_mfma_f32_16x16x32_bf16 v[78:81], v[130:133], v[240:243], v[78:81]
	v_mfma_f32_16x16x32_bf16 v[122:125], v[138:141], v[194:197], v[122:125]
	v_mfma_f32_16x16x32_bf16 v[106:109], v[138:141], v[202:205], v[106:109]
	v_mfma_f32_16x16x32_bf16 v[90:93], v[138:141], v[232:235], v[90:93]
	v_mfma_f32_16x16x32_bf16 v[74:77], v[138:141], v[240:243], v[74:77]
	v_mfma_f32_16x16x32_bf16 v[126:129], v[134:137], v[198:201], v[126:129]
	v_mfma_f32_16x16x32_bf16 v[110:113], v[134:137], v[228:231], v[110:113]
	v_mfma_f32_16x16x32_bf16 v[94:97], v[134:137], v[236:239], v[94:97]
	v_mfma_f32_16x16x32_bf16 v[78:81], v[134:137], v[244:247], v[78:81]
	v_mfma_f32_16x16x32_bf16 v[122:125], v[142:145], v[198:201], v[122:125]
	v_mfma_f32_16x16x32_bf16 v[106:109], v[142:145], v[228:231], v[106:109]
	v_mfma_f32_16x16x32_bf16 v[90:93], v[142:145], v[236:239], v[90:93]
	v_mfma_f32_16x16x32_bf16 v[74:77], v[142:145], v[244:247], v[74:77]
	v_mfma_f32_16x16x32_bf16 v[118:121], v[154:157], v[194:197], v[118:121]
	v_mfma_f32_16x16x32_bf16 v[102:105], v[154:157], v[202:205], v[102:105]
	v_mfma_f32_16x16x32_bf16 v[86:89], v[154:157], v[232:235], v[86:89]
	v_mfma_f32_16x16x32_bf16 v[70:73], v[154:157], v[240:243], v[70:73]
	v_mfma_f32_16x16x32_bf16 v[114:117], v[178:181], v[194:197], v[114:117]
	v_mfma_f32_16x16x32_bf16 v[98:101], v[178:181], v[202:205], v[98:101]
	v_mfma_f32_16x16x32_bf16 v[82:85], v[178:181], v[232:235], v[82:85]
	v_mfma_f32_16x16x32_bf16 v[66:69], v[178:181], v[240:243], v[66:69]
	v_mfma_f32_16x16x32_bf16 v[118:121], v[174:177], v[198:201], v[118:121]
	v_mfma_f32_16x16x32_bf16 v[102:105], v[174:177], v[228:231], v[102:105]
	v_mfma_f32_16x16x32_bf16 v[86:89], v[174:177], v[236:239], v[86:89]
	v_mfma_f32_16x16x32_bf16 v[70:73], v[174:177], v[244:247], v[70:73]
	v_mfma_f32_16x16x32_bf16 v[114:117], v[190:193], v[198:201], v[114:117]
	v_mfma_f32_16x16x32_bf16 v[98:101], v[190:193], v[228:231], v[98:101]
	v_mfma_f32_16x16x32_bf16 v[82:85], v[190:193], v[236:239], v[82:85]
	v_mfma_f32_16x16x32_bf16 v[66:69], v[190:193], v[244:247], v[66:69]
	s_barrier
	s_setprio 0
	s_mov_b32 m0, s16
	s_mov_b32 s46, s62
	s_mov_b32 s47, s63
	ds_read_b128 v[194:197], v189 offset:16384
	ds_read_b128 v[198:201], v189 offset:17408
	ds_read_b128 v[202:205], v189 offset:18432
	ds_read_b128 v[228:231], v189 offset:19456
	ds_read_b128 v[232:235], v189 offset:20480
	ds_read_b128 v[236:239], v189 offset:21504
	ds_read_b128 v[240:243], v189 offset:22528
	ds_read_b128 v[244:247], v189 offset:23552
	buffer_load_dwordx4 v185, s[44:47], s25 offen lds
	s_mov_b32 m0, s18
	s_add_i32 s53, s25, 0x80000
	buffer_load_dwordx4 v187, s[44:47], s25 offen lds
	s_mov_b32 m0, s19
	s_nop 0
	buffer_load_dwordx4 v185, s[44:47], s53 offen lds
	s_mov_b32 m0, s23
	s_nop 0
	buffer_load_dwordx4 v187, s[44:47], s53 offen lds
	s_mov_b32 m0, s15
	s_nop 0
	buffer_load_dwordx4 v184, s[60:63], s52 offen lds
	s_mov_b32 m0, s26
	s_nop 0
	buffer_load_dwordx4 v186, s[60:63], s52 offen lds
	s_waitcnt vmcnt(8)
	s_waitcnt lgkmcnt(0)
	s_setprio 1
	s_barrier
	v_mfma_f32_16x16x32_bf16 v[62:65], v[130:133], v[194:197], v[62:65]
	v_mfma_f32_16x16x32_bf16 v[46:49], v[130:133], v[202:205], v[46:49]
	v_mfma_f32_16x16x32_bf16 v[30:33], v[130:133], v[232:235], v[30:33]
	v_mfma_f32_16x16x32_bf16 v[14:17], v[130:133], v[240:243], v[14:17]
	v_mfma_f32_16x16x32_bf16 v[58:61], v[138:141], v[194:197], v[58:61]
	v_mfma_f32_16x16x32_bf16 v[42:45], v[138:141], v[202:205], v[42:45]
	v_mfma_f32_16x16x32_bf16 v[26:29], v[138:141], v[232:235], v[26:29]
	v_mfma_f32_16x16x32_bf16 v[10:13], v[138:141], v[240:243], v[10:13]
	v_mfma_f32_16x16x32_bf16 v[62:65], v[134:137], v[198:201], v[62:65]
	v_mfma_f32_16x16x32_bf16 v[46:49], v[134:137], v[228:231], v[46:49]
	v_mfma_f32_16x16x32_bf16 v[30:33], v[134:137], v[236:239], v[30:33]
	v_mfma_f32_16x16x32_bf16 v[14:17], v[134:137], v[244:247], v[14:17]
	v_mfma_f32_16x16x32_bf16 v[58:61], v[142:145], v[198:201], v[58:61]
	v_mfma_f32_16x16x32_bf16 v[42:45], v[142:145], v[228:231], v[42:45]
	v_mfma_f32_16x16x32_bf16 v[26:29], v[142:145], v[236:239], v[26:29]
	v_mfma_f32_16x16x32_bf16 v[10:13], v[142:145], v[244:247], v[10:13]
	v_mfma_f32_16x16x32_bf16 v[54:57], v[154:157], v[194:197], v[54:57]
	v_mfma_f32_16x16x32_bf16 v[38:41], v[154:157], v[202:205], v[38:41]
	v_mfma_f32_16x16x32_bf16 v[22:25], v[154:157], v[232:235], v[22:25]
	v_mfma_f32_16x16x32_bf16 v[6:9], v[154:157], v[240:243], v[6:9]
	v_mfma_f32_16x16x32_bf16 v[50:53], v[178:181], v[194:197], v[50:53]
	v_mfma_f32_16x16x32_bf16 v[34:37], v[178:181], v[202:205], v[34:37]
	v_mfma_f32_16x16x32_bf16 v[18:21], v[178:181], v[232:235], v[18:21]
	v_mfma_f32_16x16x32_bf16 v[2:5], v[178:181], v[240:243], v[2:5]
	v_mfma_f32_16x16x32_bf16 v[54:57], v[174:177], v[198:201], v[54:57]
	v_mfma_f32_16x16x32_bf16 v[38:41], v[174:177], v[228:231], v[38:41]
	v_mfma_f32_16x16x32_bf16 v[22:25], v[174:177], v[236:239], v[22:25]
	v_mfma_f32_16x16x32_bf16 v[6:9], v[174:177], v[244:247], v[6:9]
	v_mfma_f32_16x16x32_bf16 v[50:53], v[190:193], v[198:201], v[50:53]
	v_mfma_f32_16x16x32_bf16 v[34:37], v[190:193], v[228:231], v[34:37]
	v_mfma_f32_16x16x32_bf16 v[18:21], v[190:193], v[236:239], v[18:21]
	v_mfma_f32_16x16x32_bf16 v[2:5], v[190:193], v[244:247], v[2:5]
	s_barrier
	s_setprio 0
	v_add_u32_e32 v142, 0x18000, v188
	v_add_u32_e32 v182, 0x1c000, v188
	ds_read_b128 v[130:133], v142
	ds_read_b128 v[134:137], v142 offset:1024
	ds_read_b128 v[138:141], v142 offset:2048
	ds_read_b128 v[142:145], v142 offset:3072
	ds_read_b128 v[154:157], v182
	ds_read_b128 v[174:177], v182 offset:1024
	ds_read_b128 v[178:181], v182 offset:2048
	ds_read_b128 v[190:193], v182 offset:3072
	s_add_i32 s52, s52, 0x80000
	s_mov_b32 m0, s27
	ds_read_b128 v[194:197], v189 offset:32768
	ds_read_b128 v[198:201], v189 offset:33792
	ds_read_b128 v[202:205], v189 offset:34816
	ds_read_b128 v[228:231], v189 offset:35840
	ds_read_b128 v[232:235], v189 offset:36864
	ds_read_b128 v[236:239], v189 offset:37888
	ds_read_b128 v[240:243], v189 offset:38912
	ds_read_b128 v[244:247], v189 offset:39936
	buffer_load_dwordx4 v184, s[60:63], s52 offen lds
	s_mov_b32 m0, s30
	s_nop 0
	buffer_load_dwordx4 v186, s[60:63], s52 offen lds
	s_waitcnt vmcnt(8)
	s_waitcnt lgkmcnt(0)
	s_setprio 1
	s_barrier
	v_mfma_f32_16x16x32_bf16 v[126:129], v[130:133], v[194:197], v[126:129]
	v_mfma_f32_16x16x32_bf16 v[110:113], v[130:133], v[202:205], v[110:113]
	v_mfma_f32_16x16x32_bf16 v[94:97], v[130:133], v[232:235], v[94:97]
	v_mfma_f32_16x16x32_bf16 v[78:81], v[130:133], v[240:243], v[78:81]
	v_mfma_f32_16x16x32_bf16 v[122:125], v[138:141], v[194:197], v[122:125]
	v_mfma_f32_16x16x32_bf16 v[106:109], v[138:141], v[202:205], v[106:109]
	v_mfma_f32_16x16x32_bf16 v[90:93], v[138:141], v[232:235], v[90:93]
	v_mfma_f32_16x16x32_bf16 v[74:77], v[138:141], v[240:243], v[74:77]
	v_mfma_f32_16x16x32_bf16 v[126:129], v[134:137], v[198:201], v[126:129]
	v_mfma_f32_16x16x32_bf16 v[110:113], v[134:137], v[228:231], v[110:113]
	v_mfma_f32_16x16x32_bf16 v[94:97], v[134:137], v[236:239], v[94:97]
	v_mfma_f32_16x16x32_bf16 v[78:81], v[134:137], v[244:247], v[78:81]
	v_mfma_f32_16x16x32_bf16 v[122:125], v[142:145], v[198:201], v[122:125]
	v_mfma_f32_16x16x32_bf16 v[106:109], v[142:145], v[228:231], v[106:109]
	v_mfma_f32_16x16x32_bf16 v[90:93], v[142:145], v[236:239], v[90:93]
	v_mfma_f32_16x16x32_bf16 v[74:77], v[142:145], v[244:247], v[74:77]
	v_mfma_f32_16x16x32_bf16 v[118:121], v[154:157], v[194:197], v[118:121]
	v_mfma_f32_16x16x32_bf16 v[102:105], v[154:157], v[202:205], v[102:105]
	v_mfma_f32_16x16x32_bf16 v[86:89], v[154:157], v[232:235], v[86:89]
	v_mfma_f32_16x16x32_bf16 v[70:73], v[154:157], v[240:243], v[70:73]
	v_mfma_f32_16x16x32_bf16 v[114:117], v[178:181], v[194:197], v[114:117]
	v_mfma_f32_16x16x32_bf16 v[98:101], v[178:181], v[202:205], v[98:101]
	v_mfma_f32_16x16x32_bf16 v[82:85], v[178:181], v[232:235], v[82:85]
	v_mfma_f32_16x16x32_bf16 v[66:69], v[178:181], v[240:243], v[66:69]
	v_mfma_f32_16x16x32_bf16 v[118:121], v[174:177], v[198:201], v[118:121]
	v_mfma_f32_16x16x32_bf16 v[102:105], v[174:177], v[228:231], v[102:105]
	v_mfma_f32_16x16x32_bf16 v[86:89], v[174:177], v[236:239], v[86:89]
	v_mfma_f32_16x16x32_bf16 v[70:73], v[174:177], v[244:247], v[70:73]
	v_mfma_f32_16x16x32_bf16 v[114:117], v[190:193], v[198:201], v[114:117]
	v_mfma_f32_16x16x32_bf16 v[98:101], v[190:193], v[228:231], v[98:101]
	v_mfma_f32_16x16x32_bf16 v[82:85], v[190:193], v[236:239], v[82:85]
	v_mfma_f32_16x16x32_bf16 v[66:69], v[190:193], v[244:247], v[66:69]
	s_barrier
	s_setprio 0
	s_mov_b32 m0, s36
	s_or_b32 s52, s25, 0x80
	ds_read_b128 v[194:197], v189 offset:49152
	ds_read_b128 v[198:201], v189 offset:50176
	ds_read_b128 v[202:205], v189 offset:51200
	ds_read_b128 v[228:231], v189 offset:52224
	ds_read_b128 v[232:235], v189 offset:53248
	ds_read_b128 v[236:239], v189 offset:54272
	ds_read_b128 v[240:243], v189 offset:55296
	ds_read_b128 v[244:247], v189 offset:56320
	buffer_load_dwordx4 v185, s[44:47], s52 offen lds
	s_mov_b32 m0, s37
	s_add_i32 s25, s25, 0x80080
	buffer_load_dwordx4 v187, s[44:47], s52 offen lds
	s_mov_b32 m0, s66
	s_nop 0
	buffer_load_dwordx4 v185, s[44:47], s25 offen lds
	s_mov_b32 m0, s67
	s_nop 0
	buffer_load_dwordx4 v187, s[44:47], s25 offen lds
	s_mov_b32 m0, s48
	s_nop 0
	buffer_load_dwordx4 v184, s[60:63], s24 offen lds
	s_mov_b32 m0, s49
	s_nop 0
	buffer_load_dwordx4 v186, s[60:63], s24 offen lds
	s_waitcnt vmcnt(8)
	s_waitcnt lgkmcnt(0)
	s_setprio 1
	s_barrier
	v_mfma_f32_16x16x32_bf16 v[62:65], v[130:133], v[194:197], v[62:65]
	v_mfma_f32_16x16x32_bf16 v[46:49], v[130:133], v[202:205], v[46:49]
	v_mfma_f32_16x16x32_bf16 v[30:33], v[130:133], v[232:235], v[30:33]
	v_mfma_f32_16x16x32_bf16 v[14:17], v[130:133], v[240:243], v[14:17]
	v_mfma_f32_16x16x32_bf16 v[58:61], v[138:141], v[194:197], v[58:61]
	v_mfma_f32_16x16x32_bf16 v[42:45], v[138:141], v[202:205], v[42:45]
	v_mfma_f32_16x16x32_bf16 v[26:29], v[138:141], v[232:235], v[26:29]
	v_mfma_f32_16x16x32_bf16 v[10:13], v[138:141], v[240:243], v[10:13]
	v_mfma_f32_16x16x32_bf16 v[62:65], v[134:137], v[198:201], v[62:65]
	v_mfma_f32_16x16x32_bf16 v[46:49], v[134:137], v[228:231], v[46:49]
	v_mfma_f32_16x16x32_bf16 v[30:33], v[134:137], v[236:239], v[30:33]
	v_mfma_f32_16x16x32_bf16 v[14:17], v[134:137], v[244:247], v[14:17]
	v_mfma_f32_16x16x32_bf16 v[58:61], v[142:145], v[198:201], v[58:61]
	v_mfma_f32_16x16x32_bf16 v[42:45], v[142:145], v[228:231], v[42:45]
	v_mfma_f32_16x16x32_bf16 v[26:29], v[142:145], v[236:239], v[26:29]
	v_mfma_f32_16x16x32_bf16 v[10:13], v[142:145], v[244:247], v[10:13]
	v_mfma_f32_16x16x32_bf16 v[54:57], v[154:157], v[194:197], v[54:57]
	v_mfma_f32_16x16x32_bf16 v[38:41], v[154:157], v[202:205], v[38:41]
	v_mfma_f32_16x16x32_bf16 v[22:25], v[154:157], v[232:235], v[22:25]
	v_mfma_f32_16x16x32_bf16 v[6:9], v[154:157], v[240:243], v[6:9]
	v_mfma_f32_16x16x32_bf16 v[50:53], v[178:181], v[194:197], v[50:53]
	v_mfma_f32_16x16x32_bf16 v[34:37], v[178:181], v[202:205], v[34:37]
	v_mfma_f32_16x16x32_bf16 v[18:21], v[178:181], v[232:235], v[18:21]
	v_mfma_f32_16x16x32_bf16 v[2:5], v[178:181], v[240:243], v[2:5]
	v_mfma_f32_16x16x32_bf16 v[54:57], v[174:177], v[198:201], v[54:57]
	v_mfma_f32_16x16x32_bf16 v[38:41], v[174:177], v[228:231], v[38:41]
	v_mfma_f32_16x16x32_bf16 v[22:25], v[174:177], v[236:239], v[22:25]
	v_mfma_f32_16x16x32_bf16 v[6:9], v[174:177], v[244:247], v[6:9]
	v_mfma_f32_16x16x32_bf16 v[50:53], v[190:193], v[198:201], v[50:53]
	v_mfma_f32_16x16x32_bf16 v[34:37], v[190:193], v[228:231], v[34:37]
	v_mfma_f32_16x16x32_bf16 v[18:21], v[190:193], v[236:239], v[18:21]
	v_mfma_f32_16x16x32_bf16 v[2:5], v[190:193], v[244:247], v[2:5]
	s_barrier
	s_setprio 0
	s_add_i32 s22, s22, 2
	s_addk_i32 s13, 0x100
	s_addk_i32 s21, 0x100
	s_cmp_gt_u32 s22, 29
	s_cbranch_scc0 .LBB0_2450
	s_and_b64 vcc, exec, s[64:65]
	s_cbranch_vccz .LBB0_2453
	s_barrier
